# NSA compressed-block branch rewritten by hand (row-major V + transposed LDS reads, batched bias reads, constant-bias far tiles, scalar tile addresses); also includes memory cross-attention loop rewrit
# speedup vs baseline: 1.1417x; 1.0176x over previous
; #define LAS __attribute__((address_space(3)))
; __device__ __forceinline__ void nsa_unit(LAS unsigned char* lds, const Ctx& P, int l, int b, int hkv, int tb) {
;     ...
;         f32x4 o[4], oi[4]; float m = NEGBIG, lsum = 0.f;
; #pragma unroll
;         for (int dt = 0; dt < 4; ++dt) { o[dt] = (f32x4){0.f, 0.f, 0.f, 0.f}; oi[dt] = (f32x4){0.f, 0.f, 0.f, 0.f}; }
;         bf16x8 ovA[2], ovB[2];
; #pragma unroll
;         for (int st = 0; st < 2; ++st)
; #pragma unroll
;             for (int j = 0; j < 8; ++j) { const int nl = 32 * st + (j < 4 ? 4 * i + j : 16 + 4 * i + (j - 4));
;                 float a = 0.f; if ((nl >> 2) == c) a = ((nl & 3) == 3) ? 0.5f : 1.0f; else if ((nl >> 2) == c - 1 && (nl & 3) == 3) a = 0.5f;
;                 const float bb = (c == 0 && nl == 63) ? 0.5f : 0.f;
;                 ovA[st][j] = (short)(__float_as_uint(a) >> 16); ovB[st][j] = (short)(__float_as_uint(bb) >> 16); }
;         const int ntile = ((t0 >> 4) + 2) / 64 + 1;
;         const int tqs = t0 + 32 * th + 16 * sb + c;
;         bf16x8 qs[2];
; #pragma unroll
;         for (int ks = 0; ks < 2; ++ks) qs[ks] = load_q_scaled(H + ((size_t)b * SEQ + tqs) * LDH + C_Q + hq * 64 + ks * 32 + 8 * i, 0.125f);
; #pragma unroll
;         for (int pr = 0; pr < 2; ++pr) if (2 * pr < ntile) {
;             const bool hasb = 2 * pr + 1 < ntile;
;             __syncthreads();
;             load2(KC, VC, 64, 128 * pr, 128 * pr + 64, hasb, 255);
;             __syncthreads();
; #pragma unroll
;             for (int sl = 0; sl < 2; ++sl) if (sl == 0 || hasb) {
;                 const int kt = 2 * pr + sl; const LAS bf16_t* Ks = KV + sl * 9216; const LAS bf16_t* Vt = Ks + 4608; const int nb = kt * 64;
;                 attn_step<64>(qs, Ks, Vt, o, m, lsum, alpha, pf, pf1, lane,
;                     [&](int kk, float s) { const int dist = tqs - (16 * (nb + kk) + 31); return dist >= 0 ? s * LOG2E + lut[min((unsigned)dist, 1023u)] : NEGBIG; });
.LBB0_203:
	v_add_u32_e32 v132, v150, v148
	v_lshrrev_b32_e32 v86, 2, v97
	v_lshl_add_u32 v86, v103, 2, v86
	v_mul_u32_u24_e32 v86, 0x90, v86
	v_and_b32_e32 v87, 3, v97
	v_lshl_add_u32 v133, v87, 3, v86
	v_lshlrev_b32_e32 v139, 4, v234
	ds_read_b32 v165, v131 offset:3160
	v_add_u32_e32 v86, 0, v103
	v_cmp_eq_u32_e32 vcc, v86, v97
	v_mov_b32_e32 v87, 0x3f803f80
	v_add_u32_e32 v89, 1, v86
	s_nop 1
	v_cndmask_b32_e32 v160, 0, v87, vcc
	v_mov_b32_e32 v87, 0x3f80
	v_cndmask_b32_e32 v88, 0, v87, vcc
	v_cmp_eq_u32_e64 s[0:1], v89, v97
	v_mov_b32_e32 v87, 0x3f000000
	s_or_b64 vcc, vcc, s[0:1]
	s_nop 3
	v_cndmask_b32_e32 v87, 0, v87, vcc
	v_or_b32_e32 v161, v87, v88
	v_add_u32_e32 v86, 4, v103
	v_cmp_eq_u32_e32 vcc, v86, v97
	v_mov_b32_e32 v87, 0x3f803f80
	v_add_u32_e32 v89, 1, v86
	s_nop 1
	v_cndmask_b32_e32 v162, 0, v87, vcc
	v_mov_b32_e32 v87, 0x3f80
	v_cndmask_b32_e32 v88, 0, v87, vcc
	v_cmp_eq_u32_e64 s[0:1], v89, v97
	v_mov_b32_e32 v87, 0x3f000000
	s_or_b64 vcc, vcc, s[0:1]
	s_nop 3
	v_cndmask_b32_e32 v87, 0, v87, vcc
	v_or_b32_e32 v163, v87, v88
	v_add_u32_e32 v86, 8, v103
	v_cmp_eq_u32_e32 vcc, v86, v97
	v_mov_b32_e32 v87, 0x3f803f80
	v_add_u32_e32 v89, 1, v86
	s_nop 1
	v_cndmask_b32_e32 v170, 0, v87, vcc
	v_mov_b32_e32 v87, 0x3f80
	v_cndmask_b32_e32 v88, 0, v87, vcc
	v_cmp_eq_u32_e64 s[0:1], v89, v97
	v_mov_b32_e32 v87, 0x3f000000
	s_or_b64 vcc, vcc, s[0:1]
	s_nop 3
	v_cndmask_b32_e32 v87, 0, v87, vcc
	v_or_b32_e32 v171, v87, v88
	v_add_u32_e32 v86, 12, v103
	v_cmp_eq_u32_e32 vcc, v86, v97
	v_mov_b32_e32 v87, 0x3f803f80
	v_add_u32_e32 v89, 1, v86
	s_nop 1
	v_cndmask_b32_e32 v172, 0, v87, vcc
	v_mov_b32_e32 v87, 0x3f80
	v_cndmask_b32_e32 v88, 0, v87, vcc
	v_cmp_eq_u32_e64 s[0:1], v89, v97
	v_mov_b32_e32 v87, 0x3f000000
	s_or_b64 vcc, vcc, s[0:1]
	s_nop 3
	v_cndmask_b32_e32 v87, 0, v87, vcc
	v_or_b32_e32 v173, v87, v88
	v_mov_b32_e32 v230, 0
	v_mov_b32_e32 v231, 0
	v_mov_b32_e32 v232, 0
	v_cmp_eq_u32_e32 vcc, 0, v97
	v_cmp_eq_u32_e64 s[0:1], 3, v103
	v_mov_b32_e32 v87, 0x3f000000
	s_and_b64 vcc, vcc, s[0:1]
	s_nop 3
	v_cndmask_b32_e32 v233, 0, v87, vcc
	s_lshr_b32 s26, s55, 4
	s_add_u32 s26, s26, 2
	s_lshr_b32 s26, s26, 6
	s_add_u32 s26, s26, 1
	s_mov_b64 s[24:25], -1
	s_waitcnt lgkmcnt(0)
	s_lshl_b32 s44, s61, 2
	s_or_b32 s44, s44, s60
	s_lshl_b32 s44, s44, 15
	s_add_u32 s44, s44, 0x33203000
	s_add_u32 s20, s68, s44
	s_addc_u32 s21, s69, 0
	v_mov_b32_e32 v30, 0
	v_mov_b32_e32 v46, 0
	v_mov_b32_e32 v31, 0
	v_mov_b32_e32 v47, 0
	v_mov_b32_e32 v32, 0
	v_mov_b32_e32 v48, 0
	v_mov_b32_e32 v33, 0
	v_mov_b32_e32 v49, 0
	v_mov_b32_e32 v34, 0
	v_mov_b32_e32 v50, 0
	v_mov_b32_e32 v35, 0
	v_mov_b32_e32 v51, 0
	v_mov_b32_e32 v36, 0
	v_mov_b32_e32 v52, 0
	v_mov_b32_e32 v37, 0
	v_mov_b32_e32 v53, 0
	v_mov_b32_e32 v38, 0
	v_mov_b32_e32 v54, 0
	v_mov_b32_e32 v39, 0
	v_mov_b32_e32 v55, 0
	v_mov_b32_e32 v40, 0
	v_mov_b32_e32 v56, 0
	v_mov_b32_e32 v41, 0
	v_mov_b32_e32 v57, 0
	v_mov_b32_e32 v42, 0
	v_mov_b32_e32 v58, 0
	v_mov_b32_e32 v43, 0
	v_mov_b32_e32 v59, 0
	v_mov_b32_e32 v44, 0
	v_mov_b32_e32 v60, 0
	v_mov_b32_e32 v45, 0
	v_mov_b32_e32 v61, 0
	v_mov_b32_e32 v137, 0xf149f2ca
	v_mov_b32_e32 v138, 0
	v_mov_b32_e32 v86, v139
	v_add_u32_e32 v87, 0x80000, v86
	global_load_dwordx4 v[198:201], v86, s[20:21]
	global_load_dwordx4 v[202:205], v87, s[20:21]
	s_cmp_lt_u32 s26, 2
	s_cbranch_scc1 .Lcm_lnb_2
	v_add_u32_e32 v86, 0x2000, v86
	v_add_u32_e32 v87, 0x2000, v87
	global_load_dwordx4 v[206:209], v86, s[20:21]
	global_load_dwordx4 v[210:213], v87, s[20:21]
.Lcm_lnb_2:
	s_waitcnt lgkmcnt(0)
	s_barrier
	s_waitcnt vmcnt(0)
	ds_write_b128 v146, v[198:201] offset:16384
	ds_write_b128 v146, v[202:205] offset:25600
	s_cmp_lt_u32 s26, 2
	s_cbranch_scc1 .Lcm_wnb_3
	ds_write_b128 v146, v[206:209] offset:34816
	ds_write_b128 v146, v[210:213] offset:44032
.Lcm_wnb_3:
	s_waitcnt lgkmcnt(0)
	s_barrier
	s_sub_i32 s44, s55, 0
	s_cmp_ge_i32 s44, 0x725
	s_cbranch_scc0 .Lcm_gen_4
	ds_read_b128 v[198:201], v132 offset:16384
	ds_read_b128 v[206:209], v132 offset:18688
	ds_read_b128 v[202:205], v132 offset:16448
	ds_read_b128 v[210:213], v132 offset:18752
	ds_read_b128 v[214:217], v132 offset:20992
	ds_read_b128 v[222:225], v132 offset:23296
	ds_read_b128 v[218:221], v132 offset:21056
	ds_read_b128 v[226:229], v132 offset:23360
	s_waitcnt lgkmcnt(6)
	v_mfma_f32_16x16x32_bf16 v[62:65], v[198:201], v[2:5], 0
	v_mfma_f32_16x16x32_bf16 v[66:69], v[206:209], v[2:5], 0
	s_waitcnt lgkmcnt(4)
	v_mfma_f32_16x16x32_bf16 v[62:65], v[202:205], v[6:9], v[62:65]
	v_mfma_f32_16x16x32_bf16 v[66:69], v[210:213], v[6:9], v[66:69]
	s_waitcnt lgkmcnt(2)
	v_mfma_f32_16x16x32_bf16 v[70:73], v[214:217], v[2:5], 0
	v_mfma_f32_16x16x32_bf16 v[74:77], v[222:225], v[2:5], 0
	s_waitcnt lgkmcnt(0)
; template <int D, class SF>
; __device__ __forceinline__ void attn_step(const bf16x8 (&qf)[D / 32], const LAS bf16_t* Ks, const LAS bf16_t* Vt, f32x4 (&o)[D / 16], float& m, float& lsum, float& alpha_out, bf16x8& pf0_out, bf16x8& pf1_out, const int lane, SF sf) {
;     ...
;     float mx = fmaxf(fmaxf(fmaxf(v[0], v[1]), fmaxf(v[2], v[3])), fmaxf(fmaxf(v[4], v[5]), fmaxf(v[6], v[7])));
;     mx = fmaxf(mx, fmaxf(fmaxf(fmaxf(v[8], v[9]), fmaxf(v[10], v[11])), fmaxf(fmaxf(v[12], v[13]), fmaxf(v[14], v[15]))));
;     mx = rows_max(mx);
;     const float mnew = fmaxf(m, mx);
;     const float mc = fmaxf(mnew, -1e20f);
;     const float alpha = __builtin_amdgcn_exp2f(fmaxf(m, -1e20f) - mc);
;     float p[16], rs = 0.f;
; #pragma unroll
;     for (int r = 0; r < 16; ++r) { p[r] = __builtin_amdgcn_exp2f(v[r] - mc); rs += p[r]; }
;     rs = rows_sum(rs);
;     lsum = lsum * alpha + rs; m = mnew;
;     union { u32x4 u; bf16x8 b; } pk0, pk1;
;     pk0.u.x = cvt_pk_bf16(p[0], p[1]); pk0.u.y = cvt_pk_bf16(p[2], p[3]); pk0.u.z = cvt_pk_bf16(p[4], p[5]); pk0.u.w = cvt_pk_bf16(p[6], p[7]);
;     pk1.u.x = cvt_pk_bf16(p[8], p[9]); pk1.u.y = cvt_pk_bf16(p[10], p[11]); pk1.u.z = cvt_pk_bf16(p[12], p[13]); pk1.u.w = cvt_pk_bf16(p[14], p[15]);
;     if (__builtin_amdgcn_ballot_w64(alpha != 1.0f) != 0ull) {
; #pragma unroll
;         for (int dt = 0; dt < D / 16; ++dt) o[dt] *= alpha;
;     }
; #pragma unroll
;     for (int dt = 0; dt < D / 16; ++dt) {
;         const LAS bf16_t* vp = Vt + (16 * dt + c) * 72 + 4 * i;
;         union { u32x4 u; bf16x8 b; } vf0, vf1; const u32x2 a0 = *(const LAS u32x2*)vp, a1 = *(const LAS u32x2*)(vp + 16), b0 = *(const LAS u32x2*)(vp + 32), b1 = *(const LAS u32x2*)(vp + 48);
;         vf0.u.x = a0.x; vf0.u.y = a0.y; vf0.u.z = a1.x; vf0.u.w = a1.y; vf1.u.x = b0.x; vf1.u.y = b0.y; vf1.u.z = b1.x; vf1.u.w = b1.y;
;         o[dt] = mfma16(vf0.b, pk0.b, o[dt]); o[dt] = mfma16(vf1.b, pk1.b, o[dt]);
;     }
;     alpha_out = alpha; pf0_out = pk0.b; pf1_out = pk1.b;
; __device__ __forceinline__ void nsa_unit(LAS unsigned char* lds, const Ctx& P, int l, int b, int hkv, int tb) {
;     ...
;                 attn_step<64>(qs, Ks, Vt, o, m, lsum, alpha, pf, pf1, lane,
;                     [&](int kk, float s) { const int dist = tqs - (16 * (nb + kk) + 31); return dist >= 0 ? s * LOG2E + lut[min((unsigned)dist, 1023u)] : NEGBIG; });
; #pragma unroll
	v_mfma_f32_16x16x32_bf16 v[70:73], v[218:221], v[6:9], v[70:73]
	v_mfma_f32_16x16x32_bf16 v[74:77], v[226:229], v[6:9], v[74:77]
	ds_read_b64_tr_b16 v[198:199], v133 offset:25600
	ds_read_b64_tr_b16 v[200:201], v133 offset:27904
	ds_read_b64_tr_b16 v[202:203], v133 offset:30208
	ds_read_b64_tr_b16 v[204:205], v133 offset:32512
	ds_read_b64_tr_b16 v[206:207], v133 offset:25632
	ds_read_b64_tr_b16 v[208:209], v133 offset:27936
	ds_read_b64_tr_b16 v[210:211], v133 offset:30240
	ds_read_b64_tr_b16 v[212:213], v133 offset:32544
	ds_read_b64_tr_b16 v[214:215], v133 offset:25664
	ds_read_b64_tr_b16 v[216:217], v133 offset:27968
	ds_read_b64_tr_b16 v[218:219], v133 offset:30272
	ds_read_b64_tr_b16 v[220:221], v133 offset:32576
	ds_read_b64_tr_b16 v[222:223], v133 offset:25696
	ds_read_b64_tr_b16 v[224:225], v133 offset:28000
	ds_read_b64_tr_b16 v[226:227], v133 offset:30304
	ds_read_b64_tr_b16 v[228:229], v133 offset:32608
	v_max3_f32 v86, v62, v63, v64
	v_max3_f32 v87, v65, v66, v67
	v_max3_f32 v88, v68, v69, v70
	v_max3_f32 v89, v71, v72, v73
	v_max3_f32 v91, v74, v75, v76
	v_max3_f32 v86, v86, v87, v77
	v_max3_f32 v88, v88, v89, v91
	v_max_f32_e32 v86, v86, v88
	v_mov_b32_e32 v87, v86
	s_nop 1
	v_permlane16_swap_b32_e32 v86, v87
	v_max_f32_e32 v86, v86, v87
	v_mov_b32_e32 v87, v86
	s_nop 1
	v_permlane32_swap_b32_e32 v86, v87
	v_max_f32_e32 v86, v86, v87
	v_fmamk_f32 v86, v86, 0x3fb8aa3b, v165
	v_cndmask_b32_e64 v86, v243, v86, s[24:25]
	v_max_f32_e32 v88, v137, v86
	v_max_f32_e32 v90, 0xe0ad78ec, v137
	v_max_f32_e32 v89, 0xe0ad78ec, v88
	v_sub_f32_e32 v90, v90, v89
	v_mov_b32_e32 v137, v88
	v_exp_f32_e32 v90, v90
	v_sub_f32_e32 v91, v165, v89
	v_cndmask_b32_e64 v91, v243, v91, s[24:25]
	v_fmamk_f32 v62, v62, 0x3fb8aa3b, v91
	v_fmamk_f32 v63, v63, 0x3fb8aa3b, v91
	v_fmamk_f32 v64, v64, 0x3fb8aa3b, v91
	v_fmamk_f32 v65, v65, 0x3fb8aa3b, v91
	v_exp_f32_e32 v62, v62
	v_exp_f32_e32 v63, v63
	v_exp_f32_e32 v64, v64
	v_exp_f32_e32 v65, v65
	v_fmamk_f32 v66, v66, 0x3fb8aa3b, v91
	v_fmamk_f32 v67, v67, 0x3fb8aa3b, v91
	v_fmamk_f32 v68, v68, 0x3fb8aa3b, v91
	v_fmamk_f32 v69, v69, 0x3fb8aa3b, v91
	v_exp_f32_e32 v66, v66
	v_exp_f32_e32 v67, v67
	v_exp_f32_e32 v68, v68
	v_exp_f32_e32 v69, v69
	v_fmamk_f32 v70, v70, 0x3fb8aa3b, v91
	v_fmamk_f32 v71, v71, 0x3fb8aa3b, v91
	v_fmamk_f32 v72, v72, 0x3fb8aa3b, v91
	v_fmamk_f32 v73, v73, 0x3fb8aa3b, v91
	v_exp_f32_e32 v70, v70
	v_exp_f32_e32 v71, v71
	v_exp_f32_e32 v72, v72
	v_exp_f32_e32 v73, v73
	v_fmamk_f32 v74, v74, 0x3fb8aa3b, v91
	v_fmamk_f32 v75, v75, 0x3fb8aa3b, v91
	v_fmamk_f32 v76, v76, 0x3fb8aa3b, v91
	v_fmamk_f32 v77, v77, 0x3fb8aa3b, v91
	v_exp_f32_e32 v74, v74
	v_exp_f32_e32 v75, v75
	v_exp_f32_e32 v76, v76
	v_exp_f32_e32 v77, v77
	s_nop 0
	v_add_f32_e32 v86, v62, v63
	v_add_f32_e32 v87, v64, v65
	v_add_f32_e32 v88, v66, v67
	v_add_f32_e32 v89, v68, v69
	v_add_f32_e32 v86, v86, v70
	v_add_f32_e32 v87, v87, v71
	v_add_f32_e32 v88, v88, v72
	v_add_f32_e32 v89, v89, v73
	v_add_f32_e32 v86, v86, v74
	v_add_f32_e32 v87, v87, v75
	v_add_f32_e32 v88, v88, v76
	v_add_f32_e32 v89, v89, v77
	v_add_f32_e32 v86, v86, v87
	v_add_f32_e32 v88, v88, v89
	v_add_f32_e32 v86, v86, v88
	v_cvt_pk_bf16_f32 v78, v62, v63
	v_cvt_pk_bf16_f32 v79, v64, v65
	v_cvt_pk_bf16_f32 v80, v66, v67
	v_cvt_pk_bf16_f32 v81, v68, v69
	v_cvt_pk_bf16_f32 v82, v70, v71
	v_cvt_pk_bf16_f32 v83, v72, v73
	v_cvt_pk_bf16_f32 v84, v74, v75
	v_cvt_pk_bf16_f32 v85, v76, v77
	v_mov_b32_e32 v87, v86
	s_nop 1
	v_permlane16_swap_b32_e32 v86, v87
	v_add_f32_e32 v86, v86, v87
	v_mov_b32_e32 v87, v86
	s_nop 1
	v_permlane32_swap_b32_e32 v86, v87
	v_add_f32_e32 v86, v86, v87
	v_fma_f32 v138, v138, v90, v86
	v_cmp_neq_f32_e64 s[0:1], 1.0, v90
	s_cmp_eq_u64 s[0:1], 0
	s_cbranch_scc1 .Lcm_nosc_6
	v_pk_mul_f32 v[30:31], v[30:31], v[90:91] op_sel_hi:[1,0]
	v_pk_mul_f32 v[32:33], v[32:33], v[90:91] op_sel_hi:[1,0]
	v_pk_mul_f32 v[34:35], v[34:35], v[90:91] op_sel_hi:[1,0]
	v_pk_mul_f32 v[36:37], v[36:37], v[90:91] op_sel_hi:[1,0]
	v_pk_mul_f32 v[38:39], v[38:39], v[90:91] op_sel_hi:[1,0]
	v_pk_mul_f32 v[40:41], v[40:41], v[90:91] op_sel_hi:[1,0]
	v_pk_mul_f32 v[42:43], v[42:43], v[90:91] op_sel_hi:[1,0]
	v_pk_mul_f32 v[44:45], v[44:45], v[90:91] op_sel_hi:[1,0]
	v_pk_mul_f32 v[46:47], v[46:47], v[90:91] op_sel_hi:[1,0]
	v_pk_mul_f32 v[48:49], v[48:49], v[90:91] op_sel_hi:[1,0]
	v_pk_mul_f32 v[50:51], v[50:51], v[90:91] op_sel_hi:[1,0]
	v_pk_mul_f32 v[52:53], v[52:53], v[90:91] op_sel_hi:[1,0]
	v_pk_mul_f32 v[54:55], v[54:55], v[90:91] op_sel_hi:[1,0]
	v_pk_mul_f32 v[56:57], v[56:57], v[90:91] op_sel_hi:[1,0]
	v_pk_mul_f32 v[58:59], v[58:59], v[90:91] op_sel_hi:[1,0]
	v_pk_mul_f32 v[60:61], v[60:61], v[90:91] op_sel_hi:[1,0]
.Lcm_nosc_6:
	s_waitcnt lgkmcnt(0)
	s_nop 1
	v_mfma_f32_16x16x32_bf16 v[30:33], v[198:201], v[78:81], v[30:33]
	v_mfma_f32_16x16x32_bf16 v[34:37], v[206:209], v[78:81], v[34:37]
	v_mfma_f32_16x16x32_bf16 v[38:41], v[214:217], v[78:81], v[38:41]
	v_mfma_f32_16x16x32_bf16 v[42:45], v[222:225], v[78:81], v[42:45]
	v_mfma_f32_16x16x32_bf16 v[30:33], v[202:205], v[82:85], v[30:33]
	v_mfma_f32_16x16x32_bf16 v[34:37], v[210:213], v[82:85], v[34:37]
	v_mfma_f32_16x16x32_bf16 v[38:41], v[218:221], v[82:85], v[38:41]
	v_mfma_f32_16x16x32_bf16 v[42:45], v[226:229], v[82:85], v[42:45]
	v_mfma_f32_16x16x32_bf16 v[46:49], v[160:163], v[78:81], v[46:49]
	v_mfma_f32_16x16x32_bf16 v[50:53], v[230:233], v[82:85], v[50:53]
	v_mfma_f32_16x16x32_bf16 v[46:49], v[170:173], v[82:85], v[46:49]
	s_branch .Lcm_td_5
; #define LAS __attribute__((address_space(3)))
; __device__ __forceinline__ f32x4 mfma16(bf16x8 a, bf16x8 b, f32x4 c) { return __builtin_amdgcn_mfma_f32_16x16x32_bf16(a, b, c, 0, 0, 0); }
; template <int D, class SF>
; __device__ __forceinline__ void attn_step(const bf16x8 (&qf)[D / 32], const LAS bf16_t* Ks, const LAS bf16_t* Vt, f32x4 (&o)[D / 16], float& m, float& lsum, float& alpha_out, bf16x8& pf0_out, bf16x8& pf1_out, const int lane, SF sf) {
;     ...
;     for (int ks = 0; ks < D / 32; ++ks) {
; #pragma unroll
;         for (int t = 0; t < 4; ++t) { const bf16x8 kf = *(const LAS bf16x8*)(Ks + (16 * t + c) * KSTR + ks * 32 + 8 * i); s[t] = mfma16(kf, qf[ks], s[t]); }
;     }
;     float v[16];
; #pragma unroll
;     for (int t = 0; t < 4; ++t)
; #pragma unroll
;         for (int r = 0; r < 4; ++r) v[4 * t + r] = sf(16 * t + 4 * i + r, s[t][r]);
; __device__ __forceinline__ void nsa_unit(LAS unsigned char* lds, const Ctx& P, int l, int b, int hkv, int tb) {
;     ...
;                 attn_step<64>(qs, Ks, Vt, o, m, lsum, alpha, pf, pf1, lane,
;                     [&](int kk, float s) { const int dist = tqs - (16 * (nb + kk) + 31); return dist >= 0 ? s * LOG2E + lut[min((unsigned)dist, 1023u)] : NEGBIG; });
.Lcm_gen_4:
	v_lshlrev_b32_e32 v86, 6, v103
	v_sub_u32_e32 v86, v130, v86
	v_add_u32_e32 v86, 0xffffffe1, v86
	v_subrev_u32_e32 v78, 0, v86
	v_min_u32_e32 v78, 0x3ff, v78
	v_lshl_add_u32 v78, v78, 2, v131
	ds_read_b32 v78, v78
	v_subrev_u32_e32 v79, 16, v86
	v_min_u32_e32 v79, 0x3ff, v79
	v_lshl_add_u32 v79, v79, 2, v131
	ds_read_b32 v79, v79
	v_subrev_u32_e32 v80, 32, v86
	v_min_u32_e32 v80, 0x3ff, v80
	v_lshl_add_u32 v80, v80, 2, v131
	ds_read_b32 v80, v80
	v_subrev_u32_e32 v81, 48, v86
	v_min_u32_e32 v81, 0x3ff, v81
	v_lshl_add_u32 v81, v81, 2, v131
	ds_read_b32 v81, v81
	v_subrev_u32_e32 v82, 256, v86
	v_min_u32_e32 v82, 0x3ff, v82
	v_lshl_add_u32 v82, v82, 2, v131
	ds_read_b32 v82, v82
	v_subrev_u32_e32 v83, 272, v86
	v_min_u32_e32 v83, 0x3ff, v83
	v_lshl_add_u32 v83, v83, 2, v131
	ds_read_b32 v83, v83
	v_subrev_u32_e32 v84, 288, v86
	v_min_u32_e32 v84, 0x3ff, v84
	v_lshl_add_u32 v84, v84, 2, v131
	ds_read_b32 v84, v84
	v_subrev_u32_e32 v85, 304, v86
	v_min_u32_e32 v85, 0x3ff, v85
	v_lshl_add_u32 v85, v85, 2, v131
	ds_read_b32 v85, v85
	ds_read_b128 v[198:201], v132 offset:16384
	ds_read_b128 v[206:209], v132 offset:18688
	ds_read_b128 v[202:205], v132 offset:16448
	ds_read_b128 v[210:213], v132 offset:18752
	ds_read_b128 v[214:217], v132 offset:20992
	ds_read_b128 v[222:225], v132 offset:23296
	ds_read_b128 v[218:221], v132 offset:21056
	ds_read_b128 v[226:229], v132 offset:23360
	s_waitcnt lgkmcnt(6)
	v_mfma_f32_16x16x32_bf16 v[62:65], v[198:201], v[2:5], 0
	v_mfma_f32_16x16x32_bf16 v[66:69], v[206:209], v[2:5], 0
	s_waitcnt lgkmcnt(4)
	v_mfma_f32_16x16x32_bf16 v[62:65], v[202:205], v[6:9], v[62:65]
	v_mfma_f32_16x16x32_bf16 v[66:69], v[210:213], v[6:9], v[66:69]
	s_waitcnt lgkmcnt(2)
	v_mfma_f32_16x16x32_bf16 v[70:73], v[214:217], v[2:5], 0
	v_mfma_f32_16x16x32_bf16 v[74:77], v[222:225], v[2:5], 0
	s_waitcnt lgkmcnt(0)
	v_mfma_f32_16x16x32_bf16 v[70:73], v[218:221], v[6:9], v[70:73]
	v_mfma_f32_16x16x32_bf16 v[74:77], v[226:229], v[6:9], v[74:77]
	ds_read_b64_tr_b16 v[198:199], v133 offset:25600
	ds_read_b64_tr_b16 v[200:201], v133 offset:27904
	ds_read_b64_tr_b16 v[202:203], v133 offset:30208
	ds_read_b64_tr_b16 v[204:205], v133 offset:32512
	ds_read_b64_tr_b16 v[206:207], v133 offset:25632
	ds_read_b64_tr_b16 v[208:209], v133 offset:27936
	ds_read_b64_tr_b16 v[210:211], v133 offset:30240
	v_fmamk_f32 v62, v62, 0x3fb8aa3b, v78
	v_fmamk_f32 v63, v63, 0x3fb8aa3b, v79
	v_fmamk_f32 v64, v64, 0x3fb8aa3b, v80
	v_fmamk_f32 v65, v65, 0x3fb8aa3b, v81
	v_fmamk_f32 v66, v66, 0x3fb8aa3b, v82
	v_fmamk_f32 v67, v67, 0x3fb8aa3b, v83
	v_fmamk_f32 v68, v68, 0x3fb8aa3b, v84
	v_fmamk_f32 v69, v69, 0x3fb8aa3b, v85
	v_cmp_le_i32_e32 vcc, 0, v86
	s_nop 1
	v_cndmask_b32_e32 v62, v243, v62, vcc
	v_cmp_le_i32_e32 vcc, 16, v86
	s_nop 1
	v_cndmask_b32_e32 v63, v243, v63, vcc
	v_cmp_le_i32_e32 vcc, 32, v86
	s_nop 1
	v_cndmask_b32_e32 v64, v243, v64, vcc
	v_cmp_le_i32_e32 vcc, 48, v86
	s_nop 1
	v_cndmask_b32_e32 v65, v243, v65, vcc
	v_cmp_le_i32_e32 vcc, 256, v86
	s_nop 1
	v_cndmask_b32_e32 v66, v243, v66, vcc
	v_cmp_le_i32_e32 vcc, 272, v86
	s_nop 1
	v_cndmask_b32_e32 v67, v243, v67, vcc
	v_cmp_le_i32_e32 vcc, 288, v86
	s_nop 1
	v_cndmask_b32_e32 v68, v243, v68, vcc
	v_cmp_le_i32_e32 vcc, 304, v86
	s_nop 1
	v_cndmask_b32_e32 v69, v243, v69, vcc
	v_subrev_u32_e32 v78, 512, v86
	v_min_u32_e32 v78, 0x3ff, v78
	v_lshl_add_u32 v78, v78, 2, v131
	ds_read_b32 v78, v78
	v_subrev_u32_e32 v79, 528, v86
	v_min_u32_e32 v79, 0x3ff, v79
	v_lshl_add_u32 v79, v79, 2, v131
	ds_read_b32 v79, v79
	v_subrev_u32_e32 v80, 544, v86
	v_min_u32_e32 v80, 0x3ff, v80
	v_lshl_add_u32 v80, v80, 2, v131
	ds_read_b32 v80, v80
	v_subrev_u32_e32 v81, 560, v86
	v_min_u32_e32 v81, 0x3ff, v81
	v_lshl_add_u32 v81, v81, 2, v131
	ds_read_b32 v81, v81
	v_subrev_u32_e32 v82, 768, v86
	v_min_u32_e32 v82, 0x3ff, v82
	v_lshl_add_u32 v82, v82, 2, v131
	ds_read_b32 v82, v82
	v_subrev_u32_e32 v83, 784, v86
	v_min_u32_e32 v83, 0x3ff, v83
	v_lshl_add_u32 v83, v83, 2, v131
	ds_read_b32 v83, v83
	v_subrev_u32_e32 v84, 800, v86
	v_min_u32_e32 v84, 0x3ff, v84
	v_lshl_add_u32 v84, v84, 2, v131
	ds_read_b32 v84, v84
	v_subrev_u32_e32 v85, 816, v86
	v_min_u32_e32 v85, 0x3ff, v85
	v_lshl_add_u32 v85, v85, 2, v131
	ds_read_b32 v85, v85
	ds_read_b64_tr_b16 v[212:213], v133 offset:32544
	ds_read_b64_tr_b16 v[214:215], v133 offset:25664
	ds_read_b64_tr_b16 v[216:217], v133 offset:27968
	ds_read_b64_tr_b16 v[218:219], v133 offset:30272
	ds_read_b64_tr_b16 v[220:221], v133 offset:32576
	ds_read_b64_tr_b16 v[222:223], v133 offset:25696
	ds_read_b64_tr_b16 v[224:225], v133 offset:28000
	ds_read_b64_tr_b16 v[226:227], v133 offset:30304
	ds_read_b64_tr_b16 v[228:229], v133 offset:32608
	s_waitcnt lgkmcnt(9)
; template <int D, class SF>
; __device__ __forceinline__ void attn_step(const bf16x8 (&qf)[D / 32], const LAS bf16_t* Ks, const LAS bf16_t* Vt, f32x4 (&o)[D / 16], float& m, float& lsum, float& alpha_out, bf16x8& pf0_out, bf16x8& pf1_out, const int lane, SF sf) {
;     ...
;         for (int r = 0; r < 4; ++r) v[4 * t + r] = sf(16 * t + 4 * i + r, s[t][r]);
;     float mx = fmaxf(fmaxf(fmaxf(v[0], v[1]), fmaxf(v[2], v[3])), fmaxf(fmaxf(v[4], v[5]), fmaxf(v[6], v[7])));
;     mx = fmaxf(mx, fmaxf(fmaxf(fmaxf(v[8], v[9]), fmaxf(v[10], v[11])), fmaxf(fmaxf(v[12], v[13]), fmaxf(v[14], v[15]))));
;     mx = rows_max(mx);
;     const float mnew = fmaxf(m, mx);
;     const float mc = fmaxf(mnew, -1e20f);
;     const float alpha = __builtin_amdgcn_exp2f(fmaxf(m, -1e20f) - mc);
;     float p[16], rs = 0.f;
; #pragma unroll
;     for (int r = 0; r < 16; ++r) { p[r] = __builtin_amdgcn_exp2f(v[r] - mc); rs += p[r]; }
;     rs = rows_sum(rs);
;     lsum = lsum * alpha + rs; m = mnew;
;     union { u32x4 u; bf16x8 b; } pk0, pk1;
;     pk0.u.x = cvt_pk_bf16(p[0], p[1]); pk0.u.y = cvt_pk_bf16(p[2], p[3]); pk0.u.z = cvt_pk_bf16(p[4], p[5]); pk0.u.w = cvt_pk_bf16(p[6], p[7]);
;     pk1.u.x = cvt_pk_bf16(p[8], p[9]); pk1.u.y = cvt_pk_bf16(p[10], p[11]); pk1.u.z = cvt_pk_bf16(p[12], p[13]); pk1.u.w = cvt_pk_bf16(p[14], p[15]);
;     if (__builtin_amdgcn_ballot_w64(alpha != 1.0f) != 0ull) {
; #pragma unroll
;         for (int dt = 0; dt < D / 16; ++dt) o[dt] *= alpha;
;     }
; #pragma unroll
;     for (int dt = 0; dt < D / 16; ++dt) {
;         const LAS bf16_t* vp = Vt + (16 * dt + c) * 72 + 4 * i;
;         union { u32x4 u; bf16x8 b; } vf0, vf1; const u32x2 a0 = *(const LAS u32x2*)vp, a1 = *(const LAS u32x2*)(vp + 16), b0 = *(const LAS u32x2*)(vp + 32), b1 = *(const LAS u32x2*)(vp + 48);
;         vf0.u.x = a0.x; vf0.u.y = a0.y; vf0.u.z = a1.x; vf0.u.w = a1.y; vf1.u.x = b0.x; vf1.u.y = b0.y; vf1.u.z = b1.x; vf1.u.w = b1.y;
;         o[dt] = mfma16(vf0.b, pk0.b, o[dt]); o[dt] = mfma16(vf1.b, pk1.b, o[dt]);
;     }
;     alpha_out = alpha; pf0_out = pk0.b; pf1_out = pk1.b;
; __device__ __forceinline__ void nsa_unit(LAS unsigned char* lds, const Ctx& P, int l, int b, int hkv, int tb) {
;     ...
; #pragma unroll
;                 for (int jt = 0; jt < 4; ++jt) oi[jt] *= alpha;
;                 oi[kt] = mfma16(ovA[0], pf, oi[kt]); oi[kt] = mfma16(ovA[1], pf1, oi[kt]);
	v_fmamk_f32 v70, v70, 0x3fb8aa3b, v78
	v_fmamk_f32 v71, v71, 0x3fb8aa3b, v79
	v_fmamk_f32 v72, v72, 0x3fb8aa3b, v80
	v_fmamk_f32 v73, v73, 0x3fb8aa3b, v81
	v_fmamk_f32 v74, v74, 0x3fb8aa3b, v82
	v_fmamk_f32 v75, v75, 0x3fb8aa3b, v83
	v_fmamk_f32 v76, v76, 0x3fb8aa3b, v84
	v_fmamk_f32 v77, v77, 0x3fb8aa3b, v85
	v_cmp_le_i32_e32 vcc, 512, v86
	s_nop 1
	v_cndmask_b32_e32 v70, v243, v70, vcc
	v_cmp_le_i32_e32 vcc, 528, v86
	s_nop 1
	v_cndmask_b32_e32 v71, v243, v71, vcc
	v_cmp_le_i32_e32 vcc, 544, v86
	s_nop 1
	v_cndmask_b32_e32 v72, v243, v72, vcc
	v_cmp_le_i32_e32 vcc, 560, v86
	s_nop 1
	v_cndmask_b32_e32 v73, v243, v73, vcc
	v_cmp_le_i32_e32 vcc, 768, v86
	s_nop 1
	v_cndmask_b32_e32 v74, v243, v74, vcc
	v_cmp_le_i32_e32 vcc, 784, v86
	s_nop 1
	v_cndmask_b32_e32 v75, v243, v75, vcc
	v_cmp_le_i32_e32 vcc, 800, v86
	s_nop 1
	v_cndmask_b32_e32 v76, v243, v76, vcc
	v_cmp_le_i32_e32 vcc, 816, v86
	s_nop 1
	v_cndmask_b32_e32 v77, v243, v77, vcc
	v_max3_f32 v92, v62, v63, v64
	v_max3_f32 v87, v65, v66, v67
	v_max3_f32 v88, v68, v69, v70
	v_max3_f32 v89, v71, v72, v73
	v_max3_f32 v91, v74, v75, v76
	v_max3_f32 v92, v92, v87, v77
	v_max3_f32 v88, v88, v89, v91
	v_max_f32_e32 v92, v92, v88
	v_mov_b32_e32 v87, v92
	s_nop 1
	v_permlane16_swap_b32_e32 v92, v87
	v_max_f32_e32 v92, v92, v87
	v_mov_b32_e32 v87, v92
	s_nop 1
	v_permlane32_swap_b32_e32 v92, v87
	v_max_f32_e32 v92, v92, v87
	v_max_f32_e32 v88, v137, v92
	v_max_f32_e32 v90, 0xe0ad78ec, v137
	v_max_f32_e32 v89, 0xe0ad78ec, v88
	v_sub_f32_e32 v90, v90, v89
	v_mov_b32_e32 v137, v88
	v_exp_f32_e32 v90, v90
	v_sub_f32_e32 v62, v62, v89
	v_sub_f32_e32 v63, v63, v89
	v_sub_f32_e32 v64, v64, v89
	v_sub_f32_e32 v65, v65, v89
	v_exp_f32_e32 v62, v62
	v_exp_f32_e32 v63, v63
	v_exp_f32_e32 v64, v64
	v_exp_f32_e32 v65, v65
	v_sub_f32_e32 v66, v66, v89
	v_sub_f32_e32 v67, v67, v89
	v_sub_f32_e32 v68, v68, v89
	v_sub_f32_e32 v69, v69, v89
	v_exp_f32_e32 v66, v66
	v_exp_f32_e32 v67, v67
	v_exp_f32_e32 v68, v68
	v_exp_f32_e32 v69, v69
	v_sub_f32_e32 v70, v70, v89
	v_sub_f32_e32 v71, v71, v89
	v_sub_f32_e32 v72, v72, v89
	v_sub_f32_e32 v73, v73, v89
	v_exp_f32_e32 v70, v70
	v_exp_f32_e32 v71, v71
	v_exp_f32_e32 v72, v72
	v_exp_f32_e32 v73, v73
	v_sub_f32_e32 v74, v74, v89
	v_sub_f32_e32 v75, v75, v89
	v_sub_f32_e32 v76, v76, v89
	v_sub_f32_e32 v77, v77, v89
	v_exp_f32_e32 v74, v74
	v_exp_f32_e32 v75, v75
	v_exp_f32_e32 v76, v76
	v_exp_f32_e32 v77, v77
	s_nop 0
	v_add_f32_e32 v86, v62, v63
	v_add_f32_e32 v87, v64, v65
	v_add_f32_e32 v88, v66, v67
	v_add_f32_e32 v89, v68, v69
	v_add_f32_e32 v86, v86, v70
	v_add_f32_e32 v87, v87, v71
	v_add_f32_e32 v88, v88, v72
	v_add_f32_e32 v89, v89, v73
	v_add_f32_e32 v86, v86, v74
	v_add_f32_e32 v87, v87, v75
	v_add_f32_e32 v88, v88, v76
	v_add_f32_e32 v89, v89, v77
	v_add_f32_e32 v86, v86, v87
	v_add_f32_e32 v88, v88, v89
	v_add_f32_e32 v86, v86, v88
	v_cvt_pk_bf16_f32 v78, v62, v63
	v_cvt_pk_bf16_f32 v79, v64, v65
	v_cvt_pk_bf16_f32 v80, v66, v67
	v_cvt_pk_bf16_f32 v81, v68, v69
	v_cvt_pk_bf16_f32 v82, v70, v71
	v_cvt_pk_bf16_f32 v83, v72, v73
	v_cvt_pk_bf16_f32 v84, v74, v75
	v_cvt_pk_bf16_f32 v85, v76, v77
	v_mov_b32_e32 v87, v86
	s_nop 1
	v_permlane16_swap_b32_e32 v86, v87
	v_add_f32_e32 v86, v86, v87
	v_mov_b32_e32 v87, v86
	s_nop 1
	v_permlane32_swap_b32_e32 v86, v87
	v_add_f32_e32 v86, v86, v87
	v_fma_f32 v138, v138, v90, v86
	v_cmp_neq_f32_e64 s[0:1], 1.0, v90
	s_cmp_eq_u64 s[0:1], 0
	s_cbranch_scc1 .Lcm_nosc_7
	v_pk_mul_f32 v[30:31], v[30:31], v[90:91] op_sel_hi:[1,0]
	v_pk_mul_f32 v[32:33], v[32:33], v[90:91] op_sel_hi:[1,0]
	v_pk_mul_f32 v[34:35], v[34:35], v[90:91] op_sel_hi:[1,0]
	v_pk_mul_f32 v[36:37], v[36:37], v[90:91] op_sel_hi:[1,0]
	v_pk_mul_f32 v[38:39], v[38:39], v[90:91] op_sel_hi:[1,0]
	v_pk_mul_f32 v[40:41], v[40:41], v[90:91] op_sel_hi:[1,0]
	v_pk_mul_f32 v[42:43], v[42:43], v[90:91] op_sel_hi:[1,0]
	v_pk_mul_f32 v[44:45], v[44:45], v[90:91] op_sel_hi:[1,0]
	v_pk_mul_f32 v[46:47], v[46:47], v[90:91] op_sel_hi:[1,0]
	v_pk_mul_f32 v[48:49], v[48:49], v[90:91] op_sel_hi:[1,0]
	v_pk_mul_f32 v[50:51], v[50:51], v[90:91] op_sel_hi:[1,0]
	v_pk_mul_f32 v[52:53], v[52:53], v[90:91] op_sel_hi:[1,0]
	v_pk_mul_f32 v[54:55], v[54:55], v[90:91] op_sel_hi:[1,0]
	v_pk_mul_f32 v[56:57], v[56:57], v[90:91] op_sel_hi:[1,0]
	v_pk_mul_f32 v[58:59], v[58:59], v[90:91] op_sel_hi:[1,0]
	v_pk_mul_f32 v[60:61], v[60:61], v[90:91] op_sel_hi:[1,0]
.Lcm_nosc_7:
	s_waitcnt lgkmcnt(0)
	s_nop 1
	v_mfma_f32_16x16x32_bf16 v[30:33], v[198:201], v[78:81], v[30:33]
	v_mfma_f32_16x16x32_bf16 v[34:37], v[206:209], v[78:81], v[34:37]
	v_mfma_f32_16x16x32_bf16 v[38:41], v[214:217], v[78:81], v[38:41]
	v_mfma_f32_16x16x32_bf16 v[42:45], v[222:225], v[78:81], v[42:45]
	v_mfma_f32_16x16x32_bf16 v[30:33], v[202:205], v[82:85], v[30:33]
	v_mfma_f32_16x16x32_bf16 v[34:37], v[210:213], v[82:85], v[34:37]
	v_mfma_f32_16x16x32_bf16 v[38:41], v[218:221], v[82:85], v[38:41]
	v_mfma_f32_16x16x32_bf16 v[42:45], v[226:229], v[82:85], v[42:45]
	v_mfma_f32_16x16x32_bf16 v[46:49], v[160:163], v[78:81], v[46:49]
	v_mfma_f32_16x16x32_bf16 v[50:53], v[230:233], v[82:85], v[50:53]
	v_mfma_f32_16x16x32_bf16 v[46:49], v[170:173], v[82:85], v[46:49]
; template <int D, class SF>
; __device__ __forceinline__ void attn_step(const bf16x8 (&qf)[D / 32], const LAS bf16_t* Ks, const LAS bf16_t* Vt, f32x4 (&o)[D / 16], float& m, float& lsum, float& alpha_out, bf16x8& pf0_out, bf16x8& pf1_out, const int lane, SF sf) {
;     ...
;     float mx = fmaxf(fmaxf(fmaxf(v[0], v[1]), fmaxf(v[2], v[3])), fmaxf(fmaxf(v[4], v[5]), fmaxf(v[6], v[7])));
;     mx = fmaxf(mx, fmaxf(fmaxf(fmaxf(v[8], v[9]), fmaxf(v[10], v[11])), fmaxf(fmaxf(v[12], v[13]), fmaxf(v[14], v[15]))));
;     mx = rows_max(mx);
;     const float mnew = fmaxf(m, mx);
;     const float mc = fmaxf(mnew, -1e20f);
;     const float alpha = __builtin_amdgcn_exp2f(fmaxf(m, -1e20f) - mc);
;     float p[16], rs = 0.f;
; #pragma unroll
;     for (int r = 0; r < 16; ++r) { p[r] = __builtin_amdgcn_exp2f(v[r] - mc); rs += p[r]; }
;     rs = rows_sum(rs);
;     lsum = lsum * alpha + rs; m = mnew;
;     union { u32x4 u; bf16x8 b; } pk0, pk1;
;     pk0.u.x = cvt_pk_bf16(p[0], p[1]); pk0.u.y = cvt_pk_bf16(p[2], p[3]); pk0.u.z = cvt_pk_bf16(p[4], p[5]); pk0.u.w = cvt_pk_bf16(p[6], p[7]);
;     pk1.u.x = cvt_pk_bf16(p[8], p[9]); pk1.u.y = cvt_pk_bf16(p[10], p[11]); pk1.u.z = cvt_pk_bf16(p[12], p[13]); pk1.u.w = cvt_pk_bf16(p[14], p[15]);
;     if (__builtin_amdgcn_ballot_w64(alpha != 1.0f) != 0ull) {
; #pragma unroll
;         for (int dt = 0; dt < D / 16; ++dt) o[dt] *= alpha;
;     }
; #pragma unroll
;     for (int dt = 0; dt < D / 16; ++dt) {
;         const LAS bf16_t* vp = Vt + (16 * dt + c) * 72 + 4 * i;
; __device__ __forceinline__ void nsa_unit(LAS unsigned char* lds, const Ctx& P, int l, int b, int hkv, int tb) {
;     ...
;         for (int pr = 0; pr < 2; ++pr) if (2 * pr < ntile) {
;             const bool hasb = 2 * pr + 1 < ntile;
;             __syncthreads();
;             load2(KC, VC, 64, 128 * pr, 128 * pr + 64, hasb, 255);
;             __syncthreads();
; #pragma unroll
;             for (int sl = 0; sl < 2; ++sl) if (sl == 0 || hasb) {
;                 const int kt = 2 * pr + sl; const LAS bf16_t* Ks = KV + sl * 9216; const LAS bf16_t* Vt = Ks + 4608; const int nb = kt * 64;
;                 attn_step<64>(qs, Ks, Vt, o, m, lsum, alpha, pf, pf1, lane,
;                     [&](int kk, float s) { const int dist = tqs - (16 * (nb + kk) + 31); return dist >= 0 ? s * LOG2E + lut[min((unsigned)dist, 1023u)] : NEGBIG; });
; #pragma unroll
.Lcm_td_5:
	s_cmp_lt_u32 s26, 2
	s_cbranch_scc1 .Lcm_nb_8
	s_sub_i32 s44, s55, 1024
	s_cmp_ge_i32 s44, 0x725
	s_cbranch_scc0 .Lcm_gen_9
	ds_read_b128 v[198:201], v132 offset:34816
	ds_read_b128 v[206:209], v132 offset:37120
	ds_read_b128 v[202:205], v132 offset:34880
	ds_read_b128 v[210:213], v132 offset:37184
	ds_read_b128 v[214:217], v132 offset:39424
	ds_read_b128 v[222:225], v132 offset:41728
	ds_read_b128 v[218:221], v132 offset:39488
	ds_read_b128 v[226:229], v132 offset:41792
	s_waitcnt lgkmcnt(6)
	v_mfma_f32_16x16x32_bf16 v[62:65], v[198:201], v[2:5], 0
	v_mfma_f32_16x16x32_bf16 v[66:69], v[206:209], v[2:5], 0
	s_waitcnt lgkmcnt(4)
	v_mfma_f32_16x16x32_bf16 v[62:65], v[202:205], v[6:9], v[62:65]
	v_mfma_f32_16x16x32_bf16 v[66:69], v[210:213], v[6:9], v[66:69]
	s_waitcnt lgkmcnt(2)
	v_mfma_f32_16x16x32_bf16 v[70:73], v[214:217], v[2:5], 0
	v_mfma_f32_16x16x32_bf16 v[74:77], v[222:225], v[2:5], 0
	s_waitcnt lgkmcnt(0)
	v_mfma_f32_16x16x32_bf16 v[70:73], v[218:221], v[6:9], v[70:73]
	v_mfma_f32_16x16x32_bf16 v[74:77], v[226:229], v[6:9], v[74:77]
	ds_read_b64_tr_b16 v[198:199], v133 offset:44032
	ds_read_b64_tr_b16 v[200:201], v133 offset:46336
	ds_read_b64_tr_b16 v[202:203], v133 offset:48640
	ds_read_b64_tr_b16 v[204:205], v133 offset:50944
	ds_read_b64_tr_b16 v[206:207], v133 offset:44064
	ds_read_b64_tr_b16 v[208:209], v133 offset:46368
	ds_read_b64_tr_b16 v[210:211], v133 offset:48672
	ds_read_b64_tr_b16 v[212:213], v133 offset:50976
	ds_read_b64_tr_b16 v[214:215], v133 offset:44096
	ds_read_b64_tr_b16 v[216:217], v133 offset:46400
	ds_read_b64_tr_b16 v[218:219], v133 offset:48704
	ds_read_b64_tr_b16 v[220:221], v133 offset:51008
	ds_read_b64_tr_b16 v[222:223], v133 offset:44128
	ds_read_b64_tr_b16 v[224:225], v133 offset:46432
	ds_read_b64_tr_b16 v[226:227], v133 offset:48736
	ds_read_b64_tr_b16 v[228:229], v133 offset:51040
	v_max3_f32 v86, v62, v63, v64
	v_max3_f32 v87, v65, v66, v67
	v_max3_f32 v88, v68, v69, v70
	v_max3_f32 v89, v71, v72, v73
	v_max3_f32 v91, v74, v75, v76
	v_max3_f32 v86, v86, v87, v77
	v_max3_f32 v88, v88, v89, v91
	v_max_f32_e32 v86, v86, v88
	v_mov_b32_e32 v87, v86
	s_nop 1
	v_permlane16_swap_b32_e32 v86, v87
	v_max_f32_e32 v86, v86, v87
	v_mov_b32_e32 v87, v86
	s_nop 1
	v_permlane32_swap_b32_e32 v86, v87
	v_max_f32_e32 v86, v86, v87
	v_fmamk_f32 v86, v86, 0x3fb8aa3b, v165
	v_cndmask_b32_e64 v86, v243, v86, s[24:25]
	v_max_f32_e32 v88, v137, v86
	v_max_f32_e32 v90, 0xe0ad78ec, v137
	v_max_f32_e32 v89, 0xe0ad78ec, v88
	v_sub_f32_e32 v90, v90, v89
	v_mov_b32_e32 v137, v88
	v_exp_f32_e32 v90, v90
	v_sub_f32_e32 v91, v165, v89
	v_cndmask_b32_e64 v91, v243, v91, s[24:25]
	v_fmamk_f32 v62, v62, 0x3fb8aa3b, v91
	v_fmamk_f32 v63, v63, 0x3fb8aa3b, v91
	v_fmamk_f32 v64, v64, 0x3fb8aa3b, v91
	v_fmamk_f32 v65, v65, 0x3fb8aa3b, v91
	v_exp_f32_e32 v62, v62
	v_exp_f32_e32 v63, v63
	v_exp_f32_e32 v64, v64
	v_exp_f32_e32 v65, v65
	v_fmamk_f32 v66, v66, 0x3fb8aa3b, v91
	v_fmamk_f32 v67, v67, 0x3fb8aa3b, v91
	v_fmamk_f32 v68, v68, 0x3fb8aa3b, v91
	v_fmamk_f32 v69, v69, 0x3fb8aa3b, v91
	v_exp_f32_e32 v66, v66
	v_exp_f32_e32 v67, v67
	v_exp_f32_e32 v68, v68
	v_exp_f32_e32 v69, v69
	v_fmamk_f32 v70, v70, 0x3fb8aa3b, v91
	v_fmamk_f32 v71, v71, 0x3fb8aa3b, v91
	v_fmamk_f32 v72, v72, 0x3fb8aa3b, v91
	v_fmamk_f32 v73, v73, 0x3fb8aa3b, v91
	v_exp_f32_e32 v70, v70
	v_exp_f32_e32 v71, v71
	v_exp_f32_e32 v72, v72
	v_exp_f32_e32 v73, v73
	v_fmamk_f32 v74, v74, 0x3fb8aa3b, v91
	v_fmamk_f32 v75, v75, 0x3fb8aa3b, v91
	v_fmamk_f32 v76, v76, 0x3fb8aa3b, v91
	v_fmamk_f32 v77, v77, 0x3fb8aa3b, v91
	v_exp_f32_e32 v74, v74
	v_exp_f32_e32 v75, v75
	v_exp_f32_e32 v76, v76
	v_exp_f32_e32 v77, v77
	s_nop 0
	v_add_f32_e32 v86, v62, v63
	v_add_f32_e32 v87, v64, v65
	v_add_f32_e32 v88, v66, v67
	v_add_f32_e32 v89, v68, v69
	v_add_f32_e32 v86, v86, v70
	v_add_f32_e32 v87, v87, v71
	v_add_f32_e32 v88, v88, v72
	v_add_f32_e32 v89, v89, v73
	v_add_f32_e32 v86, v86, v74
	v_add_f32_e32 v87, v87, v75
	v_add_f32_e32 v88, v88, v76
	v_add_f32_e32 v89, v89, v77
	v_add_f32_e32 v86, v86, v87
	v_add_f32_e32 v88, v88, v89
	v_add_f32_e32 v86, v86, v88
	v_cvt_pk_bf16_f32 v78, v62, v63
	v_cvt_pk_bf16_f32 v79, v64, v65
	v_cvt_pk_bf16_f32 v80, v66, v67
	v_cvt_pk_bf16_f32 v81, v68, v69
	v_cvt_pk_bf16_f32 v82, v70, v71
	v_cvt_pk_bf16_f32 v83, v72, v73
	v_cvt_pk_bf16_f32 v84, v74, v75
	v_cvt_pk_bf16_f32 v85, v76, v77
	v_mov_b32_e32 v87, v86
	s_nop 1
	v_permlane16_swap_b32_e32 v86, v87
	v_add_f32_e32 v86, v86, v87
	v_mov_b32_e32 v87, v86
	s_nop 1
	v_permlane32_swap_b32_e32 v86, v87
	v_add_f32_e32 v86, v86, v87
	v_fma_f32 v138, v138, v90, v86
	v_cmp_neq_f32_e64 s[0:1], 1.0, v90
	s_cmp_eq_u64 s[0:1], 0
	s_cbranch_scc1 .Lcm_nosc_11
	v_pk_mul_f32 v[30:31], v[30:31], v[90:91] op_sel_hi:[1,0]
	v_pk_mul_f32 v[32:33], v[32:33], v[90:91] op_sel_hi:[1,0]
	v_pk_mul_f32 v[34:35], v[34:35], v[90:91] op_sel_hi:[1,0]
	v_pk_mul_f32 v[36:37], v[36:37], v[90:91] op_sel_hi:[1,0]
	v_pk_mul_f32 v[38:39], v[38:39], v[90:91] op_sel_hi:[1,0]
	v_pk_mul_f32 v[40:41], v[40:41], v[90:91] op_sel_hi:[1,0]
	v_pk_mul_f32 v[42:43], v[42:43], v[90:91] op_sel_hi:[1,0]
	v_pk_mul_f32 v[44:45], v[44:45], v[90:91] op_sel_hi:[1,0]
	v_pk_mul_f32 v[46:47], v[46:47], v[90:91] op_sel_hi:[1,0]
	v_pk_mul_f32 v[48:49], v[48:49], v[90:91] op_sel_hi:[1,0]
	v_pk_mul_f32 v[50:51], v[50:51], v[90:91] op_sel_hi:[1,0]
	v_pk_mul_f32 v[52:53], v[52:53], v[90:91] op_sel_hi:[1,0]
	v_pk_mul_f32 v[54:55], v[54:55], v[90:91] op_sel_hi:[1,0]
	v_pk_mul_f32 v[56:57], v[56:57], v[90:91] op_sel_hi:[1,0]
	v_pk_mul_f32 v[58:59], v[58:59], v[90:91] op_sel_hi:[1,0]
	v_pk_mul_f32 v[60:61], v[60:61], v[90:91] op_sel_hi:[1,0]
; #define LAS __attribute__((address_space(3)))
; __device__ __forceinline__ f32x4 mfma16(bf16x8 a, bf16x8 b, f32x4 c) { return __builtin_amdgcn_mfma_f32_16x16x32_bf16(a, b, c, 0, 0, 0); }
; template <int D, class SF>
; __device__ __forceinline__ void attn_step(const bf16x8 (&qf)[D / 32], const LAS bf16_t* Ks, const LAS bf16_t* Vt, f32x4 (&o)[D / 16], float& m, float& lsum, float& alpha_out, bf16x8& pf0_out, bf16x8& pf1_out, const int lane, SF sf) {
;     ...
;     for (int ks = 0; ks < D / 32; ++ks) {
; #pragma unroll
;         for (int t = 0; t < 4; ++t) { const bf16x8 kf = *(const LAS bf16x8*)(Ks + (16 * t + c) * KSTR + ks * 32 + 8 * i); s[t] = mfma16(kf, qf[ks], s[t]); }
;     }
;     float v[16];
; #pragma unroll
;     for (int t = 0; t < 4; ++t)
; #pragma unroll
;         for (int r = 0; r < 4; ++r) v[4 * t + r] = sf(16 * t + 4 * i + r, s[t][r]);
; __device__ __forceinline__ void nsa_unit(LAS unsigned char* lds, const Ctx& P, int l, int b, int hkv, int tb) {
;     ...
;                 attn_step<64>(qs, Ks, Vt, o, m, lsum, alpha, pf, pf1, lane,
;                     [&](int kk, float s) { const int dist = tqs - (16 * (nb + kk) + 31); return dist >= 0 ? s * LOG2E + lut[min((unsigned)dist, 1023u)] : NEGBIG; });
; #pragma unroll
;                 for (int jt = 0; jt < 4; ++jt) oi[jt] *= alpha;
;                 oi[kt] = mfma16(ovA[0], pf, oi[kt]); oi[kt] = mfma16(ovA[1], pf1, oi[kt]);
;                 if (kt + 1 < 4) { oi[kt + 1 < 4 ? kt + 1 : 3] = mfma16(ovB[0], pf, oi[kt + 1 < 4 ? kt + 1 : 3]); oi[kt + 1 < 4 ? kt + 1 : 3] = mfma16(ovB[1], pf1, oi[kt + 1 < 4 ? kt + 1 : 3]); }
.Lcm_nosc_11:
	s_waitcnt lgkmcnt(0)
	s_nop 1
	v_mfma_f32_16x16x32_bf16 v[30:33], v[198:201], v[78:81], v[30:33]
	v_mfma_f32_16x16x32_bf16 v[34:37], v[206:209], v[78:81], v[34:37]
	v_mfma_f32_16x16x32_bf16 v[38:41], v[214:217], v[78:81], v[38:41]
	v_mfma_f32_16x16x32_bf16 v[42:45], v[222:225], v[78:81], v[42:45]
	v_mfma_f32_16x16x32_bf16 v[30:33], v[202:205], v[82:85], v[30:33]
	v_mfma_f32_16x16x32_bf16 v[34:37], v[210:213], v[82:85], v[34:37]
	v_mfma_f32_16x16x32_bf16 v[38:41], v[218:221], v[82:85], v[38:41]
	v_mfma_f32_16x16x32_bf16 v[42:45], v[226:229], v[82:85], v[42:45]
	v_mfma_f32_16x16x32_bf16 v[50:53], v[160:163], v[78:81], v[50:53]
	v_mfma_f32_16x16x32_bf16 v[54:57], v[230:233], v[82:85], v[54:57]
	v_mfma_f32_16x16x32_bf16 v[50:53], v[170:173], v[82:85], v[50:53]
	s_branch .Lcm_td_10
.Lcm_gen_9:
	v_lshlrev_b32_e32 v86, 6, v103
	v_sub_u32_e32 v86, v130, v86
	v_add_u32_e32 v86, 0xfffffbe1, v86
	v_subrev_u32_e32 v78, 0, v86
	v_min_u32_e32 v78, 0x3ff, v78
	v_lshl_add_u32 v78, v78, 2, v131
	ds_read_b32 v78, v78
	v_subrev_u32_e32 v79, 16, v86
	v_min_u32_e32 v79, 0x3ff, v79
	v_lshl_add_u32 v79, v79, 2, v131
	ds_read_b32 v79, v79
	v_subrev_u32_e32 v80, 32, v86
	v_min_u32_e32 v80, 0x3ff, v80
	v_lshl_add_u32 v80, v80, 2, v131
	ds_read_b32 v80, v80
	v_subrev_u32_e32 v81, 48, v86
	v_min_u32_e32 v81, 0x3ff, v81
	v_lshl_add_u32 v81, v81, 2, v131
	ds_read_b32 v81, v81
	v_subrev_u32_e32 v82, 256, v86
	v_min_u32_e32 v82, 0x3ff, v82
	v_lshl_add_u32 v82, v82, 2, v131
	ds_read_b32 v82, v82
	v_subrev_u32_e32 v83, 272, v86
	v_min_u32_e32 v83, 0x3ff, v83
	v_lshl_add_u32 v83, v83, 2, v131
	ds_read_b32 v83, v83
	v_subrev_u32_e32 v84, 288, v86
	v_min_u32_e32 v84, 0x3ff, v84
	v_lshl_add_u32 v84, v84, 2, v131
	ds_read_b32 v84, v84
	v_subrev_u32_e32 v85, 304, v86
	v_min_u32_e32 v85, 0x3ff, v85
	v_lshl_add_u32 v85, v85, 2, v131
	ds_read_b32 v85, v85
	ds_read_b128 v[198:201], v132 offset:34816
	ds_read_b128 v[206:209], v132 offset:37120
	ds_read_b128 v[202:205], v132 offset:34880
	ds_read_b128 v[210:213], v132 offset:37184
	ds_read_b128 v[214:217], v132 offset:39424
	ds_read_b128 v[222:225], v132 offset:41728
	ds_read_b128 v[218:221], v132 offset:39488
	ds_read_b128 v[226:229], v132 offset:41792
	s_waitcnt lgkmcnt(6)
	v_mfma_f32_16x16x32_bf16 v[62:65], v[198:201], v[2:5], 0
	v_mfma_f32_16x16x32_bf16 v[66:69], v[206:209], v[2:5], 0
	s_waitcnt lgkmcnt(4)
	v_mfma_f32_16x16x32_bf16 v[62:65], v[202:205], v[6:9], v[62:65]
	v_mfma_f32_16x16x32_bf16 v[66:69], v[210:213], v[6:9], v[66:69]
	s_waitcnt lgkmcnt(2)
	v_mfma_f32_16x16x32_bf16 v[70:73], v[214:217], v[2:5], 0
	v_mfma_f32_16x16x32_bf16 v[74:77], v[222:225], v[2:5], 0
	s_waitcnt lgkmcnt(0)
	v_mfma_f32_16x16x32_bf16 v[70:73], v[218:221], v[6:9], v[70:73]
	v_mfma_f32_16x16x32_bf16 v[74:77], v[226:229], v[6:9], v[74:77]
	ds_read_b64_tr_b16 v[198:199], v133 offset:44032
	ds_read_b64_tr_b16 v[200:201], v133 offset:46336
	ds_read_b64_tr_b16 v[202:203], v133 offset:48640
	ds_read_b64_tr_b16 v[204:205], v133 offset:50944
	ds_read_b64_tr_b16 v[206:207], v133 offset:44064
	ds_read_b64_tr_b16 v[208:209], v133 offset:46368
	ds_read_b64_tr_b16 v[210:211], v133 offset:48672
	v_fmamk_f32 v62, v62, 0x3fb8aa3b, v78
	v_fmamk_f32 v63, v63, 0x3fb8aa3b, v79
	v_fmamk_f32 v64, v64, 0x3fb8aa3b, v80
	v_fmamk_f32 v65, v65, 0x3fb8aa3b, v81
	v_fmamk_f32 v66, v66, 0x3fb8aa3b, v82
	v_fmamk_f32 v67, v67, 0x3fb8aa3b, v83
	v_fmamk_f32 v68, v68, 0x3fb8aa3b, v84
	v_fmamk_f32 v69, v69, 0x3fb8aa3b, v85
	v_cmp_le_i32_e32 vcc, 0, v86
	s_nop 1
	v_cndmask_b32_e32 v62, v243, v62, vcc
	v_cmp_le_i32_e32 vcc, 16, v86
	s_nop 1
	v_cndmask_b32_e32 v63, v243, v63, vcc
	v_cmp_le_i32_e32 vcc, 32, v86
	s_nop 1
	v_cndmask_b32_e32 v64, v243, v64, vcc
	v_cmp_le_i32_e32 vcc, 48, v86
	s_nop 1
	v_cndmask_b32_e32 v65, v243, v65, vcc
	v_cmp_le_i32_e32 vcc, 256, v86
	s_nop 1
	v_cndmask_b32_e32 v66, v243, v66, vcc
	v_cmp_le_i32_e32 vcc, 272, v86
	s_nop 1
	v_cndmask_b32_e32 v67, v243, v67, vcc
	v_cmp_le_i32_e32 vcc, 288, v86
	s_nop 1
	v_cndmask_b32_e32 v68, v243, v68, vcc
	v_cmp_le_i32_e32 vcc, 304, v86
	s_nop 1
	v_cndmask_b32_e32 v69, v243, v69, vcc
	v_subrev_u32_e32 v78, 512, v86
	v_min_u32_e32 v78, 0x3ff, v78
	v_lshl_add_u32 v78, v78, 2, v131
	ds_read_b32 v78, v78
	v_subrev_u32_e32 v79, 528, v86
	v_min_u32_e32 v79, 0x3ff, v79
	v_lshl_add_u32 v79, v79, 2, v131
	ds_read_b32 v79, v79
	v_subrev_u32_e32 v80, 544, v86
	v_min_u32_e32 v80, 0x3ff, v80
	v_lshl_add_u32 v80, v80, 2, v131
	ds_read_b32 v80, v80
	v_subrev_u32_e32 v81, 560, v86
	v_min_u32_e32 v81, 0x3ff, v81
	v_lshl_add_u32 v81, v81, 2, v131
	ds_read_b32 v81, v81
	v_subrev_u32_e32 v82, 768, v86
	v_min_u32_e32 v82, 0x3ff, v82
	v_lshl_add_u32 v82, v82, 2, v131
	ds_read_b32 v82, v82
	v_subrev_u32_e32 v83, 784, v86
	v_min_u32_e32 v83, 0x3ff, v83
	v_lshl_add_u32 v83, v83, 2, v131
	ds_read_b32 v83, v83
	v_subrev_u32_e32 v84, 800, v86
	v_min_u32_e32 v84, 0x3ff, v84
	v_lshl_add_u32 v84, v84, 2, v131
	ds_read_b32 v84, v84
	v_subrev_u32_e32 v85, 816, v86
	v_min_u32_e32 v85, 0x3ff, v85
	v_lshl_add_u32 v85, v85, 2, v131
	ds_read_b32 v85, v85
	ds_read_b64_tr_b16 v[212:213], v133 offset:50976
	ds_read_b64_tr_b16 v[214:215], v133 offset:44096
	ds_read_b64_tr_b16 v[216:217], v133 offset:46400
	ds_read_b64_tr_b16 v[218:219], v133 offset:48704
	ds_read_b64_tr_b16 v[220:221], v133 offset:51008
	ds_read_b64_tr_b16 v[222:223], v133 offset:44128
	ds_read_b64_tr_b16 v[224:225], v133 offset:46432
	ds_read_b64_tr_b16 v[226:227], v133 offset:48736
	ds_read_b64_tr_b16 v[228:229], v133 offset:51040
	s_waitcnt lgkmcnt(9)
; #define LAS __attribute__((address_space(3)))
; template <int D, class SF>
; __device__ __forceinline__ void attn_step(const bf16x8 (&qf)[D / 32], const LAS bf16_t* Ks, const LAS bf16_t* Vt, f32x4 (&o)[D / 16], float& m, float& lsum, float& alpha_out, bf16x8& pf0_out, bf16x8& pf1_out, const int lane, SF sf) {
;     ...
;         for (int r = 0; r < 4; ++r) v[4 * t + r] = sf(16 * t + 4 * i + r, s[t][r]);
;     float mx = fmaxf(fmaxf(fmaxf(v[0], v[1]), fmaxf(v[2], v[3])), fmaxf(fmaxf(v[4], v[5]), fmaxf(v[6], v[7])));
;     mx = fmaxf(mx, fmaxf(fmaxf(fmaxf(v[8], v[9]), fmaxf(v[10], v[11])), fmaxf(fmaxf(v[12], v[13]), fmaxf(v[14], v[15]))));
;     mx = rows_max(mx);
;     const float mnew = fmaxf(m, mx);
;     const float mc = fmaxf(mnew, -1e20f);
;     const float alpha = __builtin_amdgcn_exp2f(fmaxf(m, -1e20f) - mc);
;     float p[16], rs = 0.f;
; #pragma unroll
;     for (int r = 0; r < 16; ++r) { p[r] = __builtin_amdgcn_exp2f(v[r] - mc); rs += p[r]; }
;     rs = rows_sum(rs);
;     lsum = lsum * alpha + rs; m = mnew;
;     union { u32x4 u; bf16x8 b; } pk0, pk1;
;     pk0.u.x = cvt_pk_bf16(p[0], p[1]); pk0.u.y = cvt_pk_bf16(p[2], p[3]); pk0.u.z = cvt_pk_bf16(p[4], p[5]); pk0.u.w = cvt_pk_bf16(p[6], p[7]);
;     pk1.u.x = cvt_pk_bf16(p[8], p[9]); pk1.u.y = cvt_pk_bf16(p[10], p[11]); pk1.u.z = cvt_pk_bf16(p[12], p[13]); pk1.u.w = cvt_pk_bf16(p[14], p[15]);
;     if (__builtin_amdgcn_ballot_w64(alpha != 1.0f) != 0ull) {
; #pragma unroll
;         for (int dt = 0; dt < D / 16; ++dt) o[dt] *= alpha;
;     }
; #pragma unroll
;     for (int dt = 0; dt < D / 16; ++dt) {
;         const LAS bf16_t* vp = Vt + (16 * dt + c) * 72 + 4 * i;
;         union { u32x4 u; bf16x8 b; } vf0, vf1; const u32x2 a0 = *(const LAS u32x2*)vp, a1 = *(const LAS u32x2*)(vp + 16), b0 = *(const LAS u32x2*)(vp + 32), b1 = *(const LAS u32x2*)(vp + 48);
;         vf0.u.x = a0.x; vf0.u.y = a0.y; vf0.u.z = a1.x; vf0.u.w = a1.y; vf1.u.x = b0.x; vf1.u.y = b0.y; vf1.u.z = b1.x; vf1.u.w = b1.y;
;         o[dt] = mfma16(vf0.b, pk0.b, o[dt]); o[dt] = mfma16(vf1.b, pk1.b, o[dt]);
;     }
;     alpha_out = alpha; pf0_out = pk0.b; pf1_out = pk1.b;
; __device__ __forceinline__ void nsa_unit(LAS unsigned char* lds, const Ctx& P, int l, int b, int hkv, int tb) {
;     ...
;         for (int pr = 0; pr < 2; ++pr) if (2 * pr < ntile) {
;             const bool hasb = 2 * pr + 1 < ntile;
;             __syncthreads();
	v_fmamk_f32 v70, v70, 0x3fb8aa3b, v78
	v_fmamk_f32 v71, v71, 0x3fb8aa3b, v79
	v_fmamk_f32 v72, v72, 0x3fb8aa3b, v80
	v_fmamk_f32 v73, v73, 0x3fb8aa3b, v81
	v_fmamk_f32 v74, v74, 0x3fb8aa3b, v82
	v_fmamk_f32 v75, v75, 0x3fb8aa3b, v83
	v_fmamk_f32 v76, v76, 0x3fb8aa3b, v84
	v_fmamk_f32 v77, v77, 0x3fb8aa3b, v85
	v_cmp_le_i32_e32 vcc, 512, v86
	s_nop 1
	v_cndmask_b32_e32 v70, v243, v70, vcc
	v_cmp_le_i32_e32 vcc, 528, v86
	s_nop 1
	v_cndmask_b32_e32 v71, v243, v71, vcc
	v_cmp_le_i32_e32 vcc, 544, v86
	s_nop 1
	v_cndmask_b32_e32 v72, v243, v72, vcc
	v_cmp_le_i32_e32 vcc, 560, v86
	s_nop 1
	v_cndmask_b32_e32 v73, v243, v73, vcc
	v_cmp_le_i32_e32 vcc, 768, v86
	s_nop 1
	v_cndmask_b32_e32 v74, v243, v74, vcc
	v_cmp_le_i32_e32 vcc, 784, v86
	s_nop 1
	v_cndmask_b32_e32 v75, v243, v75, vcc
	v_cmp_le_i32_e32 vcc, 800, v86
	s_nop 1
	v_cndmask_b32_e32 v76, v243, v76, vcc
	v_cmp_le_i32_e32 vcc, 816, v86
	s_nop 1
	v_cndmask_b32_e32 v77, v243, v77, vcc
	v_max3_f32 v92, v62, v63, v64
	v_max3_f32 v87, v65, v66, v67
	v_max3_f32 v88, v68, v69, v70
	v_max3_f32 v89, v71, v72, v73
	v_max3_f32 v91, v74, v75, v76
	v_max3_f32 v92, v92, v87, v77
	v_max3_f32 v88, v88, v89, v91
	v_max_f32_e32 v92, v92, v88
	v_mov_b32_e32 v87, v92
	s_nop 1
	v_permlane16_swap_b32_e32 v92, v87
	v_max_f32_e32 v92, v92, v87
	v_mov_b32_e32 v87, v92
	s_nop 1
	v_permlane32_swap_b32_e32 v92, v87
	v_max_f32_e32 v92, v92, v87
	v_max_f32_e32 v88, v137, v92
	v_max_f32_e32 v90, 0xe0ad78ec, v137
	v_max_f32_e32 v89, 0xe0ad78ec, v88
	v_sub_f32_e32 v90, v90, v89
	v_mov_b32_e32 v137, v88
	v_exp_f32_e32 v90, v90
	v_sub_f32_e32 v62, v62, v89
	v_sub_f32_e32 v63, v63, v89
	v_sub_f32_e32 v64, v64, v89
	v_sub_f32_e32 v65, v65, v89
	v_exp_f32_e32 v62, v62
	v_exp_f32_e32 v63, v63
	v_exp_f32_e32 v64, v64
	v_exp_f32_e32 v65, v65
	v_sub_f32_e32 v66, v66, v89
	v_sub_f32_e32 v67, v67, v89
	v_sub_f32_e32 v68, v68, v89
	v_sub_f32_e32 v69, v69, v89
	v_exp_f32_e32 v66, v66
	v_exp_f32_e32 v67, v67
	v_exp_f32_e32 v68, v68
	v_exp_f32_e32 v69, v69
	v_sub_f32_e32 v70, v70, v89
	v_sub_f32_e32 v71, v71, v89
	v_sub_f32_e32 v72, v72, v89
	v_sub_f32_e32 v73, v73, v89
	v_exp_f32_e32 v70, v70
	v_exp_f32_e32 v71, v71
	v_exp_f32_e32 v72, v72
	v_exp_f32_e32 v73, v73
	v_sub_f32_e32 v74, v74, v89
	v_sub_f32_e32 v75, v75, v89
	v_sub_f32_e32 v76, v76, v89
	v_sub_f32_e32 v77, v77, v89
	v_exp_f32_e32 v74, v74
	v_exp_f32_e32 v75, v75
	v_exp_f32_e32 v76, v76
	v_exp_f32_e32 v77, v77
	s_nop 0
	v_add_f32_e32 v86, v62, v63
	v_add_f32_e32 v87, v64, v65
	v_add_f32_e32 v88, v66, v67
	v_add_f32_e32 v89, v68, v69
	v_add_f32_e32 v86, v86, v70
	v_add_f32_e32 v87, v87, v71
	v_add_f32_e32 v88, v88, v72
	v_add_f32_e32 v89, v89, v73
	v_add_f32_e32 v86, v86, v74
	v_add_f32_e32 v87, v87, v75
	v_add_f32_e32 v88, v88, v76
	v_add_f32_e32 v89, v89, v77
	v_add_f32_e32 v86, v86, v87
	v_add_f32_e32 v88, v88, v89
	v_add_f32_e32 v86, v86, v88
	v_cvt_pk_bf16_f32 v78, v62, v63
	v_cvt_pk_bf16_f32 v79, v64, v65
	v_cvt_pk_bf16_f32 v80, v66, v67
	v_cvt_pk_bf16_f32 v81, v68, v69
	v_cvt_pk_bf16_f32 v82, v70, v71
	v_cvt_pk_bf16_f32 v83, v72, v73
	v_cvt_pk_bf16_f32 v84, v74, v75
	v_cvt_pk_bf16_f32 v85, v76, v77
	v_mov_b32_e32 v87, v86
	s_nop 1
	v_permlane16_swap_b32_e32 v86, v87
	v_add_f32_e32 v86, v86, v87
	v_mov_b32_e32 v87, v86
	s_nop 1
	v_permlane32_swap_b32_e32 v86, v87
	v_add_f32_e32 v86, v86, v87
	v_fma_f32 v138, v138, v90, v86
	v_cmp_neq_f32_e64 s[0:1], 1.0, v90
	s_cmp_eq_u64 s[0:1], 0
	s_cbranch_scc1 .Lcm_nosc_12
	v_pk_mul_f32 v[30:31], v[30:31], v[90:91] op_sel_hi:[1,0]
	v_pk_mul_f32 v[32:33], v[32:33], v[90:91] op_sel_hi:[1,0]
	v_pk_mul_f32 v[34:35], v[34:35], v[90:91] op_sel_hi:[1,0]
	v_pk_mul_f32 v[36:37], v[36:37], v[90:91] op_sel_hi:[1,0]
	v_pk_mul_f32 v[38:39], v[38:39], v[90:91] op_sel_hi:[1,0]
	v_pk_mul_f32 v[40:41], v[40:41], v[90:91] op_sel_hi:[1,0]
	v_pk_mul_f32 v[42:43], v[42:43], v[90:91] op_sel_hi:[1,0]
	v_pk_mul_f32 v[44:45], v[44:45], v[90:91] op_sel_hi:[1,0]
	v_pk_mul_f32 v[46:47], v[46:47], v[90:91] op_sel_hi:[1,0]
	v_pk_mul_f32 v[48:49], v[48:49], v[90:91] op_sel_hi:[1,0]
	v_pk_mul_f32 v[50:51], v[50:51], v[90:91] op_sel_hi:[1,0]
	v_pk_mul_f32 v[52:53], v[52:53], v[90:91] op_sel_hi:[1,0]
	v_pk_mul_f32 v[54:55], v[54:55], v[90:91] op_sel_hi:[1,0]
	v_pk_mul_f32 v[56:57], v[56:57], v[90:91] op_sel_hi:[1,0]
	v_pk_mul_f32 v[58:59], v[58:59], v[90:91] op_sel_hi:[1,0]
	v_pk_mul_f32 v[60:61], v[60:61], v[90:91] op_sel_hi:[1,0]
.Lcm_nosc_12:
	s_waitcnt lgkmcnt(0)
	s_nop 1
	v_mfma_f32_16x16x32_bf16 v[30:33], v[198:201], v[78:81], v[30:33]
	v_mfma_f32_16x16x32_bf16 v[34:37], v[206:209], v[78:81], v[34:37]
	v_mfma_f32_16x16x32_bf16 v[38:41], v[214:217], v[78:81], v[38:41]
	v_mfma_f32_16x16x32_bf16 v[42:45], v[222:225], v[78:81], v[42:45]
	v_mfma_f32_16x16x32_bf16 v[30:33], v[202:205], v[82:85], v[30:33]
	v_mfma_f32_16x16x32_bf16 v[34:37], v[210:213], v[82:85], v[34:37]
	v_mfma_f32_16x16x32_bf16 v[38:41], v[218:221], v[82:85], v[38:41]
	v_mfma_f32_16x16x32_bf16 v[42:45], v[226:229], v[82:85], v[42:45]
	v_mfma_f32_16x16x32_bf16 v[50:53], v[160:163], v[78:81], v[50:53]
	v_mfma_f32_16x16x32_bf16 v[54:57], v[230:233], v[82:85], v[54:57]
	v_mfma_f32_16x16x32_bf16 v[50:53], v[170:173], v[82:85], v[50:53]
.Lcm_td_10:
.Lcm_nb_8:
	s_cmp_lt_u32 s26, 3
	s_cbranch_scc1 .Lcm_fin_1
	v_add_u32_e32 v86, 0x4000, v139
	v_add_u32_e32 v87, 0x80000, v86
	global_load_dwordx4 v[198:201], v86, s[20:21]
	global_load_dwordx4 v[202:205], v87, s[20:21]
	s_cmp_lt_u32 s26, 4
	s_cbranch_scc1 .Lcm_lnb_13
	v_add_u32_e32 v86, 0x2000, v86
	v_add_u32_e32 v87, 0x2000, v87
	global_load_dwordx4 v[206:209], v86, s[20:21]
	global_load_dwordx4 v[210:213], v87, s[20:21]
; #define LAS __attribute__((address_space(3)))
; __device__ __forceinline__ void nsa_unit(LAS unsigned char* lds, const Ctx& P, int l, int b, int hkv, int tb) {
;     ...
;         for (int pr = 0; pr < 2; ++pr) if (2 * pr < ntile) {
;             const bool hasb = 2 * pr + 1 < ntile;
;             __syncthreads();
;             load2(KC, VC, 64, 128 * pr, 128 * pr + 64, hasb, 255);
;             __syncthreads();
; #pragma unroll
;             for (int sl = 0; sl < 2; ++sl) if (sl == 0 || hasb) {
;                 const int kt = 2 * pr + sl; const LAS bf16_t* Ks = KV + sl * 9216; const LAS bf16_t* Vt = Ks + 4608; const int nb = kt * 64;
;                 attn_step<64>(qs, Ks, Vt, o, m, lsum, alpha, pf, pf1, lane,
;                     [&](int kk, float s) { const int dist = tqs - (16 * (nb + kk) + 31); return dist >= 0 ? s * LOG2E + lut[min((unsigned)dist, 1023u)] : NEGBIG; });
; #pragma unroll
.Lcm_lnb_13:
	s_waitcnt lgkmcnt(0)
	s_barrier
	s_waitcnt vmcnt(0)
	ds_write_b128 v146, v[198:201] offset:16384
	ds_write_b128 v146, v[202:205] offset:25600
	s_cmp_lt_u32 s26, 4
	s_cbranch_scc1 .Lcm_wnb_14
	ds_write_b128 v146, v[206:209] offset:34816
	ds_write_b128 v146, v[210:213] offset:44032
.Lcm_wnb_14:
	s_waitcnt lgkmcnt(0)
	s_barrier
	s_sub_i32 s44, s55, 2048
	s_cmp_ge_i32 s44, 0x725
	s_cbranch_scc0 .Lcm_gen_15
	ds_read_b128 v[198:201], v132 offset:16384
	ds_read_b128 v[206:209], v132 offset:18688
	ds_read_b128 v[202:205], v132 offset:16448
	ds_read_b128 v[210:213], v132 offset:18752
	ds_read_b128 v[214:217], v132 offset:20992
	ds_read_b128 v[222:225], v132 offset:23296
	ds_read_b128 v[218:221], v132 offset:21056
	ds_read_b128 v[226:229], v132 offset:23360
	s_waitcnt lgkmcnt(6)
	v_mfma_f32_16x16x32_bf16 v[62:65], v[198:201], v[2:5], 0
	v_mfma_f32_16x16x32_bf16 v[66:69], v[206:209], v[2:5], 0
	s_waitcnt lgkmcnt(4)
	v_mfma_f32_16x16x32_bf16 v[62:65], v[202:205], v[6:9], v[62:65]
	v_mfma_f32_16x16x32_bf16 v[66:69], v[210:213], v[6:9], v[66:69]
	s_waitcnt lgkmcnt(2)
	v_mfma_f32_16x16x32_bf16 v[70:73], v[214:217], v[2:5], 0
	v_mfma_f32_16x16x32_bf16 v[74:77], v[222:225], v[2:5], 0
	s_waitcnt lgkmcnt(0)
	v_mfma_f32_16x16x32_bf16 v[70:73], v[218:221], v[6:9], v[70:73]
	v_mfma_f32_16x16x32_bf16 v[74:77], v[226:229], v[6:9], v[74:77]
	ds_read_b64_tr_b16 v[198:199], v133 offset:25600
	ds_read_b64_tr_b16 v[200:201], v133 offset:27904
	ds_read_b64_tr_b16 v[202:203], v133 offset:30208
	ds_read_b64_tr_b16 v[204:205], v133 offset:32512
	ds_read_b64_tr_b16 v[206:207], v133 offset:25632
	ds_read_b64_tr_b16 v[208:209], v133 offset:27936
	ds_read_b64_tr_b16 v[210:211], v133 offset:30240
	ds_read_b64_tr_b16 v[212:213], v133 offset:32544
	ds_read_b64_tr_b16 v[214:215], v133 offset:25664
	ds_read_b64_tr_b16 v[216:217], v133 offset:27968
	ds_read_b64_tr_b16 v[218:219], v133 offset:30272
	ds_read_b64_tr_b16 v[220:221], v133 offset:32576
	ds_read_b64_tr_b16 v[222:223], v133 offset:25696
	ds_read_b64_tr_b16 v[224:225], v133 offset:28000
	ds_read_b64_tr_b16 v[226:227], v133 offset:30304
	ds_read_b64_tr_b16 v[228:229], v133 offset:32608
	v_max3_f32 v86, v62, v63, v64
	v_max3_f32 v87, v65, v66, v67
	v_max3_f32 v88, v68, v69, v70
	v_max3_f32 v89, v71, v72, v73
	v_max3_f32 v91, v74, v75, v76
	v_max3_f32 v86, v86, v87, v77
	v_max3_f32 v88, v88, v89, v91
	v_max_f32_e32 v86, v86, v88
	v_mov_b32_e32 v87, v86
	s_nop 1
	v_permlane16_swap_b32_e32 v86, v87
	v_max_f32_e32 v86, v86, v87
	v_mov_b32_e32 v87, v86
	s_nop 1
	v_permlane32_swap_b32_e32 v86, v87
	v_max_f32_e32 v86, v86, v87
	v_fmamk_f32 v86, v86, 0x3fb8aa3b, v165
	v_cndmask_b32_e64 v86, v243, v86, s[24:25]
	v_max_f32_e32 v88, v137, v86
	v_max_f32_e32 v90, 0xe0ad78ec, v137
	v_max_f32_e32 v89, 0xe0ad78ec, v88
	v_sub_f32_e32 v90, v90, v89
	v_mov_b32_e32 v137, v88
	v_exp_f32_e32 v90, v90
	v_sub_f32_e32 v91, v165, v89
	v_cndmask_b32_e64 v91, v243, v91, s[24:25]
	v_fmamk_f32 v62, v62, 0x3fb8aa3b, v91
	v_fmamk_f32 v63, v63, 0x3fb8aa3b, v91
	v_fmamk_f32 v64, v64, 0x3fb8aa3b, v91
	v_fmamk_f32 v65, v65, 0x3fb8aa3b, v91
	v_exp_f32_e32 v62, v62
	v_exp_f32_e32 v63, v63
	v_exp_f32_e32 v64, v64
	v_exp_f32_e32 v65, v65
	v_fmamk_f32 v66, v66, 0x3fb8aa3b, v91
	v_fmamk_f32 v67, v67, 0x3fb8aa3b, v91
	v_fmamk_f32 v68, v68, 0x3fb8aa3b, v91
	v_fmamk_f32 v69, v69, 0x3fb8aa3b, v91
	v_exp_f32_e32 v66, v66
	v_exp_f32_e32 v67, v67
	v_exp_f32_e32 v68, v68
	v_exp_f32_e32 v69, v69
	v_fmamk_f32 v70, v70, 0x3fb8aa3b, v91
	v_fmamk_f32 v71, v71, 0x3fb8aa3b, v91
	v_fmamk_f32 v72, v72, 0x3fb8aa3b, v91
	v_fmamk_f32 v73, v73, 0x3fb8aa3b, v91
	v_exp_f32_e32 v70, v70
	v_exp_f32_e32 v71, v71
	v_exp_f32_e32 v72, v72
	v_exp_f32_e32 v73, v73
	v_fmamk_f32 v74, v74, 0x3fb8aa3b, v91
	v_fmamk_f32 v75, v75, 0x3fb8aa3b, v91
	v_fmamk_f32 v76, v76, 0x3fb8aa3b, v91
	v_fmamk_f32 v77, v77, 0x3fb8aa3b, v91
	v_exp_f32_e32 v74, v74
	v_exp_f32_e32 v75, v75
	v_exp_f32_e32 v76, v76
	v_exp_f32_e32 v77, v77
	s_nop 0
	v_add_f32_e32 v86, v62, v63
	v_add_f32_e32 v87, v64, v65
	v_add_f32_e32 v88, v66, v67
	v_add_f32_e32 v89, v68, v69
	v_add_f32_e32 v86, v86, v70
	v_add_f32_e32 v87, v87, v71
	v_add_f32_e32 v88, v88, v72
	v_add_f32_e32 v89, v89, v73
	v_add_f32_e32 v86, v86, v74
	v_add_f32_e32 v87, v87, v75
	v_add_f32_e32 v88, v88, v76
	v_add_f32_e32 v89, v89, v77
	v_add_f32_e32 v86, v86, v87
	v_add_f32_e32 v88, v88, v89
	v_add_f32_e32 v86, v86, v88
	v_cvt_pk_bf16_f32 v78, v62, v63
	v_cvt_pk_bf16_f32 v79, v64, v65
	v_cvt_pk_bf16_f32 v80, v66, v67
	v_cvt_pk_bf16_f32 v81, v68, v69
	v_cvt_pk_bf16_f32 v82, v70, v71
	v_cvt_pk_bf16_f32 v83, v72, v73
	v_cvt_pk_bf16_f32 v84, v74, v75
	v_cvt_pk_bf16_f32 v85, v76, v77
	v_mov_b32_e32 v87, v86
	s_nop 1
	v_permlane16_swap_b32_e32 v86, v87
	v_add_f32_e32 v86, v86, v87
	v_mov_b32_e32 v87, v86
	s_nop 1
	v_permlane32_swap_b32_e32 v86, v87
	v_add_f32_e32 v86, v86, v87
	v_fma_f32 v138, v138, v90, v86
	v_cmp_neq_f32_e64 s[0:1], 1.0, v90
	s_cmp_eq_u64 s[0:1], 0
	s_cbranch_scc1 .Lcm_nosc_17
	v_pk_mul_f32 v[30:31], v[30:31], v[90:91] op_sel_hi:[1,0]
	v_pk_mul_f32 v[32:33], v[32:33], v[90:91] op_sel_hi:[1,0]
	v_pk_mul_f32 v[34:35], v[34:35], v[90:91] op_sel_hi:[1,0]
	v_pk_mul_f32 v[36:37], v[36:37], v[90:91] op_sel_hi:[1,0]
	v_pk_mul_f32 v[38:39], v[38:39], v[90:91] op_sel_hi:[1,0]
	v_pk_mul_f32 v[40:41], v[40:41], v[90:91] op_sel_hi:[1,0]
	v_pk_mul_f32 v[42:43], v[42:43], v[90:91] op_sel_hi:[1,0]
	v_pk_mul_f32 v[44:45], v[44:45], v[90:91] op_sel_hi:[1,0]
	v_pk_mul_f32 v[46:47], v[46:47], v[90:91] op_sel_hi:[1,0]
	v_pk_mul_f32 v[48:49], v[48:49], v[90:91] op_sel_hi:[1,0]
	v_pk_mul_f32 v[50:51], v[50:51], v[90:91] op_sel_hi:[1,0]
	v_pk_mul_f32 v[52:53], v[52:53], v[90:91] op_sel_hi:[1,0]
	v_pk_mul_f32 v[54:55], v[54:55], v[90:91] op_sel_hi:[1,0]
	v_pk_mul_f32 v[56:57], v[56:57], v[90:91] op_sel_hi:[1,0]
	v_pk_mul_f32 v[58:59], v[58:59], v[90:91] op_sel_hi:[1,0]
	v_pk_mul_f32 v[60:61], v[60:61], v[90:91] op_sel_hi:[1,0]
; #define LAS __attribute__((address_space(3)))
; __device__ __forceinline__ f32x4 mfma16(bf16x8 a, bf16x8 b, f32x4 c) { return __builtin_amdgcn_mfma_f32_16x16x32_bf16(a, b, c, 0, 0, 0); }
; template <int D, class SF>
; __device__ __forceinline__ void attn_step(const bf16x8 (&qf)[D / 32], const LAS bf16_t* Ks, const LAS bf16_t* Vt, f32x4 (&o)[D / 16], float& m, float& lsum, float& alpha_out, bf16x8& pf0_out, bf16x8& pf1_out, const int lane, SF sf) {
;     ...
;     for (int ks = 0; ks < D / 32; ++ks) {
; #pragma unroll
;         for (int t = 0; t < 4; ++t) { const bf16x8 kf = *(const LAS bf16x8*)(Ks + (16 * t + c) * KSTR + ks * 32 + 8 * i); s[t] = mfma16(kf, qf[ks], s[t]); }
;     }
;     float v[16];
; #pragma unroll
;     for (int t = 0; t < 4; ++t)
; #pragma unroll
;         for (int r = 0; r < 4; ++r) v[4 * t + r] = sf(16 * t + 4 * i + r, s[t][r]);
; __device__ __forceinline__ void nsa_unit(LAS unsigned char* lds, const Ctx& P, int l, int b, int hkv, int tb) {
;     ...
;                 attn_step<64>(qs, Ks, Vt, o, m, lsum, alpha, pf, pf1, lane,
;                     [&](int kk, float s) { const int dist = tqs - (16 * (nb + kk) + 31); return dist >= 0 ? s * LOG2E + lut[min((unsigned)dist, 1023u)] : NEGBIG; });
; #pragma unroll
;                 for (int jt = 0; jt < 4; ++jt) oi[jt] *= alpha;
;                 oi[kt] = mfma16(ovA[0], pf, oi[kt]); oi[kt] = mfma16(ovA[1], pf1, oi[kt]);
;                 if (kt + 1 < 4) { oi[kt + 1 < 4 ? kt + 1 : 3] = mfma16(ovB[0], pf, oi[kt + 1 < 4 ? kt + 1 : 3]); oi[kt + 1 < 4 ? kt + 1 : 3] = mfma16(ovB[1], pf1, oi[kt + 1 < 4 ? kt + 1 : 3]); }
.Lcm_nosc_17:
	s_waitcnt lgkmcnt(0)
	s_nop 1
	v_mfma_f32_16x16x32_bf16 v[30:33], v[198:201], v[78:81], v[30:33]
	v_mfma_f32_16x16x32_bf16 v[34:37], v[206:209], v[78:81], v[34:37]
	v_mfma_f32_16x16x32_bf16 v[38:41], v[214:217], v[78:81], v[38:41]
	v_mfma_f32_16x16x32_bf16 v[42:45], v[222:225], v[78:81], v[42:45]
	v_mfma_f32_16x16x32_bf16 v[30:33], v[202:205], v[82:85], v[30:33]
	v_mfma_f32_16x16x32_bf16 v[34:37], v[210:213], v[82:85], v[34:37]
	v_mfma_f32_16x16x32_bf16 v[38:41], v[218:221], v[82:85], v[38:41]
	v_mfma_f32_16x16x32_bf16 v[42:45], v[226:229], v[82:85], v[42:45]
	v_mfma_f32_16x16x32_bf16 v[54:57], v[160:163], v[78:81], v[54:57]
	v_mfma_f32_16x16x32_bf16 v[58:61], v[230:233], v[82:85], v[58:61]
	v_mfma_f32_16x16x32_bf16 v[54:57], v[170:173], v[82:85], v[54:57]
	s_branch .Lcm_td_16
.Lcm_gen_15:
	v_lshlrev_b32_e32 v86, 6, v103
	v_sub_u32_e32 v86, v130, v86
	v_add_u32_e32 v86, 0xfffff7e1, v86
	v_subrev_u32_e32 v78, 0, v86
	v_min_u32_e32 v78, 0x3ff, v78
	v_lshl_add_u32 v78, v78, 2, v131
	ds_read_b32 v78, v78
	v_subrev_u32_e32 v79, 16, v86
	v_min_u32_e32 v79, 0x3ff, v79
	v_lshl_add_u32 v79, v79, 2, v131
	ds_read_b32 v79, v79
	v_subrev_u32_e32 v80, 32, v86
	v_min_u32_e32 v80, 0x3ff, v80
	v_lshl_add_u32 v80, v80, 2, v131
	ds_read_b32 v80, v80
	v_subrev_u32_e32 v81, 48, v86
	v_min_u32_e32 v81, 0x3ff, v81
	v_lshl_add_u32 v81, v81, 2, v131
	ds_read_b32 v81, v81
	v_subrev_u32_e32 v82, 256, v86
	v_min_u32_e32 v82, 0x3ff, v82
	v_lshl_add_u32 v82, v82, 2, v131
	ds_read_b32 v82, v82
	v_subrev_u32_e32 v83, 272, v86
	v_min_u32_e32 v83, 0x3ff, v83
	v_lshl_add_u32 v83, v83, 2, v131
	ds_read_b32 v83, v83
	v_subrev_u32_e32 v84, 288, v86
	v_min_u32_e32 v84, 0x3ff, v84
	v_lshl_add_u32 v84, v84, 2, v131
	ds_read_b32 v84, v84
	v_subrev_u32_e32 v85, 304, v86
	v_min_u32_e32 v85, 0x3ff, v85
	v_lshl_add_u32 v85, v85, 2, v131
	ds_read_b32 v85, v85
	ds_read_b128 v[198:201], v132 offset:16384
	ds_read_b128 v[206:209], v132 offset:18688
	ds_read_b128 v[202:205], v132 offset:16448
	ds_read_b128 v[210:213], v132 offset:18752
	ds_read_b128 v[214:217], v132 offset:20992
	ds_read_b128 v[222:225], v132 offset:23296
	ds_read_b128 v[218:221], v132 offset:21056
	ds_read_b128 v[226:229], v132 offset:23360
	s_waitcnt lgkmcnt(6)
	v_mfma_f32_16x16x32_bf16 v[62:65], v[198:201], v[2:5], 0
	v_mfma_f32_16x16x32_bf16 v[66:69], v[206:209], v[2:5], 0
	s_waitcnt lgkmcnt(4)
	v_mfma_f32_16x16x32_bf16 v[62:65], v[202:205], v[6:9], v[62:65]
	v_mfma_f32_16x16x32_bf16 v[66:69], v[210:213], v[6:9], v[66:69]
	s_waitcnt lgkmcnt(2)
	v_mfma_f32_16x16x32_bf16 v[70:73], v[214:217], v[2:5], 0
	v_mfma_f32_16x16x32_bf16 v[74:77], v[222:225], v[2:5], 0
	s_waitcnt lgkmcnt(0)
	v_mfma_f32_16x16x32_bf16 v[70:73], v[218:221], v[6:9], v[70:73]
	v_mfma_f32_16x16x32_bf16 v[74:77], v[226:229], v[6:9], v[74:77]
	ds_read_b64_tr_b16 v[198:199], v133 offset:25600
	ds_read_b64_tr_b16 v[200:201], v133 offset:27904
	ds_read_b64_tr_b16 v[202:203], v133 offset:30208
	ds_read_b64_tr_b16 v[204:205], v133 offset:32512
	ds_read_b64_tr_b16 v[206:207], v133 offset:25632
	ds_read_b64_tr_b16 v[208:209], v133 offset:27936
	ds_read_b64_tr_b16 v[210:211], v133 offset:30240
	v_fmamk_f32 v62, v62, 0x3fb8aa3b, v78
	v_fmamk_f32 v63, v63, 0x3fb8aa3b, v79
	v_fmamk_f32 v64, v64, 0x3fb8aa3b, v80
	v_fmamk_f32 v65, v65, 0x3fb8aa3b, v81
	v_fmamk_f32 v66, v66, 0x3fb8aa3b, v82
	v_fmamk_f32 v67, v67, 0x3fb8aa3b, v83
	v_fmamk_f32 v68, v68, 0x3fb8aa3b, v84
	v_fmamk_f32 v69, v69, 0x3fb8aa3b, v85
	v_cmp_le_i32_e32 vcc, 0, v86
	s_nop 1
	v_cndmask_b32_e32 v62, v243, v62, vcc
	v_cmp_le_i32_e32 vcc, 16, v86
	s_nop 1
	v_cndmask_b32_e32 v63, v243, v63, vcc
	v_cmp_le_i32_e32 vcc, 32, v86
	s_nop 1
	v_cndmask_b32_e32 v64, v243, v64, vcc
	v_cmp_le_i32_e32 vcc, 48, v86
	s_nop 1
	v_cndmask_b32_e32 v65, v243, v65, vcc
	v_cmp_le_i32_e32 vcc, 256, v86
	s_nop 1
	v_cndmask_b32_e32 v66, v243, v66, vcc
	v_cmp_le_i32_e32 vcc, 272, v86
	s_nop 1
	v_cndmask_b32_e32 v67, v243, v67, vcc
	v_cmp_le_i32_e32 vcc, 288, v86
	s_nop 1
	v_cndmask_b32_e32 v68, v243, v68, vcc
	v_cmp_le_i32_e32 vcc, 304, v86
	s_nop 1
	v_cndmask_b32_e32 v69, v243, v69, vcc
	v_subrev_u32_e32 v78, 512, v86
	v_min_u32_e32 v78, 0x3ff, v78
	v_lshl_add_u32 v78, v78, 2, v131
	ds_read_b32 v78, v78
	v_subrev_u32_e32 v79, 528, v86
	v_min_u32_e32 v79, 0x3ff, v79
	v_lshl_add_u32 v79, v79, 2, v131
	ds_read_b32 v79, v79
	v_subrev_u32_e32 v80, 544, v86
	v_min_u32_e32 v80, 0x3ff, v80
	v_lshl_add_u32 v80, v80, 2, v131
	ds_read_b32 v80, v80
	v_subrev_u32_e32 v81, 560, v86
	v_min_u32_e32 v81, 0x3ff, v81
	v_lshl_add_u32 v81, v81, 2, v131
	ds_read_b32 v81, v81
	v_subrev_u32_e32 v82, 768, v86
	v_min_u32_e32 v82, 0x3ff, v82
	v_lshl_add_u32 v82, v82, 2, v131
	ds_read_b32 v82, v82
	v_subrev_u32_e32 v83, 784, v86
	v_min_u32_e32 v83, 0x3ff, v83
	v_lshl_add_u32 v83, v83, 2, v131
	ds_read_b32 v83, v83
	v_subrev_u32_e32 v84, 800, v86
	v_min_u32_e32 v84, 0x3ff, v84
	v_lshl_add_u32 v84, v84, 2, v131
	ds_read_b32 v84, v84
	v_subrev_u32_e32 v85, 816, v86
	v_min_u32_e32 v85, 0x3ff, v85
	v_lshl_add_u32 v85, v85, 2, v131
	ds_read_b32 v85, v85
	ds_read_b64_tr_b16 v[212:213], v133 offset:32544
	ds_read_b64_tr_b16 v[214:215], v133 offset:25664
	ds_read_b64_tr_b16 v[216:217], v133 offset:27968
	ds_read_b64_tr_b16 v[218:219], v133 offset:30272
	ds_read_b64_tr_b16 v[220:221], v133 offset:32576
	ds_read_b64_tr_b16 v[222:223], v133 offset:25696
	ds_read_b64_tr_b16 v[224:225], v133 offset:28000
	ds_read_b64_tr_b16 v[226:227], v133 offset:30304
	ds_read_b64_tr_b16 v[228:229], v133 offset:32608
	s_waitcnt lgkmcnt(9)
; template <int D, class SF>
; __device__ __forceinline__ void attn_step(const bf16x8 (&qf)[D / 32], const LAS bf16_t* Ks, const LAS bf16_t* Vt, f32x4 (&o)[D / 16], float& m, float& lsum, float& alpha_out, bf16x8& pf0_out, bf16x8& pf1_out, const int lane, SF sf) {
;     ...
;         for (int r = 0; r < 4; ++r) v[4 * t + r] = sf(16 * t + 4 * i + r, s[t][r]);
;     float mx = fmaxf(fmaxf(fmaxf(v[0], v[1]), fmaxf(v[2], v[3])), fmaxf(fmaxf(v[4], v[5]), fmaxf(v[6], v[7])));
;     mx = fmaxf(mx, fmaxf(fmaxf(fmaxf(v[8], v[9]), fmaxf(v[10], v[11])), fmaxf(fmaxf(v[12], v[13]), fmaxf(v[14], v[15]))));
;     mx = rows_max(mx);
;     const float mnew = fmaxf(m, mx);
;     const float mc = fmaxf(mnew, -1e20f);
;     const float alpha = __builtin_amdgcn_exp2f(fmaxf(m, -1e20f) - mc);
;     float p[16], rs = 0.f;
; #pragma unroll
;     for (int r = 0; r < 16; ++r) { p[r] = __builtin_amdgcn_exp2f(v[r] - mc); rs += p[r]; }
;     rs = rows_sum(rs);
;     lsum = lsum * alpha + rs; m = mnew;
;     union { u32x4 u; bf16x8 b; } pk0, pk1;
;     pk0.u.x = cvt_pk_bf16(p[0], p[1]); pk0.u.y = cvt_pk_bf16(p[2], p[3]); pk0.u.z = cvt_pk_bf16(p[4], p[5]); pk0.u.w = cvt_pk_bf16(p[6], p[7]);
;     pk1.u.x = cvt_pk_bf16(p[8], p[9]); pk1.u.y = cvt_pk_bf16(p[10], p[11]); pk1.u.z = cvt_pk_bf16(p[12], p[13]); pk1.u.w = cvt_pk_bf16(p[14], p[15]);
;     if (__builtin_amdgcn_ballot_w64(alpha != 1.0f) != 0ull) {
; #pragma unroll
;         for (int dt = 0; dt < D / 16; ++dt) o[dt] *= alpha;
;     }
; #pragma unroll
;     for (int dt = 0; dt < D / 16; ++dt) {
;         const LAS bf16_t* vp = Vt + (16 * dt + c) * 72 + 4 * i;
;         union { u32x4 u; bf16x8 b; } vf0, vf1; const u32x2 a0 = *(const LAS u32x2*)vp, a1 = *(const LAS u32x2*)(vp + 16), b0 = *(const LAS u32x2*)(vp + 32), b1 = *(const LAS u32x2*)(vp + 48);
;         vf0.u.x = a0.x; vf0.u.y = a0.y; vf0.u.z = a1.x; vf0.u.w = a1.y; vf1.u.x = b0.x; vf1.u.y = b0.y; vf1.u.z = b1.x; vf1.u.w = b1.y;
;         o[dt] = mfma16(vf0.b, pk0.b, o[dt]); o[dt] = mfma16(vf1.b, pk1.b, o[dt]);
;     }
;     alpha_out = alpha; pf0_out = pk0.b; pf1_out = pk1.b;
; __device__ __forceinline__ void nsa_unit(LAS unsigned char* lds, const Ctx& P, int l, int b, int hkv, int tb) {
;     ...
; #pragma unroll
;                 for (int jt = 0; jt < 4; ++jt) oi[jt] *= alpha;
;                 oi[kt] = mfma16(ovA[0], pf, oi[kt]); oi[kt] = mfma16(ovA[1], pf1, oi[kt]);
	v_fmamk_f32 v70, v70, 0x3fb8aa3b, v78
	v_fmamk_f32 v71, v71, 0x3fb8aa3b, v79
	v_fmamk_f32 v72, v72, 0x3fb8aa3b, v80
	v_fmamk_f32 v73, v73, 0x3fb8aa3b, v81
	v_fmamk_f32 v74, v74, 0x3fb8aa3b, v82
	v_fmamk_f32 v75, v75, 0x3fb8aa3b, v83
	v_fmamk_f32 v76, v76, 0x3fb8aa3b, v84
	v_fmamk_f32 v77, v77, 0x3fb8aa3b, v85
	v_cmp_le_i32_e32 vcc, 512, v86
	s_nop 1
	v_cndmask_b32_e32 v70, v243, v70, vcc
	v_cmp_le_i32_e32 vcc, 528, v86
	s_nop 1
	v_cndmask_b32_e32 v71, v243, v71, vcc
	v_cmp_le_i32_e32 vcc, 544, v86
	s_nop 1
	v_cndmask_b32_e32 v72, v243, v72, vcc
	v_cmp_le_i32_e32 vcc, 560, v86
	s_nop 1
	v_cndmask_b32_e32 v73, v243, v73, vcc
	v_cmp_le_i32_e32 vcc, 768, v86
	s_nop 1
	v_cndmask_b32_e32 v74, v243, v74, vcc
	v_cmp_le_i32_e32 vcc, 784, v86
	s_nop 1
	v_cndmask_b32_e32 v75, v243, v75, vcc
	v_cmp_le_i32_e32 vcc, 800, v86
	s_nop 1
	v_cndmask_b32_e32 v76, v243, v76, vcc
	v_cmp_le_i32_e32 vcc, 816, v86
	s_nop 1
	v_cndmask_b32_e32 v77, v243, v77, vcc
	v_max3_f32 v92, v62, v63, v64
	v_max3_f32 v87, v65, v66, v67
	v_max3_f32 v88, v68, v69, v70
	v_max3_f32 v89, v71, v72, v73
	v_max3_f32 v91, v74, v75, v76
	v_max3_f32 v92, v92, v87, v77
	v_max3_f32 v88, v88, v89, v91
	v_max_f32_e32 v92, v92, v88
	v_mov_b32_e32 v87, v92
	s_nop 1
	v_permlane16_swap_b32_e32 v92, v87
	v_max_f32_e32 v92, v92, v87
	v_mov_b32_e32 v87, v92
	s_nop 1
	v_permlane32_swap_b32_e32 v92, v87
	v_max_f32_e32 v92, v92, v87
	v_max_f32_e32 v88, v137, v92
	v_max_f32_e32 v90, 0xe0ad78ec, v137
	v_max_f32_e32 v89, 0xe0ad78ec, v88
	v_sub_f32_e32 v90, v90, v89
	v_mov_b32_e32 v137, v88
	v_exp_f32_e32 v90, v90
	v_sub_f32_e32 v62, v62, v89
	v_sub_f32_e32 v63, v63, v89
	v_sub_f32_e32 v64, v64, v89
	v_sub_f32_e32 v65, v65, v89
	v_exp_f32_e32 v62, v62
	v_exp_f32_e32 v63, v63
	v_exp_f32_e32 v64, v64
	v_exp_f32_e32 v65, v65
	v_sub_f32_e32 v66, v66, v89
	v_sub_f32_e32 v67, v67, v89
	v_sub_f32_e32 v68, v68, v89
	v_sub_f32_e32 v69, v69, v89
	v_exp_f32_e32 v66, v66
	v_exp_f32_e32 v67, v67
	v_exp_f32_e32 v68, v68
	v_exp_f32_e32 v69, v69
	v_sub_f32_e32 v70, v70, v89
	v_sub_f32_e32 v71, v71, v89
	v_sub_f32_e32 v72, v72, v89
	v_sub_f32_e32 v73, v73, v89
	v_exp_f32_e32 v70, v70
	v_exp_f32_e32 v71, v71
	v_exp_f32_e32 v72, v72
	v_exp_f32_e32 v73, v73
	v_sub_f32_e32 v74, v74, v89
	v_sub_f32_e32 v75, v75, v89
	v_sub_f32_e32 v76, v76, v89
	v_sub_f32_e32 v77, v77, v89
	v_exp_f32_e32 v74, v74
	v_exp_f32_e32 v75, v75
	v_exp_f32_e32 v76, v76
	v_exp_f32_e32 v77, v77
	s_nop 0
	v_add_f32_e32 v86, v62, v63
	v_add_f32_e32 v87, v64, v65
	v_add_f32_e32 v88, v66, v67
	v_add_f32_e32 v89, v68, v69
	v_add_f32_e32 v86, v86, v70
	v_add_f32_e32 v87, v87, v71
	v_add_f32_e32 v88, v88, v72
	v_add_f32_e32 v89, v89, v73
	v_add_f32_e32 v86, v86, v74
	v_add_f32_e32 v87, v87, v75
	v_add_f32_e32 v88, v88, v76
	v_add_f32_e32 v89, v89, v77
	v_add_f32_e32 v86, v86, v87
	v_add_f32_e32 v88, v88, v89
	v_add_f32_e32 v86, v86, v88
	v_cvt_pk_bf16_f32 v78, v62, v63
	v_cvt_pk_bf16_f32 v79, v64, v65
	v_cvt_pk_bf16_f32 v80, v66, v67
	v_cvt_pk_bf16_f32 v81, v68, v69
	v_cvt_pk_bf16_f32 v82, v70, v71
	v_cvt_pk_bf16_f32 v83, v72, v73
	v_cvt_pk_bf16_f32 v84, v74, v75
	v_cvt_pk_bf16_f32 v85, v76, v77
	v_mov_b32_e32 v87, v86
	s_nop 1
	v_permlane16_swap_b32_e32 v86, v87
	v_add_f32_e32 v86, v86, v87
	v_mov_b32_e32 v87, v86
	s_nop 1
	v_permlane32_swap_b32_e32 v86, v87
	v_add_f32_e32 v86, v86, v87
	v_fma_f32 v138, v138, v90, v86
	v_cmp_neq_f32_e64 s[0:1], 1.0, v90
	s_cmp_eq_u64 s[0:1], 0
	s_cbranch_scc1 .Lcm_nosc_18
	v_pk_mul_f32 v[30:31], v[30:31], v[90:91] op_sel_hi:[1,0]
	v_pk_mul_f32 v[32:33], v[32:33], v[90:91] op_sel_hi:[1,0]
	v_pk_mul_f32 v[34:35], v[34:35], v[90:91] op_sel_hi:[1,0]
	v_pk_mul_f32 v[36:37], v[36:37], v[90:91] op_sel_hi:[1,0]
	v_pk_mul_f32 v[38:39], v[38:39], v[90:91] op_sel_hi:[1,0]
	v_pk_mul_f32 v[40:41], v[40:41], v[90:91] op_sel_hi:[1,0]
	v_pk_mul_f32 v[42:43], v[42:43], v[90:91] op_sel_hi:[1,0]
	v_pk_mul_f32 v[44:45], v[44:45], v[90:91] op_sel_hi:[1,0]
	v_pk_mul_f32 v[46:47], v[46:47], v[90:91] op_sel_hi:[1,0]
	v_pk_mul_f32 v[48:49], v[48:49], v[90:91] op_sel_hi:[1,0]
	v_pk_mul_f32 v[50:51], v[50:51], v[90:91] op_sel_hi:[1,0]
	v_pk_mul_f32 v[52:53], v[52:53], v[90:91] op_sel_hi:[1,0]
	v_pk_mul_f32 v[54:55], v[54:55], v[90:91] op_sel_hi:[1,0]
	v_pk_mul_f32 v[56:57], v[56:57], v[90:91] op_sel_hi:[1,0]
	v_pk_mul_f32 v[58:59], v[58:59], v[90:91] op_sel_hi:[1,0]
	v_pk_mul_f32 v[60:61], v[60:61], v[90:91] op_sel_hi:[1,0]
.Lcm_nosc_18:
	s_waitcnt lgkmcnt(0)
	s_nop 1
	v_mfma_f32_16x16x32_bf16 v[30:33], v[198:201], v[78:81], v[30:33]
	v_mfma_f32_16x16x32_bf16 v[34:37], v[206:209], v[78:81], v[34:37]
	v_mfma_f32_16x16x32_bf16 v[38:41], v[214:217], v[78:81], v[38:41]
	v_mfma_f32_16x16x32_bf16 v[42:45], v[222:225], v[78:81], v[42:45]
	v_mfma_f32_16x16x32_bf16 v[30:33], v[202:205], v[82:85], v[30:33]
	v_mfma_f32_16x16x32_bf16 v[34:37], v[210:213], v[82:85], v[34:37]
	v_mfma_f32_16x16x32_bf16 v[38:41], v[218:221], v[82:85], v[38:41]
	v_mfma_f32_16x16x32_bf16 v[42:45], v[226:229], v[82:85], v[42:45]
	v_mfma_f32_16x16x32_bf16 v[54:57], v[160:163], v[78:81], v[54:57]
	v_mfma_f32_16x16x32_bf16 v[58:61], v[230:233], v[82:85], v[58:61]
	v_mfma_f32_16x16x32_bf16 v[54:57], v[170:173], v[82:85], v[54:57]
; #define LAS __attribute__((address_space(3)))
; __device__ __forceinline__ f32x4 mfma16(bf16x8 a, bf16x8 b, f32x4 c) { return __builtin_amdgcn_mfma_f32_16x16x32_bf16(a, b, c, 0, 0, 0); }
; template <int D, class SF>
; __device__ __forceinline__ void attn_step(const bf16x8 (&qf)[D / 32], const LAS bf16_t* Ks, const LAS bf16_t* Vt, f32x4 (&o)[D / 16], float& m, float& lsum, float& alpha_out, bf16x8& pf0_out, bf16x8& pf1_out, const int lane, SF sf) {
;     ...
;     for (int ks = 0; ks < D / 32; ++ks) {
; #pragma unroll
;         for (int t = 0; t < 4; ++t) { const bf16x8 kf = *(const LAS bf16x8*)(Ks + (16 * t + c) * KSTR + ks * 32 + 8 * i); s[t] = mfma16(kf, qf[ks], s[t]); }
;     }
;     float v[16];
; #pragma unroll
;     for (int t = 0; t < 4; ++t)
; #pragma unroll
;         for (int r = 0; r < 4; ++r) v[4 * t + r] = sf(16 * t + 4 * i + r, s[t][r]);
; __device__ __forceinline__ void nsa_unit(LAS unsigned char* lds, const Ctx& P, int l, int b, int hkv, int tb) {
;     ...
;         for (int pr = 0; pr < 2; ++pr) if (2 * pr < ntile) {
;             const bool hasb = 2 * pr + 1 < ntile;
;             __syncthreads();
;             load2(KC, VC, 64, 128 * pr, 128 * pr + 64, hasb, 255);
;             __syncthreads();
; #pragma unroll
;             for (int sl = 0; sl < 2; ++sl) if (sl == 0 || hasb) {
;                 const int kt = 2 * pr + sl; const LAS bf16_t* Ks = KV + sl * 9216; const LAS bf16_t* Vt = Ks + 4608; const int nb = kt * 64;
;                 attn_step<64>(qs, Ks, Vt, o, m, lsum, alpha, pf, pf1, lane,
;                     [&](int kk, float s) { const int dist = tqs - (16 * (nb + kk) + 31); return dist >= 0 ? s * LOG2E + lut[min((unsigned)dist, 1023u)] : NEGBIG; });
; #pragma unroll
.Lcm_td_16:
	s_cmp_lt_u32 s26, 4
	s_cbranch_scc1 .Lcm_nb_19
	v_lshlrev_b32_e32 v86, 6, v103
	v_sub_u32_e32 v86, v130, v86
	v_add_u32_e32 v86, 0xfffff3e1, v86
	v_subrev_u32_e32 v78, 0, v86
	v_min_u32_e32 v78, 0x3ff, v78
	v_lshl_add_u32 v78, v78, 2, v131
	ds_read_b32 v78, v78
	v_subrev_u32_e32 v79, 16, v86
	v_min_u32_e32 v79, 0x3ff, v79
	v_lshl_add_u32 v79, v79, 2, v131
	ds_read_b32 v79, v79
	v_subrev_u32_e32 v80, 32, v86
	v_min_u32_e32 v80, 0x3ff, v80
	v_lshl_add_u32 v80, v80, 2, v131
	ds_read_b32 v80, v80
	v_subrev_u32_e32 v81, 48, v86
	v_min_u32_e32 v81, 0x3ff, v81
	v_lshl_add_u32 v81, v81, 2, v131
	ds_read_b32 v81, v81
	v_subrev_u32_e32 v82, 256, v86
	v_min_u32_e32 v82, 0x3ff, v82
	v_lshl_add_u32 v82, v82, 2, v131
	ds_read_b32 v82, v82
	v_subrev_u32_e32 v83, 272, v86
	v_min_u32_e32 v83, 0x3ff, v83
	v_lshl_add_u32 v83, v83, 2, v131
	ds_read_b32 v83, v83
	v_subrev_u32_e32 v84, 288, v86
	v_min_u32_e32 v84, 0x3ff, v84
	v_lshl_add_u32 v84, v84, 2, v131
	ds_read_b32 v84, v84
	v_subrev_u32_e32 v85, 304, v86
	v_min_u32_e32 v85, 0x3ff, v85
	v_lshl_add_u32 v85, v85, 2, v131
	ds_read_b32 v85, v85
	ds_read_b128 v[198:201], v132 offset:34816
	ds_read_b128 v[206:209], v132 offset:37120
	ds_read_b128 v[202:205], v132 offset:34880
	ds_read_b128 v[210:213], v132 offset:37184
	ds_read_b128 v[214:217], v132 offset:39424
	ds_read_b128 v[222:225], v132 offset:41728
	ds_read_b128 v[218:221], v132 offset:39488
	ds_read_b128 v[226:229], v132 offset:41792
	s_waitcnt lgkmcnt(6)
	v_mfma_f32_16x16x32_bf16 v[62:65], v[198:201], v[2:5], 0
	v_mfma_f32_16x16x32_bf16 v[66:69], v[206:209], v[2:5], 0
	s_waitcnt lgkmcnt(4)
	v_mfma_f32_16x16x32_bf16 v[62:65], v[202:205], v[6:9], v[62:65]
	v_mfma_f32_16x16x32_bf16 v[66:69], v[210:213], v[6:9], v[66:69]
	s_waitcnt lgkmcnt(2)
	v_mfma_f32_16x16x32_bf16 v[70:73], v[214:217], v[2:5], 0
	v_mfma_f32_16x16x32_bf16 v[74:77], v[222:225], v[2:5], 0
	s_waitcnt lgkmcnt(0)
	v_mfma_f32_16x16x32_bf16 v[70:73], v[218:221], v[6:9], v[70:73]
	v_mfma_f32_16x16x32_bf16 v[74:77], v[226:229], v[6:9], v[74:77]
	ds_read_b64_tr_b16 v[198:199], v133 offset:44032
	ds_read_b64_tr_b16 v[200:201], v133 offset:46336
	ds_read_b64_tr_b16 v[202:203], v133 offset:48640
	ds_read_b64_tr_b16 v[204:205], v133 offset:50944
	ds_read_b64_tr_b16 v[206:207], v133 offset:44064
	ds_read_b64_tr_b16 v[208:209], v133 offset:46368
	ds_read_b64_tr_b16 v[210:211], v133 offset:48672
	v_fmamk_f32 v62, v62, 0x3fb8aa3b, v78
	v_fmamk_f32 v63, v63, 0x3fb8aa3b, v79
	v_fmamk_f32 v64, v64, 0x3fb8aa3b, v80
	v_fmamk_f32 v65, v65, 0x3fb8aa3b, v81
	v_fmamk_f32 v66, v66, 0x3fb8aa3b, v82
	v_fmamk_f32 v67, v67, 0x3fb8aa3b, v83
	v_fmamk_f32 v68, v68, 0x3fb8aa3b, v84
	v_fmamk_f32 v69, v69, 0x3fb8aa3b, v85
	v_cmp_le_i32_e32 vcc, 0, v86
	s_nop 1
	v_cndmask_b32_e32 v62, v243, v62, vcc
	v_cmp_le_i32_e32 vcc, 16, v86
	s_nop 1
	v_cndmask_b32_e32 v63, v243, v63, vcc
	v_cmp_le_i32_e32 vcc, 32, v86
	s_nop 1
	v_cndmask_b32_e32 v64, v243, v64, vcc
	v_cmp_le_i32_e32 vcc, 48, v86
	s_nop 1
	v_cndmask_b32_e32 v65, v243, v65, vcc
	v_cmp_le_i32_e32 vcc, 256, v86
	s_nop 1
	v_cndmask_b32_e32 v66, v243, v66, vcc
	v_cmp_le_i32_e32 vcc, 272, v86
	s_nop 1
	v_cndmask_b32_e32 v67, v243, v67, vcc
	v_cmp_le_i32_e32 vcc, 288, v86
	s_nop 1
	v_cndmask_b32_e32 v68, v243, v68, vcc
	v_cmp_le_i32_e32 vcc, 304, v86
	s_nop 1
	v_cndmask_b32_e32 v69, v243, v69, vcc
	v_subrev_u32_e32 v78, 512, v86
	v_min_u32_e32 v78, 0x3ff, v78
	v_lshl_add_u32 v78, v78, 2, v131
	ds_read_b32 v78, v78
	v_subrev_u32_e32 v79, 528, v86
	v_min_u32_e32 v79, 0x3ff, v79
	v_lshl_add_u32 v79, v79, 2, v131
	ds_read_b32 v79, v79
	v_subrev_u32_e32 v80, 544, v86
	v_min_u32_e32 v80, 0x3ff, v80
	v_lshl_add_u32 v80, v80, 2, v131
	ds_read_b32 v80, v80
	v_subrev_u32_e32 v81, 560, v86
	v_min_u32_e32 v81, 0x3ff, v81
	v_lshl_add_u32 v81, v81, 2, v131
	ds_read_b32 v81, v81
	v_subrev_u32_e32 v82, 768, v86
	v_min_u32_e32 v82, 0x3ff, v82
	v_lshl_add_u32 v82, v82, 2, v131
	ds_read_b32 v82, v82
	v_subrev_u32_e32 v83, 784, v86
	v_min_u32_e32 v83, 0x3ff, v83
	v_lshl_add_u32 v83, v83, 2, v131
	ds_read_b32 v83, v83
	v_subrev_u32_e32 v84, 800, v86
	v_min_u32_e32 v84, 0x3ff, v84
	v_lshl_add_u32 v84, v84, 2, v131
	ds_read_b32 v84, v84
	v_subrev_u32_e32 v85, 816, v86
	v_min_u32_e32 v85, 0x3ff, v85
	v_lshl_add_u32 v85, v85, 2, v131
	ds_read_b32 v85, v85
	ds_read_b64_tr_b16 v[212:213], v133 offset:50976
	ds_read_b64_tr_b16 v[214:215], v133 offset:44096
	ds_read_b64_tr_b16 v[216:217], v133 offset:46400
	ds_read_b64_tr_b16 v[218:219], v133 offset:48704
	ds_read_b64_tr_b16 v[220:221], v133 offset:51008
	ds_read_b64_tr_b16 v[222:223], v133 offset:44128
	ds_read_b64_tr_b16 v[224:225], v133 offset:46432
	ds_read_b64_tr_b16 v[226:227], v133 offset:48736
	ds_read_b64_tr_b16 v[228:229], v133 offset:51040
	s_waitcnt lgkmcnt(9)
; #define LAS __attribute__((address_space(3)))
; __device__ __forceinline__ unsigned cvt_pk_bf16(float lo, float hi) { unsigned r; asm("v_cvt_pk_bf16_f32 %0, %1, %2" : "=v"(r) : "v"(lo), "v"(hi)); return r; }
; template <int D, class SF>
; __device__ __forceinline__ void attn_step(const bf16x8 (&qf)[D / 32], const LAS bf16_t* Ks, const LAS bf16_t* Vt, f32x4 (&o)[D / 16], float& m, float& lsum, float& alpha_out, bf16x8& pf0_out, bf16x8& pf1_out, const int lane, SF sf) {
;     ...
;         for (int r = 0; r < 4; ++r) v[4 * t + r] = sf(16 * t + 4 * i + r, s[t][r]);
;     float mx = fmaxf(fmaxf(fmaxf(v[0], v[1]), fmaxf(v[2], v[3])), fmaxf(fmaxf(v[4], v[5]), fmaxf(v[6], v[7])));
;     mx = fmaxf(mx, fmaxf(fmaxf(fmaxf(v[8], v[9]), fmaxf(v[10], v[11])), fmaxf(fmaxf(v[12], v[13]), fmaxf(v[14], v[15]))));
;     mx = rows_max(mx);
;     const float mnew = fmaxf(m, mx);
;     const float mc = fmaxf(mnew, -1e20f);
;     const float alpha = __builtin_amdgcn_exp2f(fmaxf(m, -1e20f) - mc);
;     float p[16], rs = 0.f;
; #pragma unroll
;     for (int r = 0; r < 16; ++r) { p[r] = __builtin_amdgcn_exp2f(v[r] - mc); rs += p[r]; }
;     rs = rows_sum(rs);
;     lsum = lsum * alpha + rs; m = mnew;
;     union { u32x4 u; bf16x8 b; } pk0, pk1;
;     pk0.u.x = cvt_pk_bf16(p[0], p[1]); pk0.u.y = cvt_pk_bf16(p[2], p[3]); pk0.u.z = cvt_pk_bf16(p[4], p[5]); pk0.u.w = cvt_pk_bf16(p[6], p[7]);
;     pk1.u.x = cvt_pk_bf16(p[8], p[9]); pk1.u.y = cvt_pk_bf16(p[10], p[11]); pk1.u.z = cvt_pk_bf16(p[12], p[13]); pk1.u.w = cvt_pk_bf16(p[14], p[15]);
;     if (__builtin_amdgcn_ballot_w64(alpha != 1.0f) != 0ull) {
; #pragma unroll
;         for (int dt = 0; dt < D / 16; ++dt) o[dt] *= alpha;
;     }
; #pragma unroll
;     for (int dt = 0; dt < D / 16; ++dt) {
;         const LAS bf16_t* vp = Vt + (16 * dt + c) * 72 + 4 * i;
;         union { u32x4 u; bf16x8 b; } vf0, vf1; const u32x2 a0 = *(const LAS u32x2*)vp, a1 = *(const LAS u32x2*)(vp + 16), b0 = *(const LAS u32x2*)(vp + 32), b1 = *(const LAS u32x2*)(vp + 48);
;         vf0.u.x = a0.x; vf0.u.y = a0.y; vf0.u.z = a1.x; vf0.u.w = a1.y; vf1.u.x = b0.x; vf1.u.y = b0.y; vf1.u.z = b1.x; vf1.u.w = b1.y;
;         o[dt] = mfma16(vf0.b, pk0.b, o[dt]); o[dt] = mfma16(vf1.b, pk1.b, o[dt]);
;     }
;     alpha_out = alpha; pf0_out = pk0.b; pf1_out = pk1.b;
	v_fmamk_f32 v70, v70, 0x3fb8aa3b, v78
	v_fmamk_f32 v71, v71, 0x3fb8aa3b, v79
	v_fmamk_f32 v72, v72, 0x3fb8aa3b, v80
	v_fmamk_f32 v73, v73, 0x3fb8aa3b, v81
	v_fmamk_f32 v74, v74, 0x3fb8aa3b, v82
	v_fmamk_f32 v75, v75, 0x3fb8aa3b, v83
	v_fmamk_f32 v76, v76, 0x3fb8aa3b, v84
	v_fmamk_f32 v77, v77, 0x3fb8aa3b, v85
	v_cmp_le_i32_e32 vcc, 512, v86
	s_nop 1
	v_cndmask_b32_e32 v70, v243, v70, vcc
	v_cmp_le_i32_e32 vcc, 528, v86
	s_nop 1
	v_cndmask_b32_e32 v71, v243, v71, vcc
	v_cmp_le_i32_e32 vcc, 544, v86
	s_nop 1
	v_cndmask_b32_e32 v72, v243, v72, vcc
	v_cmp_le_i32_e32 vcc, 560, v86
	s_nop 1
	v_cndmask_b32_e32 v73, v243, v73, vcc
	v_cmp_le_i32_e32 vcc, 768, v86
	s_nop 1
	v_cndmask_b32_e32 v74, v243, v74, vcc
	v_cmp_le_i32_e32 vcc, 784, v86
	s_nop 1
	v_cndmask_b32_e32 v75, v243, v75, vcc
	v_cmp_le_i32_e32 vcc, 800, v86
	s_nop 1
	v_cndmask_b32_e32 v76, v243, v76, vcc
	v_cmp_le_i32_e32 vcc, 816, v86
	s_nop 1
	v_cndmask_b32_e32 v77, v243, v77, vcc
	v_max3_f32 v92, v62, v63, v64
	v_max3_f32 v87, v65, v66, v67
	v_max3_f32 v88, v68, v69, v70
	v_max3_f32 v89, v71, v72, v73
	v_max3_f32 v91, v74, v75, v76
	v_max3_f32 v92, v92, v87, v77
	v_max3_f32 v88, v88, v89, v91
	v_max_f32_e32 v92, v92, v88
	v_mov_b32_e32 v87, v92
	s_nop 1
	v_permlane16_swap_b32_e32 v92, v87
	v_max_f32_e32 v92, v92, v87
	v_mov_b32_e32 v87, v92
	s_nop 1
	v_permlane32_swap_b32_e32 v92, v87
	v_max_f32_e32 v92, v92, v87
	v_max_f32_e32 v88, v137, v92
	v_max_f32_e32 v90, 0xe0ad78ec, v137
	v_max_f32_e32 v89, 0xe0ad78ec, v88
	v_sub_f32_e32 v90, v90, v89
	v_mov_b32_e32 v137, v88
	v_exp_f32_e32 v90, v90
	v_sub_f32_e32 v62, v62, v89
	v_sub_f32_e32 v63, v63, v89
	v_sub_f32_e32 v64, v64, v89
	v_sub_f32_e32 v65, v65, v89
	v_exp_f32_e32 v62, v62
	v_exp_f32_e32 v63, v63
	v_exp_f32_e32 v64, v64
	v_exp_f32_e32 v65, v65
	v_sub_f32_e32 v66, v66, v89
	v_sub_f32_e32 v67, v67, v89
	v_sub_f32_e32 v68, v68, v89
	v_sub_f32_e32 v69, v69, v89
	v_exp_f32_e32 v66, v66
	v_exp_f32_e32 v67, v67
	v_exp_f32_e32 v68, v68
	v_exp_f32_e32 v69, v69
	v_sub_f32_e32 v70, v70, v89
	v_sub_f32_e32 v71, v71, v89
	v_sub_f32_e32 v72, v72, v89
	v_sub_f32_e32 v73, v73, v89
	v_exp_f32_e32 v70, v70
	v_exp_f32_e32 v71, v71
	v_exp_f32_e32 v72, v72
	v_exp_f32_e32 v73, v73
	v_sub_f32_e32 v74, v74, v89
	v_sub_f32_e32 v75, v75, v89
	v_sub_f32_e32 v76, v76, v89
	v_sub_f32_e32 v77, v77, v89
	v_exp_f32_e32 v74, v74
	v_exp_f32_e32 v75, v75
	v_exp_f32_e32 v76, v76
	v_exp_f32_e32 v77, v77
	s_nop 0
	v_add_f32_e32 v86, v62, v63
	v_add_f32_e32 v87, v64, v65
	v_add_f32_e32 v88, v66, v67
	v_add_f32_e32 v89, v68, v69
	v_add_f32_e32 v86, v86, v70
	v_add_f32_e32 v87, v87, v71
	v_add_f32_e32 v88, v88, v72
	v_add_f32_e32 v89, v89, v73
	v_add_f32_e32 v86, v86, v74
	v_add_f32_e32 v87, v87, v75
	v_add_f32_e32 v88, v88, v76
	v_add_f32_e32 v89, v89, v77
	v_add_f32_e32 v86, v86, v87
	v_add_f32_e32 v88, v88, v89
	v_add_f32_e32 v86, v86, v88
	v_cvt_pk_bf16_f32 v78, v62, v63
	v_cvt_pk_bf16_f32 v79, v64, v65
	v_cvt_pk_bf16_f32 v80, v66, v67
	v_cvt_pk_bf16_f32 v81, v68, v69
	v_cvt_pk_bf16_f32 v82, v70, v71
	v_cvt_pk_bf16_f32 v83, v72, v73
	v_cvt_pk_bf16_f32 v84, v74, v75
	v_cvt_pk_bf16_f32 v85, v76, v77
	v_mov_b32_e32 v87, v86
	s_nop 1
	v_permlane16_swap_b32_e32 v86, v87
	v_add_f32_e32 v86, v86, v87
	v_mov_b32_e32 v87, v86
	s_nop 1
	v_permlane32_swap_b32_e32 v86, v87
	v_add_f32_e32 v86, v86, v87
	v_fma_f32 v138, v138, v90, v86
	v_cmp_neq_f32_e64 s[0:1], 1.0, v90
	s_cmp_eq_u64 s[0:1], 0
	s_cbranch_scc1 .Lcm_nosc_20
	v_pk_mul_f32 v[30:31], v[30:31], v[90:91] op_sel_hi:[1,0]
	v_pk_mul_f32 v[32:33], v[32:33], v[90:91] op_sel_hi:[1,0]
	v_pk_mul_f32 v[34:35], v[34:35], v[90:91] op_sel_hi:[1,0]
	v_pk_mul_f32 v[36:37], v[36:37], v[90:91] op_sel_hi:[1,0]
	v_pk_mul_f32 v[38:39], v[38:39], v[90:91] op_sel_hi:[1,0]
	v_pk_mul_f32 v[40:41], v[40:41], v[90:91] op_sel_hi:[1,0]
	v_pk_mul_f32 v[42:43], v[42:43], v[90:91] op_sel_hi:[1,0]
	v_pk_mul_f32 v[44:45], v[44:45], v[90:91] op_sel_hi:[1,0]
	v_pk_mul_f32 v[46:47], v[46:47], v[90:91] op_sel_hi:[1,0]
	v_pk_mul_f32 v[48:49], v[48:49], v[90:91] op_sel_hi:[1,0]
	v_pk_mul_f32 v[50:51], v[50:51], v[90:91] op_sel_hi:[1,0]
	v_pk_mul_f32 v[52:53], v[52:53], v[90:91] op_sel_hi:[1,0]
	v_pk_mul_f32 v[54:55], v[54:55], v[90:91] op_sel_hi:[1,0]
	v_pk_mul_f32 v[56:57], v[56:57], v[90:91] op_sel_hi:[1,0]
	v_pk_mul_f32 v[58:59], v[58:59], v[90:91] op_sel_hi:[1,0]
	v_pk_mul_f32 v[60:61], v[60:61], v[90:91] op_sel_hi:[1,0]
; #define LAS __attribute__((address_space(3)))
; __device__ __forceinline__ float bf2f(bf16_t v) { return __uint_as_float(((unsigned)v) << 16); }
; __device__ __forceinline__ float sigmoidf_(float x) { return __builtin_amdgcn_rcpf(1.0f + __expf(-x)); }
; __device__ __forceinline__ f32x4 mfma16(bf16x8 a, bf16x8 b, f32x4 c) { return __builtin_amdgcn_mfma_f32_16x16x32_bf16(a, b, c, 0, 0, 0); }
; __device__ __forceinline__ void nsa_unit(LAS unsigned char* lds, const Ctx& P, int l, int b, int hkv, int tb) {
;     ...
;     auto load2 = [&](const bf16_t* ksrc, const bf16_t* vsrc, size_t ld, int p0a, int p0b, bool hasb, int pmax) {
;         TileRegs ra, rb; tile_issue(ra, tid, ksrc, vsrc, ld, p0a, pmax); if (hasb) tile_issue(rb, tid, ksrc, vsrc, ld, p0b, pmax);
;         tile_commit(ra, tid, KV, KV + 4608); if (hasb) tile_commit(rb, tid, KV + 9216, KV + 9216 + 4608); };
;     ...
;                 for (int jt = 0; jt < 4; ++jt) oi[jt] *= alpha;
;                 oi[kt] = mfma16(ovA[0], pf, oi[kt]); oi[kt] = mfma16(ovA[1], pf1, oi[kt]);
;                 if (kt + 1 < 4) { oi[kt + 1 < 4 ? kt + 1 : 3] = mfma16(ovB[0], pf, oi[kt + 1 < 4 ? kt + 1 : 3]); oi[kt + 1 < 4 ? kt + 1 : 3] = mfma16(ovB[1], pf1, oi[kt + 1 < 4 ? kt + 1 : 3]); }
;             }
;         }
;         const float inv = 1.0f / fmaxf(lsum, 1e-30f);
;         const float g0 = sigmoidf_(bf2f(H[((size_t)b * SEQ + tqs) * LDH + C_GL + hq]) + P.in[21][l * 48 + hq]) * inv;
; #pragma unroll
;         for (int dt = 0; dt < 4; ++dt) { park[(sb * 4 + dt) * 64] = o[dt] * g0;
;             *(LAS f32x4*)(impb + (g * 64 + 32 * th + 16 * sb + c) * 64 + 16 * dt + 4 * i) = oi[dt] * inv; }
.Lcm_nosc_20:
	s_waitcnt lgkmcnt(0)
	s_nop 1
	v_mfma_f32_16x16x32_bf16 v[30:33], v[198:201], v[78:81], v[30:33]
	v_mfma_f32_16x16x32_bf16 v[34:37], v[206:209], v[78:81], v[34:37]
	v_mfma_f32_16x16x32_bf16 v[38:41], v[214:217], v[78:81], v[38:41]
	v_mfma_f32_16x16x32_bf16 v[42:45], v[222:225], v[78:81], v[42:45]
	v_mfma_f32_16x16x32_bf16 v[30:33], v[202:205], v[82:85], v[30:33]
	v_mfma_f32_16x16x32_bf16 v[34:37], v[210:213], v[82:85], v[34:37]
	v_mfma_f32_16x16x32_bf16 v[38:41], v[218:221], v[82:85], v[38:41]
	v_mfma_f32_16x16x32_bf16 v[42:45], v[226:229], v[82:85], v[42:45]
	v_mfma_f32_16x16x32_bf16 v[58:61], v[160:163], v[78:81], v[58:61]
	v_mfma_f32_16x16x32_bf16 v[58:61], v[170:173], v[82:85], v[58:61]
.Lcm_nb_19:
.Lcm_fin_1:
	v_lshlrev_b32_e32 v86, 1, v96
	v_add_u32_e32 v86, 0x5400, v86
	v_add_co_u32_e32 v62, vcc, v86, v128
	s_nop 1
	v_addc_co_u32_e32 v63, vcc, 0, v129, vcc
	global_load_ushort v64, v[62:63], off
	v_mov_b32_e32 v65, s74
	ds_read_b64 v[66:67], v65
	s_waitcnt lgkmcnt(0)
	v_readfirstlane_b32 s20, v66
	v_readfirstlane_b32 s21, v67
	s_nop 4
	s_nop 0
	global_load_dword v65, v158, s[20:21]
	v_max_f32_e32 v86, v138, v138
	v_max_f32_e32 v86, 0xda24260, v86
	v_div_scale_f32 v87, s[0:1], v86, v86, 1.0
	v_rcp_f32_e32 v88, v87
	s_nop 0
	v_fma_f32 v89, -v87, v88, 1.0
	v_fmac_f32_e32 v88, v89, v88
	v_div_scale_f32 v89, vcc, 1.0, v86, 1.0
	v_mul_f32_e32 v91, v89, v88
	v_fma_f32 v92, -v87, v91, v89
	v_fmac_f32_e32 v91, v92, v88
	v_fma_f32 v87, -v87, v91, v89
	v_div_fmas_f32 v87, v87, v88, v91
	v_div_fixup_f32 v68, v87, v86, 1.0
	s_waitcnt vmcnt(0)
	v_lshlrev_b32_e32 v64, 16, v64
	v_add_f32_e32 v64, v65, v64
	v_mul_f32_e32 v64, 0xbfb8aa3b, v64
	v_exp_f32_e32 v64, v64
	s_nop 0
	v_add_f32_e32 v64, 1.0, v64
	v_rcp_f32_e32 v64, v64
	s_nop 0
	v_mul_f32_e32 v70, v68, v64
	s_nop 4
	v_pk_mul_f32 v[30:31], v[30:31], v[70:71] op_sel_hi:[1,0]
	v_pk_mul_f32 v[32:33], v[32:33], v[70:71] op_sel_hi:[1,0]
	global_store_dwordx4 v[124:125], v[30:33], off
	v_pk_mul_f32 v[34:35], v[34:35], v[70:71] op_sel_hi:[1,0]
	v_pk_mul_f32 v[36:37], v[36:37], v[70:71] op_sel_hi:[1,0]
	global_store_dwordx4 v[124:125], v[34:37], off offset:1024
	v_pk_mul_f32 v[38:39], v[38:39], v[70:71] op_sel_hi:[1,0]
	v_pk_mul_f32 v[40:41], v[40:41], v[70:71] op_sel_hi:[1,0]
	global_store_dwordx4 v[124:125], v[38:41], off offset:2048
	v_pk_mul_f32 v[42:43], v[42:43], v[70:71] op_sel_hi:[1,0]
	v_pk_mul_f32 v[44:45], v[44:45], v[70:71] op_sel_hi:[1,0]
	global_store_dwordx4 v[124:125], v[42:45], off offset:3072
	v_mov_b32_e32 v74, v156
	v_lshl_add_u32 v74, v74, 8, v150
	v_pk_mul_f32 v[46:47], v[46:47], v[68:69] op_sel_hi:[1,0]
	v_pk_mul_f32 v[48:49], v[48:49], v[68:69] op_sel_hi:[1,0]
	ds_write_b128 v74, v[46:49] offset:53248
	v_pk_mul_f32 v[50:51], v[50:51], v[68:69] op_sel_hi:[1,0]
	v_pk_mul_f32 v[52:53], v[52:53], v[68:69] op_sel_hi:[1,0]
	ds_write_b128 v74, v[50:53] offset:53312
	v_pk_mul_f32 v[54:55], v[54:55], v[68:69] op_sel_hi:[1,0]
	v_pk_mul_f32 v[56:57], v[56:57], v[68:69] op_sel_hi:[1,0]
	ds_write_b128 v74, v[54:57] offset:53376
	v_pk_mul_f32 v[58:59], v[58:59], v[68:69] op_sel_hi:[1,0]
	v_pk_mul_f32 v[60:61], v[60:61], v[68:69] op_sel_hi:[1,0]
	ds_write_b128 v74, v[58:61] offset:53440
	s_lshl_b32 s44, s61, 2
	s_or_b32 s44, s44, s60
	s_lshl_b32 s44, s44, 15
	s_add_u32 s44, s44, 0x33203000
	s_add_u32 s20, s68, s44
	s_addc_u32 s21, s69, 0
	v_mov_b32_e32 v30, 0
	v_mov_b32_e32 v46, 0
	v_mov_b32_e32 v31, 0
	v_mov_b32_e32 v47, 0
	v_mov_b32_e32 v32, 0
	v_mov_b32_e32 v48, 0
	v_mov_b32_e32 v33, 0
	v_mov_b32_e32 v49, 0
	v_mov_b32_e32 v34, 0
	v_mov_b32_e32 v50, 0
	v_mov_b32_e32 v35, 0
	v_mov_b32_e32 v51, 0
	v_mov_b32_e32 v36, 0
	v_mov_b32_e32 v52, 0
	v_mov_b32_e32 v37, 0
	v_mov_b32_e32 v53, 0
	v_mov_b32_e32 v38, 0
	v_mov_b32_e32 v54, 0
	v_mov_b32_e32 v39, 0
	v_mov_b32_e32 v55, 0
	v_mov_b32_e32 v40, 0
	v_mov_b32_e32 v56, 0
	v_mov_b32_e32 v41, 0
	v_mov_b32_e32 v57, 0
	v_mov_b32_e32 v42, 0
	v_mov_b32_e32 v58, 0
	v_mov_b32_e32 v43, 0
	v_mov_b32_e32 v59, 0
	v_mov_b32_e32 v44, 0
	v_mov_b32_e32 v60, 0
	v_mov_b32_e32 v45, 0
	v_mov_b32_e32 v61, 0
	v_mov_b32_e32 v137, 0xf149f2ca
	v_mov_b32_e32 v138, 0
	v_mov_b32_e32 v86, v139
	v_add_u32_e32 v87, 0x80000, v86
	global_load_dwordx4 v[198:201], v86, s[20:21]
	global_load_dwordx4 v[202:205], v87, s[20:21]
	s_cmp_lt_u32 s26, 2
	s_cbranch_scc1 .Lcm_lnb_22
	v_add_u32_e32 v86, 0x2000, v86
	v_add_u32_e32 v87, 0x2000, v87
	global_load_dwordx4 v[206:209], v86, s[20:21]
	global_load_dwordx4 v[210:213], v87, s[20:21]

; template <int D, class SF>
; __device__ __forceinline__ void attn_step(const bf16x8 (&qf)[D / 32], const LAS bf16_t* Ks, const LAS bf16_t* Vt, f32x4 (&o)[D / 16], float& m, float& lsum, float& alpha_out, bf16x8& pf0_out, bf16x8& pf1_out, const int lane, SF sf) {
;     ...
;     float mx = fmaxf(fmaxf(fmaxf(v[0], v[1]), fmaxf(v[2], v[3])), fmaxf(fmaxf(v[4], v[5]), fmaxf(v[6], v[7])));
;     mx = fmaxf(mx, fmaxf(fmaxf(fmaxf(v[8], v[9]), fmaxf(v[10], v[11])), fmaxf(fmaxf(v[12], v[13]), fmaxf(v[14], v[15]))));
;     mx = rows_max(mx);
;     const float mnew = fmaxf(m, mx);
;     const float mc = fmaxf(mnew, -1e20f);
;     const float alpha = __builtin_amdgcn_exp2f(fmaxf(m, -1e20f) - mc);
;     float p[16], rs = 0.f;
; #pragma unroll
;     for (int r = 0; r < 16; ++r) { p[r] = __builtin_amdgcn_exp2f(v[r] - mc); rs += p[r]; }
;     rs = rows_sum(rs);
;     lsum = lsum * alpha + rs; m = mnew;
;     union { u32x4 u; bf16x8 b; } pk0, pk1;
;     pk0.u.x = cvt_pk_bf16(p[0], p[1]); pk0.u.y = cvt_pk_bf16(p[2], p[3]); pk0.u.z = cvt_pk_bf16(p[4], p[5]); pk0.u.w = cvt_pk_bf16(p[6], p[7]);
;     pk1.u.x = cvt_pk_bf16(p[8], p[9]); pk1.u.y = cvt_pk_bf16(p[10], p[11]); pk1.u.z = cvt_pk_bf16(p[12], p[13]); pk1.u.w = cvt_pk_bf16(p[14], p[15]);
;     if (__builtin_amdgcn_ballot_w64(alpha != 1.0f) != 0ull) {
; #pragma unroll
;         for (int dt = 0; dt < D / 16; ++dt) o[dt] *= alpha;
;     }
; #pragma unroll
;     for (int dt = 0; dt < D / 16; ++dt) {
;         const LAS bf16_t* vp = Vt + (16 * dt + c) * 72 + 4 * i;
; __device__ __forceinline__ void nsa_unit(LAS unsigned char* lds, const Ctx& P, int l, int b, int hkv, int tb) {
;     ...
;         for (int pr = 0; pr < 2; ++pr) if (2 * pr < ntile) {
;             const bool hasb = 2 * pr + 1 < ntile;
;             __syncthreads();
;             load2(KC, VC, 64, 128 * pr, 128 * pr + 64, hasb, 255);
;             __syncthreads();
; #pragma unroll
;             for (int sl = 0; sl < 2; ++sl) if (sl == 0 || hasb) {
;                 const int kt = 2 * pr + sl; const LAS bf16_t* Ks = KV + sl * 9216; const LAS bf16_t* Vt = Ks + 4608; const int nb = kt * 64;
;                 attn_step<64>(qs, Ks, Vt, o, m, lsum, alpha, pf, pf1, lane,
;                     [&](int kk, float s) { const int dist = tqs - (16 * (nb + kk) + 31); return dist >= 0 ? s * LOG2E + lut[min((unsigned)dist, 1023u)] : NEGBIG; });
; #pragma unroll
.Lcm_wnb_23:
	s_waitcnt lgkmcnt(0)
	s_barrier
	s_sub_i32 s44, s55, 0
	s_cmp_ge_i32 s44, 0x725
	s_cbranch_scc0 .Lcm_gen_24
	ds_read_b128 v[198:201], v132 offset:16384
	ds_read_b128 v[206:209], v132 offset:18688
	ds_read_b128 v[202:205], v132 offset:16448
	ds_read_b128 v[210:213], v132 offset:18752
	ds_read_b128 v[214:217], v132 offset:20992
	ds_read_b128 v[222:225], v132 offset:23296
	ds_read_b128 v[218:221], v132 offset:21056
	ds_read_b128 v[226:229], v132 offset:23360
	s_waitcnt lgkmcnt(6)
	v_mfma_f32_16x16x32_bf16 v[62:65], v[198:201], v[10:13], 0
	v_mfma_f32_16x16x32_bf16 v[66:69], v[206:209], v[10:13], 0
	s_waitcnt lgkmcnt(4)
	v_mfma_f32_16x16x32_bf16 v[62:65], v[202:205], v[14:17], v[62:65]
	v_mfma_f32_16x16x32_bf16 v[66:69], v[210:213], v[14:17], v[66:69]
	s_waitcnt lgkmcnt(2)
	v_mfma_f32_16x16x32_bf16 v[70:73], v[214:217], v[10:13], 0
	v_mfma_f32_16x16x32_bf16 v[74:77], v[222:225], v[10:13], 0
	s_waitcnt lgkmcnt(0)
	v_mfma_f32_16x16x32_bf16 v[70:73], v[218:221], v[14:17], v[70:73]
	v_mfma_f32_16x16x32_bf16 v[74:77], v[226:229], v[14:17], v[74:77]
	ds_read_b64_tr_b16 v[198:199], v133 offset:25600
	ds_read_b64_tr_b16 v[200:201], v133 offset:27904
	ds_read_b64_tr_b16 v[202:203], v133 offset:30208
	ds_read_b64_tr_b16 v[204:205], v133 offset:32512
	ds_read_b64_tr_b16 v[206:207], v133 offset:25632
	ds_read_b64_tr_b16 v[208:209], v133 offset:27936
	ds_read_b64_tr_b16 v[210:211], v133 offset:30240
	ds_read_b64_tr_b16 v[212:213], v133 offset:32544
	ds_read_b64_tr_b16 v[214:215], v133 offset:25664
	ds_read_b64_tr_b16 v[216:217], v133 offset:27968
	ds_read_b64_tr_b16 v[218:219], v133 offset:30272
	ds_read_b64_tr_b16 v[220:221], v133 offset:32576
	ds_read_b64_tr_b16 v[222:223], v133 offset:25696
	ds_read_b64_tr_b16 v[224:225], v133 offset:28000
	ds_read_b64_tr_b16 v[226:227], v133 offset:30304
	ds_read_b64_tr_b16 v[228:229], v133 offset:32608
	v_max3_f32 v86, v62, v63, v64
	v_max3_f32 v87, v65, v66, v67
	v_max3_f32 v88, v68, v69, v70
	v_max3_f32 v89, v71, v72, v73
	v_max3_f32 v91, v74, v75, v76
	v_max3_f32 v86, v86, v87, v77
	v_max3_f32 v88, v88, v89, v91
	v_max_f32_e32 v86, v86, v88
	v_mov_b32_e32 v87, v86
	s_nop 1
	v_permlane16_swap_b32_e32 v86, v87
	v_max_f32_e32 v86, v86, v87
	v_mov_b32_e32 v87, v86
	s_nop 1
	v_permlane32_swap_b32_e32 v86, v87
	v_max_f32_e32 v86, v86, v87
	v_fmamk_f32 v86, v86, 0x3fb8aa3b, v165
	v_cndmask_b32_e64 v86, v243, v86, s[24:25]
	v_max_f32_e32 v88, v137, v86
	v_max_f32_e32 v90, 0xe0ad78ec, v137
	v_max_f32_e32 v89, 0xe0ad78ec, v88
	v_sub_f32_e32 v90, v90, v89
	v_mov_b32_e32 v137, v88
	v_exp_f32_e32 v90, v90
	v_sub_f32_e32 v91, v165, v89
	v_cndmask_b32_e64 v91, v243, v91, s[24:25]
	v_fmamk_f32 v62, v62, 0x3fb8aa3b, v91
	v_fmamk_f32 v63, v63, 0x3fb8aa3b, v91
	v_fmamk_f32 v64, v64, 0x3fb8aa3b, v91
	v_fmamk_f32 v65, v65, 0x3fb8aa3b, v91
	v_exp_f32_e32 v62, v62
	v_exp_f32_e32 v63, v63
	v_exp_f32_e32 v64, v64
	v_exp_f32_e32 v65, v65
	v_fmamk_f32 v66, v66, 0x3fb8aa3b, v91
	v_fmamk_f32 v67, v67, 0x3fb8aa3b, v91
	v_fmamk_f32 v68, v68, 0x3fb8aa3b, v91
	v_fmamk_f32 v69, v69, 0x3fb8aa3b, v91
	v_exp_f32_e32 v66, v66
	v_exp_f32_e32 v67, v67
	v_exp_f32_e32 v68, v68
	v_exp_f32_e32 v69, v69
	v_fmamk_f32 v70, v70, 0x3fb8aa3b, v91
	v_fmamk_f32 v71, v71, 0x3fb8aa3b, v91
	v_fmamk_f32 v72, v72, 0x3fb8aa3b, v91
	v_fmamk_f32 v73, v73, 0x3fb8aa3b, v91
	v_exp_f32_e32 v70, v70
	v_exp_f32_e32 v71, v71
	v_exp_f32_e32 v72, v72
	v_exp_f32_e32 v73, v73
	v_fmamk_f32 v74, v74, 0x3fb8aa3b, v91
	v_fmamk_f32 v75, v75, 0x3fb8aa3b, v91
	v_fmamk_f32 v76, v76, 0x3fb8aa3b, v91
	v_fmamk_f32 v77, v77, 0x3fb8aa3b, v91
	v_exp_f32_e32 v74, v74
	v_exp_f32_e32 v75, v75
	v_exp_f32_e32 v76, v76
	v_exp_f32_e32 v77, v77
	s_nop 0
	v_add_f32_e32 v86, v62, v63
	v_add_f32_e32 v87, v64, v65
	v_add_f32_e32 v88, v66, v67
	v_add_f32_e32 v89, v68, v69
	v_add_f32_e32 v86, v86, v70
	v_add_f32_e32 v87, v87, v71
	v_add_f32_e32 v88, v88, v72
	v_add_f32_e32 v89, v89, v73
	v_add_f32_e32 v86, v86, v74
	v_add_f32_e32 v87, v87, v75
	v_add_f32_e32 v88, v88, v76
	v_add_f32_e32 v89, v89, v77
	v_add_f32_e32 v86, v86, v87
	v_add_f32_e32 v88, v88, v89
	v_add_f32_e32 v86, v86, v88
	v_cvt_pk_bf16_f32 v78, v62, v63
	v_cvt_pk_bf16_f32 v79, v64, v65
	v_cvt_pk_bf16_f32 v80, v66, v67
	v_cvt_pk_bf16_f32 v81, v68, v69
	v_cvt_pk_bf16_f32 v82, v70, v71
	v_cvt_pk_bf16_f32 v83, v72, v73
	v_cvt_pk_bf16_f32 v84, v74, v75
	v_cvt_pk_bf16_f32 v85, v76, v77
	v_mov_b32_e32 v87, v86
	s_nop 1
	v_permlane16_swap_b32_e32 v86, v87
	v_add_f32_e32 v86, v86, v87
	v_mov_b32_e32 v87, v86
	s_nop 1
	v_permlane32_swap_b32_e32 v86, v87
	v_add_f32_e32 v86, v86, v87
	v_fma_f32 v138, v138, v90, v86
	v_cmp_neq_f32_e64 s[0:1], 1.0, v90
	s_cmp_eq_u64 s[0:1], 0
	s_cbranch_scc1 .Lcm_nosc_26
	v_pk_mul_f32 v[30:31], v[30:31], v[90:91] op_sel_hi:[1,0]
	v_pk_mul_f32 v[32:33], v[32:33], v[90:91] op_sel_hi:[1,0]
	v_pk_mul_f32 v[34:35], v[34:35], v[90:91] op_sel_hi:[1,0]
	v_pk_mul_f32 v[36:37], v[36:37], v[90:91] op_sel_hi:[1,0]
	v_pk_mul_f32 v[38:39], v[38:39], v[90:91] op_sel_hi:[1,0]
	v_pk_mul_f32 v[40:41], v[40:41], v[90:91] op_sel_hi:[1,0]
	v_pk_mul_f32 v[42:43], v[42:43], v[90:91] op_sel_hi:[1,0]
	v_pk_mul_f32 v[44:45], v[44:45], v[90:91] op_sel_hi:[1,0]
	v_pk_mul_f32 v[46:47], v[46:47], v[90:91] op_sel_hi:[1,0]
	v_pk_mul_f32 v[48:49], v[48:49], v[90:91] op_sel_hi:[1,0]
	v_pk_mul_f32 v[50:51], v[50:51], v[90:91] op_sel_hi:[1,0]
	v_pk_mul_f32 v[52:53], v[52:53], v[90:91] op_sel_hi:[1,0]
	v_pk_mul_f32 v[54:55], v[54:55], v[90:91] op_sel_hi:[1,0]
	v_pk_mul_f32 v[56:57], v[56:57], v[90:91] op_sel_hi:[1,0]
	v_pk_mul_f32 v[58:59], v[58:59], v[90:91] op_sel_hi:[1,0]
	v_pk_mul_f32 v[60:61], v[60:61], v[90:91] op_sel_hi:[1,0]

; #define LAS __attribute__((address_space(3)))
; __device__ __forceinline__ f32x4 mfma16(bf16x8 a, bf16x8 b, f32x4 c) { return __builtin_amdgcn_mfma_f32_16x16x32_bf16(a, b, c, 0, 0, 0); }
; template <int D, class SF>
; __device__ __forceinline__ void attn_step(const bf16x8 (&qf)[D / 32], const LAS bf16_t* Ks, const LAS bf16_t* Vt, f32x4 (&o)[D / 16], float& m, float& lsum, float& alpha_out, bf16x8& pf0_out, bf16x8& pf1_out, const int lane, SF sf) {
;     ...
;     for (int ks = 0; ks < D / 32; ++ks) {
; #pragma unroll
;         for (int t = 0; t < 4; ++t) { const bf16x8 kf = *(const LAS bf16x8*)(Ks + (16 * t + c) * KSTR + ks * 32 + 8 * i); s[t] = mfma16(kf, qf[ks], s[t]); }
;     }
;     float v[16];
; #pragma unroll
;     for (int t = 0; t < 4; ++t)
; #pragma unroll
;         for (int r = 0; r < 4; ++r) v[4 * t + r] = sf(16 * t + 4 * i + r, s[t][r]);
; __device__ __forceinline__ void nsa_unit(LAS unsigned char* lds, const Ctx& P, int l, int b, int hkv, int tb) {
;     ...
;                 attn_step<64>(qs, Ks, Vt, o, m, lsum, alpha, pf, pf1, lane,
;                     [&](int kk, float s) { const int dist = tqs - (16 * (nb + kk) + 31); return dist >= 0 ? s * LOG2E + lut[min((unsigned)dist, 1023u)] : NEGBIG; });
.Lcm_gen_24:
	v_lshlrev_b32_e32 v86, 6, v103
	v_sub_u32_e32 v86, v98, v86
	v_add_u32_e32 v86, 0xffffffe1, v86
	v_subrev_u32_e32 v78, 0, v86
	v_min_u32_e32 v78, 0x3ff, v78
	v_lshl_add_u32 v78, v78, 2, v131
	ds_read_b32 v78, v78
	v_subrev_u32_e32 v79, 16, v86
	v_min_u32_e32 v79, 0x3ff, v79
	v_lshl_add_u32 v79, v79, 2, v131
	ds_read_b32 v79, v79
	v_subrev_u32_e32 v80, 32, v86
	v_min_u32_e32 v80, 0x3ff, v80
	v_lshl_add_u32 v80, v80, 2, v131
	ds_read_b32 v80, v80
	v_subrev_u32_e32 v81, 48, v86
	v_min_u32_e32 v81, 0x3ff, v81
	v_lshl_add_u32 v81, v81, 2, v131
	ds_read_b32 v81, v81
	v_subrev_u32_e32 v82, 256, v86
	v_min_u32_e32 v82, 0x3ff, v82
	v_lshl_add_u32 v82, v82, 2, v131
	ds_read_b32 v82, v82
	v_subrev_u32_e32 v83, 272, v86
	v_min_u32_e32 v83, 0x3ff, v83
	v_lshl_add_u32 v83, v83, 2, v131
	ds_read_b32 v83, v83
	v_subrev_u32_e32 v84, 288, v86
	v_min_u32_e32 v84, 0x3ff, v84
	v_lshl_add_u32 v84, v84, 2, v131
	ds_read_b32 v84, v84
	v_subrev_u32_e32 v85, 304, v86
	v_min_u32_e32 v85, 0x3ff, v85
	v_lshl_add_u32 v85, v85, 2, v131
	ds_read_b32 v85, v85
	ds_read_b128 v[198:201], v132 offset:16384
	ds_read_b128 v[206:209], v132 offset:18688
	ds_read_b128 v[202:205], v132 offset:16448
	ds_read_b128 v[210:213], v132 offset:18752
	ds_read_b128 v[214:217], v132 offset:20992
	ds_read_b128 v[222:225], v132 offset:23296
	ds_read_b128 v[218:221], v132 offset:21056
	ds_read_b128 v[226:229], v132 offset:23360
	s_waitcnt lgkmcnt(6)
	v_mfma_f32_16x16x32_bf16 v[62:65], v[198:201], v[10:13], 0
	v_mfma_f32_16x16x32_bf16 v[66:69], v[206:209], v[10:13], 0
	s_waitcnt lgkmcnt(4)
	v_mfma_f32_16x16x32_bf16 v[62:65], v[202:205], v[14:17], v[62:65]
	v_mfma_f32_16x16x32_bf16 v[66:69], v[210:213], v[14:17], v[66:69]
	s_waitcnt lgkmcnt(2)
	v_mfma_f32_16x16x32_bf16 v[70:73], v[214:217], v[10:13], 0
	v_mfma_f32_16x16x32_bf16 v[74:77], v[222:225], v[10:13], 0
	s_waitcnt lgkmcnt(0)
	v_mfma_f32_16x16x32_bf16 v[70:73], v[218:221], v[14:17], v[70:73]
	v_mfma_f32_16x16x32_bf16 v[74:77], v[226:229], v[14:17], v[74:77]
	ds_read_b64_tr_b16 v[198:199], v133 offset:25600
	ds_read_b64_tr_b16 v[200:201], v133 offset:27904
	ds_read_b64_tr_b16 v[202:203], v133 offset:30208
	ds_read_b64_tr_b16 v[204:205], v133 offset:32512
	ds_read_b64_tr_b16 v[206:207], v133 offset:25632
	ds_read_b64_tr_b16 v[208:209], v133 offset:27936
	ds_read_b64_tr_b16 v[210:211], v133 offset:30240
	v_fmamk_f32 v62, v62, 0x3fb8aa3b, v78
	v_fmamk_f32 v63, v63, 0x3fb8aa3b, v79
	v_fmamk_f32 v64, v64, 0x3fb8aa3b, v80
	v_fmamk_f32 v65, v65, 0x3fb8aa3b, v81
	v_fmamk_f32 v66, v66, 0x3fb8aa3b, v82
	v_fmamk_f32 v67, v67, 0x3fb8aa3b, v83
	v_fmamk_f32 v68, v68, 0x3fb8aa3b, v84
	v_fmamk_f32 v69, v69, 0x3fb8aa3b, v85
	v_cmp_le_i32_e32 vcc, 0, v86
	s_nop 1
	v_cndmask_b32_e32 v62, v243, v62, vcc
	v_cmp_le_i32_e32 vcc, 16, v86
	s_nop 1
	v_cndmask_b32_e32 v63, v243, v63, vcc
	v_cmp_le_i32_e32 vcc, 32, v86
	s_nop 1
	v_cndmask_b32_e32 v64, v243, v64, vcc
	v_cmp_le_i32_e32 vcc, 48, v86
	s_nop 1
	v_cndmask_b32_e32 v65, v243, v65, vcc
	v_cmp_le_i32_e32 vcc, 256, v86
	s_nop 1
	v_cndmask_b32_e32 v66, v243, v66, vcc
	v_cmp_le_i32_e32 vcc, 272, v86
	s_nop 1
	v_cndmask_b32_e32 v67, v243, v67, vcc
	v_cmp_le_i32_e32 vcc, 288, v86
	s_nop 1
	v_cndmask_b32_e32 v68, v243, v68, vcc
	v_cmp_le_i32_e32 vcc, 304, v86
	s_nop 1
	v_cndmask_b32_e32 v69, v243, v69, vcc
	v_subrev_u32_e32 v78, 512, v86
	v_min_u32_e32 v78, 0x3ff, v78
	v_lshl_add_u32 v78, v78, 2, v131
	ds_read_b32 v78, v78
	v_subrev_u32_e32 v79, 528, v86
	v_min_u32_e32 v79, 0x3ff, v79
	v_lshl_add_u32 v79, v79, 2, v131
	ds_read_b32 v79, v79
	v_subrev_u32_e32 v80, 544, v86
	v_min_u32_e32 v80, 0x3ff, v80
	v_lshl_add_u32 v80, v80, 2, v131
	ds_read_b32 v80, v80
	v_subrev_u32_e32 v81, 560, v86
	v_min_u32_e32 v81, 0x3ff, v81
	v_lshl_add_u32 v81, v81, 2, v131
	ds_read_b32 v81, v81
	v_subrev_u32_e32 v82, 768, v86
	v_min_u32_e32 v82, 0x3ff, v82
	v_lshl_add_u32 v82, v82, 2, v131
	ds_read_b32 v82, v82
	v_subrev_u32_e32 v83, 784, v86
	v_min_u32_e32 v83, 0x3ff, v83
	v_lshl_add_u32 v83, v83, 2, v131
	ds_read_b32 v83, v83
	v_subrev_u32_e32 v84, 800, v86
	v_min_u32_e32 v84, 0x3ff, v84
	v_lshl_add_u32 v84, v84, 2, v131
	ds_read_b32 v84, v84
	v_subrev_u32_e32 v85, 816, v86
	v_min_u32_e32 v85, 0x3ff, v85
	v_lshl_add_u32 v85, v85, 2, v131
	ds_read_b32 v85, v85
	ds_read_b64_tr_b16 v[212:213], v133 offset:32544
	ds_read_b64_tr_b16 v[214:215], v133 offset:25664
	ds_read_b64_tr_b16 v[216:217], v133 offset:27968
	ds_read_b64_tr_b16 v[218:219], v133 offset:30272
	ds_read_b64_tr_b16 v[220:221], v133 offset:32576
	ds_read_b64_tr_b16 v[222:223], v133 offset:25696
	ds_read_b64_tr_b16 v[224:225], v133 offset:28000
	ds_read_b64_tr_b16 v[226:227], v133 offset:30304
	ds_read_b64_tr_b16 v[228:229], v133 offset:32608
	s_waitcnt lgkmcnt(9)
; template <int D, class SF>
; __device__ __forceinline__ void attn_step(const bf16x8 (&qf)[D / 32], const LAS bf16_t* Ks, const LAS bf16_t* Vt, f32x4 (&o)[D / 16], float& m, float& lsum, float& alpha_out, bf16x8& pf0_out, bf16x8& pf1_out, const int lane, SF sf) {
;     ...
;         for (int r = 0; r < 4; ++r) v[4 * t + r] = sf(16 * t + 4 * i + r, s[t][r]);
;     float mx = fmaxf(fmaxf(fmaxf(v[0], v[1]), fmaxf(v[2], v[3])), fmaxf(fmaxf(v[4], v[5]), fmaxf(v[6], v[7])));
;     mx = fmaxf(mx, fmaxf(fmaxf(fmaxf(v[8], v[9]), fmaxf(v[10], v[11])), fmaxf(fmaxf(v[12], v[13]), fmaxf(v[14], v[15]))));
;     mx = rows_max(mx);
;     const float mnew = fmaxf(m, mx);
;     const float mc = fmaxf(mnew, -1e20f);
;     const float alpha = __builtin_amdgcn_exp2f(fmaxf(m, -1e20f) - mc);
;     float p[16], rs = 0.f;
; #pragma unroll
;     for (int r = 0; r < 16; ++r) { p[r] = __builtin_amdgcn_exp2f(v[r] - mc); rs += p[r]; }
;     rs = rows_sum(rs);
;     lsum = lsum * alpha + rs; m = mnew;
;     union { u32x4 u; bf16x8 b; } pk0, pk1;
;     pk0.u.x = cvt_pk_bf16(p[0], p[1]); pk0.u.y = cvt_pk_bf16(p[2], p[3]); pk0.u.z = cvt_pk_bf16(p[4], p[5]); pk0.u.w = cvt_pk_bf16(p[6], p[7]);
;     pk1.u.x = cvt_pk_bf16(p[8], p[9]); pk1.u.y = cvt_pk_bf16(p[10], p[11]); pk1.u.z = cvt_pk_bf16(p[12], p[13]); pk1.u.w = cvt_pk_bf16(p[14], p[15]);
;     if (__builtin_amdgcn_ballot_w64(alpha != 1.0f) != 0ull) {
; #pragma unroll
;         for (int dt = 0; dt < D / 16; ++dt) o[dt] *= alpha;
;     }
; #pragma unroll
;     for (int dt = 0; dt < D / 16; ++dt) {
;         const LAS bf16_t* vp = Vt + (16 * dt + c) * 72 + 4 * i;
;         union { u32x4 u; bf16x8 b; } vf0, vf1; const u32x2 a0 = *(const LAS u32x2*)vp, a1 = *(const LAS u32x2*)(vp + 16), b0 = *(const LAS u32x2*)(vp + 32), b1 = *(const LAS u32x2*)(vp + 48);
;         vf0.u.x = a0.x; vf0.u.y = a0.y; vf0.u.z = a1.x; vf0.u.w = a1.y; vf1.u.x = b0.x; vf1.u.y = b0.y; vf1.u.z = b1.x; vf1.u.w = b1.y;
;         o[dt] = mfma16(vf0.b, pk0.b, o[dt]); o[dt] = mfma16(vf1.b, pk1.b, o[dt]);
;     }
;     alpha_out = alpha; pf0_out = pk0.b; pf1_out = pk1.b;
; __device__ __forceinline__ void nsa_unit(LAS unsigned char* lds, const Ctx& P, int l, int b, int hkv, int tb) {
;     ...
; #pragma unroll
;                 for (int jt = 0; jt < 4; ++jt) oi[jt] *= alpha;
;                 oi[kt] = mfma16(ovA[0], pf, oi[kt]); oi[kt] = mfma16(ovA[1], pf1, oi[kt]);
	v_fmamk_f32 v70, v70, 0x3fb8aa3b, v78
	v_fmamk_f32 v71, v71, 0x3fb8aa3b, v79
	v_fmamk_f32 v72, v72, 0x3fb8aa3b, v80
	v_fmamk_f32 v73, v73, 0x3fb8aa3b, v81
	v_fmamk_f32 v74, v74, 0x3fb8aa3b, v82
	v_fmamk_f32 v75, v75, 0x3fb8aa3b, v83
	v_fmamk_f32 v76, v76, 0x3fb8aa3b, v84
	v_fmamk_f32 v77, v77, 0x3fb8aa3b, v85
	v_cmp_le_i32_e32 vcc, 512, v86
	s_nop 1
	v_cndmask_b32_e32 v70, v243, v70, vcc
	v_cmp_le_i32_e32 vcc, 528, v86
	s_nop 1
	v_cndmask_b32_e32 v71, v243, v71, vcc
	v_cmp_le_i32_e32 vcc, 544, v86
	s_nop 1
	v_cndmask_b32_e32 v72, v243, v72, vcc
	v_cmp_le_i32_e32 vcc, 560, v86
	s_nop 1
	v_cndmask_b32_e32 v73, v243, v73, vcc
	v_cmp_le_i32_e32 vcc, 768, v86
	s_nop 1
	v_cndmask_b32_e32 v74, v243, v74, vcc
	v_cmp_le_i32_e32 vcc, 784, v86
	s_nop 1
	v_cndmask_b32_e32 v75, v243, v75, vcc
	v_cmp_le_i32_e32 vcc, 800, v86
	s_nop 1
	v_cndmask_b32_e32 v76, v243, v76, vcc
	v_cmp_le_i32_e32 vcc, 816, v86
	s_nop 1
	v_cndmask_b32_e32 v77, v243, v77, vcc
	v_max3_f32 v92, v62, v63, v64
	v_max3_f32 v87, v65, v66, v67
	v_max3_f32 v88, v68, v69, v70
	v_max3_f32 v89, v71, v72, v73
	v_max3_f32 v91, v74, v75, v76
	v_max3_f32 v92, v92, v87, v77
	v_max3_f32 v88, v88, v89, v91
	v_max_f32_e32 v92, v92, v88
	v_mov_b32_e32 v87, v92
	s_nop 1
	v_permlane16_swap_b32_e32 v92, v87
	v_max_f32_e32 v92, v92, v87
	v_mov_b32_e32 v87, v92
	s_nop 1
	v_permlane32_swap_b32_e32 v92, v87
	v_max_f32_e32 v92, v92, v87
	v_max_f32_e32 v88, v137, v92
	v_max_f32_e32 v90, 0xe0ad78ec, v137
	v_max_f32_e32 v89, 0xe0ad78ec, v88
	v_sub_f32_e32 v90, v90, v89
	v_mov_b32_e32 v137, v88
	v_exp_f32_e32 v90, v90
	v_sub_f32_e32 v62, v62, v89
	v_sub_f32_e32 v63, v63, v89
	v_sub_f32_e32 v64, v64, v89
	v_sub_f32_e32 v65, v65, v89
	v_exp_f32_e32 v62, v62
	v_exp_f32_e32 v63, v63
	v_exp_f32_e32 v64, v64
	v_exp_f32_e32 v65, v65
	v_sub_f32_e32 v66, v66, v89
	v_sub_f32_e32 v67, v67, v89
	v_sub_f32_e32 v68, v68, v89
	v_sub_f32_e32 v69, v69, v89
	v_exp_f32_e32 v66, v66
	v_exp_f32_e32 v67, v67
	v_exp_f32_e32 v68, v68
	v_exp_f32_e32 v69, v69
	v_sub_f32_e32 v70, v70, v89
	v_sub_f32_e32 v71, v71, v89
	v_sub_f32_e32 v72, v72, v89
	v_sub_f32_e32 v73, v73, v89
	v_exp_f32_e32 v70, v70
	v_exp_f32_e32 v71, v71
	v_exp_f32_e32 v72, v72
	v_exp_f32_e32 v73, v73
	v_sub_f32_e32 v74, v74, v89
	v_sub_f32_e32 v75, v75, v89
	v_sub_f32_e32 v76, v76, v89
	v_sub_f32_e32 v77, v77, v89
	v_exp_f32_e32 v74, v74
	v_exp_f32_e32 v75, v75
	v_exp_f32_e32 v76, v76
	v_exp_f32_e32 v77, v77
	s_nop 0
	v_add_f32_e32 v86, v62, v63
	v_add_f32_e32 v87, v64, v65
	v_add_f32_e32 v88, v66, v67
	v_add_f32_e32 v89, v68, v69
	v_add_f32_e32 v86, v86, v70
	v_add_f32_e32 v87, v87, v71
	v_add_f32_e32 v88, v88, v72
	v_add_f32_e32 v89, v89, v73
	v_add_f32_e32 v86, v86, v74
	v_add_f32_e32 v87, v87, v75
	v_add_f32_e32 v88, v88, v76
	v_add_f32_e32 v89, v89, v77
	v_add_f32_e32 v86, v86, v87
	v_add_f32_e32 v88, v88, v89
	v_add_f32_e32 v86, v86, v88
	v_cvt_pk_bf16_f32 v78, v62, v63
	v_cvt_pk_bf16_f32 v79, v64, v65
	v_cvt_pk_bf16_f32 v80, v66, v67
	v_cvt_pk_bf16_f32 v81, v68, v69
	v_cvt_pk_bf16_f32 v82, v70, v71
	v_cvt_pk_bf16_f32 v83, v72, v73
	v_cvt_pk_bf16_f32 v84, v74, v75
	v_cvt_pk_bf16_f32 v85, v76, v77
	v_mov_b32_e32 v87, v86
	s_nop 1
	v_permlane16_swap_b32_e32 v86, v87
	v_add_f32_e32 v86, v86, v87
	v_mov_b32_e32 v87, v86
	s_nop 1
	v_permlane32_swap_b32_e32 v86, v87
	v_add_f32_e32 v86, v86, v87
	v_fma_f32 v138, v138, v90, v86
	v_cmp_neq_f32_e64 s[0:1], 1.0, v90
	s_cmp_eq_u64 s[0:1], 0
	s_cbranch_scc1 .Lcm_nosc_27
	v_pk_mul_f32 v[30:31], v[30:31], v[90:91] op_sel_hi:[1,0]
	v_pk_mul_f32 v[32:33], v[32:33], v[90:91] op_sel_hi:[1,0]
	v_pk_mul_f32 v[34:35], v[34:35], v[90:91] op_sel_hi:[1,0]
	v_pk_mul_f32 v[36:37], v[36:37], v[90:91] op_sel_hi:[1,0]
	v_pk_mul_f32 v[38:39], v[38:39], v[90:91] op_sel_hi:[1,0]
	v_pk_mul_f32 v[40:41], v[40:41], v[90:91] op_sel_hi:[1,0]
	v_pk_mul_f32 v[42:43], v[42:43], v[90:91] op_sel_hi:[1,0]
	v_pk_mul_f32 v[44:45], v[44:45], v[90:91] op_sel_hi:[1,0]
	v_pk_mul_f32 v[46:47], v[46:47], v[90:91] op_sel_hi:[1,0]
	v_pk_mul_f32 v[48:49], v[48:49], v[90:91] op_sel_hi:[1,0]
	v_pk_mul_f32 v[50:51], v[50:51], v[90:91] op_sel_hi:[1,0]
	v_pk_mul_f32 v[52:53], v[52:53], v[90:91] op_sel_hi:[1,0]
	v_pk_mul_f32 v[54:55], v[54:55], v[90:91] op_sel_hi:[1,0]
	v_pk_mul_f32 v[56:57], v[56:57], v[90:91] op_sel_hi:[1,0]
	v_pk_mul_f32 v[58:59], v[58:59], v[90:91] op_sel_hi:[1,0]
	v_pk_mul_f32 v[60:61], v[60:61], v[90:91] op_sel_hi:[1,0]

; template <int D, class SF>
; __device__ __forceinline__ void attn_step(const bf16x8 (&qf)[D / 32], const LAS bf16_t* Ks, const LAS bf16_t* Vt, f32x4 (&o)[D / 16], float& m, float& lsum, float& alpha_out, bf16x8& pf0_out, bf16x8& pf1_out, const int lane, SF sf) {
;     ...
;     float mx = fmaxf(fmaxf(fmaxf(v[0], v[1]), fmaxf(v[2], v[3])), fmaxf(fmaxf(v[4], v[5]), fmaxf(v[6], v[7])));
;     mx = fmaxf(mx, fmaxf(fmaxf(fmaxf(v[8], v[9]), fmaxf(v[10], v[11])), fmaxf(fmaxf(v[12], v[13]), fmaxf(v[14], v[15]))));
;     mx = rows_max(mx);
;     const float mnew = fmaxf(m, mx);
;     const float mc = fmaxf(mnew, -1e20f);
;     const float alpha = __builtin_amdgcn_exp2f(fmaxf(m, -1e20f) - mc);
;     float p[16], rs = 0.f;
; #pragma unroll
;     for (int r = 0; r < 16; ++r) { p[r] = __builtin_amdgcn_exp2f(v[r] - mc); rs += p[r]; }
;     rs = rows_sum(rs);
;     lsum = lsum * alpha + rs; m = mnew;
;     union { u32x4 u; bf16x8 b; } pk0, pk1;
;     pk0.u.x = cvt_pk_bf16(p[0], p[1]); pk0.u.y = cvt_pk_bf16(p[2], p[3]); pk0.u.z = cvt_pk_bf16(p[4], p[5]); pk0.u.w = cvt_pk_bf16(p[6], p[7]);
;     pk1.u.x = cvt_pk_bf16(p[8], p[9]); pk1.u.y = cvt_pk_bf16(p[10], p[11]); pk1.u.z = cvt_pk_bf16(p[12], p[13]); pk1.u.w = cvt_pk_bf16(p[14], p[15]);
;     if (__builtin_amdgcn_ballot_w64(alpha != 1.0f) != 0ull) {
; #pragma unroll
;         for (int dt = 0; dt < D / 16; ++dt) o[dt] *= alpha;
;     }
; #pragma unroll
;     for (int dt = 0; dt < D / 16; ++dt) {
;         const LAS bf16_t* vp = Vt + (16 * dt + c) * 72 + 4 * i;
; __device__ __forceinline__ void nsa_unit(LAS unsigned char* lds, const Ctx& P, int l, int b, int hkv, int tb) {
;     ...
;         for (int pr = 0; pr < 2; ++pr) if (2 * pr < ntile) {
;             const bool hasb = 2 * pr + 1 < ntile;
;             __syncthreads();
;             load2(KC, VC, 64, 128 * pr, 128 * pr + 64, hasb, 255);
;             __syncthreads();
; #pragma unroll
;             for (int sl = 0; sl < 2; ++sl) if (sl == 0 || hasb) {
;                 const int kt = 2 * pr + sl; const LAS bf16_t* Ks = KV + sl * 9216; const LAS bf16_t* Vt = Ks + 4608; const int nb = kt * 64;
;                 attn_step<64>(qs, Ks, Vt, o, m, lsum, alpha, pf, pf1, lane,
;                     [&](int kk, float s) { const int dist = tqs - (16 * (nb + kk) + 31); return dist >= 0 ? s * LOG2E + lut[min((unsigned)dist, 1023u)] : NEGBIG; });
; #pragma unroll
.Lcm_td_25:
	s_cmp_lt_u32 s26, 2
	s_cbranch_scc1 .Lcm_nb_28
	s_sub_i32 s44, s55, 1024
	s_cmp_ge_i32 s44, 0x725
	s_cbranch_scc0 .Lcm_gen_29
	ds_read_b128 v[198:201], v132 offset:34816
	ds_read_b128 v[206:209], v132 offset:37120
	ds_read_b128 v[202:205], v132 offset:34880
	ds_read_b128 v[210:213], v132 offset:37184
	ds_read_b128 v[214:217], v132 offset:39424
	ds_read_b128 v[222:225], v132 offset:41728
	ds_read_b128 v[218:221], v132 offset:39488
	ds_read_b128 v[226:229], v132 offset:41792
	s_waitcnt lgkmcnt(6)
	v_mfma_f32_16x16x32_bf16 v[62:65], v[198:201], v[10:13], 0
	v_mfma_f32_16x16x32_bf16 v[66:69], v[206:209], v[10:13], 0
	s_waitcnt lgkmcnt(4)
	v_mfma_f32_16x16x32_bf16 v[62:65], v[202:205], v[14:17], v[62:65]
	v_mfma_f32_16x16x32_bf16 v[66:69], v[210:213], v[14:17], v[66:69]
	s_waitcnt lgkmcnt(2)
	v_mfma_f32_16x16x32_bf16 v[70:73], v[214:217], v[10:13], 0
	v_mfma_f32_16x16x32_bf16 v[74:77], v[222:225], v[10:13], 0
	s_waitcnt lgkmcnt(0)
	v_mfma_f32_16x16x32_bf16 v[70:73], v[218:221], v[14:17], v[70:73]
	v_mfma_f32_16x16x32_bf16 v[74:77], v[226:229], v[14:17], v[74:77]
	ds_read_b64_tr_b16 v[198:199], v133 offset:44032
	ds_read_b64_tr_b16 v[200:201], v133 offset:46336
	ds_read_b64_tr_b16 v[202:203], v133 offset:48640
	ds_read_b64_tr_b16 v[204:205], v133 offset:50944
	ds_read_b64_tr_b16 v[206:207], v133 offset:44064
	ds_read_b64_tr_b16 v[208:209], v133 offset:46368
	ds_read_b64_tr_b16 v[210:211], v133 offset:48672
	ds_read_b64_tr_b16 v[212:213], v133 offset:50976
	ds_read_b64_tr_b16 v[214:215], v133 offset:44096
	ds_read_b64_tr_b16 v[216:217], v133 offset:46400
	ds_read_b64_tr_b16 v[218:219], v133 offset:48704
	ds_read_b64_tr_b16 v[220:221], v133 offset:51008
	ds_read_b64_tr_b16 v[222:223], v133 offset:44128
	ds_read_b64_tr_b16 v[224:225], v133 offset:46432
	ds_read_b64_tr_b16 v[226:227], v133 offset:48736
	ds_read_b64_tr_b16 v[228:229], v133 offset:51040
	v_max3_f32 v86, v62, v63, v64
	v_max3_f32 v87, v65, v66, v67
	v_max3_f32 v88, v68, v69, v70
	v_max3_f32 v89, v71, v72, v73
	v_max3_f32 v91, v74, v75, v76
	v_max3_f32 v86, v86, v87, v77
	v_max3_f32 v88, v88, v89, v91
	v_max_f32_e32 v86, v86, v88
	v_mov_b32_e32 v87, v86
	s_nop 1
	v_permlane16_swap_b32_e32 v86, v87
	v_max_f32_e32 v86, v86, v87
	v_mov_b32_e32 v87, v86
	s_nop 1
	v_permlane32_swap_b32_e32 v86, v87
	v_max_f32_e32 v86, v86, v87
	v_fmamk_f32 v86, v86, 0x3fb8aa3b, v165
	v_cndmask_b32_e64 v86, v243, v86, s[24:25]
	v_max_f32_e32 v88, v137, v86
	v_max_f32_e32 v90, 0xe0ad78ec, v137
	v_max_f32_e32 v89, 0xe0ad78ec, v88
	v_sub_f32_e32 v90, v90, v89
	v_mov_b32_e32 v137, v88
	v_exp_f32_e32 v90, v90
	v_sub_f32_e32 v91, v165, v89
	v_cndmask_b32_e64 v91, v243, v91, s[24:25]
	v_fmamk_f32 v62, v62, 0x3fb8aa3b, v91
	v_fmamk_f32 v63, v63, 0x3fb8aa3b, v91
	v_fmamk_f32 v64, v64, 0x3fb8aa3b, v91
	v_fmamk_f32 v65, v65, 0x3fb8aa3b, v91
	v_exp_f32_e32 v62, v62
	v_exp_f32_e32 v63, v63
	v_exp_f32_e32 v64, v64
	v_exp_f32_e32 v65, v65
	v_fmamk_f32 v66, v66, 0x3fb8aa3b, v91
	v_fmamk_f32 v67, v67, 0x3fb8aa3b, v91
	v_fmamk_f32 v68, v68, 0x3fb8aa3b, v91
	v_fmamk_f32 v69, v69, 0x3fb8aa3b, v91
	v_exp_f32_e32 v66, v66
	v_exp_f32_e32 v67, v67
	v_exp_f32_e32 v68, v68
	v_exp_f32_e32 v69, v69
	v_fmamk_f32 v70, v70, 0x3fb8aa3b, v91
	v_fmamk_f32 v71, v71, 0x3fb8aa3b, v91
	v_fmamk_f32 v72, v72, 0x3fb8aa3b, v91
	v_fmamk_f32 v73, v73, 0x3fb8aa3b, v91
	v_exp_f32_e32 v70, v70
	v_exp_f32_e32 v71, v71
	v_exp_f32_e32 v72, v72
	v_exp_f32_e32 v73, v73
	v_fmamk_f32 v74, v74, 0x3fb8aa3b, v91
	v_fmamk_f32 v75, v75, 0x3fb8aa3b, v91
	v_fmamk_f32 v76, v76, 0x3fb8aa3b, v91
	v_fmamk_f32 v77, v77, 0x3fb8aa3b, v91
	v_exp_f32_e32 v74, v74
	v_exp_f32_e32 v75, v75
	v_exp_f32_e32 v76, v76
	v_exp_f32_e32 v77, v77
	s_nop 0
	v_add_f32_e32 v86, v62, v63
	v_add_f32_e32 v87, v64, v65
	v_add_f32_e32 v88, v66, v67
	v_add_f32_e32 v89, v68, v69
	v_add_f32_e32 v86, v86, v70
	v_add_f32_e32 v87, v87, v71
	v_add_f32_e32 v88, v88, v72
	v_add_f32_e32 v89, v89, v73
	v_add_f32_e32 v86, v86, v74
	v_add_f32_e32 v87, v87, v75
	v_add_f32_e32 v88, v88, v76
	v_add_f32_e32 v89, v89, v77
	v_add_f32_e32 v86, v86, v87
	v_add_f32_e32 v88, v88, v89
	v_add_f32_e32 v86, v86, v88
	v_cvt_pk_bf16_f32 v78, v62, v63
	v_cvt_pk_bf16_f32 v79, v64, v65
	v_cvt_pk_bf16_f32 v80, v66, v67
	v_cvt_pk_bf16_f32 v81, v68, v69
	v_cvt_pk_bf16_f32 v82, v70, v71
	v_cvt_pk_bf16_f32 v83, v72, v73
	v_cvt_pk_bf16_f32 v84, v74, v75
	v_cvt_pk_bf16_f32 v85, v76, v77
	v_mov_b32_e32 v87, v86
	s_nop 1
	v_permlane16_swap_b32_e32 v86, v87
	v_add_f32_e32 v86, v86, v87
	v_mov_b32_e32 v87, v86
	s_nop 1
	v_permlane32_swap_b32_e32 v86, v87
	v_add_f32_e32 v86, v86, v87
	v_fma_f32 v138, v138, v90, v86
	v_cmp_neq_f32_e64 s[0:1], 1.0, v90
	s_cmp_eq_u64 s[0:1], 0
	s_cbranch_scc1 .Lcm_nosc_31
	v_pk_mul_f32 v[30:31], v[30:31], v[90:91] op_sel_hi:[1,0]
	v_pk_mul_f32 v[32:33], v[32:33], v[90:91] op_sel_hi:[1,0]
	v_pk_mul_f32 v[34:35], v[34:35], v[90:91] op_sel_hi:[1,0]
	v_pk_mul_f32 v[36:37], v[36:37], v[90:91] op_sel_hi:[1,0]
	v_pk_mul_f32 v[38:39], v[38:39], v[90:91] op_sel_hi:[1,0]
	v_pk_mul_f32 v[40:41], v[40:41], v[90:91] op_sel_hi:[1,0]
	v_pk_mul_f32 v[42:43], v[42:43], v[90:91] op_sel_hi:[1,0]
	v_pk_mul_f32 v[44:45], v[44:45], v[90:91] op_sel_hi:[1,0]
	v_pk_mul_f32 v[46:47], v[46:47], v[90:91] op_sel_hi:[1,0]
	v_pk_mul_f32 v[48:49], v[48:49], v[90:91] op_sel_hi:[1,0]
	v_pk_mul_f32 v[50:51], v[50:51], v[90:91] op_sel_hi:[1,0]
	v_pk_mul_f32 v[52:53], v[52:53], v[90:91] op_sel_hi:[1,0]
	v_pk_mul_f32 v[54:55], v[54:55], v[90:91] op_sel_hi:[1,0]
	v_pk_mul_f32 v[56:57], v[56:57], v[90:91] op_sel_hi:[1,0]
	v_pk_mul_f32 v[58:59], v[58:59], v[90:91] op_sel_hi:[1,0]
	v_pk_mul_f32 v[60:61], v[60:61], v[90:91] op_sel_hi:[1,0]

; #define LAS __attribute__((address_space(3)))
; __device__ __forceinline__ f32x4 mfma16(bf16x8 a, bf16x8 b, f32x4 c) { return __builtin_amdgcn_mfma_f32_16x16x32_bf16(a, b, c, 0, 0, 0); }
; template <int D, class SF>
; __device__ __forceinline__ void attn_step(const bf16x8 (&qf)[D / 32], const LAS bf16_t* Ks, const LAS bf16_t* Vt, f32x4 (&o)[D / 16], float& m, float& lsum, float& alpha_out, bf16x8& pf0_out, bf16x8& pf1_out, const int lane, SF sf) {
;     ...
;     for (int ks = 0; ks < D / 32; ++ks) {
; #pragma unroll
;         for (int t = 0; t < 4; ++t) { const bf16x8 kf = *(const LAS bf16x8*)(Ks + (16 * t + c) * KSTR + ks * 32 + 8 * i); s[t] = mfma16(kf, qf[ks], s[t]); }
;     }
;     float v[16];
; #pragma unroll
;     for (int t = 0; t < 4; ++t)
; #pragma unroll
;         for (int r = 0; r < 4; ++r) v[4 * t + r] = sf(16 * t + 4 * i + r, s[t][r]);
; __device__ __forceinline__ void nsa_unit(LAS unsigned char* lds, const Ctx& P, int l, int b, int hkv, int tb) {
;     ...
;                 attn_step<64>(qs, Ks, Vt, o, m, lsum, alpha, pf, pf1, lane,
;                     [&](int kk, float s) { const int dist = tqs - (16 * (nb + kk) + 31); return dist >= 0 ? s * LOG2E + lut[min((unsigned)dist, 1023u)] : NEGBIG; });
.Lcm_gen_29:
	v_lshlrev_b32_e32 v86, 6, v103
	v_sub_u32_e32 v86, v98, v86
	v_add_u32_e32 v86, 0xfffffbe1, v86
	v_subrev_u32_e32 v78, 0, v86
	v_min_u32_e32 v78, 0x3ff, v78
	v_lshl_add_u32 v78, v78, 2, v131
	ds_read_b32 v78, v78
	v_subrev_u32_e32 v79, 16, v86
	v_min_u32_e32 v79, 0x3ff, v79
	v_lshl_add_u32 v79, v79, 2, v131
	ds_read_b32 v79, v79
	v_subrev_u32_e32 v80, 32, v86
	v_min_u32_e32 v80, 0x3ff, v80
	v_lshl_add_u32 v80, v80, 2, v131
	ds_read_b32 v80, v80
	v_subrev_u32_e32 v81, 48, v86
	v_min_u32_e32 v81, 0x3ff, v81
	v_lshl_add_u32 v81, v81, 2, v131
	ds_read_b32 v81, v81
	v_subrev_u32_e32 v82, 256, v86
	v_min_u32_e32 v82, 0x3ff, v82
	v_lshl_add_u32 v82, v82, 2, v131
	ds_read_b32 v82, v82
	v_subrev_u32_e32 v83, 272, v86
	v_min_u32_e32 v83, 0x3ff, v83
	v_lshl_add_u32 v83, v83, 2, v131
	ds_read_b32 v83, v83
	v_subrev_u32_e32 v84, 288, v86
	v_min_u32_e32 v84, 0x3ff, v84
	v_lshl_add_u32 v84, v84, 2, v131
	ds_read_b32 v84, v84
	v_subrev_u32_e32 v85, 304, v86
	v_min_u32_e32 v85, 0x3ff, v85
	v_lshl_add_u32 v85, v85, 2, v131
	ds_read_b32 v85, v85
	ds_read_b128 v[198:201], v132 offset:34816
	ds_read_b128 v[206:209], v132 offset:37120
	ds_read_b128 v[202:205], v132 offset:34880
	ds_read_b128 v[210:213], v132 offset:37184
	ds_read_b128 v[214:217], v132 offset:39424
	ds_read_b128 v[222:225], v132 offset:41728
	ds_read_b128 v[218:221], v132 offset:39488
	ds_read_b128 v[226:229], v132 offset:41792
	s_waitcnt lgkmcnt(6)
	v_mfma_f32_16x16x32_bf16 v[62:65], v[198:201], v[10:13], 0
	v_mfma_f32_16x16x32_bf16 v[66:69], v[206:209], v[10:13], 0
	s_waitcnt lgkmcnt(4)
	v_mfma_f32_16x16x32_bf16 v[62:65], v[202:205], v[14:17], v[62:65]
	v_mfma_f32_16x16x32_bf16 v[66:69], v[210:213], v[14:17], v[66:69]
	s_waitcnt lgkmcnt(2)
	v_mfma_f32_16x16x32_bf16 v[70:73], v[214:217], v[10:13], 0
	v_mfma_f32_16x16x32_bf16 v[74:77], v[222:225], v[10:13], 0
	s_waitcnt lgkmcnt(0)
	v_mfma_f32_16x16x32_bf16 v[70:73], v[218:221], v[14:17], v[70:73]
	v_mfma_f32_16x16x32_bf16 v[74:77], v[226:229], v[14:17], v[74:77]
	ds_read_b64_tr_b16 v[198:199], v133 offset:44032
	ds_read_b64_tr_b16 v[200:201], v133 offset:46336
	ds_read_b64_tr_b16 v[202:203], v133 offset:48640
	ds_read_b64_tr_b16 v[204:205], v133 offset:50944
	ds_read_b64_tr_b16 v[206:207], v133 offset:44064
	ds_read_b64_tr_b16 v[208:209], v133 offset:46368
	ds_read_b64_tr_b16 v[210:211], v133 offset:48672
	v_fmamk_f32 v62, v62, 0x3fb8aa3b, v78
	v_fmamk_f32 v63, v63, 0x3fb8aa3b, v79
	v_fmamk_f32 v64, v64, 0x3fb8aa3b, v80
	v_fmamk_f32 v65, v65, 0x3fb8aa3b, v81
	v_fmamk_f32 v66, v66, 0x3fb8aa3b, v82
	v_fmamk_f32 v67, v67, 0x3fb8aa3b, v83
	v_fmamk_f32 v68, v68, 0x3fb8aa3b, v84
	v_fmamk_f32 v69, v69, 0x3fb8aa3b, v85
	v_cmp_le_i32_e32 vcc, 0, v86
	s_nop 1
	v_cndmask_b32_e32 v62, v243, v62, vcc
	v_cmp_le_i32_e32 vcc, 16, v86
	s_nop 1
	v_cndmask_b32_e32 v63, v243, v63, vcc
	v_cmp_le_i32_e32 vcc, 32, v86
	s_nop 1
	v_cndmask_b32_e32 v64, v243, v64, vcc
	v_cmp_le_i32_e32 vcc, 48, v86
	s_nop 1
	v_cndmask_b32_e32 v65, v243, v65, vcc
	v_cmp_le_i32_e32 vcc, 256, v86
	s_nop 1
	v_cndmask_b32_e32 v66, v243, v66, vcc
	v_cmp_le_i32_e32 vcc, 272, v86
	s_nop 1
	v_cndmask_b32_e32 v67, v243, v67, vcc
	v_cmp_le_i32_e32 vcc, 288, v86
	s_nop 1
	v_cndmask_b32_e32 v68, v243, v68, vcc
	v_cmp_le_i32_e32 vcc, 304, v86
	s_nop 1
	v_cndmask_b32_e32 v69, v243, v69, vcc
	v_subrev_u32_e32 v78, 512, v86
	v_min_u32_e32 v78, 0x3ff, v78
	v_lshl_add_u32 v78, v78, 2, v131
	ds_read_b32 v78, v78
	v_subrev_u32_e32 v79, 528, v86
	v_min_u32_e32 v79, 0x3ff, v79
	v_lshl_add_u32 v79, v79, 2, v131
	ds_read_b32 v79, v79
	v_subrev_u32_e32 v80, 544, v86
	v_min_u32_e32 v80, 0x3ff, v80
	v_lshl_add_u32 v80, v80, 2, v131
	ds_read_b32 v80, v80
	v_subrev_u32_e32 v81, 560, v86
	v_min_u32_e32 v81, 0x3ff, v81
	v_lshl_add_u32 v81, v81, 2, v131
	ds_read_b32 v81, v81
	v_subrev_u32_e32 v82, 768, v86
	v_min_u32_e32 v82, 0x3ff, v82
	v_lshl_add_u32 v82, v82, 2, v131
	ds_read_b32 v82, v82
	v_subrev_u32_e32 v83, 784, v86
	v_min_u32_e32 v83, 0x3ff, v83
	v_lshl_add_u32 v83, v83, 2, v131
	ds_read_b32 v83, v83
	v_subrev_u32_e32 v84, 800, v86
	v_min_u32_e32 v84, 0x3ff, v84
	v_lshl_add_u32 v84, v84, 2, v131
	ds_read_b32 v84, v84
	v_subrev_u32_e32 v85, 816, v86
	v_min_u32_e32 v85, 0x3ff, v85
	v_lshl_add_u32 v85, v85, 2, v131
	ds_read_b32 v85, v85
	ds_read_b64_tr_b16 v[212:213], v133 offset:50976
	ds_read_b64_tr_b16 v[214:215], v133 offset:44096
	ds_read_b64_tr_b16 v[216:217], v133 offset:46400
	ds_read_b64_tr_b16 v[218:219], v133 offset:48704
	ds_read_b64_tr_b16 v[220:221], v133 offset:51008
	ds_read_b64_tr_b16 v[222:223], v133 offset:44128
	ds_read_b64_tr_b16 v[224:225], v133 offset:46432
	ds_read_b64_tr_b16 v[226:227], v133 offset:48736
	ds_read_b64_tr_b16 v[228:229], v133 offset:51040
	s_waitcnt lgkmcnt(9)
; #define LAS __attribute__((address_space(3)))
; __device__ __forceinline__ unsigned cvt_pk_bf16(float lo, float hi) { unsigned r; asm("v_cvt_pk_bf16_f32 %0, %1, %2" : "=v"(r) : "v"(lo), "v"(hi)); return r; }
; template <int D, class SF>
; __device__ __forceinline__ void attn_step(const bf16x8 (&qf)[D / 32], const LAS bf16_t* Ks, const LAS bf16_t* Vt, f32x4 (&o)[D / 16], float& m, float& lsum, float& alpha_out, bf16x8& pf0_out, bf16x8& pf1_out, const int lane, SF sf) {
;     ...
;         for (int r = 0; r < 4; ++r) v[4 * t + r] = sf(16 * t + 4 * i + r, s[t][r]);
;     float mx = fmaxf(fmaxf(fmaxf(v[0], v[1]), fmaxf(v[2], v[3])), fmaxf(fmaxf(v[4], v[5]), fmaxf(v[6], v[7])));
;     mx = fmaxf(mx, fmaxf(fmaxf(fmaxf(v[8], v[9]), fmaxf(v[10], v[11])), fmaxf(fmaxf(v[12], v[13]), fmaxf(v[14], v[15]))));
;     mx = rows_max(mx);
;     const float mnew = fmaxf(m, mx);
;     const float mc = fmaxf(mnew, -1e20f);
;     const float alpha = __builtin_amdgcn_exp2f(fmaxf(m, -1e20f) - mc);
;     float p[16], rs = 0.f;
; #pragma unroll
;     for (int r = 0; r < 16; ++r) { p[r] = __builtin_amdgcn_exp2f(v[r] - mc); rs += p[r]; }
;     rs = rows_sum(rs);
;     lsum = lsum * alpha + rs; m = mnew;
;     union { u32x4 u; bf16x8 b; } pk0, pk1;
;     pk0.u.x = cvt_pk_bf16(p[0], p[1]); pk0.u.y = cvt_pk_bf16(p[2], p[3]); pk0.u.z = cvt_pk_bf16(p[4], p[5]); pk0.u.w = cvt_pk_bf16(p[6], p[7]);
;     pk1.u.x = cvt_pk_bf16(p[8], p[9]); pk1.u.y = cvt_pk_bf16(p[10], p[11]); pk1.u.z = cvt_pk_bf16(p[12], p[13]); pk1.u.w = cvt_pk_bf16(p[14], p[15]);
;     if (__builtin_amdgcn_ballot_w64(alpha != 1.0f) != 0ull) {
; #pragma unroll
;         for (int dt = 0; dt < D / 16; ++dt) o[dt] *= alpha;
;     }
; #pragma unroll
;     for (int dt = 0; dt < D / 16; ++dt) {
;         const LAS bf16_t* vp = Vt + (16 * dt + c) * 72 + 4 * i;
;         union { u32x4 u; bf16x8 b; } vf0, vf1; const u32x2 a0 = *(const LAS u32x2*)vp, a1 = *(const LAS u32x2*)(vp + 16), b0 = *(const LAS u32x2*)(vp + 32), b1 = *(const LAS u32x2*)(vp + 48);
;         vf0.u.x = a0.x; vf0.u.y = a0.y; vf0.u.z = a1.x; vf0.u.w = a1.y; vf1.u.x = b0.x; vf1.u.y = b0.y; vf1.u.z = b1.x; vf1.u.w = b1.y;
;         o[dt] = mfma16(vf0.b, pk0.b, o[dt]); o[dt] = mfma16(vf1.b, pk1.b, o[dt]);
;     }
;     alpha_out = alpha; pf0_out = pk0.b; pf1_out = pk1.b;
	v_fmamk_f32 v70, v70, 0x3fb8aa3b, v78
	v_fmamk_f32 v71, v71, 0x3fb8aa3b, v79
	v_fmamk_f32 v72, v72, 0x3fb8aa3b, v80
	v_fmamk_f32 v73, v73, 0x3fb8aa3b, v81
	v_fmamk_f32 v74, v74, 0x3fb8aa3b, v82
	v_fmamk_f32 v75, v75, 0x3fb8aa3b, v83
	v_fmamk_f32 v76, v76, 0x3fb8aa3b, v84
	v_fmamk_f32 v77, v77, 0x3fb8aa3b, v85
	v_cmp_le_i32_e32 vcc, 512, v86
	s_nop 1
	v_cndmask_b32_e32 v70, v243, v70, vcc
	v_cmp_le_i32_e32 vcc, 528, v86
	s_nop 1
	v_cndmask_b32_e32 v71, v243, v71, vcc
	v_cmp_le_i32_e32 vcc, 544, v86
	s_nop 1
	v_cndmask_b32_e32 v72, v243, v72, vcc
	v_cmp_le_i32_e32 vcc, 560, v86
	s_nop 1
	v_cndmask_b32_e32 v73, v243, v73, vcc
	v_cmp_le_i32_e32 vcc, 768, v86
	s_nop 1
	v_cndmask_b32_e32 v74, v243, v74, vcc
	v_cmp_le_i32_e32 vcc, 784, v86
	s_nop 1
	v_cndmask_b32_e32 v75, v243, v75, vcc
	v_cmp_le_i32_e32 vcc, 800, v86
	s_nop 1
	v_cndmask_b32_e32 v76, v243, v76, vcc
	v_cmp_le_i32_e32 vcc, 816, v86
	s_nop 1
	v_cndmask_b32_e32 v77, v243, v77, vcc
	v_max3_f32 v92, v62, v63, v64
	v_max3_f32 v87, v65, v66, v67
	v_max3_f32 v88, v68, v69, v70
	v_max3_f32 v89, v71, v72, v73
	v_max3_f32 v91, v74, v75, v76
	v_max3_f32 v92, v92, v87, v77
	v_max3_f32 v88, v88, v89, v91
	v_max_f32_e32 v92, v92, v88
	v_mov_b32_e32 v87, v92
	s_nop 1
	v_permlane16_swap_b32_e32 v92, v87
	v_max_f32_e32 v92, v92, v87
	v_mov_b32_e32 v87, v92
	s_nop 1
	v_permlane32_swap_b32_e32 v92, v87
	v_max_f32_e32 v92, v92, v87
	v_max_f32_e32 v88, v137, v92
	v_max_f32_e32 v90, 0xe0ad78ec, v137
	v_max_f32_e32 v89, 0xe0ad78ec, v88
	v_sub_f32_e32 v90, v90, v89
	v_mov_b32_e32 v137, v88
	v_exp_f32_e32 v90, v90
	v_sub_f32_e32 v62, v62, v89
	v_sub_f32_e32 v63, v63, v89
	v_sub_f32_e32 v64, v64, v89
	v_sub_f32_e32 v65, v65, v89
	v_exp_f32_e32 v62, v62
	v_exp_f32_e32 v63, v63
	v_exp_f32_e32 v64, v64
	v_exp_f32_e32 v65, v65
	v_sub_f32_e32 v66, v66, v89
	v_sub_f32_e32 v67, v67, v89
	v_sub_f32_e32 v68, v68, v89
	v_sub_f32_e32 v69, v69, v89
	v_exp_f32_e32 v66, v66
	v_exp_f32_e32 v67, v67
	v_exp_f32_e32 v68, v68
	v_exp_f32_e32 v69, v69
	v_sub_f32_e32 v70, v70, v89
	v_sub_f32_e32 v71, v71, v89
	v_sub_f32_e32 v72, v72, v89
	v_sub_f32_e32 v73, v73, v89
	v_exp_f32_e32 v70, v70
	v_exp_f32_e32 v71, v71
	v_exp_f32_e32 v72, v72
	v_exp_f32_e32 v73, v73
	v_sub_f32_e32 v74, v74, v89
	v_sub_f32_e32 v75, v75, v89
	v_sub_f32_e32 v76, v76, v89
	v_sub_f32_e32 v77, v77, v89
	v_exp_f32_e32 v74, v74
	v_exp_f32_e32 v75, v75
	v_exp_f32_e32 v76, v76
	v_exp_f32_e32 v77, v77
	s_nop 0
	v_add_f32_e32 v86, v62, v63
	v_add_f32_e32 v87, v64, v65
	v_add_f32_e32 v88, v66, v67
	v_add_f32_e32 v89, v68, v69
	v_add_f32_e32 v86, v86, v70
	v_add_f32_e32 v87, v87, v71
	v_add_f32_e32 v88, v88, v72
	v_add_f32_e32 v89, v89, v73
	v_add_f32_e32 v86, v86, v74
	v_add_f32_e32 v87, v87, v75
	v_add_f32_e32 v88, v88, v76
	v_add_f32_e32 v89, v89, v77
	v_add_f32_e32 v86, v86, v87
	v_add_f32_e32 v88, v88, v89
	v_add_f32_e32 v86, v86, v88
	v_cvt_pk_bf16_f32 v78, v62, v63
	v_cvt_pk_bf16_f32 v79, v64, v65
	v_cvt_pk_bf16_f32 v80, v66, v67
	v_cvt_pk_bf16_f32 v81, v68, v69
	v_cvt_pk_bf16_f32 v82, v70, v71
	v_cvt_pk_bf16_f32 v83, v72, v73
	v_cvt_pk_bf16_f32 v84, v74, v75
	v_cvt_pk_bf16_f32 v85, v76, v77
	v_mov_b32_e32 v87, v86
	s_nop 1
	v_permlane16_swap_b32_e32 v86, v87
	v_add_f32_e32 v86, v86, v87
	v_mov_b32_e32 v87, v86
	s_nop 1
	v_permlane32_swap_b32_e32 v86, v87
	v_add_f32_e32 v86, v86, v87
	v_fma_f32 v138, v138, v90, v86
	v_cmp_neq_f32_e64 s[0:1], 1.0, v90
	s_cmp_eq_u64 s[0:1], 0
	s_cbranch_scc1 .Lcm_nosc_32
	v_pk_mul_f32 v[30:31], v[30:31], v[90:91] op_sel_hi:[1,0]
	v_pk_mul_f32 v[32:33], v[32:33], v[90:91] op_sel_hi:[1,0]
	v_pk_mul_f32 v[34:35], v[34:35], v[90:91] op_sel_hi:[1,0]
	v_pk_mul_f32 v[36:37], v[36:37], v[90:91] op_sel_hi:[1,0]
	v_pk_mul_f32 v[38:39], v[38:39], v[90:91] op_sel_hi:[1,0]
	v_pk_mul_f32 v[40:41], v[40:41], v[90:91] op_sel_hi:[1,0]
	v_pk_mul_f32 v[42:43], v[42:43], v[90:91] op_sel_hi:[1,0]
	v_pk_mul_f32 v[44:45], v[44:45], v[90:91] op_sel_hi:[1,0]
	v_pk_mul_f32 v[46:47], v[46:47], v[90:91] op_sel_hi:[1,0]
	v_pk_mul_f32 v[48:49], v[48:49], v[90:91] op_sel_hi:[1,0]
	v_pk_mul_f32 v[50:51], v[50:51], v[90:91] op_sel_hi:[1,0]
	v_pk_mul_f32 v[52:53], v[52:53], v[90:91] op_sel_hi:[1,0]
	v_pk_mul_f32 v[54:55], v[54:55], v[90:91] op_sel_hi:[1,0]
	v_pk_mul_f32 v[56:57], v[56:57], v[90:91] op_sel_hi:[1,0]
	v_pk_mul_f32 v[58:59], v[58:59], v[90:91] op_sel_hi:[1,0]
	v_pk_mul_f32 v[60:61], v[60:61], v[90:91] op_sel_hi:[1,0]

; template <int D, class SF>
; __device__ __forceinline__ void attn_step(const bf16x8 (&qf)[D / 32], const LAS bf16_t* Ks, const LAS bf16_t* Vt, f32x4 (&o)[D / 16], float& m, float& lsum, float& alpha_out, bf16x8& pf0_out, bf16x8& pf1_out, const int lane, SF sf) {
;     ...
;     float mx = fmaxf(fmaxf(fmaxf(v[0], v[1]), fmaxf(v[2], v[3])), fmaxf(fmaxf(v[4], v[5]), fmaxf(v[6], v[7])));
;     mx = fmaxf(mx, fmaxf(fmaxf(fmaxf(v[8], v[9]), fmaxf(v[10], v[11])), fmaxf(fmaxf(v[12], v[13]), fmaxf(v[14], v[15]))));
;     mx = rows_max(mx);
;     const float mnew = fmaxf(m, mx);
;     const float mc = fmaxf(mnew, -1e20f);
;     const float alpha = __builtin_amdgcn_exp2f(fmaxf(m, -1e20f) - mc);
;     float p[16], rs = 0.f;
; #pragma unroll
;     for (int r = 0; r < 16; ++r) { p[r] = __builtin_amdgcn_exp2f(v[r] - mc); rs += p[r]; }
;     rs = rows_sum(rs);
;     lsum = lsum * alpha + rs; m = mnew;
;     union { u32x4 u; bf16x8 b; } pk0, pk1;
;     pk0.u.x = cvt_pk_bf16(p[0], p[1]); pk0.u.y = cvt_pk_bf16(p[2], p[3]); pk0.u.z = cvt_pk_bf16(p[4], p[5]); pk0.u.w = cvt_pk_bf16(p[6], p[7]);
;     pk1.u.x = cvt_pk_bf16(p[8], p[9]); pk1.u.y = cvt_pk_bf16(p[10], p[11]); pk1.u.z = cvt_pk_bf16(p[12], p[13]); pk1.u.w = cvt_pk_bf16(p[14], p[15]);
;     if (__builtin_amdgcn_ballot_w64(alpha != 1.0f) != 0ull) {
; #pragma unroll
;         for (int dt = 0; dt < D / 16; ++dt) o[dt] *= alpha;
;     }
; #pragma unroll
;     for (int dt = 0; dt < D / 16; ++dt) {
;         const LAS bf16_t* vp = Vt + (16 * dt + c) * 72 + 4 * i;
; __device__ __forceinline__ void nsa_unit(LAS unsigned char* lds, const Ctx& P, int l, int b, int hkv, int tb) {
;     ...
;         for (int pr = 0; pr < 2; ++pr) if (2 * pr < ntile) {
;             const bool hasb = 2 * pr + 1 < ntile;
;             __syncthreads();
;             load2(KC, VC, 64, 128 * pr, 128 * pr + 64, hasb, 255);
;             __syncthreads();
; #pragma unroll
;             for (int sl = 0; sl < 2; ++sl) if (sl == 0 || hasb) {
;                 const int kt = 2 * pr + sl; const LAS bf16_t* Ks = KV + sl * 9216; const LAS bf16_t* Vt = Ks + 4608; const int nb = kt * 64;
;                 attn_step<64>(qs, Ks, Vt, o, m, lsum, alpha, pf, pf1, lane,
;                     [&](int kk, float s) { const int dist = tqs - (16 * (nb + kk) + 31); return dist >= 0 ? s * LOG2E + lut[min((unsigned)dist, 1023u)] : NEGBIG; });
; #pragma unroll
.Lcm_wnb_34:
	s_waitcnt lgkmcnt(0)
	s_barrier
	s_sub_i32 s44, s55, 2048
	s_cmp_ge_i32 s44, 0x725
	s_cbranch_scc0 .Lcm_gen_35
	ds_read_b128 v[198:201], v132 offset:16384
	ds_read_b128 v[206:209], v132 offset:18688
	ds_read_b128 v[202:205], v132 offset:16448
	ds_read_b128 v[210:213], v132 offset:18752
	ds_read_b128 v[214:217], v132 offset:20992
	ds_read_b128 v[222:225], v132 offset:23296
	ds_read_b128 v[218:221], v132 offset:21056
	ds_read_b128 v[226:229], v132 offset:23360
	s_waitcnt lgkmcnt(6)
	v_mfma_f32_16x16x32_bf16 v[62:65], v[198:201], v[10:13], 0
	v_mfma_f32_16x16x32_bf16 v[66:69], v[206:209], v[10:13], 0
	s_waitcnt lgkmcnt(4)
	v_mfma_f32_16x16x32_bf16 v[62:65], v[202:205], v[14:17], v[62:65]
	v_mfma_f32_16x16x32_bf16 v[66:69], v[210:213], v[14:17], v[66:69]
	s_waitcnt lgkmcnt(2)
	v_mfma_f32_16x16x32_bf16 v[70:73], v[214:217], v[10:13], 0
	v_mfma_f32_16x16x32_bf16 v[74:77], v[222:225], v[10:13], 0
	s_waitcnt lgkmcnt(0)
	v_mfma_f32_16x16x32_bf16 v[70:73], v[218:221], v[14:17], v[70:73]
	v_mfma_f32_16x16x32_bf16 v[74:77], v[226:229], v[14:17], v[74:77]
	ds_read_b64_tr_b16 v[198:199], v133 offset:25600
	ds_read_b64_tr_b16 v[200:201], v133 offset:27904
	ds_read_b64_tr_b16 v[202:203], v133 offset:30208
	ds_read_b64_tr_b16 v[204:205], v133 offset:32512
	ds_read_b64_tr_b16 v[206:207], v133 offset:25632
	ds_read_b64_tr_b16 v[208:209], v133 offset:27936
	ds_read_b64_tr_b16 v[210:211], v133 offset:30240
	ds_read_b64_tr_b16 v[212:213], v133 offset:32544
	ds_read_b64_tr_b16 v[214:215], v133 offset:25664
	ds_read_b64_tr_b16 v[216:217], v133 offset:27968
	ds_read_b64_tr_b16 v[218:219], v133 offset:30272
	ds_read_b64_tr_b16 v[220:221], v133 offset:32576
	ds_read_b64_tr_b16 v[222:223], v133 offset:25696
	ds_read_b64_tr_b16 v[224:225], v133 offset:28000
	ds_read_b64_tr_b16 v[226:227], v133 offset:30304
	ds_read_b64_tr_b16 v[228:229], v133 offset:32608
	v_max3_f32 v86, v62, v63, v64
	v_max3_f32 v87, v65, v66, v67
	v_max3_f32 v88, v68, v69, v70
	v_max3_f32 v89, v71, v72, v73
	v_max3_f32 v91, v74, v75, v76
	v_max3_f32 v86, v86, v87, v77
	v_max3_f32 v88, v88, v89, v91
	v_max_f32_e32 v86, v86, v88
	v_mov_b32_e32 v87, v86
	s_nop 1
	v_permlane16_swap_b32_e32 v86, v87
	v_max_f32_e32 v86, v86, v87
	v_mov_b32_e32 v87, v86
	s_nop 1
	v_permlane32_swap_b32_e32 v86, v87
	v_max_f32_e32 v86, v86, v87
	v_fmamk_f32 v86, v86, 0x3fb8aa3b, v165
	v_cndmask_b32_e64 v86, v243, v86, s[24:25]
	v_max_f32_e32 v88, v137, v86
	v_max_f32_e32 v90, 0xe0ad78ec, v137
	v_max_f32_e32 v89, 0xe0ad78ec, v88
	v_sub_f32_e32 v90, v90, v89
	v_mov_b32_e32 v137, v88
	v_exp_f32_e32 v90, v90
	v_sub_f32_e32 v91, v165, v89
	v_cndmask_b32_e64 v91, v243, v91, s[24:25]
	v_fmamk_f32 v62, v62, 0x3fb8aa3b, v91
	v_fmamk_f32 v63, v63, 0x3fb8aa3b, v91
	v_fmamk_f32 v64, v64, 0x3fb8aa3b, v91
	v_fmamk_f32 v65, v65, 0x3fb8aa3b, v91
	v_exp_f32_e32 v62, v62
	v_exp_f32_e32 v63, v63
	v_exp_f32_e32 v64, v64
	v_exp_f32_e32 v65, v65
	v_fmamk_f32 v66, v66, 0x3fb8aa3b, v91
	v_fmamk_f32 v67, v67, 0x3fb8aa3b, v91
	v_fmamk_f32 v68, v68, 0x3fb8aa3b, v91
	v_fmamk_f32 v69, v69, 0x3fb8aa3b, v91
	v_exp_f32_e32 v66, v66
	v_exp_f32_e32 v67, v67
	v_exp_f32_e32 v68, v68
	v_exp_f32_e32 v69, v69
	v_fmamk_f32 v70, v70, 0x3fb8aa3b, v91
	v_fmamk_f32 v71, v71, 0x3fb8aa3b, v91
	v_fmamk_f32 v72, v72, 0x3fb8aa3b, v91
	v_fmamk_f32 v73, v73, 0x3fb8aa3b, v91
	v_exp_f32_e32 v70, v70
	v_exp_f32_e32 v71, v71
	v_exp_f32_e32 v72, v72
	v_exp_f32_e32 v73, v73
	v_fmamk_f32 v74, v74, 0x3fb8aa3b, v91
	v_fmamk_f32 v75, v75, 0x3fb8aa3b, v91
	v_fmamk_f32 v76, v76, 0x3fb8aa3b, v91
	v_fmamk_f32 v77, v77, 0x3fb8aa3b, v91
	v_exp_f32_e32 v74, v74
	v_exp_f32_e32 v75, v75
	v_exp_f32_e32 v76, v76
	v_exp_f32_e32 v77, v77
	s_nop 0
	v_add_f32_e32 v86, v62, v63
	v_add_f32_e32 v87, v64, v65
	v_add_f32_e32 v88, v66, v67
	v_add_f32_e32 v89, v68, v69
	v_add_f32_e32 v86, v86, v70
	v_add_f32_e32 v87, v87, v71
	v_add_f32_e32 v88, v88, v72
	v_add_f32_e32 v89, v89, v73
	v_add_f32_e32 v86, v86, v74
	v_add_f32_e32 v87, v87, v75
	v_add_f32_e32 v88, v88, v76
	v_add_f32_e32 v89, v89, v77
	v_add_f32_e32 v86, v86, v87
	v_add_f32_e32 v88, v88, v89
	v_add_f32_e32 v86, v86, v88
	v_cvt_pk_bf16_f32 v78, v62, v63
	v_cvt_pk_bf16_f32 v79, v64, v65
	v_cvt_pk_bf16_f32 v80, v66, v67
	v_cvt_pk_bf16_f32 v81, v68, v69
	v_cvt_pk_bf16_f32 v82, v70, v71
	v_cvt_pk_bf16_f32 v83, v72, v73
	v_cvt_pk_bf16_f32 v84, v74, v75
	v_cvt_pk_bf16_f32 v85, v76, v77
	v_mov_b32_e32 v87, v86
	s_nop 1
	v_permlane16_swap_b32_e32 v86, v87
	v_add_f32_e32 v86, v86, v87
	v_mov_b32_e32 v87, v86
	s_nop 1
	v_permlane32_swap_b32_e32 v86, v87
	v_add_f32_e32 v86, v86, v87
	v_fma_f32 v138, v138, v90, v86
	v_cmp_neq_f32_e64 s[0:1], 1.0, v90
	s_cmp_eq_u64 s[0:1], 0
	s_cbranch_scc1 .Lcm_nosc_37
	v_pk_mul_f32 v[30:31], v[30:31], v[90:91] op_sel_hi:[1,0]
	v_pk_mul_f32 v[32:33], v[32:33], v[90:91] op_sel_hi:[1,0]
	v_pk_mul_f32 v[34:35], v[34:35], v[90:91] op_sel_hi:[1,0]
	v_pk_mul_f32 v[36:37], v[36:37], v[90:91] op_sel_hi:[1,0]
	v_pk_mul_f32 v[38:39], v[38:39], v[90:91] op_sel_hi:[1,0]
	v_pk_mul_f32 v[40:41], v[40:41], v[90:91] op_sel_hi:[1,0]
	v_pk_mul_f32 v[42:43], v[42:43], v[90:91] op_sel_hi:[1,0]
	v_pk_mul_f32 v[44:45], v[44:45], v[90:91] op_sel_hi:[1,0]
	v_pk_mul_f32 v[46:47], v[46:47], v[90:91] op_sel_hi:[1,0]
	v_pk_mul_f32 v[48:49], v[48:49], v[90:91] op_sel_hi:[1,0]
	v_pk_mul_f32 v[50:51], v[50:51], v[90:91] op_sel_hi:[1,0]
	v_pk_mul_f32 v[52:53], v[52:53], v[90:91] op_sel_hi:[1,0]
	v_pk_mul_f32 v[54:55], v[54:55], v[90:91] op_sel_hi:[1,0]
	v_pk_mul_f32 v[56:57], v[56:57], v[90:91] op_sel_hi:[1,0]
	v_pk_mul_f32 v[58:59], v[58:59], v[90:91] op_sel_hi:[1,0]
	v_pk_mul_f32 v[60:61], v[60:61], v[90:91] op_sel_hi:[1,0]

; #define LAS __attribute__((address_space(3)))
; __device__ __forceinline__ f32x4 mfma16(bf16x8 a, bf16x8 b, f32x4 c) { return __builtin_amdgcn_mfma_f32_16x16x32_bf16(a, b, c, 0, 0, 0); }
; template <int D, class SF>
; __device__ __forceinline__ void attn_step(const bf16x8 (&qf)[D / 32], const LAS bf16_t* Ks, const LAS bf16_t* Vt, f32x4 (&o)[D / 16], float& m, float& lsum, float& alpha_out, bf16x8& pf0_out, bf16x8& pf1_out, const int lane, SF sf) {
;     ...
;     for (int ks = 0; ks < D / 32; ++ks) {
; #pragma unroll
;         for (int t = 0; t < 4; ++t) { const bf16x8 kf = *(const LAS bf16x8*)(Ks + (16 * t + c) * KSTR + ks * 32 + 8 * i); s[t] = mfma16(kf, qf[ks], s[t]); }
;     }
;     float v[16];
; #pragma unroll
;     for (int t = 0; t < 4; ++t)
; #pragma unroll
;         for (int r = 0; r < 4; ++r) v[4 * t + r] = sf(16 * t + 4 * i + r, s[t][r]);
; __device__ __forceinline__ void nsa_unit(LAS unsigned char* lds, const Ctx& P, int l, int b, int hkv, int tb) {
;     ...
;                 attn_step<64>(qs, Ks, Vt, o, m, lsum, alpha, pf, pf1, lane,
;                     [&](int kk, float s) { const int dist = tqs - (16 * (nb + kk) + 31); return dist >= 0 ? s * LOG2E + lut[min((unsigned)dist, 1023u)] : NEGBIG; });
.Lcm_gen_35:
	v_lshlrev_b32_e32 v86, 6, v103
	v_sub_u32_e32 v86, v98, v86
	v_add_u32_e32 v86, 0xfffff7e1, v86
	v_subrev_u32_e32 v78, 0, v86
	v_min_u32_e32 v78, 0x3ff, v78
	v_lshl_add_u32 v78, v78, 2, v131
	ds_read_b32 v78, v78
	v_subrev_u32_e32 v79, 16, v86
	v_min_u32_e32 v79, 0x3ff, v79
	v_lshl_add_u32 v79, v79, 2, v131
	ds_read_b32 v79, v79
	v_subrev_u32_e32 v80, 32, v86
	v_min_u32_e32 v80, 0x3ff, v80
	v_lshl_add_u32 v80, v80, 2, v131
	ds_read_b32 v80, v80
	v_subrev_u32_e32 v81, 48, v86
	v_min_u32_e32 v81, 0x3ff, v81
	v_lshl_add_u32 v81, v81, 2, v131
	ds_read_b32 v81, v81
	v_subrev_u32_e32 v82, 256, v86
	v_min_u32_e32 v82, 0x3ff, v82
	v_lshl_add_u32 v82, v82, 2, v131
	ds_read_b32 v82, v82
	v_subrev_u32_e32 v83, 272, v86
	v_min_u32_e32 v83, 0x3ff, v83
	v_lshl_add_u32 v83, v83, 2, v131
	ds_read_b32 v83, v83
	v_subrev_u32_e32 v84, 288, v86
	v_min_u32_e32 v84, 0x3ff, v84
	v_lshl_add_u32 v84, v84, 2, v131
	ds_read_b32 v84, v84
	v_subrev_u32_e32 v85, 304, v86
	v_min_u32_e32 v85, 0x3ff, v85
	v_lshl_add_u32 v85, v85, 2, v131
	ds_read_b32 v85, v85
	ds_read_b128 v[198:201], v132 offset:16384
	ds_read_b128 v[206:209], v132 offset:18688
	ds_read_b128 v[202:205], v132 offset:16448
	ds_read_b128 v[210:213], v132 offset:18752
	ds_read_b128 v[214:217], v132 offset:20992
	ds_read_b128 v[222:225], v132 offset:23296
	ds_read_b128 v[218:221], v132 offset:21056
	ds_read_b128 v[226:229], v132 offset:23360
	s_waitcnt lgkmcnt(6)
	v_mfma_f32_16x16x32_bf16 v[62:65], v[198:201], v[10:13], 0
	v_mfma_f32_16x16x32_bf16 v[66:69], v[206:209], v[10:13], 0
	s_waitcnt lgkmcnt(4)
	v_mfma_f32_16x16x32_bf16 v[62:65], v[202:205], v[14:17], v[62:65]
	v_mfma_f32_16x16x32_bf16 v[66:69], v[210:213], v[14:17], v[66:69]
	s_waitcnt lgkmcnt(2)
	v_mfma_f32_16x16x32_bf16 v[70:73], v[214:217], v[10:13], 0
	v_mfma_f32_16x16x32_bf16 v[74:77], v[222:225], v[10:13], 0
	s_waitcnt lgkmcnt(0)
	v_mfma_f32_16x16x32_bf16 v[70:73], v[218:221], v[14:17], v[70:73]
	v_mfma_f32_16x16x32_bf16 v[74:77], v[226:229], v[14:17], v[74:77]
	ds_read_b64_tr_b16 v[198:199], v133 offset:25600
	ds_read_b64_tr_b16 v[200:201], v133 offset:27904
	ds_read_b64_tr_b16 v[202:203], v133 offset:30208
	ds_read_b64_tr_b16 v[204:205], v133 offset:32512
	ds_read_b64_tr_b16 v[206:207], v133 offset:25632
	ds_read_b64_tr_b16 v[208:209], v133 offset:27936
	ds_read_b64_tr_b16 v[210:211], v133 offset:30240
	v_fmamk_f32 v62, v62, 0x3fb8aa3b, v78
	v_fmamk_f32 v63, v63, 0x3fb8aa3b, v79
	v_fmamk_f32 v64, v64, 0x3fb8aa3b, v80
	v_fmamk_f32 v65, v65, 0x3fb8aa3b, v81
	v_fmamk_f32 v66, v66, 0x3fb8aa3b, v82
	v_fmamk_f32 v67, v67, 0x3fb8aa3b, v83
	v_fmamk_f32 v68, v68, 0x3fb8aa3b, v84
	v_fmamk_f32 v69, v69, 0x3fb8aa3b, v85
	v_cmp_le_i32_e32 vcc, 0, v86
	s_nop 1
	v_cndmask_b32_e32 v62, v243, v62, vcc
	v_cmp_le_i32_e32 vcc, 16, v86
	s_nop 1
	v_cndmask_b32_e32 v63, v243, v63, vcc
	v_cmp_le_i32_e32 vcc, 32, v86
	s_nop 1
	v_cndmask_b32_e32 v64, v243, v64, vcc
	v_cmp_le_i32_e32 vcc, 48, v86
	s_nop 1
	v_cndmask_b32_e32 v65, v243, v65, vcc
	v_cmp_le_i32_e32 vcc, 256, v86
	s_nop 1
	v_cndmask_b32_e32 v66, v243, v66, vcc
	v_cmp_le_i32_e32 vcc, 272, v86
	s_nop 1
	v_cndmask_b32_e32 v67, v243, v67, vcc
	v_cmp_le_i32_e32 vcc, 288, v86
	s_nop 1
	v_cndmask_b32_e32 v68, v243, v68, vcc
	v_cmp_le_i32_e32 vcc, 304, v86
	s_nop 1
	v_cndmask_b32_e32 v69, v243, v69, vcc
	v_subrev_u32_e32 v78, 512, v86
	v_min_u32_e32 v78, 0x3ff, v78
	v_lshl_add_u32 v78, v78, 2, v131
	ds_read_b32 v78, v78
	v_subrev_u32_e32 v79, 528, v86
	v_min_u32_e32 v79, 0x3ff, v79
	v_lshl_add_u32 v79, v79, 2, v131
	ds_read_b32 v79, v79
	v_subrev_u32_e32 v80, 544, v86
	v_min_u32_e32 v80, 0x3ff, v80
	v_lshl_add_u32 v80, v80, 2, v131
	ds_read_b32 v80, v80
	v_subrev_u32_e32 v81, 560, v86
	v_min_u32_e32 v81, 0x3ff, v81
	v_lshl_add_u32 v81, v81, 2, v131
	ds_read_b32 v81, v81
	v_subrev_u32_e32 v82, 768, v86
	v_min_u32_e32 v82, 0x3ff, v82
	v_lshl_add_u32 v82, v82, 2, v131
	ds_read_b32 v82, v82
	v_subrev_u32_e32 v83, 784, v86
	v_min_u32_e32 v83, 0x3ff, v83
	v_lshl_add_u32 v83, v83, 2, v131
	ds_read_b32 v83, v83
	v_subrev_u32_e32 v84, 800, v86
	v_min_u32_e32 v84, 0x3ff, v84
	v_lshl_add_u32 v84, v84, 2, v131
	ds_read_b32 v84, v84
	v_subrev_u32_e32 v85, 816, v86
	v_min_u32_e32 v85, 0x3ff, v85
	v_lshl_add_u32 v85, v85, 2, v131
	ds_read_b32 v85, v85
	ds_read_b64_tr_b16 v[212:213], v133 offset:32544
	ds_read_b64_tr_b16 v[214:215], v133 offset:25664
	ds_read_b64_tr_b16 v[216:217], v133 offset:27968
	ds_read_b64_tr_b16 v[218:219], v133 offset:30272
	ds_read_b64_tr_b16 v[220:221], v133 offset:32576
	ds_read_b64_tr_b16 v[222:223], v133 offset:25696
	ds_read_b64_tr_b16 v[224:225], v133 offset:28000
	ds_read_b64_tr_b16 v[226:227], v133 offset:30304
	ds_read_b64_tr_b16 v[228:229], v133 offset:32608
	s_waitcnt lgkmcnt(9)
; #define LAS __attribute__((address_space(3)))
; __device__ __forceinline__ unsigned cvt_pk_bf16(float lo, float hi) { unsigned r; asm("v_cvt_pk_bf16_f32 %0, %1, %2" : "=v"(r) : "v"(lo), "v"(hi)); return r; }
; template <int D, class SF>
; __device__ __forceinline__ void attn_step(const bf16x8 (&qf)[D / 32], const LAS bf16_t* Ks, const LAS bf16_t* Vt, f32x4 (&o)[D / 16], float& m, float& lsum, float& alpha_out, bf16x8& pf0_out, bf16x8& pf1_out, const int lane, SF sf) {
;     ...
;         for (int r = 0; r < 4; ++r) v[4 * t + r] = sf(16 * t + 4 * i + r, s[t][r]);
;     float mx = fmaxf(fmaxf(fmaxf(v[0], v[1]), fmaxf(v[2], v[3])), fmaxf(fmaxf(v[4], v[5]), fmaxf(v[6], v[7])));
;     mx = fmaxf(mx, fmaxf(fmaxf(fmaxf(v[8], v[9]), fmaxf(v[10], v[11])), fmaxf(fmaxf(v[12], v[13]), fmaxf(v[14], v[15]))));
;     mx = rows_max(mx);
;     const float mnew = fmaxf(m, mx);
;     const float mc = fmaxf(mnew, -1e20f);
;     const float alpha = __builtin_amdgcn_exp2f(fmaxf(m, -1e20f) - mc);
;     float p[16], rs = 0.f;
; #pragma unroll
;     for (int r = 0; r < 16; ++r) { p[r] = __builtin_amdgcn_exp2f(v[r] - mc); rs += p[r]; }
;     rs = rows_sum(rs);
;     lsum = lsum * alpha + rs; m = mnew;
;     union { u32x4 u; bf16x8 b; } pk0, pk1;
;     pk0.u.x = cvt_pk_bf16(p[0], p[1]); pk0.u.y = cvt_pk_bf16(p[2], p[3]); pk0.u.z = cvt_pk_bf16(p[4], p[5]); pk0.u.w = cvt_pk_bf16(p[6], p[7]);
;     pk1.u.x = cvt_pk_bf16(p[8], p[9]); pk1.u.y = cvt_pk_bf16(p[10], p[11]); pk1.u.z = cvt_pk_bf16(p[12], p[13]); pk1.u.w = cvt_pk_bf16(p[14], p[15]);
;     if (__builtin_amdgcn_ballot_w64(alpha != 1.0f) != 0ull) {
; #pragma unroll
;         for (int dt = 0; dt < D / 16; ++dt) o[dt] *= alpha;
;     }
; #pragma unroll
;     for (int dt = 0; dt < D / 16; ++dt) {
;         const LAS bf16_t* vp = Vt + (16 * dt + c) * 72 + 4 * i;
;         union { u32x4 u; bf16x8 b; } vf0, vf1; const u32x2 a0 = *(const LAS u32x2*)vp, a1 = *(const LAS u32x2*)(vp + 16), b0 = *(const LAS u32x2*)(vp + 32), b1 = *(const LAS u32x2*)(vp + 48);
;         vf0.u.x = a0.x; vf0.u.y = a0.y; vf0.u.z = a1.x; vf0.u.w = a1.y; vf1.u.x = b0.x; vf1.u.y = b0.y; vf1.u.z = b1.x; vf1.u.w = b1.y;
;         o[dt] = mfma16(vf0.b, pk0.b, o[dt]); o[dt] = mfma16(vf1.b, pk1.b, o[dt]);
;     }
;     alpha_out = alpha; pf0_out = pk0.b; pf1_out = pk1.b;
	v_fmamk_f32 v70, v70, 0x3fb8aa3b, v78
	v_fmamk_f32 v71, v71, 0x3fb8aa3b, v79
	v_fmamk_f32 v72, v72, 0x3fb8aa3b, v80
	v_fmamk_f32 v73, v73, 0x3fb8aa3b, v81
	v_fmamk_f32 v74, v74, 0x3fb8aa3b, v82
	v_fmamk_f32 v75, v75, 0x3fb8aa3b, v83
	v_fmamk_f32 v76, v76, 0x3fb8aa3b, v84
	v_fmamk_f32 v77, v77, 0x3fb8aa3b, v85
	v_cmp_le_i32_e32 vcc, 512, v86
	s_nop 1
	v_cndmask_b32_e32 v70, v243, v70, vcc
	v_cmp_le_i32_e32 vcc, 528, v86
	s_nop 1
	v_cndmask_b32_e32 v71, v243, v71, vcc
	v_cmp_le_i32_e32 vcc, 544, v86
	s_nop 1
	v_cndmask_b32_e32 v72, v243, v72, vcc
	v_cmp_le_i32_e32 vcc, 560, v86
	s_nop 1
	v_cndmask_b32_e32 v73, v243, v73, vcc
	v_cmp_le_i32_e32 vcc, 768, v86
	s_nop 1
	v_cndmask_b32_e32 v74, v243, v74, vcc
	v_cmp_le_i32_e32 vcc, 784, v86
	s_nop 1
	v_cndmask_b32_e32 v75, v243, v75, vcc
	v_cmp_le_i32_e32 vcc, 800, v86
	s_nop 1
	v_cndmask_b32_e32 v76, v243, v76, vcc
	v_cmp_le_i32_e32 vcc, 816, v86
	s_nop 1
	v_cndmask_b32_e32 v77, v243, v77, vcc
	v_max3_f32 v92, v62, v63, v64
	v_max3_f32 v87, v65, v66, v67
	v_max3_f32 v88, v68, v69, v70
	v_max3_f32 v89, v71, v72, v73
	v_max3_f32 v91, v74, v75, v76
	v_max3_f32 v92, v92, v87, v77
	v_max3_f32 v88, v88, v89, v91
	v_max_f32_e32 v92, v92, v88
	v_mov_b32_e32 v87, v92
	s_nop 1
	v_permlane16_swap_b32_e32 v92, v87
	v_max_f32_e32 v92, v92, v87
	v_mov_b32_e32 v87, v92
	s_nop 1
	v_permlane32_swap_b32_e32 v92, v87
	v_max_f32_e32 v92, v92, v87
	v_max_f32_e32 v88, v137, v92
	v_max_f32_e32 v90, 0xe0ad78ec, v137
	v_max_f32_e32 v89, 0xe0ad78ec, v88
	v_sub_f32_e32 v90, v90, v89
	v_mov_b32_e32 v137, v88
	v_exp_f32_e32 v90, v90
	v_sub_f32_e32 v62, v62, v89
	v_sub_f32_e32 v63, v63, v89
	v_sub_f32_e32 v64, v64, v89
	v_sub_f32_e32 v65, v65, v89
	v_exp_f32_e32 v62, v62
	v_exp_f32_e32 v63, v63
	v_exp_f32_e32 v64, v64
	v_exp_f32_e32 v65, v65
	v_sub_f32_e32 v66, v66, v89
	v_sub_f32_e32 v67, v67, v89
	v_sub_f32_e32 v68, v68, v89
	v_sub_f32_e32 v69, v69, v89
	v_exp_f32_e32 v66, v66
	v_exp_f32_e32 v67, v67
	v_exp_f32_e32 v68, v68
	v_exp_f32_e32 v69, v69
	v_sub_f32_e32 v70, v70, v89
	v_sub_f32_e32 v71, v71, v89
	v_sub_f32_e32 v72, v72, v89
	v_sub_f32_e32 v73, v73, v89
	v_exp_f32_e32 v70, v70
	v_exp_f32_e32 v71, v71
	v_exp_f32_e32 v72, v72
	v_exp_f32_e32 v73, v73
	v_sub_f32_e32 v74, v74, v89
	v_sub_f32_e32 v75, v75, v89
	v_sub_f32_e32 v76, v76, v89
	v_sub_f32_e32 v77, v77, v89
	v_exp_f32_e32 v74, v74
	v_exp_f32_e32 v75, v75
	v_exp_f32_e32 v76, v76
	v_exp_f32_e32 v77, v77
	s_nop 0
	v_add_f32_e32 v86, v62, v63
	v_add_f32_e32 v87, v64, v65
	v_add_f32_e32 v88, v66, v67
	v_add_f32_e32 v89, v68, v69
	v_add_f32_e32 v86, v86, v70
	v_add_f32_e32 v87, v87, v71
	v_add_f32_e32 v88, v88, v72
	v_add_f32_e32 v89, v89, v73
	v_add_f32_e32 v86, v86, v74
	v_add_f32_e32 v87, v87, v75
	v_add_f32_e32 v88, v88, v76
	v_add_f32_e32 v89, v89, v77
	v_add_f32_e32 v86, v86, v87
	v_add_f32_e32 v88, v88, v89
	v_add_f32_e32 v86, v86, v88
	v_cvt_pk_bf16_f32 v78, v62, v63
	v_cvt_pk_bf16_f32 v79, v64, v65
	v_cvt_pk_bf16_f32 v80, v66, v67
	v_cvt_pk_bf16_f32 v81, v68, v69
	v_cvt_pk_bf16_f32 v82, v70, v71
	v_cvt_pk_bf16_f32 v83, v72, v73
	v_cvt_pk_bf16_f32 v84, v74, v75
	v_cvt_pk_bf16_f32 v85, v76, v77
	v_mov_b32_e32 v87, v86
	s_nop 1
	v_permlane16_swap_b32_e32 v86, v87
	v_add_f32_e32 v86, v86, v87
	v_mov_b32_e32 v87, v86
	s_nop 1
	v_permlane32_swap_b32_e32 v86, v87
	v_add_f32_e32 v86, v86, v87
	v_fma_f32 v138, v138, v90, v86
	v_cmp_neq_f32_e64 s[0:1], 1.0, v90
	s_cmp_eq_u64 s[0:1], 0
	s_cbranch_scc1 .Lcm_nosc_38
	v_pk_mul_f32 v[30:31], v[30:31], v[90:91] op_sel_hi:[1,0]
	v_pk_mul_f32 v[32:33], v[32:33], v[90:91] op_sel_hi:[1,0]
	v_pk_mul_f32 v[34:35], v[34:35], v[90:91] op_sel_hi:[1,0]
	v_pk_mul_f32 v[36:37], v[36:37], v[90:91] op_sel_hi:[1,0]
	v_pk_mul_f32 v[38:39], v[38:39], v[90:91] op_sel_hi:[1,0]
	v_pk_mul_f32 v[40:41], v[40:41], v[90:91] op_sel_hi:[1,0]
	v_pk_mul_f32 v[42:43], v[42:43], v[90:91] op_sel_hi:[1,0]
	v_pk_mul_f32 v[44:45], v[44:45], v[90:91] op_sel_hi:[1,0]
	v_pk_mul_f32 v[46:47], v[46:47], v[90:91] op_sel_hi:[1,0]
	v_pk_mul_f32 v[48:49], v[48:49], v[90:91] op_sel_hi:[1,0]
	v_pk_mul_f32 v[50:51], v[50:51], v[90:91] op_sel_hi:[1,0]
	v_pk_mul_f32 v[52:53], v[52:53], v[90:91] op_sel_hi:[1,0]
	v_pk_mul_f32 v[54:55], v[54:55], v[90:91] op_sel_hi:[1,0]
	v_pk_mul_f32 v[56:57], v[56:57], v[90:91] op_sel_hi:[1,0]
	v_pk_mul_f32 v[58:59], v[58:59], v[90:91] op_sel_hi:[1,0]
	v_pk_mul_f32 v[60:61], v[60:61], v[90:91] op_sel_hi:[1,0]

; #define LAS __attribute__((address_space(3)))
; __device__ __forceinline__ f32x4 mfma16(bf16x8 a, bf16x8 b, f32x4 c) { return __builtin_amdgcn_mfma_f32_16x16x32_bf16(a, b, c, 0, 0, 0); }
; template <int D, class SF>
; __device__ __forceinline__ void attn_step(const bf16x8 (&qf)[D / 32], const LAS bf16_t* Ks, const LAS bf16_t* Vt, f32x4 (&o)[D / 16], float& m, float& lsum, float& alpha_out, bf16x8& pf0_out, bf16x8& pf1_out, const int lane, SF sf) {
;     ...
;     for (int ks = 0; ks < D / 32; ++ks) {
; #pragma unroll
;         for (int t = 0; t < 4; ++t) { const bf16x8 kf = *(const LAS bf16x8*)(Ks + (16 * t + c) * KSTR + ks * 32 + 8 * i); s[t] = mfma16(kf, qf[ks], s[t]); }
;     }
;     float v[16];
; #pragma unroll
;     for (int t = 0; t < 4; ++t)
; #pragma unroll
;         for (int r = 0; r < 4; ++r) v[4 * t + r] = sf(16 * t + 4 * i + r, s[t][r]);
; __device__ __forceinline__ void nsa_unit(LAS unsigned char* lds, const Ctx& P, int l, int b, int hkv, int tb) {
;     ...
;         for (int pr = 0; pr < 2; ++pr) if (2 * pr < ntile) {
;             const bool hasb = 2 * pr + 1 < ntile;
;             __syncthreads();
;             load2(KC, VC, 64, 128 * pr, 128 * pr + 64, hasb, 255);
;             __syncthreads();
; #pragma unroll
;             for (int sl = 0; sl < 2; ++sl) if (sl == 0 || hasb) {
;                 const int kt = 2 * pr + sl; const LAS bf16_t* Ks = KV + sl * 9216; const LAS bf16_t* Vt = Ks + 4608; const int nb = kt * 64;
;                 attn_step<64>(qs, Ks, Vt, o, m, lsum, alpha, pf, pf1, lane,
;                     [&](int kk, float s) { const int dist = tqs - (16 * (nb + kk) + 31); return dist >= 0 ? s * LOG2E + lut[min((unsigned)dist, 1023u)] : NEGBIG; });
; #pragma unroll
.Lcm_td_36:
	s_cmp_lt_u32 s26, 4
	s_cbranch_scc1 .Lcm_nb_39
	v_lshlrev_b32_e32 v86, 6, v103
	v_sub_u32_e32 v86, v98, v86
	v_add_u32_e32 v86, 0xfffff3e1, v86
	v_subrev_u32_e32 v78, 0, v86
	v_min_u32_e32 v78, 0x3ff, v78
	v_lshl_add_u32 v78, v78, 2, v131
	ds_read_b32 v78, v78
	v_subrev_u32_e32 v79, 16, v86
	v_min_u32_e32 v79, 0x3ff, v79
	v_lshl_add_u32 v79, v79, 2, v131
	ds_read_b32 v79, v79
	v_subrev_u32_e32 v80, 32, v86
	v_min_u32_e32 v80, 0x3ff, v80
	v_lshl_add_u32 v80, v80, 2, v131
	ds_read_b32 v80, v80
	v_subrev_u32_e32 v81, 48, v86
	v_min_u32_e32 v81, 0x3ff, v81
	v_lshl_add_u32 v81, v81, 2, v131
	ds_read_b32 v81, v81
	v_subrev_u32_e32 v82, 256, v86
	v_min_u32_e32 v82, 0x3ff, v82
	v_lshl_add_u32 v82, v82, 2, v131
	ds_read_b32 v82, v82
	v_subrev_u32_e32 v83, 272, v86
	v_min_u32_e32 v83, 0x3ff, v83
	v_lshl_add_u32 v83, v83, 2, v131
	ds_read_b32 v83, v83
	v_subrev_u32_e32 v84, 288, v86
	v_min_u32_e32 v84, 0x3ff, v84
	v_lshl_add_u32 v84, v84, 2, v131
	ds_read_b32 v84, v84
	v_subrev_u32_e32 v85, 304, v86
	v_min_u32_e32 v85, 0x3ff, v85
	v_lshl_add_u32 v85, v85, 2, v131
	ds_read_b32 v85, v85
	ds_read_b128 v[198:201], v132 offset:34816
	ds_read_b128 v[206:209], v132 offset:37120
	ds_read_b128 v[202:205], v132 offset:34880
	ds_read_b128 v[210:213], v132 offset:37184
	ds_read_b128 v[214:217], v132 offset:39424
	ds_read_b128 v[222:225], v132 offset:41728
	ds_read_b128 v[218:221], v132 offset:39488
	ds_read_b128 v[226:229], v132 offset:41792
	s_waitcnt lgkmcnt(6)
	v_mfma_f32_16x16x32_bf16 v[62:65], v[198:201], v[10:13], 0
	v_mfma_f32_16x16x32_bf16 v[66:69], v[206:209], v[10:13], 0
	s_waitcnt lgkmcnt(4)
	v_mfma_f32_16x16x32_bf16 v[62:65], v[202:205], v[14:17], v[62:65]
	v_mfma_f32_16x16x32_bf16 v[66:69], v[210:213], v[14:17], v[66:69]
	s_waitcnt lgkmcnt(2)
	v_mfma_f32_16x16x32_bf16 v[70:73], v[214:217], v[10:13], 0
	v_mfma_f32_16x16x32_bf16 v[74:77], v[222:225], v[10:13], 0
	s_waitcnt lgkmcnt(0)
	v_mfma_f32_16x16x32_bf16 v[70:73], v[218:221], v[14:17], v[70:73]
	v_mfma_f32_16x16x32_bf16 v[74:77], v[226:229], v[14:17], v[74:77]
	ds_read_b64_tr_b16 v[198:199], v133 offset:44032
	ds_read_b64_tr_b16 v[200:201], v133 offset:46336
	ds_read_b64_tr_b16 v[202:203], v133 offset:48640
	ds_read_b64_tr_b16 v[204:205], v133 offset:50944
	ds_read_b64_tr_b16 v[206:207], v133 offset:44064
	ds_read_b64_tr_b16 v[208:209], v133 offset:46368
	ds_read_b64_tr_b16 v[210:211], v133 offset:48672
	v_fmamk_f32 v62, v62, 0x3fb8aa3b, v78
	v_fmamk_f32 v63, v63, 0x3fb8aa3b, v79
	v_fmamk_f32 v64, v64, 0x3fb8aa3b, v80
	v_fmamk_f32 v65, v65, 0x3fb8aa3b, v81
	v_fmamk_f32 v66, v66, 0x3fb8aa3b, v82
	v_fmamk_f32 v67, v67, 0x3fb8aa3b, v83
	v_fmamk_f32 v68, v68, 0x3fb8aa3b, v84
	v_fmamk_f32 v69, v69, 0x3fb8aa3b, v85
	v_cmp_le_i32_e32 vcc, 0, v86
	s_nop 1
	v_cndmask_b32_e32 v62, v243, v62, vcc
	v_cmp_le_i32_e32 vcc, 16, v86
	s_nop 1
	v_cndmask_b32_e32 v63, v243, v63, vcc
	v_cmp_le_i32_e32 vcc, 32, v86
	s_nop 1
	v_cndmask_b32_e32 v64, v243, v64, vcc
	v_cmp_le_i32_e32 vcc, 48, v86
	s_nop 1
	v_cndmask_b32_e32 v65, v243, v65, vcc
	v_cmp_le_i32_e32 vcc, 256, v86
	s_nop 1
	v_cndmask_b32_e32 v66, v243, v66, vcc
	v_cmp_le_i32_e32 vcc, 272, v86
	s_nop 1
	v_cndmask_b32_e32 v67, v243, v67, vcc
	v_cmp_le_i32_e32 vcc, 288, v86
	s_nop 1
	v_cndmask_b32_e32 v68, v243, v68, vcc
	v_cmp_le_i32_e32 vcc, 304, v86
	s_nop 1
	v_cndmask_b32_e32 v69, v243, v69, vcc
	v_subrev_u32_e32 v78, 512, v86
	v_min_u32_e32 v78, 0x3ff, v78
	v_lshl_add_u32 v78, v78, 2, v131
	ds_read_b32 v78, v78
	v_subrev_u32_e32 v79, 528, v86
	v_min_u32_e32 v79, 0x3ff, v79
	v_lshl_add_u32 v79, v79, 2, v131
	ds_read_b32 v79, v79
	v_subrev_u32_e32 v80, 544, v86
	v_min_u32_e32 v80, 0x3ff, v80
	v_lshl_add_u32 v80, v80, 2, v131
	ds_read_b32 v80, v80
	v_subrev_u32_e32 v81, 560, v86
	v_min_u32_e32 v81, 0x3ff, v81
	v_lshl_add_u32 v81, v81, 2, v131
	ds_read_b32 v81, v81
	v_subrev_u32_e32 v82, 768, v86
	v_min_u32_e32 v82, 0x3ff, v82
	v_lshl_add_u32 v82, v82, 2, v131
	ds_read_b32 v82, v82
	v_subrev_u32_e32 v83, 784, v86
	v_min_u32_e32 v83, 0x3ff, v83
	v_lshl_add_u32 v83, v83, 2, v131
	ds_read_b32 v83, v83
	v_subrev_u32_e32 v84, 800, v86
	v_min_u32_e32 v84, 0x3ff, v84
	v_lshl_add_u32 v84, v84, 2, v131
	ds_read_b32 v84, v84
	v_subrev_u32_e32 v85, 816, v86
	v_min_u32_e32 v85, 0x3ff, v85
	v_lshl_add_u32 v85, v85, 2, v131
	ds_read_b32 v85, v85
	ds_read_b64_tr_b16 v[212:213], v133 offset:50976
	ds_read_b64_tr_b16 v[214:215], v133 offset:44096
	ds_read_b64_tr_b16 v[216:217], v133 offset:46400
	ds_read_b64_tr_b16 v[218:219], v133 offset:48704
	ds_read_b64_tr_b16 v[220:221], v133 offset:51008
	ds_read_b64_tr_b16 v[222:223], v133 offset:44128
	ds_read_b64_tr_b16 v[224:225], v133 offset:46432
	ds_read_b64_tr_b16 v[226:227], v133 offset:48736
	ds_read_b64_tr_b16 v[228:229], v133 offset:51040
	s_waitcnt lgkmcnt(9)
; __device__ __forceinline__ unsigned cvt_pk_bf16(float lo, float hi) { unsigned r; asm("v_cvt_pk_bf16_f32 %0, %1, %2" : "=v"(r) : "v"(lo), "v"(hi)); return r; }
; template <int D, class SF>
; __device__ __forceinline__ void attn_step(const bf16x8 (&qf)[D / 32], const LAS bf16_t* Ks, const LAS bf16_t* Vt, f32x4 (&o)[D / 16], float& m, float& lsum, float& alpha_out, bf16x8& pf0_out, bf16x8& pf1_out, const int lane, SF sf) {
;     ...
;     float mx = fmaxf(fmaxf(fmaxf(v[0], v[1]), fmaxf(v[2], v[3])), fmaxf(fmaxf(v[4], v[5]), fmaxf(v[6], v[7])));
;     mx = fmaxf(mx, fmaxf(fmaxf(fmaxf(v[8], v[9]), fmaxf(v[10], v[11])), fmaxf(fmaxf(v[12], v[13]), fmaxf(v[14], v[15]))));
;     mx = rows_max(mx);
;     const float mnew = fmaxf(m, mx);
;     const float mc = fmaxf(mnew, -1e20f);
;     const float alpha = __builtin_amdgcn_exp2f(fmaxf(m, -1e20f) - mc);
;     float p[16], rs = 0.f;
; #pragma unroll
;     for (int r = 0; r < 16; ++r) { p[r] = __builtin_amdgcn_exp2f(v[r] - mc); rs += p[r]; }
;     rs = rows_sum(rs);
;     lsum = lsum * alpha + rs; m = mnew;
;     union { u32x4 u; bf16x8 b; } pk0, pk1;
;     pk0.u.x = cvt_pk_bf16(p[0], p[1]); pk0.u.y = cvt_pk_bf16(p[2], p[3]); pk0.u.z = cvt_pk_bf16(p[4], p[5]); pk0.u.w = cvt_pk_bf16(p[6], p[7]);
;     pk1.u.x = cvt_pk_bf16(p[8], p[9]); pk1.u.y = cvt_pk_bf16(p[10], p[11]); pk1.u.z = cvt_pk_bf16(p[12], p[13]); pk1.u.w = cvt_pk_bf16(p[14], p[15]);
;     if (__builtin_amdgcn_ballot_w64(alpha != 1.0f) != 0ull) {
; #pragma unroll
;         for (int dt = 0; dt < D / 16; ++dt) o[dt] *= alpha;
;     }
; __device__ __forceinline__ void nsa_unit(LAS unsigned char* lds, const Ctx& P, int l, int b, int hkv, int tb) {
;     ...
;                     [&](int kk, float s) { const int dist = tqs - (16 * (nb + kk) + 31); return dist >= 0 ? s * LOG2E + lut[min((unsigned)dist, 1023u)] : NEGBIG; });
; #pragma unroll
;                 for (int jt = 0; jt < 4; ++jt) oi[jt] *= alpha;
	v_fmamk_f32 v70, v70, 0x3fb8aa3b, v78
	v_fmamk_f32 v71, v71, 0x3fb8aa3b, v79
	v_fmamk_f32 v72, v72, 0x3fb8aa3b, v80
	v_fmamk_f32 v73, v73, 0x3fb8aa3b, v81
	v_fmamk_f32 v74, v74, 0x3fb8aa3b, v82
	v_fmamk_f32 v75, v75, 0x3fb8aa3b, v83
	v_fmamk_f32 v76, v76, 0x3fb8aa3b, v84
	v_fmamk_f32 v77, v77, 0x3fb8aa3b, v85
	v_cmp_le_i32_e32 vcc, 512, v86
	s_nop 1
	v_cndmask_b32_e32 v70, v243, v70, vcc
	v_cmp_le_i32_e32 vcc, 528, v86
	s_nop 1
	v_cndmask_b32_e32 v71, v243, v71, vcc
	v_cmp_le_i32_e32 vcc, 544, v86
	s_nop 1
	v_cndmask_b32_e32 v72, v243, v72, vcc
	v_cmp_le_i32_e32 vcc, 560, v86
	s_nop 1
	v_cndmask_b32_e32 v73, v243, v73, vcc
	v_cmp_le_i32_e32 vcc, 768, v86
	s_nop 1
	v_cndmask_b32_e32 v74, v243, v74, vcc
	v_cmp_le_i32_e32 vcc, 784, v86
	s_nop 1
	v_cndmask_b32_e32 v75, v243, v75, vcc
	v_cmp_le_i32_e32 vcc, 800, v86
	s_nop 1
	v_cndmask_b32_e32 v76, v243, v76, vcc
	v_cmp_le_i32_e32 vcc, 816, v86
	s_nop 1
	v_cndmask_b32_e32 v77, v243, v77, vcc
	v_max3_f32 v92, v62, v63, v64
	v_max3_f32 v87, v65, v66, v67
	v_max3_f32 v88, v68, v69, v70
	v_max3_f32 v89, v71, v72, v73
	v_max3_f32 v91, v74, v75, v76
	v_max3_f32 v92, v92, v87, v77
	v_max3_f32 v88, v88, v89, v91
	v_max_f32_e32 v92, v92, v88
	v_mov_b32_e32 v87, v92
	s_nop 1
	v_permlane16_swap_b32_e32 v92, v87
	v_max_f32_e32 v92, v92, v87
	v_mov_b32_e32 v87, v92
	s_nop 1
	v_permlane32_swap_b32_e32 v92, v87
	v_max_f32_e32 v92, v92, v87
	v_max_f32_e32 v88, v137, v92
	v_max_f32_e32 v90, 0xe0ad78ec, v137
	v_max_f32_e32 v89, 0xe0ad78ec, v88
	v_sub_f32_e32 v90, v90, v89
	v_mov_b32_e32 v137, v88
	v_exp_f32_e32 v90, v90
	v_sub_f32_e32 v62, v62, v89
	v_sub_f32_e32 v63, v63, v89
	v_sub_f32_e32 v64, v64, v89
	v_sub_f32_e32 v65, v65, v89
	v_exp_f32_e32 v62, v62
	v_exp_f32_e32 v63, v63
	v_exp_f32_e32 v64, v64
	v_exp_f32_e32 v65, v65
	v_sub_f32_e32 v66, v66, v89
	v_sub_f32_e32 v67, v67, v89
	v_sub_f32_e32 v68, v68, v89
	v_sub_f32_e32 v69, v69, v89
	v_exp_f32_e32 v66, v66
	v_exp_f32_e32 v67, v67
	v_exp_f32_e32 v68, v68
	v_exp_f32_e32 v69, v69
	v_sub_f32_e32 v70, v70, v89
	v_sub_f32_e32 v71, v71, v89
	v_sub_f32_e32 v72, v72, v89
	v_sub_f32_e32 v73, v73, v89
	v_exp_f32_e32 v70, v70
	v_exp_f32_e32 v71, v71
	v_exp_f32_e32 v72, v72
	v_exp_f32_e32 v73, v73
	v_sub_f32_e32 v74, v74, v89
	v_sub_f32_e32 v75, v75, v89
	v_sub_f32_e32 v76, v76, v89
	v_sub_f32_e32 v77, v77, v89
	v_exp_f32_e32 v74, v74
	v_exp_f32_e32 v75, v75
	v_exp_f32_e32 v76, v76
	v_exp_f32_e32 v77, v77
	s_nop 0
	v_add_f32_e32 v86, v62, v63
	v_add_f32_e32 v87, v64, v65
	v_add_f32_e32 v88, v66, v67
	v_add_f32_e32 v89, v68, v69
	v_add_f32_e32 v86, v86, v70
	v_add_f32_e32 v87, v87, v71
	v_add_f32_e32 v88, v88, v72
	v_add_f32_e32 v89, v89, v73
	v_add_f32_e32 v86, v86, v74
	v_add_f32_e32 v87, v87, v75
	v_add_f32_e32 v88, v88, v76
	v_add_f32_e32 v89, v89, v77
	v_add_f32_e32 v86, v86, v87
	v_add_f32_e32 v88, v88, v89
	v_add_f32_e32 v86, v86, v88
	v_cvt_pk_bf16_f32 v78, v62, v63
	v_cvt_pk_bf16_f32 v79, v64, v65
	v_cvt_pk_bf16_f32 v80, v66, v67
	v_cvt_pk_bf16_f32 v81, v68, v69
	v_cvt_pk_bf16_f32 v82, v70, v71
	v_cvt_pk_bf16_f32 v83, v72, v73
	v_cvt_pk_bf16_f32 v84, v74, v75
	v_cvt_pk_bf16_f32 v85, v76, v77
	v_mov_b32_e32 v87, v86
	s_nop 1
	v_permlane16_swap_b32_e32 v86, v87
	v_add_f32_e32 v86, v86, v87
	v_mov_b32_e32 v87, v86
	s_nop 1
	v_permlane32_swap_b32_e32 v86, v87
	v_add_f32_e32 v86, v86, v87
	v_fma_f32 v138, v138, v90, v86
	v_cmp_neq_f32_e64 s[0:1], 1.0, v90
	s_cmp_eq_u64 s[0:1], 0
	s_cbranch_scc1 .Lcm_nosc_40
	v_pk_mul_f32 v[30:31], v[30:31], v[90:91] op_sel_hi:[1,0]
	v_pk_mul_f32 v[32:33], v[32:33], v[90:91] op_sel_hi:[1,0]
	v_pk_mul_f32 v[34:35], v[34:35], v[90:91] op_sel_hi:[1,0]
	v_pk_mul_f32 v[36:37], v[36:37], v[90:91] op_sel_hi:[1,0]
	v_pk_mul_f32 v[38:39], v[38:39], v[90:91] op_sel_hi:[1,0]
	v_pk_mul_f32 v[40:41], v[40:41], v[90:91] op_sel_hi:[1,0]
	v_pk_mul_f32 v[42:43], v[42:43], v[90:91] op_sel_hi:[1,0]
	v_pk_mul_f32 v[44:45], v[44:45], v[90:91] op_sel_hi:[1,0]
	v_pk_mul_f32 v[46:47], v[46:47], v[90:91] op_sel_hi:[1,0]
	v_pk_mul_f32 v[48:49], v[48:49], v[90:91] op_sel_hi:[1,0]
	v_pk_mul_f32 v[50:51], v[50:51], v[90:91] op_sel_hi:[1,0]
	v_pk_mul_f32 v[52:53], v[52:53], v[90:91] op_sel_hi:[1,0]
	v_pk_mul_f32 v[54:55], v[54:55], v[90:91] op_sel_hi:[1,0]
	v_pk_mul_f32 v[56:57], v[56:57], v[90:91] op_sel_hi:[1,0]
	v_pk_mul_f32 v[58:59], v[58:59], v[90:91] op_sel_hi:[1,0]
	v_pk_mul_f32 v[60:61], v[60:61], v[90:91] op_sel_hi:[1,0]

; #define LAS __attribute__((address_space(3)))
; __device__ __forceinline__ float bf2f(bf16_t v) { return __uint_as_float(((unsigned)v) << 16); }
; __device__ __forceinline__ float sigmoidf_(float x) { return __builtin_amdgcn_rcpf(1.0f + __expf(-x)); }
; __device__ __forceinline__ void nsa_unit(LAS unsigned char* lds, const Ctx& P, int l, int b, int hkv, int tb) {
;     ...
;         const float inv = 1.0f / fmaxf(lsum, 1e-30f);
;         const float g0 = sigmoidf_(bf2f(H[((size_t)b * SEQ + tqs) * LDH + C_GL + hq]) + P.in[21][l * 48 + hq]) * inv;
; #pragma unroll
;         for (int dt = 0; dt < 4; ++dt) { park[(sb * 4 + dt) * 64] = o[dt] * g0;
;             *(LAS f32x4*)(impb + (g * 64 + 32 * th + 16 * sb + c) * 64 + 16 * dt + 4 * i) = oi[dt] * inv; }
.Lcm_nb_39:
.Lcm_fin_21:
	v_lshlrev_b32_e32 v86, 1, v96
	v_add_u32_e32 v86, 0x5400, v86
	v_add_co_u32_e32 v62, vcc, v86, v122
	s_nop 1
	v_addc_co_u32_e32 v63, vcc, 0, v123, vcc
	global_load_ushort v64, v[62:63], off
	v_mov_b32_e32 v65, s74
	ds_read_b64 v[66:67], v65
	s_waitcnt lgkmcnt(0)
	v_readfirstlane_b32 s20, v66
	v_readfirstlane_b32 s21, v67
	s_nop 4
	s_nop 0
	global_load_dword v65, v158, s[20:21]
	v_max_f32_e32 v86, v138, v138
	v_max_f32_e32 v86, 0xda24260, v86
	v_div_scale_f32 v87, s[0:1], v86, v86, 1.0
	v_rcp_f32_e32 v88, v87
	s_nop 0
	v_fma_f32 v89, -v87, v88, 1.0
	v_fmac_f32_e32 v88, v89, v88
	v_div_scale_f32 v89, vcc, 1.0, v86, 1.0
	v_mul_f32_e32 v91, v89, v88
	v_fma_f32 v92, -v87, v91, v89
	v_fmac_f32_e32 v91, v92, v88
	v_fma_f32 v87, -v87, v91, v89
	v_div_fmas_f32 v87, v87, v88, v91
	v_div_fixup_f32 v68, v87, v86, 1.0
	s_waitcnt vmcnt(0)
	v_lshlrev_b32_e32 v64, 16, v64
	v_add_f32_e32 v64, v65, v64
	v_mul_f32_e32 v64, 0xbfb8aa3b, v64
	v_exp_f32_e32 v64, v64
	s_nop 0
	v_add_f32_e32 v64, 1.0, v64
	v_rcp_f32_e32 v64, v64
	s_nop 0
	v_mul_f32_e32 v70, v68, v64
	v_add_co_u32_e32 v72, vcc, 0x1000, v124
	s_nop 1
	v_addc_co_u32_e32 v73, vcc, 0, v125, vcc
	s_nop 4
	v_pk_mul_f32 v[30:31], v[30:31], v[70:71] op_sel_hi:[1,0]
	v_pk_mul_f32 v[32:33], v[32:33], v[70:71] op_sel_hi:[1,0]
	global_store_dwordx4 v[72:73], v[30:33], off
	v_pk_mul_f32 v[34:35], v[34:35], v[70:71] op_sel_hi:[1,0]
	v_pk_mul_f32 v[36:37], v[36:37], v[70:71] op_sel_hi:[1,0]
	global_store_dwordx4 v[72:73], v[34:37], off offset:1024
	v_pk_mul_f32 v[38:39], v[38:39], v[70:71] op_sel_hi:[1,0]
	v_pk_mul_f32 v[40:41], v[40:41], v[70:71] op_sel_hi:[1,0]
	global_store_dwordx4 v[72:73], v[38:41], off offset:2048
	v_pk_mul_f32 v[42:43], v[42:43], v[70:71] op_sel_hi:[1,0]
	v_pk_mul_f32 v[44:45], v[44:45], v[70:71] op_sel_hi:[1,0]
	global_store_dwordx4 v[72:73], v[42:45], off offset:3072
	v_or_b32_e32 v74, 16, v156
	v_lshl_add_u32 v74, v74, 8, v150
	v_pk_mul_f32 v[46:47], v[46:47], v[68:69] op_sel_hi:[1,0]
	v_pk_mul_f32 v[48:49], v[48:49], v[68:69] op_sel_hi:[1,0]
	ds_write_b128 v74, v[46:49] offset:53248
	v_pk_mul_f32 v[50:51], v[50:51], v[68:69] op_sel_hi:[1,0]
	v_pk_mul_f32 v[52:53], v[52:53], v[68:69] op_sel_hi:[1,0]
	ds_write_b128 v74, v[50:53] offset:53312
	v_pk_mul_f32 v[54:55], v[54:55], v[68:69] op_sel_hi:[1,0]
	v_pk_mul_f32 v[56:57], v[56:57], v[68:69] op_sel_hi:[1,0]
	ds_write_b128 v74, v[54:57] offset:53376
	v_pk_mul_f32 v[58:59], v[58:59], v[68:69] op_sel_hi:[1,0]
	v_pk_mul_f32 v[60:61], v[60:61], v[68:69] op_sel_hi:[1,0]
	ds_write_b128 v74, v[58:61] offset:53440
	v_lshlrev_b32_e32 v0, 1, v102
	v_lshlrev_b32_e32 v132, 1, v96
	s_branch .LBB0_361

; #define LAS __attribute__((address_space(3)))
; __device__ __forceinline__ int opaque_tid() { int t = threadIdx.x; asm volatile("" : "+v"(t)); return t; }
; __device__ __forceinline__ void memattn_unit(LAS unsigned char* lds, const Ctx& P, int unit) {
;     const bf16_t* H = (const bf16_t*)(P.ws + WS_H); const bf16_t* MKV = (const bf16_t*)(P.ws + WS_MKV); bf16_t* O = (bf16_t*)(P.ws + WS_O) + (size_t)3 * MT * DBR;
;     LAS bf16_t* Ks = (LAS bf16_t*)lds; LAS bf16_t* Vt = (LAS bf16_t*)(lds + 64 * 264 * 2);
;     const int tb = unit & 31, head = (unit >> 5) & 3, b = unit >> 7;
;     const int tid = opaque_tid(), wid = tid >> 6, lane = tid & 63, c = lane & 15, i = lane >> 4;
;     const size_t tok = (size_t)b * SEQ + tb * 128 + wid * 16 + c;
;     bf16x8 qf[8];
; #pragma unroll
;     for (int ks = 0; ks < 8; ++ks) qf[ks] = load_q_scaled(H + tok * LDH + C_QM + head * 256 + ks * 32 + 8 * i, 0.0625f);
;     f32x4 o[16];
; #pragma unroll
;     for (int dt = 0; dt < 16; ++dt) o[dt] = (f32x4){0.f, 0.f, 0.f, 0.f};
;     float m = NEGBIG, lsum = 0.f, alpha; bf16x8 pf, pf1;
;     const bf16_t* kb = MKV + (size_t)b * 256 * DM + head * 256; const bf16_t* vb = kb + 1024;
;     for (int kt = 0; kt < 4; ++kt) {
;         __syncthreads();
;         { u32x4 kr[4], vr[4];
; #pragma unroll
;             for (int it = 0; it < 4; ++it) { const int idx = tid + it * 512, key = idx & 63, seg = idx >> 6; const size_t off = (size_t)(kt * 64 + key) * DM + seg * 8; kr[it] = *(const u32x4*)(kb + off); vr[it] = *(const u32x4*)(vb + off); }
.LBB0_851:
	s_or_b64 exec, exec, s[0:1]
	v_readlane_b32 s0, v253, 11
	v_readlane_b32 s1, v253, 12
	s_andn2_b64 vcc, exec, s[0:1]
	s_barrier
	s_cbranch_vccnz .LBB0_859
	v_and_b32_e32 v219, 15, v234
	v_bfe_u32 v218, v234, 4, 2
	v_mul_u32_u24_e32 v202, 528, v219
	v_lshl_add_u32 v202, v218, 4, v202
	v_add_u32_e32 v203, 67584, v202
	v_lshrrev_b32_e32 v122, 2, v219
	v_lshl_add_u32 v122, v218, 2, v122
	v_mul_u32_u24_e32 v122, 528, v122
	v_and_b32_e32 v123, 3, v219
	v_lshl_add_u32 v204, v123, 3, v122
	v_add_u32_e32 v205, 67584, v204
	v_lshrrev_b32_e32 v122, 5, v234
	v_and_b32_e32 v123, 31, v234
	v_mul_u32_u24_e32 v206, 528, v122
	v_lshl_add_u32 v206, v123, 4, v206
	v_add_u32_e32 v216, 67584, v206
	v_lshlrev_b32_e32 v209, 12, v122
	v_lshl_add_u32 v209, v123, 4, v209
	v_lshrrev_b32_e32 v122, 6, v234
	v_lshl_add_u32 v217, v122, 4, v219
	s_mov_b32 s7, s2
.Lmem_unit:
	s_cmpk_ge_u32 s7, 0x200
	s_cbranch_scc1 .Lmem_done
	s_and_b32 s0, s7, 31
	s_lshl_b32 s0, s0, 7
	s_lshr_b32 s1, s7, 7
	s_lshl_b32 s6, s1, 12
	s_add_u32 s0, s0, s6
	s_bfe_u32 s6, s7, 0x20005
	s_lshl_b32 s6, s6, 9
	s_lshl_b32 s1, s1, 20
	s_add_u32 s1, s1, s6
	s_add_u32 s1, s1, 0x20a03000
	s_add_u32 s8, s68, s1
	s_addc_u32 s9, s69, 0
	s_add_u32 s4, s6, 0x2ee03000
	s_add_u32 s4, s68, s4
	s_addc_u32 s5, s69, 0
	v_mov_b32_e32 v122, v209
	global_load_dwordx4 v[130:133], v122, s[8:9]
	global_load_dwordx4 v[146:149], v122, s[8:9] offset:2048
	v_add_u32_e32 v122, 0x10000, v209
	global_load_dwordx4 v[134:137], v122, s[8:9]
	global_load_dwordx4 v[150:153], v122, s[8:9] offset:2048
	v_add_u32_e32 v122, 0x20000, v209
	global_load_dwordx4 v[138:141], v122, s[8:9]
	global_load_dwordx4 v[154:157], v122, s[8:9] offset:2048
	v_add_u32_e32 v122, 0x30000, v209
	global_load_dwordx4 v[142:145], v122, s[8:9]
	global_load_dwordx4 v[158:161], v122, s[8:9] offset:2048
	v_add_u32_e32 v122, 0x40000, v209
	global_load_dwordx4 v[170:173], v122, s[8:9]
	global_load_dwordx4 v[186:189], v122, s[8:9] offset:2048
	v_add_u32_e32 v122, 0x50000, v209
	global_load_dwordx4 v[174:177], v122, s[8:9]
	global_load_dwordx4 v[190:193], v122, s[8:9] offset:2048
	v_add_u32_e32 v122, 0x60000, v209
	global_load_dwordx4 v[178:181], v122, s[8:9]
	global_load_dwordx4 v[194:197], v122, s[8:9] offset:2048
	v_add_u32_e32 v122, 0x70000, v209
	global_load_dwordx4 v[182:185], v122, s[8:9]
	global_load_dwordx4 v[198:201], v122, s[8:9] offset:2048
	v_add_u32_e32 v220, s0, v217
	v_mov_b64_e32 v[212:213], s[10:11]
	v_mad_u64_u32 v[210:211], s[12:13], v220, s42, v[212:213]
	v_lshlrev_b32_e32 v122, 4, v218
	s_add_u32 s12, s6, 0x4400
	v_add_u32_e32 v122, s12, v122
	v_add_co_u32_e32 v212, vcc, v122, v210
	s_nop 1
	v_addc_co_u32_e32 v213, vcc, 0, v211, vcc
	global_load_dwordx4 v[2:5], v[212:213], off
	global_load_dwordx4 v[6:9], v[212:213], off offset:64
	global_load_dwordx4 v[10:13], v[212:213], off offset:128
	global_load_dwordx4 v[14:17], v[212:213], off offset:192
	global_load_dwordx4 v[18:21], v[212:213], off offset:256
	global_load_dwordx4 v[22:25], v[212:213], off offset:320
	global_load_dwordx4 v[26:29], v[212:213], off offset:384
	global_load_dwordx4 v[30:33], v[212:213], off offset:448
	v_lshlrev_b32_e32 v122, 3, v218
	s_add_u32 s12, s6, 0x4c00
	v_add_u32_e32 v123, s12, v122
	v_add_co_u32_e32 v214, vcc, v123, v210
	s_nop 1
	v_addc_co_u32_e32 v215, vcc, 0, v211, vcc
	v_lshl_add_u32 v221, v220, 11, v122
	s_waitcnt vmcnt(0)
	v_lshlrev_b32_e32 v122, 16, v2
	v_and_b32_e32 v123, 0xffff0000, v2
	v_mul_f32_e32 v122, 0x3d800000, v122
	v_mul_f32_e32 v123, 0x3d800000, v123
	v_cvt_pk_bf16_f32 v2, v122, v123
	v_lshlrev_b32_e32 v122, 16, v3
	v_and_b32_e32 v123, 0xffff0000, v3
	v_mul_f32_e32 v122, 0x3d800000, v122
	v_mul_f32_e32 v123, 0x3d800000, v123
	v_cvt_pk_bf16_f32 v3, v122, v123
	v_lshlrev_b32_e32 v122, 16, v4
	v_and_b32_e32 v123, 0xffff0000, v4
	v_mul_f32_e32 v122, 0x3d800000, v122
	v_mul_f32_e32 v123, 0x3d800000, v123
	v_cvt_pk_bf16_f32 v4, v122, v123
	v_lshlrev_b32_e32 v122, 16, v5
	v_and_b32_e32 v123, 0xffff0000, v5
	v_mul_f32_e32 v122, 0x3d800000, v122
	v_mul_f32_e32 v123, 0x3d800000, v123
	v_cvt_pk_bf16_f32 v5, v122, v123
	v_lshlrev_b32_e32 v122, 16, v6
	v_and_b32_e32 v123, 0xffff0000, v6
	v_mul_f32_e32 v122, 0x3d800000, v122
	v_mul_f32_e32 v123, 0x3d800000, v123
	v_cvt_pk_bf16_f32 v6, v122, v123
	v_lshlrev_b32_e32 v122, 16, v7
	v_and_b32_e32 v123, 0xffff0000, v7
	v_mul_f32_e32 v122, 0x3d800000, v122
	v_mul_f32_e32 v123, 0x3d800000, v123
	v_cvt_pk_bf16_f32 v7, v122, v123
	v_lshlrev_b32_e32 v122, 16, v8
	v_and_b32_e32 v123, 0xffff0000, v8
	v_mul_f32_e32 v122, 0x3d800000, v122
	v_mul_f32_e32 v123, 0x3d800000, v123
	v_cvt_pk_bf16_f32 v8, v122, v123
	v_lshlrev_b32_e32 v122, 16, v9
	v_and_b32_e32 v123, 0xffff0000, v9
	v_mul_f32_e32 v122, 0x3d800000, v122
	v_mul_f32_e32 v123, 0x3d800000, v123
	v_cvt_pk_bf16_f32 v9, v122, v123
	v_lshlrev_b32_e32 v122, 16, v10
	v_and_b32_e32 v123, 0xffff0000, v10
	v_mul_f32_e32 v122, 0x3d800000, v122
	v_mul_f32_e32 v123, 0x3d800000, v123
	v_cvt_pk_bf16_f32 v10, v122, v123
	v_lshlrev_b32_e32 v122, 16, v11
	v_and_b32_e32 v123, 0xffff0000, v11
	v_mul_f32_e32 v122, 0x3d800000, v122
	v_mul_f32_e32 v123, 0x3d800000, v123
	v_cvt_pk_bf16_f32 v11, v122, v123
	v_lshlrev_b32_e32 v122, 16, v12
	v_and_b32_e32 v123, 0xffff0000, v12
	v_mul_f32_e32 v122, 0x3d800000, v122
	v_mul_f32_e32 v123, 0x3d800000, v123
	v_cvt_pk_bf16_f32 v12, v122, v123
	v_lshlrev_b32_e32 v122, 16, v13
	v_and_b32_e32 v123, 0xffff0000, v13
	v_mul_f32_e32 v122, 0x3d800000, v122
	v_mul_f32_e32 v123, 0x3d800000, v123
	v_cvt_pk_bf16_f32 v13, v122, v123
	v_lshlrev_b32_e32 v122, 16, v14
	v_and_b32_e32 v123, 0xffff0000, v14
	v_mul_f32_e32 v122, 0x3d800000, v122
; #define LAS __attribute__((address_space(3)))
; __device__ __forceinline__ void memattn_unit(LAS unsigned char* lds, const Ctx& P, int unit) {
;     ...
;     for (int ks = 0; ks < 8; ++ks) qf[ks] = load_q_scaled(H + tok * LDH + C_QM + head * 256 + ks * 32 + 8 * i, 0.0625f);
;     f32x4 o[16];
; #pragma unroll
;     for (int dt = 0; dt < 16; ++dt) o[dt] = (f32x4){0.f, 0.f, 0.f, 0.f};
;     float m = NEGBIG, lsum = 0.f, alpha; bf16x8 pf, pf1;
;     const bf16_t* kb = MKV + (size_t)b * 256 * DM + head * 256; const bf16_t* vb = kb + 1024;
;     for (int kt = 0; kt < 4; ++kt) {
;         __syncthreads();
;         { u32x4 kr[4], vr[4];
; #pragma unroll
;             for (int it = 0; it < 4; ++it) { const int idx = tid + it * 512, key = idx & 63, seg = idx >> 6; const size_t off = (size_t)(kt * 64 + key) * DM + seg * 8; kr[it] = *(const u32x4*)(kb + off); vr[it] = *(const u32x4*)(vb + off); }
; #pragma unroll
;             for (int it = 0; it < 4; ++it) { const int idx = tid + it * 512, key = idx & 63, seg = idx >> 6; *(LAS u32x4*)(Ks + key * 264 + seg * 8) = kr[it];
;                 LAS bf16_t* d = Vt + (seg * 8) * 72 + key; const u32x4 v = vr[it];
;                 d[0 * 72] = (bf16_t)(v.x & 0xffffu); d[1 * 72] = (bf16_t)(v.x >> 16); d[2 * 72] = (bf16_t)(v.y & 0xffffu); d[3 * 72] = (bf16_t)(v.y >> 16);
;                 d[4 * 72] = (bf16_t)(v.z & 0xffffu); d[5 * 72] = (bf16_t)(v.z >> 16); d[6 * 72] = (bf16_t)(v.w & 0xffffu); d[7 * 72] = (bf16_t)(v.w >> 16); } }
;         __syncthreads();
	v_mul_f32_e32 v123, 0x3d800000, v123
	v_cvt_pk_bf16_f32 v14, v122, v123
	v_lshlrev_b32_e32 v122, 16, v15
	v_and_b32_e32 v123, 0xffff0000, v15
	v_mul_f32_e32 v122, 0x3d800000, v122
	v_mul_f32_e32 v123, 0x3d800000, v123
	v_cvt_pk_bf16_f32 v15, v122, v123
	v_lshlrev_b32_e32 v122, 16, v16
	v_and_b32_e32 v123, 0xffff0000, v16
	v_mul_f32_e32 v122, 0x3d800000, v122
	v_mul_f32_e32 v123, 0x3d800000, v123
	v_cvt_pk_bf16_f32 v16, v122, v123
	v_lshlrev_b32_e32 v122, 16, v17
	v_and_b32_e32 v123, 0xffff0000, v17
	v_mul_f32_e32 v122, 0x3d800000, v122
	v_mul_f32_e32 v123, 0x3d800000, v123
	v_cvt_pk_bf16_f32 v17, v122, v123
	v_lshlrev_b32_e32 v122, 16, v18
	v_and_b32_e32 v123, 0xffff0000, v18
	v_mul_f32_e32 v122, 0x3d800000, v122
	v_mul_f32_e32 v123, 0x3d800000, v123
	v_cvt_pk_bf16_f32 v18, v122, v123
	v_lshlrev_b32_e32 v122, 16, v19
	v_and_b32_e32 v123, 0xffff0000, v19
	v_mul_f32_e32 v122, 0x3d800000, v122
	v_mul_f32_e32 v123, 0x3d800000, v123
	v_cvt_pk_bf16_f32 v19, v122, v123
	v_lshlrev_b32_e32 v122, 16, v20
	v_and_b32_e32 v123, 0xffff0000, v20
	v_mul_f32_e32 v122, 0x3d800000, v122
	v_mul_f32_e32 v123, 0x3d800000, v123
	v_cvt_pk_bf16_f32 v20, v122, v123
	v_lshlrev_b32_e32 v122, 16, v21
	v_and_b32_e32 v123, 0xffff0000, v21
	v_mul_f32_e32 v122, 0x3d800000, v122
	v_mul_f32_e32 v123, 0x3d800000, v123
	v_cvt_pk_bf16_f32 v21, v122, v123
	v_lshlrev_b32_e32 v122, 16, v22
	v_and_b32_e32 v123, 0xffff0000, v22
	v_mul_f32_e32 v122, 0x3d800000, v122
	v_mul_f32_e32 v123, 0x3d800000, v123
	v_cvt_pk_bf16_f32 v22, v122, v123
	v_lshlrev_b32_e32 v122, 16, v23
	v_and_b32_e32 v123, 0xffff0000, v23
	v_mul_f32_e32 v122, 0x3d800000, v122
	v_mul_f32_e32 v123, 0x3d800000, v123
	v_cvt_pk_bf16_f32 v23, v122, v123
	v_lshlrev_b32_e32 v122, 16, v24
	v_and_b32_e32 v123, 0xffff0000, v24
	v_mul_f32_e32 v122, 0x3d800000, v122
	v_mul_f32_e32 v123, 0x3d800000, v123
	v_cvt_pk_bf16_f32 v24, v122, v123
	v_lshlrev_b32_e32 v122, 16, v25
	v_and_b32_e32 v123, 0xffff0000, v25
	v_mul_f32_e32 v122, 0x3d800000, v122
	v_mul_f32_e32 v123, 0x3d800000, v123
	v_cvt_pk_bf16_f32 v25, v122, v123
	v_lshlrev_b32_e32 v122, 16, v26
	v_and_b32_e32 v123, 0xffff0000, v26
	v_mul_f32_e32 v122, 0x3d800000, v122
	v_mul_f32_e32 v123, 0x3d800000, v123
	v_cvt_pk_bf16_f32 v26, v122, v123
	v_lshlrev_b32_e32 v122, 16, v27
	v_and_b32_e32 v123, 0xffff0000, v27
	v_mul_f32_e32 v122, 0x3d800000, v122
	v_mul_f32_e32 v123, 0x3d800000, v123
	v_cvt_pk_bf16_f32 v27, v122, v123
	v_lshlrev_b32_e32 v122, 16, v28
	v_and_b32_e32 v123, 0xffff0000, v28
	v_mul_f32_e32 v122, 0x3d800000, v122
	v_mul_f32_e32 v123, 0x3d800000, v123
	v_cvt_pk_bf16_f32 v28, v122, v123
	v_lshlrev_b32_e32 v122, 16, v29
	v_and_b32_e32 v123, 0xffff0000, v29
	v_mul_f32_e32 v122, 0x3d800000, v122
	v_mul_f32_e32 v123, 0x3d800000, v123
	v_cvt_pk_bf16_f32 v29, v122, v123
	v_lshlrev_b32_e32 v122, 16, v30
	v_and_b32_e32 v123, 0xffff0000, v30
	v_mul_f32_e32 v122, 0x3d800000, v122
	v_mul_f32_e32 v123, 0x3d800000, v123
	v_cvt_pk_bf16_f32 v30, v122, v123
	v_lshlrev_b32_e32 v122, 16, v31
	v_and_b32_e32 v123, 0xffff0000, v31
	v_mul_f32_e32 v122, 0x3d800000, v122
	v_mul_f32_e32 v123, 0x3d800000, v123
	v_cvt_pk_bf16_f32 v31, v122, v123
	v_lshlrev_b32_e32 v122, 16, v32
	v_and_b32_e32 v123, 0xffff0000, v32
	v_mul_f32_e32 v122, 0x3d800000, v122
	v_mul_f32_e32 v123, 0x3d800000, v123
	v_cvt_pk_bf16_f32 v32, v122, v123
	v_lshlrev_b32_e32 v122, 16, v33
	v_and_b32_e32 v123, 0xffff0000, v33
	v_mul_f32_e32 v122, 0x3d800000, v122
	v_mul_f32_e32 v123, 0x3d800000, v123
	v_cvt_pk_bf16_f32 v33, v122, v123
	v_mov_b32_e32 v34, 0
	v_mov_b32_e32 v35, 0
	v_mov_b32_e32 v36, 0
	v_mov_b32_e32 v37, 0
	v_mov_b32_e32 v38, 0
	v_mov_b32_e32 v39, 0
	v_mov_b32_e32 v40, 0
	v_mov_b32_e32 v41, 0
	v_mov_b32_e32 v42, 0
	v_mov_b32_e32 v43, 0
	v_mov_b32_e32 v44, 0
	v_mov_b32_e32 v45, 0
	v_mov_b32_e32 v46, 0
	v_mov_b32_e32 v47, 0
	v_mov_b32_e32 v48, 0
	v_mov_b32_e32 v49, 0
	v_mov_b32_e32 v50, 0
	v_mov_b32_e32 v51, 0
	v_mov_b32_e32 v52, 0
	v_mov_b32_e32 v53, 0
	v_mov_b32_e32 v54, 0
	v_mov_b32_e32 v55, 0
	v_mov_b32_e32 v56, 0
	v_mov_b32_e32 v57, 0
	v_mov_b32_e32 v58, 0
	v_mov_b32_e32 v59, 0
	v_mov_b32_e32 v60, 0
	v_mov_b32_e32 v61, 0
	v_mov_b32_e32 v62, 0
	v_mov_b32_e32 v63, 0
	v_mov_b32_e32 v64, 0
	v_mov_b32_e32 v65, 0
	v_mov_b32_e32 v66, 0
	v_mov_b32_e32 v67, 0
	v_mov_b32_e32 v68, 0
	v_mov_b32_e32 v69, 0
	v_mov_b32_e32 v70, 0
	v_mov_b32_e32 v71, 0
	v_mov_b32_e32 v72, 0
	v_mov_b32_e32 v73, 0
	v_mov_b32_e32 v74, 0
	v_mov_b32_e32 v75, 0
	v_mov_b32_e32 v76, 0
	v_mov_b32_e32 v77, 0
	v_mov_b32_e32 v78, 0
	v_mov_b32_e32 v79, 0
	v_mov_b32_e32 v80, 0
	v_mov_b32_e32 v81, 0
	v_mov_b32_e32 v82, 0
	v_mov_b32_e32 v83, 0
	v_mov_b32_e32 v84, 0
	v_mov_b32_e32 v85, 0
	v_mov_b32_e32 v86, 0
	v_mov_b32_e32 v87, 0
	v_mov_b32_e32 v88, 0
	v_mov_b32_e32 v89, 0
	v_mov_b32_e32 v90, 0
	v_mov_b32_e32 v91, 0
	v_mov_b32_e32 v92, 0
	v_mov_b32_e32 v93, 0
	v_mov_b32_e32 v94, 0
	v_mov_b32_e32 v95, 0
	v_mov_b32_e32 v96, 0
	v_mov_b32_e32 v97, 0
	v_mov_b32_e32 v207, 0xf149f2ca
	v_mov_b32_e32 v208, 0
	s_waitcnt lgkmcnt(0)
	s_barrier
	s_waitcnt vmcnt(0)
	ds_write_b128 v206, v[130:133] offset:0
	ds_write_b128 v206, v[146:149] offset:33792
	ds_write_b128 v206, v[134:137] offset:8448
	ds_write_b128 v206, v[150:153] offset:42240
	ds_write_b128 v206, v[138:141] offset:16896
	ds_write_b128 v206, v[154:157] offset:50688
	ds_write_b128 v206, v[142:145] offset:25344
	ds_write_b128 v206, v[158:161] offset:59136
	ds_write_b128 v216, v[170:173] offset:0
	ds_write_b128 v216, v[186:189] offset:33792
	ds_write_b128 v216, v[174:177] offset:8448
	ds_write_b128 v216, v[190:193] offset:42240
	ds_write_b128 v216, v[178:181] offset:16896
	ds_write_b128 v216, v[194:197] offset:50688
	ds_write_b128 v216, v[182:185] offset:25344
	ds_write_b128 v216, v[198:201] offset:59136
	s_waitcnt lgkmcnt(0)
	s_barrier
; #define LAS __attribute__((address_space(3)))
; __device__ __forceinline__ f32x4 mfma16(bf16x8 a, bf16x8 b, f32x4 c) { return __builtin_amdgcn_mfma_f32_16x16x32_bf16(a, b, c, 0, 0, 0); }
; template <int D, class SF>
; __device__ __forceinline__ void attn_step(const bf16x8 (&qf)[D / 32], const LAS bf16_t* Ks, const LAS bf16_t* Vt, f32x4 (&o)[D / 16], float& m, float& lsum, float& alpha_out, bf16x8& pf0_out, bf16x8& pf1_out, const int lane, SF sf) {
;     ...
;     for (int ks = 0; ks < D / 32; ++ks) {
; #pragma unroll
;         for (int t = 0; t < 4; ++t) { const bf16x8 kf = *(const LAS bf16x8*)(Ks + (16 * t + c) * KSTR + ks * 32 + 8 * i); s[t] = mfma16(kf, qf[ks], s[t]); }
;     }
;     float v[16];
; #pragma unroll
;     for (int t = 0; t < 4; ++t)
; #pragma unroll
;         for (int r = 0; r < 4; ++r) v[4 * t + r] = sf(16 * t + 4 * i + r, s[t][r]);
;     float mx = fmaxf(fmaxf(fmaxf(v[0], v[1]), fmaxf(v[2], v[3])), fmaxf(fmaxf(v[4], v[5]), fmaxf(v[6], v[7])));
;     mx = fmaxf(mx, fmaxf(fmaxf(fmaxf(v[8], v[9]), fmaxf(v[10], v[11])), fmaxf(fmaxf(v[12], v[13]), fmaxf(v[14], v[15]))));
;     mx = rows_max(mx);
;     ...
;         const LAS bf16_t* vp = Vt + (16 * dt + c) * 72 + 4 * i;
;         union { u32x4 u; bf16x8 b; } vf0, vf1; const u32x2 a0 = *(const LAS u32x2*)vp, a1 = *(const LAS u32x2*)(vp + 16), b0 = *(const LAS u32x2*)(vp + 32), b1 = *(const LAS u32x2*)(vp + 48);
;         vf0.u.x = a0.x; vf0.u.y = a0.y; vf0.u.z = a1.x; vf0.u.w = a1.y; vf1.u.x = b0.x; vf1.u.y = b0.y; vf1.u.z = b1.x; vf1.u.w = b1.y;
	ds_read_b128 v[130:133], v202 offset:0
	ds_read_b128 v[134:137], v202 offset:64
	ds_read_b128 v[138:141], v202 offset:8448
	ds_read_b128 v[142:145], v202 offset:8512
	ds_read_b128 v[146:149], v202 offset:16896
	ds_read_b128 v[150:153], v202 offset:16960
	ds_read_b128 v[154:157], v202 offset:25344
	ds_read_b128 v[158:161], v202 offset:25408
	ds_read_b128 v[170:173], v202 offset:128
	ds_read_b128 v[174:177], v202 offset:192
	ds_read_b128 v[178:181], v202 offset:8576
	ds_read_b128 v[182:185], v202 offset:8640
	ds_read_b128 v[186:189], v202 offset:17024
	ds_read_b128 v[190:193], v202 offset:17088
	ds_read_b128 v[194:197], v202 offset:25472
	ds_read_b128 v[198:201], v202 offset:25536
	s_waitcnt lgkmcnt(8)
	v_mfma_f32_16x16x32_bf16 v[98:101], v[130:133], v[2:5], 0
	v_mfma_f32_16x16x32_bf16 v[102:105], v[138:141], v[2:5], 0
	v_mfma_f32_16x16x32_bf16 v[106:109], v[146:149], v[2:5], 0
	v_mfma_f32_16x16x32_bf16 v[110:113], v[154:157], v[2:5], 0
	v_mfma_f32_16x16x32_bf16 v[98:101], v[134:137], v[6:9], v[98:101]
	v_mfma_f32_16x16x32_bf16 v[102:105], v[142:145], v[6:9], v[102:105]
	v_mfma_f32_16x16x32_bf16 v[106:109], v[150:153], v[6:9], v[106:109]
	v_mfma_f32_16x16x32_bf16 v[110:113], v[158:161], v[6:9], v[110:113]
	ds_read_b128 v[130:133], v202 offset:256
	ds_read_b128 v[134:137], v202 offset:320
	ds_read_b128 v[138:141], v202 offset:8704
	ds_read_b128 v[142:145], v202 offset:8768
	ds_read_b128 v[146:149], v202 offset:17152
	ds_read_b128 v[150:153], v202 offset:17216
	ds_read_b128 v[154:157], v202 offset:25600
	ds_read_b128 v[158:161], v202 offset:25664
	s_waitcnt lgkmcnt(8)
	v_mfma_f32_16x16x32_bf16 v[98:101], v[170:173], v[10:13], v[98:101]
	v_mfma_f32_16x16x32_bf16 v[102:105], v[178:181], v[10:13], v[102:105]
	v_mfma_f32_16x16x32_bf16 v[106:109], v[186:189], v[10:13], v[106:109]
	v_mfma_f32_16x16x32_bf16 v[110:113], v[194:197], v[10:13], v[110:113]
	v_mfma_f32_16x16x32_bf16 v[98:101], v[174:177], v[14:17], v[98:101]
	v_mfma_f32_16x16x32_bf16 v[102:105], v[182:185], v[14:17], v[102:105]
	v_mfma_f32_16x16x32_bf16 v[106:109], v[190:193], v[14:17], v[106:109]
	v_mfma_f32_16x16x32_bf16 v[110:113], v[198:201], v[14:17], v[110:113]
	ds_read_b128 v[170:173], v202 offset:384
	ds_read_b128 v[174:177], v202 offset:448
	ds_read_b128 v[178:181], v202 offset:8832
	ds_read_b128 v[182:185], v202 offset:8896
	ds_read_b128 v[186:189], v202 offset:17280
	ds_read_b128 v[190:193], v202 offset:17344
	ds_read_b128 v[194:197], v202 offset:25728
	ds_read_b128 v[198:201], v202 offset:25792
	s_waitcnt lgkmcnt(8)
	v_mfma_f32_16x16x32_bf16 v[98:101], v[130:133], v[18:21], v[98:101]
	v_mfma_f32_16x16x32_bf16 v[102:105], v[138:141], v[18:21], v[102:105]
	v_mfma_f32_16x16x32_bf16 v[106:109], v[146:149], v[18:21], v[106:109]
	v_mfma_f32_16x16x32_bf16 v[110:113], v[154:157], v[18:21], v[110:113]
	v_mfma_f32_16x16x32_bf16 v[98:101], v[134:137], v[22:25], v[98:101]
	v_mfma_f32_16x16x32_bf16 v[102:105], v[142:145], v[22:25], v[102:105]
	v_mfma_f32_16x16x32_bf16 v[106:109], v[150:153], v[22:25], v[106:109]
	v_mfma_f32_16x16x32_bf16 v[110:113], v[158:161], v[22:25], v[110:113]
	s_waitcnt lgkmcnt(0)
	v_mfma_f32_16x16x32_bf16 v[98:101], v[170:173], v[26:29], v[98:101]
	v_mfma_f32_16x16x32_bf16 v[102:105], v[178:181], v[26:29], v[102:105]
	v_mfma_f32_16x16x32_bf16 v[106:109], v[186:189], v[26:29], v[106:109]
	v_mfma_f32_16x16x32_bf16 v[110:113], v[194:197], v[26:29], v[110:113]
	v_mfma_f32_16x16x32_bf16 v[98:101], v[174:177], v[30:33], v[98:101]
	v_mfma_f32_16x16x32_bf16 v[102:105], v[182:185], v[30:33], v[102:105]
	v_mfma_f32_16x16x32_bf16 v[106:109], v[190:193], v[30:33], v[106:109]
	v_mfma_f32_16x16x32_bf16 v[110:113], v[198:201], v[30:33], v[110:113]
	ds_read_b64_tr_b16 v[130:131], v204 offset:33792
	ds_read_b64_tr_b16 v[132:133], v204 offset:42240
	ds_read_b64_tr_b16 v[134:135], v204 offset:50688
	ds_read_b64_tr_b16 v[136:137], v204 offset:59136
	ds_read_b64_tr_b16 v[138:139], v204 offset:33824
	ds_read_b64_tr_b16 v[140:141], v204 offset:42272
	ds_read_b64_tr_b16 v[142:143], v204 offset:50720
	ds_read_b64_tr_b16 v[144:145], v204 offset:59168
	ds_read_b64_tr_b16 v[146:147], v204 offset:33856
	ds_read_b64_tr_b16 v[148:149], v204 offset:42304
	ds_read_b64_tr_b16 v[150:151], v204 offset:50752
	ds_read_b64_tr_b16 v[152:153], v204 offset:59200
	ds_read_b64_tr_b16 v[154:155], v204 offset:33888
	ds_read_b64_tr_b16 v[156:157], v204 offset:42336
	ds_read_b64_tr_b16 v[158:159], v204 offset:50784
	ds_read_b64_tr_b16 v[160:161], v204 offset:59232
	ds_read_b64_tr_b16 v[170:171], v204 offset:33920
	ds_read_b64_tr_b16 v[172:173], v204 offset:42368
	ds_read_b64_tr_b16 v[174:175], v204 offset:50816
	ds_read_b64_tr_b16 v[176:177], v204 offset:59264
	ds_read_b64_tr_b16 v[178:179], v204 offset:33952
	ds_read_b64_tr_b16 v[180:181], v204 offset:42400
	ds_read_b64_tr_b16 v[182:183], v204 offset:50848
	ds_read_b64_tr_b16 v[184:185], v204 offset:59296
	ds_read_b64_tr_b16 v[186:187], v204 offset:33984
	ds_read_b64_tr_b16 v[188:189], v204 offset:42432
	ds_read_b64_tr_b16 v[190:191], v204 offset:50880
	ds_read_b64_tr_b16 v[192:193], v204 offset:59328
	ds_read_b64_tr_b16 v[194:195], v204 offset:34016
	ds_read_b64_tr_b16 v[196:197], v204 offset:42464
	ds_read_b64_tr_b16 v[198:199], v204 offset:50912
	ds_read_b64_tr_b16 v[200:201], v204 offset:59360
	v_max3_f32 v122, v98, v99, v100
	v_max3_f32 v123, v101, v102, v103
	v_max3_f32 v124, v104, v105, v106
	v_max3_f32 v125, v107, v108, v109
	v_max3_f32 v127, v110, v111, v112
	v_max3_f32 v122, v122, v123, v113
	v_max3_f32 v124, v124, v125, v127
	v_max_f32_e32 v122, v122, v124
	v_mov_b32_e32 v123, v122
	s_nop 1
	v_permlane16_swap_b32_e32 v122, v123
	v_max_f32_e32 v122, v122, v123
; __device__ __forceinline__ unsigned cvt_pk_bf16(float lo, float hi) { unsigned r; asm("v_cvt_pk_bf16_f32 %0, %1, %2" : "=v"(r) : "v"(lo), "v"(hi)); return r; }
; template <int D, class SF>
; __device__ __forceinline__ void attn_step(const bf16x8 (&qf)[D / 32], const LAS bf16_t* Ks, const LAS bf16_t* Vt, f32x4 (&o)[D / 16], float& m, float& lsum, float& alpha_out, bf16x8& pf0_out, bf16x8& pf1_out, const int lane, SF sf) {
;     ...
;     mx = rows_max(mx);
;     const float mnew = fmaxf(m, mx);
;     const float mc = fmaxf(mnew, -1e20f);
;     const float alpha = __builtin_amdgcn_exp2f(fmaxf(m, -1e20f) - mc);
;     float p[16], rs = 0.f;
; #pragma unroll
;     for (int r = 0; r < 16; ++r) { p[r] = __builtin_amdgcn_exp2f(v[r] - mc); rs += p[r]; }
;     rs = rows_sum(rs);
;     lsum = lsum * alpha + rs; m = mnew;
;     union { u32x4 u; bf16x8 b; } pk0, pk1;
;     pk0.u.x = cvt_pk_bf16(p[0], p[1]); pk0.u.y = cvt_pk_bf16(p[2], p[3]); pk0.u.z = cvt_pk_bf16(p[4], p[5]); pk0.u.w = cvt_pk_bf16(p[6], p[7]);
;     pk1.u.x = cvt_pk_bf16(p[8], p[9]); pk1.u.y = cvt_pk_bf16(p[10], p[11]); pk1.u.z = cvt_pk_bf16(p[12], p[13]); pk1.u.w = cvt_pk_bf16(p[14], p[15]);
;     if (__builtin_amdgcn_ballot_w64(alpha != 1.0f) != 0ull) {
; #pragma unroll
;         for (int dt = 0; dt < D / 16; ++dt) o[dt] *= alpha;
;     }
	v_mov_b32_e32 v123, v122
	s_nop 1
	v_permlane32_swap_b32_e32 v122, v123
	v_max_f32_e32 v122, v122, v123
	v_mul_f32_e32 v122, 0x3fb8aa3b, v122
	v_max_f32_e32 v124, v207, v122
	v_max_f32_e32 v126, 0xe0ad78ec, v207
	v_max_f32_e32 v125, 0xe0ad78ec, v124
	v_sub_f32_e32 v126, v126, v125
	v_mov_b32_e32 v207, v124
	v_exp_f32_e32 v126, v126
	v_sub_f32_e32 v127, 0, v125
	v_fmamk_f32 v98, v98, 0x3fb8aa3b, v127
	v_fmamk_f32 v99, v99, 0x3fb8aa3b, v127
	v_fmamk_f32 v100, v100, 0x3fb8aa3b, v127
	v_fmamk_f32 v101, v101, 0x3fb8aa3b, v127
	v_exp_f32_e32 v98, v98
	v_exp_f32_e32 v99, v99
	v_exp_f32_e32 v100, v100
	v_exp_f32_e32 v101, v101
	v_fmamk_f32 v102, v102, 0x3fb8aa3b, v127
	v_fmamk_f32 v103, v103, 0x3fb8aa3b, v127
	v_fmamk_f32 v104, v104, 0x3fb8aa3b, v127
	v_fmamk_f32 v105, v105, 0x3fb8aa3b, v127
	v_exp_f32_e32 v102, v102
	v_exp_f32_e32 v103, v103
	v_exp_f32_e32 v104, v104
	v_exp_f32_e32 v105, v105
	v_fmamk_f32 v106, v106, 0x3fb8aa3b, v127
	v_fmamk_f32 v107, v107, 0x3fb8aa3b, v127
	v_fmamk_f32 v108, v108, 0x3fb8aa3b, v127
	v_fmamk_f32 v109, v109, 0x3fb8aa3b, v127
	v_exp_f32_e32 v106, v106
	v_exp_f32_e32 v107, v107
	v_exp_f32_e32 v108, v108
	v_exp_f32_e32 v109, v109
	v_fmamk_f32 v110, v110, 0x3fb8aa3b, v127
	v_fmamk_f32 v111, v111, 0x3fb8aa3b, v127
	v_fmamk_f32 v112, v112, 0x3fb8aa3b, v127
	v_fmamk_f32 v113, v113, 0x3fb8aa3b, v127
	v_exp_f32_e32 v110, v110
	v_exp_f32_e32 v111, v111
	v_exp_f32_e32 v112, v112
	v_exp_f32_e32 v113, v113
	s_nop 0
	v_add_f32_e32 v122, v98, v99
	v_add_f32_e32 v123, v100, v101
	v_add_f32_e32 v124, v102, v103
	v_add_f32_e32 v125, v104, v105
	v_add_f32_e32 v122, v122, v106
	v_add_f32_e32 v123, v123, v107
	v_add_f32_e32 v124, v124, v108
	v_add_f32_e32 v125, v125, v109
	v_add_f32_e32 v122, v122, v110
	v_add_f32_e32 v123, v123, v111
	v_add_f32_e32 v124, v124, v112
	v_add_f32_e32 v125, v125, v113
	v_add_f32_e32 v122, v122, v123
	v_add_f32_e32 v124, v124, v125
	v_add_f32_e32 v122, v122, v124
	v_cvt_pk_bf16_f32 v114, v98, v99
	v_cvt_pk_bf16_f32 v115, v100, v101
	v_cvt_pk_bf16_f32 v116, v102, v103
	v_cvt_pk_bf16_f32 v117, v104, v105
	v_cvt_pk_bf16_f32 v118, v106, v107
	v_cvt_pk_bf16_f32 v119, v108, v109
	v_cvt_pk_bf16_f32 v120, v110, v111
	v_cvt_pk_bf16_f32 v121, v112, v113
	v_mov_b32_e32 v123, v122
	s_nop 1
	v_permlane16_swap_b32_e32 v122, v123
	v_add_f32_e32 v122, v122, v123
	v_mov_b32_e32 v123, v122
	s_nop 1
	v_permlane32_swap_b32_e32 v122, v123
	v_add_f32_e32 v122, v122, v123
	v_fma_f32 v208, v208, v126, v122
	v_cmp_neq_f32_e64 s[0:1], 1.0, v126
	s_cmp_eq_u64 s[0:1], 0
	s_cbranch_scc1 .Lmem_nosc_1
	v_pk_mul_f32 v[34:35], v[34:35], v[126:127] op_sel_hi:[1,0]
	v_pk_mul_f32 v[36:37], v[36:37], v[126:127] op_sel_hi:[1,0]
	v_pk_mul_f32 v[38:39], v[38:39], v[126:127] op_sel_hi:[1,0]
	v_pk_mul_f32 v[40:41], v[40:41], v[126:127] op_sel_hi:[1,0]
	v_pk_mul_f32 v[42:43], v[42:43], v[126:127] op_sel_hi:[1,0]
	v_pk_mul_f32 v[44:45], v[44:45], v[126:127] op_sel_hi:[1,0]
	v_pk_mul_f32 v[46:47], v[46:47], v[126:127] op_sel_hi:[1,0]
	v_pk_mul_f32 v[48:49], v[48:49], v[126:127] op_sel_hi:[1,0]
	v_pk_mul_f32 v[50:51], v[50:51], v[126:127] op_sel_hi:[1,0]
	v_pk_mul_f32 v[52:53], v[52:53], v[126:127] op_sel_hi:[1,0]
	v_pk_mul_f32 v[54:55], v[54:55], v[126:127] op_sel_hi:[1,0]
	v_pk_mul_f32 v[56:57], v[56:57], v[126:127] op_sel_hi:[1,0]
	v_pk_mul_f32 v[58:59], v[58:59], v[126:127] op_sel_hi:[1,0]
	v_pk_mul_f32 v[60:61], v[60:61], v[126:127] op_sel_hi:[1,0]
	v_pk_mul_f32 v[62:63], v[62:63], v[126:127] op_sel_hi:[1,0]
	v_pk_mul_f32 v[64:65], v[64:65], v[126:127] op_sel_hi:[1,0]
	v_pk_mul_f32 v[66:67], v[66:67], v[126:127] op_sel_hi:[1,0]
	v_pk_mul_f32 v[68:69], v[68:69], v[126:127] op_sel_hi:[1,0]
	v_pk_mul_f32 v[70:71], v[70:71], v[126:127] op_sel_hi:[1,0]
	v_pk_mul_f32 v[72:73], v[72:73], v[126:127] op_sel_hi:[1,0]
	v_pk_mul_f32 v[74:75], v[74:75], v[126:127] op_sel_hi:[1,0]
	v_pk_mul_f32 v[76:77], v[76:77], v[126:127] op_sel_hi:[1,0]
	v_pk_mul_f32 v[78:79], v[78:79], v[126:127] op_sel_hi:[1,0]
	v_pk_mul_f32 v[80:81], v[80:81], v[126:127] op_sel_hi:[1,0]
	v_pk_mul_f32 v[82:83], v[82:83], v[126:127] op_sel_hi:[1,0]
	v_pk_mul_f32 v[84:85], v[84:85], v[126:127] op_sel_hi:[1,0]
	v_pk_mul_f32 v[86:87], v[86:87], v[126:127] op_sel_hi:[1,0]
	v_pk_mul_f32 v[88:89], v[88:89], v[126:127] op_sel_hi:[1,0]
	v_pk_mul_f32 v[90:91], v[90:91], v[126:127] op_sel_hi:[1,0]
	v_pk_mul_f32 v[92:93], v[92:93], v[126:127] op_sel_hi:[1,0]
	v_pk_mul_f32 v[94:95], v[94:95], v[126:127] op_sel_hi:[1,0]
	v_pk_mul_f32 v[96:97], v[96:97], v[126:127] op_sel_hi:[1,0]
; #define LAS __attribute__((address_space(3)))
; __device__ __forceinline__ f32x4 mfma16(bf16x8 a, bf16x8 b, f32x4 c) { return __builtin_amdgcn_mfma_f32_16x16x32_bf16(a, b, c, 0, 0, 0); }
; template <int D, class SF>
; __device__ __forceinline__ void attn_step(const bf16x8 (&qf)[D / 32], const LAS bf16_t* Ks, const LAS bf16_t* Vt, f32x4 (&o)[D / 16], float& m, float& lsum, float& alpha_out, bf16x8& pf0_out, bf16x8& pf1_out, const int lane, SF sf) {
;     ...
;     for (int ks = 0; ks < D / 32; ++ks) {
; #pragma unroll
;         for (int t = 0; t < 4; ++t) { const bf16x8 kf = *(const LAS bf16x8*)(Ks + (16 * t + c) * KSTR + ks * 32 + 8 * i); s[t] = mfma16(kf, qf[ks], s[t]); }
;     }
;     ...
;     for (int dt = 0; dt < D / 16; ++dt) {
;         const LAS bf16_t* vp = Vt + (16 * dt + c) * 72 + 4 * i;
;         union { u32x4 u; bf16x8 b; } vf0, vf1; const u32x2 a0 = *(const LAS u32x2*)vp, a1 = *(const LAS u32x2*)(vp + 16), b0 = *(const LAS u32x2*)(vp + 32), b1 = *(const LAS u32x2*)(vp + 48);
;         vf0.u.x = a0.x; vf0.u.y = a0.y; vf0.u.z = a1.x; vf0.u.w = a1.y; vf1.u.x = b0.x; vf1.u.y = b0.y; vf1.u.z = b1.x; vf1.u.w = b1.y;
;         o[dt] = mfma16(vf0.b, pk0.b, o[dt]); o[dt] = mfma16(vf1.b, pk1.b, o[dt]);
;     }
.Lmem_nosc_1:
	s_waitcnt lgkmcnt(0)
	s_nop 1
	v_mfma_f32_16x16x32_bf16 v[34:37], v[130:133], v[114:117], v[34:37]
	v_mfma_f32_16x16x32_bf16 v[38:41], v[138:141], v[114:117], v[38:41]
	v_mfma_f32_16x16x32_bf16 v[42:45], v[146:149], v[114:117], v[42:45]
	v_mfma_f32_16x16x32_bf16 v[46:49], v[154:157], v[114:117], v[46:49]
	v_mfma_f32_16x16x32_bf16 v[34:37], v[134:137], v[118:121], v[34:37]
	v_mfma_f32_16x16x32_bf16 v[38:41], v[142:145], v[118:121], v[38:41]
	v_mfma_f32_16x16x32_bf16 v[42:45], v[150:153], v[118:121], v[42:45]
	v_mfma_f32_16x16x32_bf16 v[46:49], v[158:161], v[118:121], v[46:49]
	ds_read_b64_tr_b16 v[130:131], v204 offset:34048
	ds_read_b64_tr_b16 v[132:133], v204 offset:42496
	ds_read_b64_tr_b16 v[134:135], v204 offset:50944
	ds_read_b64_tr_b16 v[136:137], v204 offset:59392
	ds_read_b64_tr_b16 v[138:139], v204 offset:34080
	ds_read_b64_tr_b16 v[140:141], v204 offset:42528
	ds_read_b64_tr_b16 v[142:143], v204 offset:50976
	ds_read_b64_tr_b16 v[144:145], v204 offset:59424
	ds_read_b64_tr_b16 v[146:147], v204 offset:34112
	ds_read_b64_tr_b16 v[148:149], v204 offset:42560
	ds_read_b64_tr_b16 v[150:151], v204 offset:51008
	ds_read_b64_tr_b16 v[152:153], v204 offset:59456
	ds_read_b64_tr_b16 v[154:155], v204 offset:34144
	ds_read_b64_tr_b16 v[156:157], v204 offset:42592
	ds_read_b64_tr_b16 v[158:159], v204 offset:51040
	ds_read_b64_tr_b16 v[160:161], v204 offset:59488
	s_waitcnt lgkmcnt(15)
	v_mfma_f32_16x16x32_bf16 v[50:53], v[170:173], v[114:117], v[50:53]
	v_mfma_f32_16x16x32_bf16 v[54:57], v[178:181], v[114:117], v[54:57]
	v_mfma_f32_16x16x32_bf16 v[58:61], v[186:189], v[114:117], v[58:61]
	v_mfma_f32_16x16x32_bf16 v[62:65], v[194:197], v[114:117], v[62:65]
	v_mfma_f32_16x16x32_bf16 v[50:53], v[174:177], v[118:121], v[50:53]
	v_mfma_f32_16x16x32_bf16 v[54:57], v[182:185], v[118:121], v[54:57]
	v_mfma_f32_16x16x32_bf16 v[58:61], v[190:193], v[118:121], v[58:61]
	v_mfma_f32_16x16x32_bf16 v[62:65], v[198:201], v[118:121], v[62:65]
	ds_read_b64_tr_b16 v[170:171], v204 offset:34176
	ds_read_b64_tr_b16 v[172:173], v204 offset:42624
	ds_read_b64_tr_b16 v[174:175], v204 offset:51072
	ds_read_b64_tr_b16 v[176:177], v204 offset:59520
	ds_read_b64_tr_b16 v[178:179], v204 offset:34208
	ds_read_b64_tr_b16 v[180:181], v204 offset:42656
	ds_read_b64_tr_b16 v[182:183], v204 offset:51104
	ds_read_b64_tr_b16 v[184:185], v204 offset:59552
	ds_read_b64_tr_b16 v[186:187], v204 offset:34240
	ds_read_b64_tr_b16 v[188:189], v204 offset:42688
	ds_read_b64_tr_b16 v[190:191], v204 offset:51136
	ds_read_b64_tr_b16 v[192:193], v204 offset:59584
	ds_read_b64_tr_b16 v[194:195], v204 offset:34272
	ds_read_b64_tr_b16 v[196:197], v204 offset:42720
	ds_read_b64_tr_b16 v[198:199], v204 offset:51168
	ds_read_b64_tr_b16 v[200:201], v204 offset:59616
	s_waitcnt lgkmcnt(15)
	v_mfma_f32_16x16x32_bf16 v[66:69], v[130:133], v[114:117], v[66:69]
	v_mfma_f32_16x16x32_bf16 v[70:73], v[138:141], v[114:117], v[70:73]
	v_mfma_f32_16x16x32_bf16 v[74:77], v[146:149], v[114:117], v[74:77]
	v_mfma_f32_16x16x32_bf16 v[78:81], v[154:157], v[114:117], v[78:81]
	v_mfma_f32_16x16x32_bf16 v[66:69], v[134:137], v[118:121], v[66:69]
	v_mfma_f32_16x16x32_bf16 v[70:73], v[142:145], v[118:121], v[70:73]
	v_mfma_f32_16x16x32_bf16 v[74:77], v[150:153], v[118:121], v[74:77]
	v_mfma_f32_16x16x32_bf16 v[78:81], v[158:161], v[118:121], v[78:81]
	s_waitcnt lgkmcnt(0)
	v_mfma_f32_16x16x32_bf16 v[82:85], v[170:173], v[114:117], v[82:85]
	v_mfma_f32_16x16x32_bf16 v[86:89], v[178:181], v[114:117], v[86:89]
	v_mfma_f32_16x16x32_bf16 v[90:93], v[186:189], v[114:117], v[90:93]
	v_mfma_f32_16x16x32_bf16 v[94:97], v[194:197], v[114:117], v[94:97]
	v_mfma_f32_16x16x32_bf16 v[82:85], v[174:177], v[118:121], v[82:85]
	v_mfma_f32_16x16x32_bf16 v[86:89], v[182:185], v[118:121], v[86:89]
	v_mfma_f32_16x16x32_bf16 v[90:93], v[190:193], v[118:121], v[90:93]
	v_mfma_f32_16x16x32_bf16 v[94:97], v[198:201], v[118:121], v[94:97]
	ds_read_b128 v[130:133], v203 offset:0
	ds_read_b128 v[134:137], v203 offset:64
	ds_read_b128 v[138:141], v203 offset:8448
	ds_read_b128 v[142:145], v203 offset:8512
	ds_read_b128 v[146:149], v203 offset:16896
	ds_read_b128 v[150:153], v203 offset:16960
	ds_read_b128 v[154:157], v203 offset:25344
	ds_read_b128 v[158:161], v203 offset:25408
	ds_read_b128 v[170:173], v203 offset:128
	ds_read_b128 v[174:177], v203 offset:192
	ds_read_b128 v[178:181], v203 offset:8576
	ds_read_b128 v[182:185], v203 offset:8640
	ds_read_b128 v[186:189], v203 offset:17024
	ds_read_b128 v[190:193], v203 offset:17088
	ds_read_b128 v[194:197], v203 offset:25472
	ds_read_b128 v[198:201], v203 offset:25536
	s_waitcnt lgkmcnt(8)
	v_mfma_f32_16x16x32_bf16 v[98:101], v[130:133], v[2:5], 0
	v_mfma_f32_16x16x32_bf16 v[102:105], v[138:141], v[2:5], 0
	v_mfma_f32_16x16x32_bf16 v[106:109], v[146:149], v[2:5], 0
	v_mfma_f32_16x16x32_bf16 v[110:113], v[154:157], v[2:5], 0
	v_mfma_f32_16x16x32_bf16 v[98:101], v[134:137], v[6:9], v[98:101]
	v_mfma_f32_16x16x32_bf16 v[102:105], v[142:145], v[6:9], v[102:105]
	v_mfma_f32_16x16x32_bf16 v[106:109], v[150:153], v[6:9], v[106:109]
	v_mfma_f32_16x16x32_bf16 v[110:113], v[158:161], v[6:9], v[110:113]
	ds_read_b128 v[130:133], v203 offset:256
	ds_read_b128 v[134:137], v203 offset:320
	ds_read_b128 v[138:141], v203 offset:8704
	ds_read_b128 v[142:145], v203 offset:8768
	ds_read_b128 v[146:149], v203 offset:17152
	ds_read_b128 v[150:153], v203 offset:17216
	ds_read_b128 v[154:157], v203 offset:25600
	ds_read_b128 v[158:161], v203 offset:25664
	s_waitcnt lgkmcnt(8)
; #define LAS __attribute__((address_space(3)))
; __device__ __forceinline__ unsigned cvt_pk_bf16(float lo, float hi) { unsigned r; asm("v_cvt_pk_bf16_f32 %0, %1, %2" : "=v"(r) : "v"(lo), "v"(hi)); return r; }
; __device__ __forceinline__ f32x4 mfma16(bf16x8 a, bf16x8 b, f32x4 c) { return __builtin_amdgcn_mfma_f32_16x16x32_bf16(a, b, c, 0, 0, 0); }
; template <int D, class SF>
; __device__ __forceinline__ void attn_step(const bf16x8 (&qf)[D / 32], const LAS bf16_t* Ks, const LAS bf16_t* Vt, f32x4 (&o)[D / 16], float& m, float& lsum, float& alpha_out, bf16x8& pf0_out, bf16x8& pf1_out, const int lane, SF sf) {
;     ...
;     for (int ks = 0; ks < D / 32; ++ks) {
; #pragma unroll
;         for (int t = 0; t < 4; ++t) { const bf16x8 kf = *(const LAS bf16x8*)(Ks + (16 * t + c) * KSTR + ks * 32 + 8 * i); s[t] = mfma16(kf, qf[ks], s[t]); }
;     }
;     float v[16];
; #pragma unroll
;     for (int t = 0; t < 4; ++t)
; #pragma unroll
;         for (int r = 0; r < 4; ++r) v[4 * t + r] = sf(16 * t + 4 * i + r, s[t][r]);
;     float mx = fmaxf(fmaxf(fmaxf(v[0], v[1]), fmaxf(v[2], v[3])), fmaxf(fmaxf(v[4], v[5]), fmaxf(v[6], v[7])));
;     mx = fmaxf(mx, fmaxf(fmaxf(fmaxf(v[8], v[9]), fmaxf(v[10], v[11])), fmaxf(fmaxf(v[12], v[13]), fmaxf(v[14], v[15]))));
;     mx = rows_max(mx);
;     const float mnew = fmaxf(m, mx);
;     const float mc = fmaxf(mnew, -1e20f);
;     const float alpha = __builtin_amdgcn_exp2f(fmaxf(m, -1e20f) - mc);
;     float p[16], rs = 0.f;
; #pragma unroll
;     for (int r = 0; r < 16; ++r) { p[r] = __builtin_amdgcn_exp2f(v[r] - mc); rs += p[r]; }
;     rs = rows_sum(rs);
;     lsum = lsum * alpha + rs; m = mnew;
;     union { u32x4 u; bf16x8 b; } pk0, pk1;
;     pk0.u.x = cvt_pk_bf16(p[0], p[1]); pk0.u.y = cvt_pk_bf16(p[2], p[3]); pk0.u.z = cvt_pk_bf16(p[4], p[5]); pk0.u.w = cvt_pk_bf16(p[6], p[7]);
;     pk1.u.x = cvt_pk_bf16(p[8], p[9]); pk1.u.y = cvt_pk_bf16(p[10], p[11]); pk1.u.z = cvt_pk_bf16(p[12], p[13]); pk1.u.w = cvt_pk_bf16(p[14], p[15]);
;     if (__builtin_amdgcn_ballot_w64(alpha != 1.0f) != 0ull) {
	v_mfma_f32_16x16x32_bf16 v[98:101], v[170:173], v[10:13], v[98:101]
	v_mfma_f32_16x16x32_bf16 v[102:105], v[178:181], v[10:13], v[102:105]
	v_mfma_f32_16x16x32_bf16 v[106:109], v[186:189], v[10:13], v[106:109]
	v_mfma_f32_16x16x32_bf16 v[110:113], v[194:197], v[10:13], v[110:113]
	v_mfma_f32_16x16x32_bf16 v[98:101], v[174:177], v[14:17], v[98:101]
	v_mfma_f32_16x16x32_bf16 v[102:105], v[182:185], v[14:17], v[102:105]
	v_mfma_f32_16x16x32_bf16 v[106:109], v[190:193], v[14:17], v[106:109]
	v_mfma_f32_16x16x32_bf16 v[110:113], v[198:201], v[14:17], v[110:113]
	ds_read_b128 v[170:173], v203 offset:384
	ds_read_b128 v[174:177], v203 offset:448
	ds_read_b128 v[178:181], v203 offset:8832
	ds_read_b128 v[182:185], v203 offset:8896
	ds_read_b128 v[186:189], v203 offset:17280
	ds_read_b128 v[190:193], v203 offset:17344
	ds_read_b128 v[194:197], v203 offset:25728
	ds_read_b128 v[198:201], v203 offset:25792
	s_waitcnt lgkmcnt(8)
	v_mfma_f32_16x16x32_bf16 v[98:101], v[130:133], v[18:21], v[98:101]
	v_mfma_f32_16x16x32_bf16 v[102:105], v[138:141], v[18:21], v[102:105]
	v_mfma_f32_16x16x32_bf16 v[106:109], v[146:149], v[18:21], v[106:109]
	v_mfma_f32_16x16x32_bf16 v[110:113], v[154:157], v[18:21], v[110:113]
	v_mfma_f32_16x16x32_bf16 v[98:101], v[134:137], v[22:25], v[98:101]
	v_mfma_f32_16x16x32_bf16 v[102:105], v[142:145], v[22:25], v[102:105]
	v_mfma_f32_16x16x32_bf16 v[106:109], v[150:153], v[22:25], v[106:109]
	v_mfma_f32_16x16x32_bf16 v[110:113], v[158:161], v[22:25], v[110:113]
	s_waitcnt lgkmcnt(0)
	v_mfma_f32_16x16x32_bf16 v[98:101], v[170:173], v[26:29], v[98:101]
	v_mfma_f32_16x16x32_bf16 v[102:105], v[178:181], v[26:29], v[102:105]
	v_mfma_f32_16x16x32_bf16 v[106:109], v[186:189], v[26:29], v[106:109]
	v_mfma_f32_16x16x32_bf16 v[110:113], v[194:197], v[26:29], v[110:113]
	v_mfma_f32_16x16x32_bf16 v[98:101], v[174:177], v[30:33], v[98:101]
	v_mfma_f32_16x16x32_bf16 v[102:105], v[182:185], v[30:33], v[102:105]
	v_mfma_f32_16x16x32_bf16 v[106:109], v[190:193], v[30:33], v[106:109]
	v_mfma_f32_16x16x32_bf16 v[110:113], v[198:201], v[30:33], v[110:113]
	ds_read_b64_tr_b16 v[130:131], v205 offset:33792
	ds_read_b64_tr_b16 v[132:133], v205 offset:42240
	ds_read_b64_tr_b16 v[134:135], v205 offset:50688
	ds_read_b64_tr_b16 v[136:137], v205 offset:59136
	ds_read_b64_tr_b16 v[138:139], v205 offset:33824
	ds_read_b64_tr_b16 v[140:141], v205 offset:42272
	ds_read_b64_tr_b16 v[142:143], v205 offset:50720
	ds_read_b64_tr_b16 v[144:145], v205 offset:59168
	ds_read_b64_tr_b16 v[146:147], v205 offset:33856
	ds_read_b64_tr_b16 v[148:149], v205 offset:42304
	ds_read_b64_tr_b16 v[150:151], v205 offset:50752
	ds_read_b64_tr_b16 v[152:153], v205 offset:59200
	ds_read_b64_tr_b16 v[154:155], v205 offset:33888
	ds_read_b64_tr_b16 v[156:157], v205 offset:42336
	ds_read_b64_tr_b16 v[158:159], v205 offset:50784
	ds_read_b64_tr_b16 v[160:161], v205 offset:59232
	ds_read_b64_tr_b16 v[170:171], v205 offset:33920
	ds_read_b64_tr_b16 v[172:173], v205 offset:42368
	ds_read_b64_tr_b16 v[174:175], v205 offset:50816
	ds_read_b64_tr_b16 v[176:177], v205 offset:59264
	ds_read_b64_tr_b16 v[178:179], v205 offset:33952
	ds_read_b64_tr_b16 v[180:181], v205 offset:42400
	ds_read_b64_tr_b16 v[182:183], v205 offset:50848
	ds_read_b64_tr_b16 v[184:185], v205 offset:59296
	ds_read_b64_tr_b16 v[186:187], v205 offset:33984
	ds_read_b64_tr_b16 v[188:189], v205 offset:42432
	ds_read_b64_tr_b16 v[190:191], v205 offset:50880
	ds_read_b64_tr_b16 v[192:193], v205 offset:59328
	ds_read_b64_tr_b16 v[194:195], v205 offset:34016
	ds_read_b64_tr_b16 v[196:197], v205 offset:42464
	ds_read_b64_tr_b16 v[198:199], v205 offset:50912
	ds_read_b64_tr_b16 v[200:201], v205 offset:59360
	v_max3_f32 v122, v98, v99, v100
	v_max3_f32 v123, v101, v102, v103
	v_max3_f32 v124, v104, v105, v106
	v_max3_f32 v125, v107, v108, v109
	v_max3_f32 v127, v110, v111, v112
	v_max3_f32 v122, v122, v123, v113
	v_max3_f32 v124, v124, v125, v127
	v_max_f32_e32 v122, v122, v124
	v_mov_b32_e32 v123, v122
	s_nop 1
	v_permlane16_swap_b32_e32 v122, v123
	v_max_f32_e32 v122, v122, v123
	v_mov_b32_e32 v123, v122
	s_nop 1
	v_permlane32_swap_b32_e32 v122, v123
	v_max_f32_e32 v122, v122, v123
	v_mul_f32_e32 v122, 0x3fb8aa3b, v122
	v_max_f32_e32 v124, v207, v122
	v_max_f32_e32 v126, 0xe0ad78ec, v207
	v_max_f32_e32 v125, 0xe0ad78ec, v124
	v_sub_f32_e32 v126, v126, v125
	v_mov_b32_e32 v207, v124
	v_exp_f32_e32 v126, v126
	v_sub_f32_e32 v127, 0, v125
	v_fmamk_f32 v98, v98, 0x3fb8aa3b, v127
	v_fmamk_f32 v99, v99, 0x3fb8aa3b, v127
	v_fmamk_f32 v100, v100, 0x3fb8aa3b, v127
	v_fmamk_f32 v101, v101, 0x3fb8aa3b, v127
	v_exp_f32_e32 v98, v98
	v_exp_f32_e32 v99, v99
	v_exp_f32_e32 v100, v100
	v_exp_f32_e32 v101, v101
	v_fmamk_f32 v102, v102, 0x3fb8aa3b, v127
	v_fmamk_f32 v103, v103, 0x3fb8aa3b, v127
	v_fmamk_f32 v104, v104, 0x3fb8aa3b, v127
	v_fmamk_f32 v105, v105, 0x3fb8aa3b, v127
	v_exp_f32_e32 v102, v102
	v_exp_f32_e32 v103, v103
	v_exp_f32_e32 v104, v104
	v_exp_f32_e32 v105, v105
	v_fmamk_f32 v106, v106, 0x3fb8aa3b, v127
	v_fmamk_f32 v107, v107, 0x3fb8aa3b, v127
	v_fmamk_f32 v108, v108, 0x3fb8aa3b, v127
	v_fmamk_f32 v109, v109, 0x3fb8aa3b, v127
	v_exp_f32_e32 v106, v106
	v_exp_f32_e32 v107, v107
	v_exp_f32_e32 v108, v108
	v_exp_f32_e32 v109, v109
	v_fmamk_f32 v110, v110, 0x3fb8aa3b, v127
	v_fmamk_f32 v111, v111, 0x3fb8aa3b, v127
	v_fmamk_f32 v112, v112, 0x3fb8aa3b, v127
	v_fmamk_f32 v113, v113, 0x3fb8aa3b, v127
	v_exp_f32_e32 v110, v110
	v_exp_f32_e32 v111, v111
	v_exp_f32_e32 v112, v112
	v_exp_f32_e32 v113, v113
	s_nop 0
	v_add_f32_e32 v122, v98, v99
	v_add_f32_e32 v123, v100, v101
	v_add_f32_e32 v124, v102, v103
	v_add_f32_e32 v125, v104, v105
	v_add_f32_e32 v122, v122, v106
	v_add_f32_e32 v123, v123, v107
	v_add_f32_e32 v124, v124, v108
	v_add_f32_e32 v125, v125, v109
	v_add_f32_e32 v122, v122, v110
	v_add_f32_e32 v123, v123, v111
	v_add_f32_e32 v124, v124, v112
	v_add_f32_e32 v125, v125, v113
	v_add_f32_e32 v122, v122, v123
	v_add_f32_e32 v124, v124, v125
	v_add_f32_e32 v122, v122, v124
	v_cvt_pk_bf16_f32 v114, v98, v99
	v_cvt_pk_bf16_f32 v115, v100, v101
	v_cvt_pk_bf16_f32 v116, v102, v103
	v_cvt_pk_bf16_f32 v117, v104, v105
	v_cvt_pk_bf16_f32 v118, v106, v107
	v_cvt_pk_bf16_f32 v119, v108, v109
	v_cvt_pk_bf16_f32 v120, v110, v111
	v_cvt_pk_bf16_f32 v121, v112, v113
	v_mov_b32_e32 v123, v122
	s_nop 1
	v_permlane16_swap_b32_e32 v122, v123
	v_add_f32_e32 v122, v122, v123
	v_mov_b32_e32 v123, v122
	s_nop 1
	v_permlane32_swap_b32_e32 v122, v123
	v_add_f32_e32 v122, v122, v123
	v_fma_f32 v208, v208, v126, v122
	v_cmp_neq_f32_e64 s[0:1], 1.0, v126
	s_cmp_eq_u64 s[0:1], 0
	s_cbranch_scc1 .Lmem_nosc_2
; #define LAS __attribute__((address_space(3)))
; __device__ __forceinline__ f32x4 mfma16(bf16x8 a, bf16x8 b, f32x4 c) { return __builtin_amdgcn_mfma_f32_16x16x32_bf16(a, b, c, 0, 0, 0); }
; template <int D, class SF>
; __device__ __forceinline__ void attn_step(const bf16x8 (&qf)[D / 32], const LAS bf16_t* Ks, const LAS bf16_t* Vt, f32x4 (&o)[D / 16], float& m, float& lsum, float& alpha_out, bf16x8& pf0_out, bf16x8& pf1_out, const int lane, SF sf) {
;     ...
;     if (__builtin_amdgcn_ballot_w64(alpha != 1.0f) != 0ull) {
; #pragma unroll
;         for (int dt = 0; dt < D / 16; ++dt) o[dt] *= alpha;
;     }
; #pragma unroll
;     for (int dt = 0; dt < D / 16; ++dt) {
;         const LAS bf16_t* vp = Vt + (16 * dt + c) * 72 + 4 * i;
;         union { u32x4 u; bf16x8 b; } vf0, vf1; const u32x2 a0 = *(const LAS u32x2*)vp, a1 = *(const LAS u32x2*)(vp + 16), b0 = *(const LAS u32x2*)(vp + 32), b1 = *(const LAS u32x2*)(vp + 48);
;         vf0.u.x = a0.x; vf0.u.y = a0.y; vf0.u.z = a1.x; vf0.u.w = a1.y; vf1.u.x = b0.x; vf1.u.y = b0.y; vf1.u.z = b1.x; vf1.u.w = b1.y;
;         o[dt] = mfma16(vf0.b, pk0.b, o[dt]); o[dt] = mfma16(vf1.b, pk1.b, o[dt]);
;     }
; __device__ __forceinline__ void memattn_unit(LAS unsigned char* lds, const Ctx& P, int unit) {
;     ...
;     for (int kt = 0; kt < 4; ++kt) {
;         __syncthreads();
;         { u32x4 kr[4], vr[4];
; #pragma unroll
;             for (int it = 0; it < 4; ++it) { const int idx = tid + it * 512, key = idx & 63, seg = idx >> 6; const size_t off = (size_t)(kt * 64 + key) * DM + seg * 8; kr[it] = *(const u32x4*)(kb + off); vr[it] = *(const u32x4*)(vb + off); }
	v_pk_mul_f32 v[34:35], v[34:35], v[126:127] op_sel_hi:[1,0]
	v_pk_mul_f32 v[36:37], v[36:37], v[126:127] op_sel_hi:[1,0]
	v_pk_mul_f32 v[38:39], v[38:39], v[126:127] op_sel_hi:[1,0]
	v_pk_mul_f32 v[40:41], v[40:41], v[126:127] op_sel_hi:[1,0]
	v_pk_mul_f32 v[42:43], v[42:43], v[126:127] op_sel_hi:[1,0]
	v_pk_mul_f32 v[44:45], v[44:45], v[126:127] op_sel_hi:[1,0]
	v_pk_mul_f32 v[46:47], v[46:47], v[126:127] op_sel_hi:[1,0]
	v_pk_mul_f32 v[48:49], v[48:49], v[126:127] op_sel_hi:[1,0]
	v_pk_mul_f32 v[50:51], v[50:51], v[126:127] op_sel_hi:[1,0]
	v_pk_mul_f32 v[52:53], v[52:53], v[126:127] op_sel_hi:[1,0]
	v_pk_mul_f32 v[54:55], v[54:55], v[126:127] op_sel_hi:[1,0]
	v_pk_mul_f32 v[56:57], v[56:57], v[126:127] op_sel_hi:[1,0]
	v_pk_mul_f32 v[58:59], v[58:59], v[126:127] op_sel_hi:[1,0]
	v_pk_mul_f32 v[60:61], v[60:61], v[126:127] op_sel_hi:[1,0]
	v_pk_mul_f32 v[62:63], v[62:63], v[126:127] op_sel_hi:[1,0]
	v_pk_mul_f32 v[64:65], v[64:65], v[126:127] op_sel_hi:[1,0]
	v_pk_mul_f32 v[66:67], v[66:67], v[126:127] op_sel_hi:[1,0]
	v_pk_mul_f32 v[68:69], v[68:69], v[126:127] op_sel_hi:[1,0]
	v_pk_mul_f32 v[70:71], v[70:71], v[126:127] op_sel_hi:[1,0]
	v_pk_mul_f32 v[72:73], v[72:73], v[126:127] op_sel_hi:[1,0]
	v_pk_mul_f32 v[74:75], v[74:75], v[126:127] op_sel_hi:[1,0]
	v_pk_mul_f32 v[76:77], v[76:77], v[126:127] op_sel_hi:[1,0]
	v_pk_mul_f32 v[78:79], v[78:79], v[126:127] op_sel_hi:[1,0]
	v_pk_mul_f32 v[80:81], v[80:81], v[126:127] op_sel_hi:[1,0]
	v_pk_mul_f32 v[82:83], v[82:83], v[126:127] op_sel_hi:[1,0]
	v_pk_mul_f32 v[84:85], v[84:85], v[126:127] op_sel_hi:[1,0]
	v_pk_mul_f32 v[86:87], v[86:87], v[126:127] op_sel_hi:[1,0]
	v_pk_mul_f32 v[88:89], v[88:89], v[126:127] op_sel_hi:[1,0]
	v_pk_mul_f32 v[90:91], v[90:91], v[126:127] op_sel_hi:[1,0]
	v_pk_mul_f32 v[92:93], v[92:93], v[126:127] op_sel_hi:[1,0]
	v_pk_mul_f32 v[94:95], v[94:95], v[126:127] op_sel_hi:[1,0]
	v_pk_mul_f32 v[96:97], v[96:97], v[126:127] op_sel_hi:[1,0]
.Lmem_nosc_2:
	s_waitcnt lgkmcnt(0)
	s_nop 1
	v_mfma_f32_16x16x32_bf16 v[34:37], v[130:133], v[114:117], v[34:37]
	v_mfma_f32_16x16x32_bf16 v[38:41], v[138:141], v[114:117], v[38:41]
	v_mfma_f32_16x16x32_bf16 v[42:45], v[146:149], v[114:117], v[42:45]
	v_mfma_f32_16x16x32_bf16 v[46:49], v[154:157], v[114:117], v[46:49]
	v_mfma_f32_16x16x32_bf16 v[34:37], v[134:137], v[118:121], v[34:37]
	v_mfma_f32_16x16x32_bf16 v[38:41], v[142:145], v[118:121], v[38:41]
	v_mfma_f32_16x16x32_bf16 v[42:45], v[150:153], v[118:121], v[42:45]
	v_mfma_f32_16x16x32_bf16 v[46:49], v[158:161], v[118:121], v[46:49]
	ds_read_b64_tr_b16 v[130:131], v205 offset:34048
	ds_read_b64_tr_b16 v[132:133], v205 offset:42496
	ds_read_b64_tr_b16 v[134:135], v205 offset:50944
	ds_read_b64_tr_b16 v[136:137], v205 offset:59392
	ds_read_b64_tr_b16 v[138:139], v205 offset:34080
	ds_read_b64_tr_b16 v[140:141], v205 offset:42528
	ds_read_b64_tr_b16 v[142:143], v205 offset:50976
	ds_read_b64_tr_b16 v[144:145], v205 offset:59424
	ds_read_b64_tr_b16 v[146:147], v205 offset:34112
	ds_read_b64_tr_b16 v[148:149], v205 offset:42560
	ds_read_b64_tr_b16 v[150:151], v205 offset:51008
	ds_read_b64_tr_b16 v[152:153], v205 offset:59456
	ds_read_b64_tr_b16 v[154:155], v205 offset:34144
	ds_read_b64_tr_b16 v[156:157], v205 offset:42592
	ds_read_b64_tr_b16 v[158:159], v205 offset:51040
	ds_read_b64_tr_b16 v[160:161], v205 offset:59488
	s_waitcnt lgkmcnt(15)
	v_mfma_f32_16x16x32_bf16 v[50:53], v[170:173], v[114:117], v[50:53]
	v_mfma_f32_16x16x32_bf16 v[54:57], v[178:181], v[114:117], v[54:57]
	v_mfma_f32_16x16x32_bf16 v[58:61], v[186:189], v[114:117], v[58:61]
	v_mfma_f32_16x16x32_bf16 v[62:65], v[194:197], v[114:117], v[62:65]
	v_mfma_f32_16x16x32_bf16 v[50:53], v[174:177], v[118:121], v[50:53]
	v_mfma_f32_16x16x32_bf16 v[54:57], v[182:185], v[118:121], v[54:57]
	v_mfma_f32_16x16x32_bf16 v[58:61], v[190:193], v[118:121], v[58:61]
	v_mfma_f32_16x16x32_bf16 v[62:65], v[198:201], v[118:121], v[62:65]
	ds_read_b64_tr_b16 v[170:171], v205 offset:34176
	ds_read_b64_tr_b16 v[172:173], v205 offset:42624
	ds_read_b64_tr_b16 v[174:175], v205 offset:51072
	ds_read_b64_tr_b16 v[176:177], v205 offset:59520
	ds_read_b64_tr_b16 v[178:179], v205 offset:34208
	ds_read_b64_tr_b16 v[180:181], v205 offset:42656
	ds_read_b64_tr_b16 v[182:183], v205 offset:51104
	ds_read_b64_tr_b16 v[184:185], v205 offset:59552
	ds_read_b64_tr_b16 v[186:187], v205 offset:34240
	ds_read_b64_tr_b16 v[188:189], v205 offset:42688
	ds_read_b64_tr_b16 v[190:191], v205 offset:51136
	ds_read_b64_tr_b16 v[192:193], v205 offset:59584
	ds_read_b64_tr_b16 v[194:195], v205 offset:34272
	ds_read_b64_tr_b16 v[196:197], v205 offset:42720
	ds_read_b64_tr_b16 v[198:199], v205 offset:51168
	ds_read_b64_tr_b16 v[200:201], v205 offset:59616
	s_waitcnt lgkmcnt(15)
	v_mfma_f32_16x16x32_bf16 v[66:69], v[130:133], v[114:117], v[66:69]
	v_mfma_f32_16x16x32_bf16 v[70:73], v[138:141], v[114:117], v[70:73]
	v_mfma_f32_16x16x32_bf16 v[74:77], v[146:149], v[114:117], v[74:77]
	v_mfma_f32_16x16x32_bf16 v[78:81], v[154:157], v[114:117], v[78:81]
	v_mfma_f32_16x16x32_bf16 v[66:69], v[134:137], v[118:121], v[66:69]
	v_mfma_f32_16x16x32_bf16 v[70:73], v[142:145], v[118:121], v[70:73]
	v_mfma_f32_16x16x32_bf16 v[74:77], v[150:153], v[118:121], v[74:77]
	v_mfma_f32_16x16x32_bf16 v[78:81], v[158:161], v[118:121], v[78:81]
	s_waitcnt lgkmcnt(0)
	v_mfma_f32_16x16x32_bf16 v[82:85], v[170:173], v[114:117], v[82:85]
	v_mfma_f32_16x16x32_bf16 v[86:89], v[178:181], v[114:117], v[86:89]
	v_mfma_f32_16x16x32_bf16 v[90:93], v[186:189], v[114:117], v[90:93]
	v_mfma_f32_16x16x32_bf16 v[94:97], v[194:197], v[114:117], v[94:97]
	v_mfma_f32_16x16x32_bf16 v[82:85], v[174:177], v[118:121], v[82:85]
	v_mfma_f32_16x16x32_bf16 v[86:89], v[182:185], v[118:121], v[86:89]
	v_mfma_f32_16x16x32_bf16 v[90:93], v[190:193], v[118:121], v[90:93]
	v_mfma_f32_16x16x32_bf16 v[94:97], v[198:201], v[118:121], v[94:97]
	v_add_u32_e32 v122, 0x80000, v209
	global_load_dwordx4 v[130:133], v122, s[8:9]
	global_load_dwordx4 v[146:149], v122, s[8:9] offset:2048
	v_add_u32_e32 v122, 0x90000, v209
	global_load_dwordx4 v[134:137], v122, s[8:9]
	global_load_dwordx4 v[150:153], v122, s[8:9] offset:2048
	v_add_u32_e32 v122, 0xa0000, v209
	global_load_dwordx4 v[138:141], v122, s[8:9]
	global_load_dwordx4 v[154:157], v122, s[8:9] offset:2048
	v_add_u32_e32 v122, 0xb0000, v209
	global_load_dwordx4 v[142:145], v122, s[8:9]
	global_load_dwordx4 v[158:161], v122, s[8:9] offset:2048
	v_add_u32_e32 v122, 0xc0000, v209
	global_load_dwordx4 v[170:173], v122, s[8:9]
	global_load_dwordx4 v[186:189], v122, s[8:9] offset:2048
	v_add_u32_e32 v122, 0xd0000, v209
	global_load_dwordx4 v[174:177], v122, s[8:9]
	global_load_dwordx4 v[190:193], v122, s[8:9] offset:2048
	v_add_u32_e32 v122, 0xe0000, v209
	global_load_dwordx4 v[178:181], v122, s[8:9]
	global_load_dwordx4 v[194:197], v122, s[8:9] offset:2048
	v_add_u32_e32 v122, 0xf0000, v209
	global_load_dwordx4 v[182:185], v122, s[8:9]
	global_load_dwordx4 v[198:201], v122, s[8:9] offset:2048
	s_waitcnt lgkmcnt(0)
	s_barrier
; #define LAS __attribute__((address_space(3)))
; __device__ __forceinline__ f32x4 mfma16(bf16x8 a, bf16x8 b, f32x4 c) { return __builtin_amdgcn_mfma_f32_16x16x32_bf16(a, b, c, 0, 0, 0); }
; template <int D, class SF>
; __device__ __forceinline__ void attn_step(const bf16x8 (&qf)[D / 32], const LAS bf16_t* Ks, const LAS bf16_t* Vt, f32x4 (&o)[D / 16], float& m, float& lsum, float& alpha_out, bf16x8& pf0_out, bf16x8& pf1_out, const int lane, SF sf) {
;     ...
;     for (int ks = 0; ks < D / 32; ++ks) {
; #pragma unroll
;         for (int t = 0; t < 4; ++t) { const bf16x8 kf = *(const LAS bf16x8*)(Ks + (16 * t + c) * KSTR + ks * 32 + 8 * i); s[t] = mfma16(kf, qf[ks], s[t]); }
;     }
; __device__ __forceinline__ void memattn_unit(LAS unsigned char* lds, const Ctx& P, int unit) {
;     ...
;         { u32x4 kr[4], vr[4];
; #pragma unroll
;             for (int it = 0; it < 4; ++it) { const int idx = tid + it * 512, key = idx & 63, seg = idx >> 6; const size_t off = (size_t)(kt * 64 + key) * DM + seg * 8; kr[it] = *(const u32x4*)(kb + off); vr[it] = *(const u32x4*)(vb + off); }
; #pragma unroll
;             for (int it = 0; it < 4; ++it) { const int idx = tid + it * 512, key = idx & 63, seg = idx >> 6; *(LAS u32x4*)(Ks + key * 264 + seg * 8) = kr[it];
;                 LAS bf16_t* d = Vt + (seg * 8) * 72 + key; const u32x4 v = vr[it];
;                 d[0 * 72] = (bf16_t)(v.x & 0xffffu); d[1 * 72] = (bf16_t)(v.x >> 16); d[2 * 72] = (bf16_t)(v.y & 0xffffu); d[3 * 72] = (bf16_t)(v.y >> 16);
;                 d[4 * 72] = (bf16_t)(v.z & 0xffffu); d[5 * 72] = (bf16_t)(v.z >> 16); d[6 * 72] = (bf16_t)(v.w & 0xffffu); d[7 * 72] = (bf16_t)(v.w >> 16); } }
;         __syncthreads();
	s_waitcnt vmcnt(0)
	ds_write_b128 v206, v[130:133] offset:0
	ds_write_b128 v206, v[146:149] offset:33792
	ds_write_b128 v206, v[134:137] offset:8448
	ds_write_b128 v206, v[150:153] offset:42240
	ds_write_b128 v206, v[138:141] offset:16896
	ds_write_b128 v206, v[154:157] offset:50688
	ds_write_b128 v206, v[142:145] offset:25344
	ds_write_b128 v206, v[158:161] offset:59136
	ds_write_b128 v216, v[170:173] offset:0
	ds_write_b128 v216, v[186:189] offset:33792
	ds_write_b128 v216, v[174:177] offset:8448
	ds_write_b128 v216, v[190:193] offset:42240
	ds_write_b128 v216, v[178:181] offset:16896
	ds_write_b128 v216, v[194:197] offset:50688
	ds_write_b128 v216, v[182:185] offset:25344
	ds_write_b128 v216, v[198:201] offset:59136
	s_waitcnt lgkmcnt(0)
	s_barrier
	ds_read_b128 v[130:133], v202 offset:0
	ds_read_b128 v[134:137], v202 offset:64
	ds_read_b128 v[138:141], v202 offset:8448
	ds_read_b128 v[142:145], v202 offset:8512
	ds_read_b128 v[146:149], v202 offset:16896
	ds_read_b128 v[150:153], v202 offset:16960
	ds_read_b128 v[154:157], v202 offset:25344
	ds_read_b128 v[158:161], v202 offset:25408
	ds_read_b128 v[170:173], v202 offset:128
	ds_read_b128 v[174:177], v202 offset:192
	ds_read_b128 v[178:181], v202 offset:8576
	ds_read_b128 v[182:185], v202 offset:8640
	ds_read_b128 v[186:189], v202 offset:17024
	ds_read_b128 v[190:193], v202 offset:17088
	ds_read_b128 v[194:197], v202 offset:25472
	ds_read_b128 v[198:201], v202 offset:25536
	s_waitcnt lgkmcnt(8)
	v_mfma_f32_16x16x32_bf16 v[98:101], v[130:133], v[2:5], 0
	v_mfma_f32_16x16x32_bf16 v[102:105], v[138:141], v[2:5], 0
	v_mfma_f32_16x16x32_bf16 v[106:109], v[146:149], v[2:5], 0
	v_mfma_f32_16x16x32_bf16 v[110:113], v[154:157], v[2:5], 0
	v_mfma_f32_16x16x32_bf16 v[98:101], v[134:137], v[6:9], v[98:101]
	v_mfma_f32_16x16x32_bf16 v[102:105], v[142:145], v[6:9], v[102:105]
	v_mfma_f32_16x16x32_bf16 v[106:109], v[150:153], v[6:9], v[106:109]
	v_mfma_f32_16x16x32_bf16 v[110:113], v[158:161], v[6:9], v[110:113]
	ds_read_b128 v[130:133], v202 offset:256
	ds_read_b128 v[134:137], v202 offset:320
	ds_read_b128 v[138:141], v202 offset:8704
	ds_read_b128 v[142:145], v202 offset:8768
	ds_read_b128 v[146:149], v202 offset:17152
	ds_read_b128 v[150:153], v202 offset:17216
	ds_read_b128 v[154:157], v202 offset:25600
	ds_read_b128 v[158:161], v202 offset:25664
	s_waitcnt lgkmcnt(8)
	v_mfma_f32_16x16x32_bf16 v[98:101], v[170:173], v[10:13], v[98:101]
	v_mfma_f32_16x16x32_bf16 v[102:105], v[178:181], v[10:13], v[102:105]
	v_mfma_f32_16x16x32_bf16 v[106:109], v[186:189], v[10:13], v[106:109]
	v_mfma_f32_16x16x32_bf16 v[110:113], v[194:197], v[10:13], v[110:113]
	v_mfma_f32_16x16x32_bf16 v[98:101], v[174:177], v[14:17], v[98:101]
	v_mfma_f32_16x16x32_bf16 v[102:105], v[182:185], v[14:17], v[102:105]
	v_mfma_f32_16x16x32_bf16 v[106:109], v[190:193], v[14:17], v[106:109]
	v_mfma_f32_16x16x32_bf16 v[110:113], v[198:201], v[14:17], v[110:113]
	ds_read_b128 v[170:173], v202 offset:384
	ds_read_b128 v[174:177], v202 offset:448
	ds_read_b128 v[178:181], v202 offset:8832
	ds_read_b128 v[182:185], v202 offset:8896
	ds_read_b128 v[186:189], v202 offset:17280
	ds_read_b128 v[190:193], v202 offset:17344
	ds_read_b128 v[194:197], v202 offset:25728
	ds_read_b128 v[198:201], v202 offset:25792
	s_waitcnt lgkmcnt(8)
	v_mfma_f32_16x16x32_bf16 v[98:101], v[130:133], v[18:21], v[98:101]
	v_mfma_f32_16x16x32_bf16 v[102:105], v[138:141], v[18:21], v[102:105]
	v_mfma_f32_16x16x32_bf16 v[106:109], v[146:149], v[18:21], v[106:109]
	v_mfma_f32_16x16x32_bf16 v[110:113], v[154:157], v[18:21], v[110:113]
	v_mfma_f32_16x16x32_bf16 v[98:101], v[134:137], v[22:25], v[98:101]
	v_mfma_f32_16x16x32_bf16 v[102:105], v[142:145], v[22:25], v[102:105]
	v_mfma_f32_16x16x32_bf16 v[106:109], v[150:153], v[22:25], v[106:109]
	v_mfma_f32_16x16x32_bf16 v[110:113], v[158:161], v[22:25], v[110:113]
	s_waitcnt lgkmcnt(0)
; #define LAS __attribute__((address_space(3)))
; __device__ __forceinline__ unsigned cvt_pk_bf16(float lo, float hi) { unsigned r; asm("v_cvt_pk_bf16_f32 %0, %1, %2" : "=v"(r) : "v"(lo), "v"(hi)); return r; }
; __device__ __forceinline__ f32x4 mfma16(bf16x8 a, bf16x8 b, f32x4 c) { return __builtin_amdgcn_mfma_f32_16x16x32_bf16(a, b, c, 0, 0, 0); }
; template <int D, class SF>
; __device__ __forceinline__ void attn_step(const bf16x8 (&qf)[D / 32], const LAS bf16_t* Ks, const LAS bf16_t* Vt, f32x4 (&o)[D / 16], float& m, float& lsum, float& alpha_out, bf16x8& pf0_out, bf16x8& pf1_out, const int lane, SF sf) {
;     ...
;     for (int ks = 0; ks < D / 32; ++ks) {
; #pragma unroll
;         for (int t = 0; t < 4; ++t) { const bf16x8 kf = *(const LAS bf16x8*)(Ks + (16 * t + c) * KSTR + ks * 32 + 8 * i); s[t] = mfma16(kf, qf[ks], s[t]); }
;     }
;     float v[16];
; #pragma unroll
;     for (int t = 0; t < 4; ++t)
; #pragma unroll
;         for (int r = 0; r < 4; ++r) v[4 * t + r] = sf(16 * t + 4 * i + r, s[t][r]);
;     float mx = fmaxf(fmaxf(fmaxf(v[0], v[1]), fmaxf(v[2], v[3])), fmaxf(fmaxf(v[4], v[5]), fmaxf(v[6], v[7])));
;     mx = fmaxf(mx, fmaxf(fmaxf(fmaxf(v[8], v[9]), fmaxf(v[10], v[11])), fmaxf(fmaxf(v[12], v[13]), fmaxf(v[14], v[15]))));
;     mx = rows_max(mx);
;     const float mnew = fmaxf(m, mx);
;     const float mc = fmaxf(mnew, -1e20f);
;     const float alpha = __builtin_amdgcn_exp2f(fmaxf(m, -1e20f) - mc);
;     float p[16], rs = 0.f;
; #pragma unroll
;     for (int r = 0; r < 16; ++r) { p[r] = __builtin_amdgcn_exp2f(v[r] - mc); rs += p[r]; }
;     rs = rows_sum(rs);
;     lsum = lsum * alpha + rs; m = mnew;
;     union { u32x4 u; bf16x8 b; } pk0, pk1;
;     pk0.u.x = cvt_pk_bf16(p[0], p[1]); pk0.u.y = cvt_pk_bf16(p[2], p[3]); pk0.u.z = cvt_pk_bf16(p[4], p[5]); pk0.u.w = cvt_pk_bf16(p[6], p[7]);
;     pk1.u.x = cvt_pk_bf16(p[8], p[9]); pk1.u.y = cvt_pk_bf16(p[10], p[11]); pk1.u.z = cvt_pk_bf16(p[12], p[13]); pk1.u.w = cvt_pk_bf16(p[14], p[15]);
;     if (__builtin_amdgcn_ballot_w64(alpha != 1.0f) != 0ull) {
; #pragma unroll
;         for (int dt = 0; dt < D / 16; ++dt) o[dt] *= alpha;
;     }
	v_mfma_f32_16x16x32_bf16 v[98:101], v[170:173], v[26:29], v[98:101]
	v_mfma_f32_16x16x32_bf16 v[102:105], v[178:181], v[26:29], v[102:105]
	v_mfma_f32_16x16x32_bf16 v[106:109], v[186:189], v[26:29], v[106:109]
	v_mfma_f32_16x16x32_bf16 v[110:113], v[194:197], v[26:29], v[110:113]
	v_mfma_f32_16x16x32_bf16 v[98:101], v[174:177], v[30:33], v[98:101]
	v_mfma_f32_16x16x32_bf16 v[102:105], v[182:185], v[30:33], v[102:105]
	v_mfma_f32_16x16x32_bf16 v[106:109], v[190:193], v[30:33], v[106:109]
	v_mfma_f32_16x16x32_bf16 v[110:113], v[198:201], v[30:33], v[110:113]
	ds_read_b64_tr_b16 v[130:131], v204 offset:33792
	ds_read_b64_tr_b16 v[132:133], v204 offset:42240
	ds_read_b64_tr_b16 v[134:135], v204 offset:50688
	ds_read_b64_tr_b16 v[136:137], v204 offset:59136
	ds_read_b64_tr_b16 v[138:139], v204 offset:33824
	ds_read_b64_tr_b16 v[140:141], v204 offset:42272
	ds_read_b64_tr_b16 v[142:143], v204 offset:50720
	ds_read_b64_tr_b16 v[144:145], v204 offset:59168
	ds_read_b64_tr_b16 v[146:147], v204 offset:33856
	ds_read_b64_tr_b16 v[148:149], v204 offset:42304
	ds_read_b64_tr_b16 v[150:151], v204 offset:50752
	ds_read_b64_tr_b16 v[152:153], v204 offset:59200
	ds_read_b64_tr_b16 v[154:155], v204 offset:33888
	ds_read_b64_tr_b16 v[156:157], v204 offset:42336
	ds_read_b64_tr_b16 v[158:159], v204 offset:50784
	ds_read_b64_tr_b16 v[160:161], v204 offset:59232
	ds_read_b64_tr_b16 v[170:171], v204 offset:33920
	ds_read_b64_tr_b16 v[172:173], v204 offset:42368
	ds_read_b64_tr_b16 v[174:175], v204 offset:50816
	ds_read_b64_tr_b16 v[176:177], v204 offset:59264
	ds_read_b64_tr_b16 v[178:179], v204 offset:33952
	ds_read_b64_tr_b16 v[180:181], v204 offset:42400
	ds_read_b64_tr_b16 v[182:183], v204 offset:50848
	ds_read_b64_tr_b16 v[184:185], v204 offset:59296
	ds_read_b64_tr_b16 v[186:187], v204 offset:33984
	ds_read_b64_tr_b16 v[188:189], v204 offset:42432
	ds_read_b64_tr_b16 v[190:191], v204 offset:50880
	ds_read_b64_tr_b16 v[192:193], v204 offset:59328
	ds_read_b64_tr_b16 v[194:195], v204 offset:34016
	ds_read_b64_tr_b16 v[196:197], v204 offset:42464
	ds_read_b64_tr_b16 v[198:199], v204 offset:50912
	ds_read_b64_tr_b16 v[200:201], v204 offset:59360
	v_max3_f32 v122, v98, v99, v100
	v_max3_f32 v123, v101, v102, v103
	v_max3_f32 v124, v104, v105, v106
	v_max3_f32 v125, v107, v108, v109
	v_max3_f32 v127, v110, v111, v112
	v_max3_f32 v122, v122, v123, v113
	v_max3_f32 v124, v124, v125, v127
	v_max_f32_e32 v122, v122, v124
	v_mov_b32_e32 v123, v122
	s_nop 1
	v_permlane16_swap_b32_e32 v122, v123
	v_max_f32_e32 v122, v122, v123
	v_mov_b32_e32 v123, v122
	s_nop 1
	v_permlane32_swap_b32_e32 v122, v123
	v_max_f32_e32 v122, v122, v123
	v_mul_f32_e32 v122, 0x3fb8aa3b, v122
	v_max_f32_e32 v124, v207, v122
	v_max_f32_e32 v126, 0xe0ad78ec, v207
	v_max_f32_e32 v125, 0xe0ad78ec, v124
	v_sub_f32_e32 v126, v126, v125
	v_mov_b32_e32 v207, v124
	v_exp_f32_e32 v126, v126
	v_sub_f32_e32 v127, 0, v125
	v_fmamk_f32 v98, v98, 0x3fb8aa3b, v127
	v_fmamk_f32 v99, v99, 0x3fb8aa3b, v127
	v_fmamk_f32 v100, v100, 0x3fb8aa3b, v127
	v_fmamk_f32 v101, v101, 0x3fb8aa3b, v127
	v_exp_f32_e32 v98, v98
	v_exp_f32_e32 v99, v99
	v_exp_f32_e32 v100, v100
	v_exp_f32_e32 v101, v101
	v_fmamk_f32 v102, v102, 0x3fb8aa3b, v127
	v_fmamk_f32 v103, v103, 0x3fb8aa3b, v127
	v_fmamk_f32 v104, v104, 0x3fb8aa3b, v127
	v_fmamk_f32 v105, v105, 0x3fb8aa3b, v127
	v_exp_f32_e32 v102, v102
	v_exp_f32_e32 v103, v103
	v_exp_f32_e32 v104, v104
	v_exp_f32_e32 v105, v105
	v_fmamk_f32 v106, v106, 0x3fb8aa3b, v127
	v_fmamk_f32 v107, v107, 0x3fb8aa3b, v127
	v_fmamk_f32 v108, v108, 0x3fb8aa3b, v127
	v_fmamk_f32 v109, v109, 0x3fb8aa3b, v127
	v_exp_f32_e32 v106, v106
	v_exp_f32_e32 v107, v107
	v_exp_f32_e32 v108, v108
	v_exp_f32_e32 v109, v109
	v_fmamk_f32 v110, v110, 0x3fb8aa3b, v127
	v_fmamk_f32 v111, v111, 0x3fb8aa3b, v127
	v_fmamk_f32 v112, v112, 0x3fb8aa3b, v127
	v_fmamk_f32 v113, v113, 0x3fb8aa3b, v127
	v_exp_f32_e32 v110, v110
	v_exp_f32_e32 v111, v111
	v_exp_f32_e32 v112, v112
	v_exp_f32_e32 v113, v113
	s_nop 0
	v_add_f32_e32 v122, v98, v99
	v_add_f32_e32 v123, v100, v101
	v_add_f32_e32 v124, v102, v103
	v_add_f32_e32 v125, v104, v105
	v_add_f32_e32 v122, v122, v106
	v_add_f32_e32 v123, v123, v107
	v_add_f32_e32 v124, v124, v108
	v_add_f32_e32 v125, v125, v109
	v_add_f32_e32 v122, v122, v110
	v_add_f32_e32 v123, v123, v111
	v_add_f32_e32 v124, v124, v112
	v_add_f32_e32 v125, v125, v113
	v_add_f32_e32 v122, v122, v123
	v_add_f32_e32 v124, v124, v125
	v_add_f32_e32 v122, v122, v124
	v_cvt_pk_bf16_f32 v114, v98, v99
	v_cvt_pk_bf16_f32 v115, v100, v101
	v_cvt_pk_bf16_f32 v116, v102, v103
	v_cvt_pk_bf16_f32 v117, v104, v105
	v_cvt_pk_bf16_f32 v118, v106, v107
	v_cvt_pk_bf16_f32 v119, v108, v109
	v_cvt_pk_bf16_f32 v120, v110, v111
	v_cvt_pk_bf16_f32 v121, v112, v113
	v_mov_b32_e32 v123, v122
	s_nop 1
	v_permlane16_swap_b32_e32 v122, v123
	v_add_f32_e32 v122, v122, v123
	v_mov_b32_e32 v123, v122
	s_nop 1
	v_permlane32_swap_b32_e32 v122, v123
	v_add_f32_e32 v122, v122, v123
	v_fma_f32 v208, v208, v126, v122
	v_cmp_neq_f32_e64 s[0:1], 1.0, v126
	s_cmp_eq_u64 s[0:1], 0
	s_cbranch_scc1 .Lmem_nosc_3
	v_pk_mul_f32 v[34:35], v[34:35], v[126:127] op_sel_hi:[1,0]
	v_pk_mul_f32 v[36:37], v[36:37], v[126:127] op_sel_hi:[1,0]
	v_pk_mul_f32 v[38:39], v[38:39], v[126:127] op_sel_hi:[1,0]
	v_pk_mul_f32 v[40:41], v[40:41], v[126:127] op_sel_hi:[1,0]
	v_pk_mul_f32 v[42:43], v[42:43], v[126:127] op_sel_hi:[1,0]
	v_pk_mul_f32 v[44:45], v[44:45], v[126:127] op_sel_hi:[1,0]
	v_pk_mul_f32 v[46:47], v[46:47], v[126:127] op_sel_hi:[1,0]
	v_pk_mul_f32 v[48:49], v[48:49], v[126:127] op_sel_hi:[1,0]
	v_pk_mul_f32 v[50:51], v[50:51], v[126:127] op_sel_hi:[1,0]
	v_pk_mul_f32 v[52:53], v[52:53], v[126:127] op_sel_hi:[1,0]
	v_pk_mul_f32 v[54:55], v[54:55], v[126:127] op_sel_hi:[1,0]
	v_pk_mul_f32 v[56:57], v[56:57], v[126:127] op_sel_hi:[1,0]
	v_pk_mul_f32 v[58:59], v[58:59], v[126:127] op_sel_hi:[1,0]
	v_pk_mul_f32 v[60:61], v[60:61], v[126:127] op_sel_hi:[1,0]
	v_pk_mul_f32 v[62:63], v[62:63], v[126:127] op_sel_hi:[1,0]
	v_pk_mul_f32 v[64:65], v[64:65], v[126:127] op_sel_hi:[1,0]
	v_pk_mul_f32 v[66:67], v[66:67], v[126:127] op_sel_hi:[1,0]
	v_pk_mul_f32 v[68:69], v[68:69], v[126:127] op_sel_hi:[1,0]
	v_pk_mul_f32 v[70:71], v[70:71], v[126:127] op_sel_hi:[1,0]
	v_pk_mul_f32 v[72:73], v[72:73], v[126:127] op_sel_hi:[1,0]
	v_pk_mul_f32 v[74:75], v[74:75], v[126:127] op_sel_hi:[1,0]
	v_pk_mul_f32 v[76:77], v[76:77], v[126:127] op_sel_hi:[1,0]
	v_pk_mul_f32 v[78:79], v[78:79], v[126:127] op_sel_hi:[1,0]
	v_pk_mul_f32 v[80:81], v[80:81], v[126:127] op_sel_hi:[1,0]
	v_pk_mul_f32 v[82:83], v[82:83], v[126:127] op_sel_hi:[1,0]
	v_pk_mul_f32 v[84:85], v[84:85], v[126:127] op_sel_hi:[1,0]
	v_pk_mul_f32 v[86:87], v[86:87], v[126:127] op_sel_hi:[1,0]
	v_pk_mul_f32 v[88:89], v[88:89], v[126:127] op_sel_hi:[1,0]
	v_pk_mul_f32 v[90:91], v[90:91], v[126:127] op_sel_hi:[1,0]
	v_pk_mul_f32 v[92:93], v[92:93], v[126:127] op_sel_hi:[1,0]
	v_pk_mul_f32 v[94:95], v[94:95], v[126:127] op_sel_hi:[1,0]
	v_pk_mul_f32 v[96:97], v[96:97], v[126:127] op_sel_hi:[1,0]

; #define LAS __attribute__((address_space(3)))
; __device__ __forceinline__ f32x4 mfma16(bf16x8 a, bf16x8 b, f32x4 c) { return __builtin_amdgcn_mfma_f32_16x16x32_bf16(a, b, c, 0, 0, 0); }
; template <int D, class SF>
; __device__ __forceinline__ void attn_step(const bf16x8 (&qf)[D / 32], const LAS bf16_t* Ks, const LAS bf16_t* Vt, f32x4 (&o)[D / 16], float& m, float& lsum, float& alpha_out, bf16x8& pf0_out, bf16x8& pf1_out, const int lane, SF sf) {
;     ...
;     for (int dt = 0; dt < D / 16; ++dt) {
;         const LAS bf16_t* vp = Vt + (16 * dt + c) * 72 + 4 * i;
;         union { u32x4 u; bf16x8 b; } vf0, vf1; const u32x2 a0 = *(const LAS u32x2*)vp, a1 = *(const LAS u32x2*)(vp + 16), b0 = *(const LAS u32x2*)(vp + 32), b1 = *(const LAS u32x2*)(vp + 48);
;         vf0.u.x = a0.x; vf0.u.y = a0.y; vf0.u.z = a1.x; vf0.u.w = a1.y; vf1.u.x = b0.x; vf1.u.y = b0.y; vf1.u.z = b1.x; vf1.u.w = b1.y;
;         o[dt] = mfma16(vf0.b, pk0.b, o[dt]); o[dt] = mfma16(vf1.b, pk1.b, o[dt]);
;     }
; __device__ __forceinline__ void memattn_unit(LAS unsigned char* lds, const Ctx& P, int unit) {
;     ...
;     const float inv = 1.0f / fmaxf(lsum, 1e-30f);
; #pragma unroll
;     for (int dt = 0; dt < 16; ++dt) { const int d0 = 16 * dt + 4 * i; const u32x2 g = *(const u32x2*)(H + tok * LDH + C_GM + head * 256 + d0);
.Lmem_nosc_4:
	s_waitcnt lgkmcnt(0)
	s_nop 1
	v_mfma_f32_16x16x32_bf16 v[34:37], v[130:133], v[114:117], v[34:37]
	v_mfma_f32_16x16x32_bf16 v[38:41], v[138:141], v[114:117], v[38:41]
	v_mfma_f32_16x16x32_bf16 v[42:45], v[146:149], v[114:117], v[42:45]
	v_mfma_f32_16x16x32_bf16 v[46:49], v[154:157], v[114:117], v[46:49]
	v_mfma_f32_16x16x32_bf16 v[34:37], v[134:137], v[118:121], v[34:37]
	v_mfma_f32_16x16x32_bf16 v[38:41], v[142:145], v[118:121], v[38:41]
	v_mfma_f32_16x16x32_bf16 v[42:45], v[150:153], v[118:121], v[42:45]
	v_mfma_f32_16x16x32_bf16 v[46:49], v[158:161], v[118:121], v[46:49]
	ds_read_b64_tr_b16 v[130:131], v205 offset:34048
	ds_read_b64_tr_b16 v[132:133], v205 offset:42496
	ds_read_b64_tr_b16 v[134:135], v205 offset:50944
	ds_read_b64_tr_b16 v[136:137], v205 offset:59392
	ds_read_b64_tr_b16 v[138:139], v205 offset:34080
	ds_read_b64_tr_b16 v[140:141], v205 offset:42528
	ds_read_b64_tr_b16 v[142:143], v205 offset:50976
	ds_read_b64_tr_b16 v[144:145], v205 offset:59424
	ds_read_b64_tr_b16 v[146:147], v205 offset:34112
	ds_read_b64_tr_b16 v[148:149], v205 offset:42560
	ds_read_b64_tr_b16 v[150:151], v205 offset:51008
	ds_read_b64_tr_b16 v[152:153], v205 offset:59456
	ds_read_b64_tr_b16 v[154:155], v205 offset:34144
	ds_read_b64_tr_b16 v[156:157], v205 offset:42592
	ds_read_b64_tr_b16 v[158:159], v205 offset:51040
	ds_read_b64_tr_b16 v[160:161], v205 offset:59488
	s_waitcnt lgkmcnt(15)
	v_mfma_f32_16x16x32_bf16 v[50:53], v[170:173], v[114:117], v[50:53]
	v_mfma_f32_16x16x32_bf16 v[54:57], v[178:181], v[114:117], v[54:57]
	v_mfma_f32_16x16x32_bf16 v[58:61], v[186:189], v[114:117], v[58:61]
	v_mfma_f32_16x16x32_bf16 v[62:65], v[194:197], v[114:117], v[62:65]
	v_mfma_f32_16x16x32_bf16 v[50:53], v[174:177], v[118:121], v[50:53]
	v_mfma_f32_16x16x32_bf16 v[54:57], v[182:185], v[118:121], v[54:57]
	v_mfma_f32_16x16x32_bf16 v[58:61], v[190:193], v[118:121], v[58:61]
	v_mfma_f32_16x16x32_bf16 v[62:65], v[198:201], v[118:121], v[62:65]
	ds_read_b64_tr_b16 v[170:171], v205 offset:34176
	ds_read_b64_tr_b16 v[172:173], v205 offset:42624
	ds_read_b64_tr_b16 v[174:175], v205 offset:51072
	ds_read_b64_tr_b16 v[176:177], v205 offset:59520
	ds_read_b64_tr_b16 v[178:179], v205 offset:34208
	ds_read_b64_tr_b16 v[180:181], v205 offset:42656
	ds_read_b64_tr_b16 v[182:183], v205 offset:51104
	ds_read_b64_tr_b16 v[184:185], v205 offset:59552
	ds_read_b64_tr_b16 v[186:187], v205 offset:34240
	ds_read_b64_tr_b16 v[188:189], v205 offset:42688
	ds_read_b64_tr_b16 v[190:191], v205 offset:51136
	ds_read_b64_tr_b16 v[192:193], v205 offset:59584
	ds_read_b64_tr_b16 v[194:195], v205 offset:34272
	ds_read_b64_tr_b16 v[196:197], v205 offset:42720
	ds_read_b64_tr_b16 v[198:199], v205 offset:51168
	ds_read_b64_tr_b16 v[200:201], v205 offset:59616
	s_waitcnt lgkmcnt(15)
	v_mfma_f32_16x16x32_bf16 v[66:69], v[130:133], v[114:117], v[66:69]
	v_mfma_f32_16x16x32_bf16 v[70:73], v[138:141], v[114:117], v[70:73]
	v_mfma_f32_16x16x32_bf16 v[74:77], v[146:149], v[114:117], v[74:77]
	v_mfma_f32_16x16x32_bf16 v[78:81], v[154:157], v[114:117], v[78:81]
	v_mfma_f32_16x16x32_bf16 v[66:69], v[134:137], v[118:121], v[66:69]
	v_mfma_f32_16x16x32_bf16 v[70:73], v[142:145], v[118:121], v[70:73]
	v_mfma_f32_16x16x32_bf16 v[74:77], v[150:153], v[118:121], v[74:77]
	v_mfma_f32_16x16x32_bf16 v[78:81], v[158:161], v[118:121], v[78:81]
	s_waitcnt lgkmcnt(0)
	v_mfma_f32_16x16x32_bf16 v[82:85], v[170:173], v[114:117], v[82:85]
	v_mfma_f32_16x16x32_bf16 v[86:89], v[178:181], v[114:117], v[86:89]
	v_mfma_f32_16x16x32_bf16 v[90:93], v[186:189], v[114:117], v[90:93]
	v_mfma_f32_16x16x32_bf16 v[94:97], v[194:197], v[114:117], v[94:97]
	v_mfma_f32_16x16x32_bf16 v[82:85], v[174:177], v[118:121], v[82:85]
	v_mfma_f32_16x16x32_bf16 v[86:89], v[182:185], v[118:121], v[86:89]
	v_mfma_f32_16x16x32_bf16 v[90:93], v[190:193], v[118:121], v[90:93]
	v_mfma_f32_16x16x32_bf16 v[94:97], v[198:201], v[118:121], v[94:97]
	global_load_dwordx2 v[130:131], v[214:215], off
	global_load_dwordx2 v[132:133], v[214:215], off offset:32
	global_load_dwordx2 v[134:135], v[214:215], off offset:64
	global_load_dwordx2 v[136:137], v[214:215], off offset:96
	global_load_dwordx2 v[138:139], v[214:215], off offset:128
	global_load_dwordx2 v[140:141], v[214:215], off offset:160
	global_load_dwordx2 v[142:143], v[214:215], off offset:192
	global_load_dwordx2 v[144:145], v[214:215], off offset:224
	global_load_dwordx2 v[170:171], v[214:215], off offset:256
	global_load_dwordx2 v[172:173], v[214:215], off offset:288
	global_load_dwordx2 v[174:175], v[214:215], off offset:320
	global_load_dwordx2 v[176:177], v[214:215], off offset:352
	global_load_dwordx2 v[178:179], v[214:215], off offset:384
	global_load_dwordx2 v[180:181], v[214:215], off offset:416
	global_load_dwordx2 v[182:183], v[214:215], off offset:448
	global_load_dwordx2 v[184:185], v[214:215], off offset:480
	v_max_f32_e32 v122, v208, v208
	v_max_f32_e32 v122, 0xda24260, v122
	v_div_scale_f32 v123, s[0:1], v122, v122, 1.0
	v_rcp_f32_e32 v124, v123
	s_nop 0
	v_fma_f32 v125, -v123, v124, 1.0
	v_fmac_f32_e32 v124, v125, v124
	v_div_scale_f32 v125, vcc, 1.0, v122, 1.0
	v_mul_f32_e32 v127, v125, v124
	v_fma_f32 v128, -v123, v127, v125
	v_fmac_f32_e32 v127, v128, v124
	v_fma_f32 v123, -v123, v127, v125
	v_div_fmas_f32 v123, v123, v124, v127
	v_div_fixup_f32 v129, v123, v122, 1.0
	s_waitcnt vmcnt(0)
; __device__ __forceinline__ unsigned cvt_pk_bf16(float lo, float hi) { unsigned r; asm("v_cvt_pk_bf16_f32 %0, %1, %2" : "=v"(r) : "v"(lo), "v"(hi)); return r; }
; __device__ __forceinline__ float bflo(unsigned w) { return __uint_as_float(w << 16); }
; __device__ __forceinline__ float bfhi(unsigned w) { return __uint_as_float(w & 0xffff0000u); }
; __device__ __forceinline__ void memattn_unit(LAS unsigned char* lds, const Ctx& P, int unit) {
;     ...
;     const float inv = 1.0f / fmaxf(lsum, 1e-30f);
; #pragma unroll
;     for (int dt = 0; dt < 16; ++dt) { const int d0 = 16 * dt + 4 * i; const u32x2 g = *(const u32x2*)(H + tok * LDH + C_GM + head * 256 + d0);
;         u32x2 w; w.x = cvt_pk_bf16(o[dt][0] * inv * bflo(g.x), o[dt][1] * inv * bfhi(g.x)); w.y = cvt_pk_bf16(o[dt][2] * inv * bflo(g.y), o[dt][3] * inv * bfhi(g.y));
;         *(u32x2*)(O + tok * DBR + head * 256 + d0) = w; }
	s_nop 7
	v_lshlrev_b32_e32 v122, 16, v130
	v_and_b32_e32 v123, 0xffff0000, v130
	v_mul_f32_e32 v124, v34, v129
	v_mul_f32_e32 v125, v35, v129
	v_mul_f32_e32 v124, v124, v122
	v_mul_f32_e32 v125, v125, v123
	v_cvt_pk_bf16_f32 v222, v124, v125
	v_lshlrev_b32_e32 v122, 16, v131
	v_and_b32_e32 v123, 0xffff0000, v131
	v_mul_f32_e32 v124, v36, v129
	v_mul_f32_e32 v125, v37, v129
	v_mul_f32_e32 v124, v124, v122
	v_mul_f32_e32 v125, v125, v123
	v_cvt_pk_bf16_f32 v223, v124, v125
	global_store_dwordx2 v221, v[222:223], s[4:5]
	v_lshlrev_b32_e32 v122, 16, v132
	v_and_b32_e32 v123, 0xffff0000, v132
	v_mul_f32_e32 v124, v38, v129
	v_mul_f32_e32 v125, v39, v129
	v_mul_f32_e32 v124, v124, v122
	v_mul_f32_e32 v125, v125, v123
	v_cvt_pk_bf16_f32 v222, v124, v125
	v_lshlrev_b32_e32 v122, 16, v133
	v_and_b32_e32 v123, 0xffff0000, v133
	v_mul_f32_e32 v124, v40, v129
	v_mul_f32_e32 v125, v41, v129
	v_mul_f32_e32 v124, v124, v122
	v_mul_f32_e32 v125, v125, v123
	v_cvt_pk_bf16_f32 v223, v124, v125
	global_store_dwordx2 v221, v[222:223], s[4:5] offset:32
	v_lshlrev_b32_e32 v122, 16, v134
	v_and_b32_e32 v123, 0xffff0000, v134
	v_mul_f32_e32 v124, v42, v129
	v_mul_f32_e32 v125, v43, v129
	v_mul_f32_e32 v124, v124, v122
	v_mul_f32_e32 v125, v125, v123
	v_cvt_pk_bf16_f32 v222, v124, v125
	v_lshlrev_b32_e32 v122, 16, v135
	v_and_b32_e32 v123, 0xffff0000, v135
	v_mul_f32_e32 v124, v44, v129
	v_mul_f32_e32 v125, v45, v129
	v_mul_f32_e32 v124, v124, v122
	v_mul_f32_e32 v125, v125, v123
	v_cvt_pk_bf16_f32 v223, v124, v125
	global_store_dwordx2 v221, v[222:223], s[4:5] offset:64
	v_lshlrev_b32_e32 v122, 16, v136
	v_and_b32_e32 v123, 0xffff0000, v136
	v_mul_f32_e32 v124, v46, v129
	v_mul_f32_e32 v125, v47, v129
	v_mul_f32_e32 v124, v124, v122
	v_mul_f32_e32 v125, v125, v123
	v_cvt_pk_bf16_f32 v222, v124, v125
	v_lshlrev_b32_e32 v122, 16, v137
	v_and_b32_e32 v123, 0xffff0000, v137
	v_mul_f32_e32 v124, v48, v129
	v_mul_f32_e32 v125, v49, v129
	v_mul_f32_e32 v124, v124, v122
	v_mul_f32_e32 v125, v125, v123
	v_cvt_pk_bf16_f32 v223, v124, v125
	global_store_dwordx2 v221, v[222:223], s[4:5] offset:96
	v_lshlrev_b32_e32 v122, 16, v138
	v_and_b32_e32 v123, 0xffff0000, v138
	v_mul_f32_e32 v124, v50, v129
	v_mul_f32_e32 v125, v51, v129
	v_mul_f32_e32 v124, v124, v122
	v_mul_f32_e32 v125, v125, v123
	v_cvt_pk_bf16_f32 v222, v124, v125
	v_lshlrev_b32_e32 v122, 16, v139
	v_and_b32_e32 v123, 0xffff0000, v139
	v_mul_f32_e32 v124, v52, v129
	v_mul_f32_e32 v125, v53, v129
	v_mul_f32_e32 v124, v124, v122
	v_mul_f32_e32 v125, v125, v123
	v_cvt_pk_bf16_f32 v223, v124, v125
	global_store_dwordx2 v221, v[222:223], s[4:5] offset:128
	v_lshlrev_b32_e32 v122, 16, v140
	v_and_b32_e32 v123, 0xffff0000, v140
	v_mul_f32_e32 v124, v54, v129
	v_mul_f32_e32 v125, v55, v129
	v_mul_f32_e32 v124, v124, v122
	v_mul_f32_e32 v125, v125, v123
	v_cvt_pk_bf16_f32 v222, v124, v125
	v_lshlrev_b32_e32 v122, 16, v141
	v_and_b32_e32 v123, 0xffff0000, v141
	v_mul_f32_e32 v124, v56, v129
	v_mul_f32_e32 v125, v57, v129
	v_mul_f32_e32 v124, v124, v122
	v_mul_f32_e32 v125, v125, v123
	v_cvt_pk_bf16_f32 v223, v124, v125
	global_store_dwordx2 v221, v[222:223], s[4:5] offset:160
	v_lshlrev_b32_e32 v122, 16, v142
	v_and_b32_e32 v123, 0xffff0000, v142
	v_mul_f32_e32 v124, v58, v129
	v_mul_f32_e32 v125, v59, v129
	v_mul_f32_e32 v124, v124, v122
	v_mul_f32_e32 v125, v125, v123
	v_cvt_pk_bf16_f32 v222, v124, v125
	v_lshlrev_b32_e32 v122, 16, v143
	v_and_b32_e32 v123, 0xffff0000, v143
	v_mul_f32_e32 v124, v60, v129
	v_mul_f32_e32 v125, v61, v129
	v_mul_f32_e32 v124, v124, v122
	v_mul_f32_e32 v125, v125, v123
	v_cvt_pk_bf16_f32 v223, v124, v125
	global_store_dwordx2 v221, v[222:223], s[4:5] offset:192
	v_lshlrev_b32_e32 v122, 16, v144
	v_and_b32_e32 v123, 0xffff0000, v144
	v_mul_f32_e32 v124, v62, v129
	v_mul_f32_e32 v125, v63, v129
	v_mul_f32_e32 v124, v124, v122
	v_mul_f32_e32 v125, v125, v123
	v_cvt_pk_bf16_f32 v222, v124, v125
	v_lshlrev_b32_e32 v122, 16, v145
	v_and_b32_e32 v123, 0xffff0000, v145
	v_mul_f32_e32 v124, v64, v129
	v_mul_f32_e32 v125, v65, v129
	v_mul_f32_e32 v124, v124, v122
	v_mul_f32_e32 v125, v125, v123
	v_cvt_pk_bf16_f32 v223, v124, v125
	global_store_dwordx2 v221, v[222:223], s[4:5] offset:224
	v_lshlrev_b32_e32 v122, 16, v170
	v_and_b32_e32 v123, 0xffff0000, v170
; __device__ __forceinline__ unsigned cvt_pk_bf16(float lo, float hi) { unsigned r; asm("v_cvt_pk_bf16_f32 %0, %1, %2" : "=v"(r) : "v"(lo), "v"(hi)); return r; }
; __device__ __forceinline__ float bflo(unsigned w) { return __uint_as_float(w << 16); }
; __device__ __forceinline__ float bfhi(unsigned w) { return __uint_as_float(w & 0xffff0000u); }
; __device__ __forceinline__ void memattn_unit(LAS unsigned char* lds, const Ctx& P, int unit) {
;     ...
;     const float inv = 1.0f / fmaxf(lsum, 1e-30f);
; #pragma unroll
;     for (int dt = 0; dt < 16; ++dt) { const int d0 = 16 * dt + 4 * i; const u32x2 g = *(const u32x2*)(H + tok * LDH + C_GM + head * 256 + d0);
;         u32x2 w; w.x = cvt_pk_bf16(o[dt][0] * inv * bflo(g.x), o[dt][1] * inv * bfhi(g.x)); w.y = cvt_pk_bf16(o[dt][2] * inv * bflo(g.y), o[dt][3] * inv * bfhi(g.y));
;         *(u32x2*)(O + tok * DBR + head * 256 + d0) = w; }
; __global__ void __launch_bounds__(512, 2) fwd_megakernel(Params PK) {
;     ...
;             for (int u = bid; u < 512; u += G) memattn_unit(lds, P, u);
	v_mul_f32_e32 v124, v66, v129
	v_mul_f32_e32 v125, v67, v129
	v_mul_f32_e32 v124, v124, v122
	v_mul_f32_e32 v125, v125, v123
	v_cvt_pk_bf16_f32 v222, v124, v125
	v_lshlrev_b32_e32 v122, 16, v171
	v_and_b32_e32 v123, 0xffff0000, v171
	v_mul_f32_e32 v124, v68, v129
	v_mul_f32_e32 v125, v69, v129
	v_mul_f32_e32 v124, v124, v122
	v_mul_f32_e32 v125, v125, v123
	v_cvt_pk_bf16_f32 v223, v124, v125
	global_store_dwordx2 v221, v[222:223], s[4:5] offset:256
	v_lshlrev_b32_e32 v122, 16, v172
	v_and_b32_e32 v123, 0xffff0000, v172
	v_mul_f32_e32 v124, v70, v129
	v_mul_f32_e32 v125, v71, v129
	v_mul_f32_e32 v124, v124, v122
	v_mul_f32_e32 v125, v125, v123
	v_cvt_pk_bf16_f32 v222, v124, v125
	v_lshlrev_b32_e32 v122, 16, v173
	v_and_b32_e32 v123, 0xffff0000, v173
	v_mul_f32_e32 v124, v72, v129
	v_mul_f32_e32 v125, v73, v129
	v_mul_f32_e32 v124, v124, v122
	v_mul_f32_e32 v125, v125, v123
	v_cvt_pk_bf16_f32 v223, v124, v125
	global_store_dwordx2 v221, v[222:223], s[4:5] offset:288
	v_lshlrev_b32_e32 v122, 16, v174
	v_and_b32_e32 v123, 0xffff0000, v174
	v_mul_f32_e32 v124, v74, v129
	v_mul_f32_e32 v125, v75, v129
	v_mul_f32_e32 v124, v124, v122
	v_mul_f32_e32 v125, v125, v123
	v_cvt_pk_bf16_f32 v222, v124, v125
	v_lshlrev_b32_e32 v122, 16, v175
	v_and_b32_e32 v123, 0xffff0000, v175
	v_mul_f32_e32 v124, v76, v129
	v_mul_f32_e32 v125, v77, v129
	v_mul_f32_e32 v124, v124, v122
	v_mul_f32_e32 v125, v125, v123
	v_cvt_pk_bf16_f32 v223, v124, v125
	global_store_dwordx2 v221, v[222:223], s[4:5] offset:320
	v_lshlrev_b32_e32 v122, 16, v176
	v_and_b32_e32 v123, 0xffff0000, v176
	v_mul_f32_e32 v124, v78, v129
	v_mul_f32_e32 v125, v79, v129
	v_mul_f32_e32 v124, v124, v122
	v_mul_f32_e32 v125, v125, v123
	v_cvt_pk_bf16_f32 v222, v124, v125
	v_lshlrev_b32_e32 v122, 16, v177
	v_and_b32_e32 v123, 0xffff0000, v177
	v_mul_f32_e32 v124, v80, v129
	v_mul_f32_e32 v125, v81, v129
	v_mul_f32_e32 v124, v124, v122
	v_mul_f32_e32 v125, v125, v123
	v_cvt_pk_bf16_f32 v223, v124, v125
	global_store_dwordx2 v221, v[222:223], s[4:5] offset:352
	v_lshlrev_b32_e32 v122, 16, v178
	v_and_b32_e32 v123, 0xffff0000, v178
	v_mul_f32_e32 v124, v82, v129
	v_mul_f32_e32 v125, v83, v129
	v_mul_f32_e32 v124, v124, v122
	v_mul_f32_e32 v125, v125, v123
	v_cvt_pk_bf16_f32 v222, v124, v125
	v_lshlrev_b32_e32 v122, 16, v179
	v_and_b32_e32 v123, 0xffff0000, v179
	v_mul_f32_e32 v124, v84, v129
	v_mul_f32_e32 v125, v85, v129
	v_mul_f32_e32 v124, v124, v122
	v_mul_f32_e32 v125, v125, v123
	v_cvt_pk_bf16_f32 v223, v124, v125
	global_store_dwordx2 v221, v[222:223], s[4:5] offset:384
	v_lshlrev_b32_e32 v122, 16, v180
	v_and_b32_e32 v123, 0xffff0000, v180
	v_mul_f32_e32 v124, v86, v129
	v_mul_f32_e32 v125, v87, v129
	v_mul_f32_e32 v124, v124, v122
	v_mul_f32_e32 v125, v125, v123
	v_cvt_pk_bf16_f32 v222, v124, v125
	v_lshlrev_b32_e32 v122, 16, v181
	v_and_b32_e32 v123, 0xffff0000, v181
	v_mul_f32_e32 v124, v88, v129
	v_mul_f32_e32 v125, v89, v129
	v_mul_f32_e32 v124, v124, v122
	v_mul_f32_e32 v125, v125, v123
	v_cvt_pk_bf16_f32 v223, v124, v125
	global_store_dwordx2 v221, v[222:223], s[4:5] offset:416
	v_lshlrev_b32_e32 v122, 16, v182
	v_and_b32_e32 v123, 0xffff0000, v182
	v_mul_f32_e32 v124, v90, v129
	v_mul_f32_e32 v125, v91, v129
	v_mul_f32_e32 v124, v124, v122
	v_mul_f32_e32 v125, v125, v123
	v_cvt_pk_bf16_f32 v222, v124, v125
	v_lshlrev_b32_e32 v122, 16, v183
	v_and_b32_e32 v123, 0xffff0000, v183
	v_mul_f32_e32 v124, v92, v129
	v_mul_f32_e32 v125, v93, v129
	v_mul_f32_e32 v124, v124, v122
	v_mul_f32_e32 v125, v125, v123
	v_cvt_pk_bf16_f32 v223, v124, v125
	global_store_dwordx2 v221, v[222:223], s[4:5] offset:448
	v_lshlrev_b32_e32 v122, 16, v184
	v_and_b32_e32 v123, 0xffff0000, v184
	v_mul_f32_e32 v124, v94, v129
	v_mul_f32_e32 v125, v95, v129
	v_mul_f32_e32 v124, v124, v122
	v_mul_f32_e32 v125, v125, v123
	v_cvt_pk_bf16_f32 v222, v124, v125
	v_lshlrev_b32_e32 v122, 16, v185
	v_and_b32_e32 v123, 0xffff0000, v185
	v_mul_f32_e32 v124, v96, v129
	v_mul_f32_e32 v125, v97, v129
	v_mul_f32_e32 v124, v124, v122
	v_mul_f32_e32 v125, v125, v123
	v_cvt_pk_bf16_f32 v223, v124, v125
	global_store_dwordx2 v221, v[222:223], s[4:5] offset:480
	s_add_u32 s7, s7, s34
	s_branch .Lmem_unit
.Lmem_done:
.LBB0_859:
	s_mov_b64 s[0:1], 0
	v_readlane_b32 s44, v255, 47
